# 127 XNACK-replay s_nop 0 pads between back-to-back global loads removed (the process runs xnack-)
# baseline (speedup 1.0000x reference)
; #define LAS __attribute__((address_space(3)))
; __device__ __forceinline__ void transpose_item_wg(const float* W, int K, int N, bf16* WT, int mode, const float* g0, const float* g1, int item, LAS float* scr, int tid, int lane, int wave) {
;     const int nblk = (N + 255) >> 8, kb = item / nblk, nb = item - kb * nblk, k0 = 64 * kb, n0 = 256 * nb, nw = min(256, N - n0);
;     const float* gk = g0 ? ((g1 && k0 >= 512) ? g1 + (k0 - 512) : g0 + k0) : nullptr;
;     if (4 * lane < nw) {
;         f32x4 v[8];
; #pragma unroll
;         for (int j = 0; j < 8; ++j) v[j] = __builtin_nontemporal_load((const f32x4*)(W + (size_t)(k0 + 8 * wave + j) * N + n0 + 4 * lane));
; #pragma unroll
;         for (int j = 0; j < 8; ++j) { const float gv = gk ? gk[8 * wave + j] : 1.0f; *(LAS f32x4*)(scr + (8 * wave + j) * 260 + 4 * lane) = v[j] * gv; }
.LBB0_32:
	s_xor_b32 s41, s41, 1
	s_mul_i32 s2, s41, 0x10400
	s_add_i32 s91, s97, 0x504
	s_add_i32 s96, s2, 0
	s_cmpk_gt_i32 s91, 0xaf
	s_mov_b64 s[2:3], -1
	s_cbranch_scc0 .LBB0_318
	s_cmpk_gt_u32 s91, 0x15f
	s_cbranch_scc0 .LBB0_299
	s_cmpk_gt_u32 s91, 0x20f
	s_cbranch_scc0 .LBB0_286
	s_cmpk_gt_u32 s91, 0x28f
	s_cbranch_scc0 .LBB0_211
	s_cmpk_gt_u32 s91, 0x29b
	s_cbranch_scc0 .LBB0_168
	s_cmpk_gt_u32 s91, 0x2a3
	s_cbranch_scc0 .LBB0_149
	s_cmpk_gt_u32 s91, 0x2e3
	s_cbranch_scc0 .LBB0_124
	s_cmpk_gt_u32 s91, 0x2f3
	s_cbranch_scc0 .LBB0_111
	s_cmpk_gt_u32 s91, 0x3a3
	s_cbranch_scc0 .LBB0_92
	s_cmpk_gt_u32 s91, 0x453
	s_cbranch_scc0 .LBB0_73
	s_cmpk_gt_u32 s91, 0x503
	s_cbranch_scc0 .LBB0_60
	s_lshr_b32 s2, s97, 2
	s_lshl_b32 s3, s2, 10
	s_lshl_b32 s18, s2, 6
	s_add_i32 s2, s40, s3
	s_min_i32 s16, s2, 0x100
	s_sub_i32 s4, 0xfffafc00, s3
	v_cmp_gt_i32_e32 vcc, s16, v141
	s_and_saveexec_b64 s[34:35], vcc
	s_cbranch_execz .LBB0_51
	v_readlane_b32 s1, v254, 27
	s_add_i32 s2, s1, s69
	s_add_i32 s2, s2, s4
	s_lshl_b64 s[30:31], s[18:19], 2
	v_readlane_b32 s1, v255, 50
	s_add_u32 s36, s1, s30
	v_readlane_b32 s1, v255, 52
	s_addc_u32 s37, s1, s31
	s_add_i32 s30, s18, s0
	s_ashr_i32 s3, s2, 31
	s_mov_b32 s31, s19
	v_lshl_add_u64 v[10:11], s[2:3], 2, v[40:41]
	s_lshl_b64 s[2:3], s[30:31], 12
	v_lshl_add_u64 v[2:3], v[10:11], 0, s[2:3]
	s_or_b32 s2, s30, 1
	s_mov_b32 s3, s19
	s_lshl_b64 s[2:3], s[2:3], 12
	v_lshl_add_u64 v[4:5], v[10:11], 0, s[2:3]
	s_or_b32 s2, s30, 2
	s_mov_b32 s3, s19
	s_lshl_b64 s[2:3], s[2:3], 12
	global_load_dwordx4 v[22:25], v[2:3], off nt
	global_load_dwordx4 v[26:29], v[4:5], off nt
	v_lshl_add_u64 v[2:3], v[10:11], 0, s[2:3]
	s_or_b32 s2, s30, 3
	s_mov_b32 s3, s19
	s_lshl_b64 s[2:3], s[2:3], 12
	v_lshl_add_u64 v[4:5], v[10:11], 0, s[2:3]
	s_or_b32 s2, s30, 4
	s_mov_b32 s3, s19
	s_lshl_b64 s[2:3], s[2:3], 12
	global_load_dwordx4 v[30:33], v[2:3], off nt
	global_load_dwordx4 v[18:21], v[4:5], off nt
	v_lshl_add_u64 v[2:3], v[10:11], 0, s[2:3]
	s_or_b32 s2, s30, 5
	s_mov_b32 s3, s19
	s_lshl_b64 s[2:3], s[2:3], 12
	v_lshl_add_u64 v[6:7], v[10:11], 0, s[2:3]
	s_or_b32 s2, s30, 6
	s_mov_b32 s3, s19
	s_lshl_b64 s[2:3], s[2:3], 12
	v_lshl_add_u64 v[12:13], v[10:11], 0, s[2:3]
	s_or_b32 s2, s30, 7
	s_mov_b32 s3, s19
	s_lshl_b64 s[2:3], s[2:3], 12
	v_lshl_add_u64 v[10:11], v[10:11], 0, s[2:3]
	global_load_dwordx4 v[2:5], v[2:3], off nt
	global_load_dwordx4 v[6:9], v[6:7], off nt
	global_load_dwordx4 v[14:17], v[12:13], off nt
	global_load_dwordx4 v[10:13], v[10:11], off nt
	v_readlane_b32 s30, v255, 54
	v_lshl_add_u32 v98, v141, 2, s96
	v_readlane_b32 s31, v255, 55
	v_readlane_b32 s17, v254, 49
	s_andn2_b64 vcc, exec, s[30:31]
	v_cndmask_b32_e64 v34, 0, 1, s[30:31]
	v_add_u32_e32 v147, s17, v98
	v_readlane_b32 s17, v252, 25
	v_cmp_ne_u32_e64 s[2:3], 1, v34
	s_nop 0
	v_add_u32_e32 v148, s17, v98
	s_cbranch_vccnz .LBB0_351
	s_lshl_b32 s17, s0, 2
	v_mov_b32_e32 v34, s17
	global_load_dwordx4 v[150:153], v34, s[36:37]
	s_waitcnt vmcnt(0)
	v_pk_mul_f32 v[36:37], v[24:25], v[150:151] op_sel_hi:[1,0]
	v_pk_mul_f32 v[34:35], v[22:23], v[150:151] op_sel_hi:[1,0]
	ds_write_b128 v147, v[34:37]
	v_pk_mul_f32 v[36:37], v[28:29], v[150:151] op_sel:[0,1]
	v_pk_mul_f32 v[34:35], v[26:27], v[150:151] op_sel:[0,1]
	ds_write_b128 v148, v[34:37]
	v_pk_mul_f32 v[36:37], v[32:33], v[152:153] op_sel_hi:[1,0]
	v_pk_mul_f32 v[34:35], v[30:31], v[152:153] op_sel_hi:[1,0]
	v_mov_b32_e32 v84, v153
	s_cbranch_execnz .LBB0_47

; #define LAS __attribute__((address_space(3)))
; __device__ __forceinline__ void transpose_item_wg(const float* W, int K, int N, bf16* WT, int mode, const float* g0, const float* g1, int item, LAS float* scr, int tid, int lane, int wave) {
;     const int nblk = (N + 255) >> 8, kb = item / nblk, nb = item - kb * nblk, k0 = 64 * kb, n0 = 256 * nb, nw = min(256, N - n0);
;     const float* gk = g0 ? ((g1 && k0 >= 512) ? g1 + (k0 - 512) : g0 + k0) : nullptr;
;     if (4 * lane < nw) {
;         f32x4 v[8];
; #pragma unroll
;         for (int j = 0; j < 8; ++j) v[j] = __builtin_nontemporal_load((const f32x4*)(W + (size_t)(k0 + 8 * wave + j) * N + n0 + 4 * lane));
; #pragma unroll
;         for (int j = 0; j < 8; ++j) { const float gv = gk ? gk[8 * wave + j] : 1.0f; *(LAS f32x4*)(scr + (8 * wave + j) * 260 + 4 * lane) = v[j] * gv; }
.LBB0_60:
	s_and_b64 vcc, exec, s[2:3]
	s_cbranch_vccz .LBB0_67
	s_lshl_b32 s2, s83, 8
	s_and_b32 s4, s2, 0xfffffc00
	s_lshl_b32 s2, s97, 4
	s_addk_i32 s2, 0xb00
	s_and_b32 s18, s2, 0xffffffc0
	s_add_i32 s2, s40, s4
	s_add_i32 s2, s2, 0xffff5000
	s_min_i32 s16, s2, 0x100
	v_cmp_gt_i32_e32 vcc, s16, v141
	s_and_saveexec_b64 s[2:3], vcc
	s_cbranch_execz .LBB0_63
	s_sub_i32 s17, s64, s4
	v_readlane_b32 s1, v254, 27
	s_add_i32 s30, s1, s17
	s_add_i32 s34, s18, s0
	s_ashr_i32 s31, s30, 31
	s_mov_b32 s35, s19
	v_lshl_add_u64 v[26:27], s[30:31], 2, v[44:45]
	s_lshl_b64 s[30:31], s[34:35], 12
	v_lshl_add_u64 v[2:3], v[26:27], 0, s[30:31]
	s_or_b32 s30, s34, 1
	s_mov_b32 s31, s19
	s_lshl_b64 s[30:31], s[30:31], 12
	v_lshl_add_u64 v[6:7], v[26:27], 0, s[30:31]
	s_or_b32 s30, s34, 2
	s_mov_b32 s31, s19
	s_lshl_b64 s[30:31], s[30:31], 12
	v_lshl_add_u64 v[10:11], v[26:27], 0, s[30:31]
	s_or_b32 s30, s34, 3
	s_mov_b32 s31, s19
	s_lshl_b64 s[30:31], s[30:31], 12
	v_lshl_add_u64 v[14:15], v[26:27], 0, s[30:31]
	s_or_b32 s30, s34, 4
	s_mov_b32 s31, s19
	s_lshl_b64 s[30:31], s[30:31], 12
	v_lshl_add_u64 v[18:19], v[26:27], 0, s[30:31]
	s_or_b32 s30, s34, 5
	s_mov_b32 s31, s19
	s_lshl_b64 s[30:31], s[30:31], 12
	v_lshl_add_u64 v[22:23], v[26:27], 0, s[30:31]
	s_or_b32 s30, s34, 6
	s_mov_b32 s31, s19
	s_lshl_b64 s[30:31], s[30:31], 12
	v_lshl_add_u64 v[28:29], v[26:27], 0, s[30:31]
	s_or_b32 s30, s34, 7
	s_mov_b32 s31, s19
	s_lshl_b64 s[30:31], s[30:31], 12
	v_lshl_add_u64 v[30:31], v[26:27], 0, s[30:31]
	global_load_dwordx4 v[2:5], v[2:3], off nt
	global_load_dwordx4 v[6:9], v[6:7], off nt
	global_load_dwordx4 v[10:13], v[10:11], off nt
	global_load_dwordx4 v[14:17], v[14:15], off nt
	global_load_dwordx4 v[18:21], v[18:19], off nt
	global_load_dwordx4 v[22:25], v[22:23], off nt
	global_load_dwordx4 v[26:29], v[28:29], off nt
	global_load_dwordx4 v[30:33], v[30:31], off nt
	v_readlane_b32 s1, v254, 49
	s_add_i32 s17, s1, s96
	v_lshl_add_u32 v34, v141, 2, s17
	s_waitcnt vmcnt(7)
	ds_write_b128 v34, v[2:5]
	s_waitcnt vmcnt(6)
	ds_write_b128 v34, v[6:9] offset:1040
	s_waitcnt vmcnt(5)
	ds_write_b128 v34, v[10:13] offset:2080
	s_waitcnt vmcnt(4)
	ds_write_b128 v34, v[14:17] offset:3120
	s_waitcnt vmcnt(3)
	ds_write_b128 v34, v[18:21] offset:4160
	s_waitcnt vmcnt(2)
	ds_write_b128 v34, v[22:25] offset:5200
	s_waitcnt vmcnt(1)
	ds_write_b128 v34, v[26:29] offset:6240
	s_waitcnt vmcnt(0)
	ds_write_b128 v34, v[30:33] offset:7280

; #define LAS __attribute__((address_space(3)))
; __device__ __forceinline__ void transpose_item_wg(const float* W, int K, int N, bf16* WT, int mode, const float* g0, const float* g1, int item, LAS float* scr, int tid, int lane, int wave) {
;     const int nblk = (N + 255) >> 8, kb = item / nblk, nb = item - kb * nblk, k0 = 64 * kb, n0 = 256 * nb, nw = min(256, N - n0);
;     const float* gk = g0 ? ((g1 && k0 >= 512) ? g1 + (k0 - 512) : g0 + k0) : nullptr;
;     if (4 * lane < nw) {
;         f32x4 v[8];
; #pragma unroll
;         for (int j = 0; j < 8; ++j) v[j] = __builtin_nontemporal_load((const f32x4*)(W + (size_t)(k0 + 8 * wave + j) * N + n0 + 4 * lane));
; #pragma unroll
;         for (int j = 0; j < 8; ++j) { const float gv = gk ? gk[8 * wave + j] : 1.0f; *(LAS f32x4*)(scr + (8 * wave + j) * 260 + 4 * lane) = v[j] * gv; }
.LBB0_74:
	s_add_i32 s3, s97, 0x160
	s_mul_i32 s4, s3, 0x75
	s_lshr_b32 s17, s4, 8
	s_sub_i32 s3, s3, s17
	s_and_b32 s2, s82, 0xff
	s_bfe_u32 s3, s3, 0x70001
	s_bfe_u32 s4, s4, 0x80008
	s_mul_hi_u32 s16, s2, 0x1745d175
	s_add_i32 s3, s3, s4
	s_mul_i32 s2, s16, 0xb00
	s_and_b32 s3, s3, 0xf8
	s_lshl_b32 s17, s3, 3
	s_add_i32 s3, s40, s2
	s_add_i32 s3, s3, 0xfffea700
	s_min_i32 s4, s3, 0x100
	v_cmp_gt_i32_e32 vcc, s4, v141
	s_and_saveexec_b64 s[34:35], vcc
	s_cbranch_execz .LBB0_82
	v_readlane_b32 s1, v254, 27
	s_add_i32 s3, s1, s69
	s_sub_i32 s2, s3, s2
	s_add_i32 s2, s2, 0xfffc5c00
	s_lshl_b32 s3, s17, 2
	v_readlane_b32 s1, v255, 46
	s_add_u32 s36, s1, s3
	v_readlane_b32 s1, v255, 48
	s_addc_u32 s37, s1, 0
	s_ashr_i32 s3, s2, 31
	s_add_i32 s18, s17, s0
	v_lshl_add_u64 v[2:3], s[2:3], 2, v[46:47]
	v_mad_u64_u32 v[4:5], s[2:3], s18, v198, v[2:3]
	s_or_b32 s2, s18, 1
	s_nop 0
	v_mad_u64_u32 v[6:7], s[2:3], s2, v198, v[2:3]
	s_or_b32 s2, s18, 2
	global_load_dwordx4 v[22:25], v[4:5], off nt
	global_load_dwordx4 v[26:29], v[6:7], off nt
	v_mad_u64_u32 v[4:5], s[2:3], s2, v198, v[2:3]
	s_or_b32 s2, s18, 3
	s_nop 0
	v_mad_u64_u32 v[6:7], s[2:3], s2, v198, v[2:3]
	s_or_b32 s2, s18, 4
	global_load_dwordx4 v[30:33], v[4:5], off nt
	global_load_dwordx4 v[18:21], v[6:7], off nt
	v_mad_u64_u32 v[4:5], s[2:3], s2, v198, v[2:3]
	s_or_b32 s2, s18, 5
	s_nop 0
	v_mad_u64_u32 v[10:11], s[2:3], s2, v198, v[2:3]
	s_or_b32 s2, s18, 6
	global_load_dwordx4 v[6:9], v[4:5], off nt
	global_load_dwordx4 v[10:13], v[10:11], off nt
	v_mad_u64_u32 v[4:5], s[2:3], s2, v198, v[2:3]
	s_or_b32 s2, s18, 7
	s_nop 0
	v_mad_u64_u32 v[2:3], s[2:3], s2, v198, v[2:3]
	global_load_dwordx4 v[14:17], v[4:5], off nt
	global_load_dwordx4 v[2:5], v[2:3], off nt
	v_lshl_add_u32 v98, v141, 2, s96
	v_readlane_b32 s18, v254, 49
	v_cndmask_b32_e64 v34, 0, 1, s[52:53]
	v_cmp_ne_u32_e64 s[2:3], 1, v34
	v_add_u32_e32 v147, s18, v98
	v_readlane_b32 s18, v252, 25
	s_andn2_b64 vcc, exec, s[52:53]
	s_nop 0
	v_add_u32_e32 v148, s18, v98
	s_cbranch_vccnz .LBB0_349
	s_lshl_b32 s18, s0, 2
	v_mov_b32_e32 v34, s18
	global_load_dwordx4 v[150:153], v34, s[36:37]
	s_waitcnt vmcnt(0)
	v_pk_mul_f32 v[36:37], v[24:25], v[150:151] op_sel_hi:[1,0]
	v_pk_mul_f32 v[34:35], v[22:23], v[150:151] op_sel_hi:[1,0]
	ds_write_b128 v147, v[34:37]
	v_pk_mul_f32 v[36:37], v[28:29], v[150:151] op_sel:[0,1]
	v_pk_mul_f32 v[34:35], v[26:27], v[150:151] op_sel:[0,1]
	ds_write_b128 v148, v[34:37]
	v_pk_mul_f32 v[36:37], v[32:33], v[152:153] op_sel_hi:[1,0]
	v_pk_mul_f32 v[34:35], v[30:31], v[152:153] op_sel_hi:[1,0]
	v_mov_b32_e32 v84, v153
	s_cbranch_execnz .LBB0_78

; #define LAS __attribute__((address_space(3)))
; __device__ __forceinline__ void transpose_item_wg(const float* W, int K, int N, bf16* WT, int mode, const float* g0, const float* g1, int item, LAS float* scr, int tid, int lane, int wave) {
;     const int nblk = (N + 255) >> 8, kb = item / nblk, nb = item - kb * nblk, k0 = 64 * kb, n0 = 256 * nb, nw = min(256, N - n0);
;     const float* gk = g0 ? ((g1 && k0 >= 512) ? g1 + (k0 - 512) : g0 + k0) : nullptr;
;     if (4 * lane < nw) {
;         f32x4 v[8];
; #pragma unroll
;         for (int j = 0; j < 8; ++j) v[j] = __builtin_nontemporal_load((const f32x4*)(W + (size_t)(k0 + 8 * wave + j) * N + n0 + 4 * lane));
; #pragma unroll
;         for (int j = 0; j < 8; ++j) { const float gv = gk ? gk[8 * wave + j] : 1.0f; *(LAS f32x4*)(scr + (8 * wave + j) * 260 + 4 * lane) = v[j] * gv; }
.LBB0_92:
	s_andn2_b64 vcc, exec, s[2:3]
	s_cbranch_vccnz .LBB0_110
	s_add_i32 s3, s97, 0x210
	s_mul_i32 s4, s3, 0x75
	s_lshr_b32 s17, s4, 8
	s_sub_i32 s3, s3, s17
	s_and_b32 s2, s80, 0xff
	s_bfe_u32 s3, s3, 0x70001
	s_bfe_u32 s4, s4, 0x80008
	s_mul_hi_u32 s16, s2, 0x1745d175
	s_add_i32 s3, s3, s4
	s_mul_i32 s2, s16, 0xb00
	s_and_b32 s3, s3, 0xf8
	s_lshl_b32 s17, s3, 3
	s_add_i32 s3, s40, s2
	s_add_i32 s3, s3, 0xfffdf700
	s_min_i32 s4, s3, 0x100
	v_cmp_gt_i32_e32 vcc, s4, v141
	s_and_saveexec_b64 s[34:35], vcc
	s_cbranch_execz .LBB0_101
	v_readlane_b32 s1, v254, 27
	s_add_i32 s3, s1, s69
	s_sub_i32 s2, s3, s2
	s_add_i32 s2, s2, 0xfffd0c00
	s_lshl_b32 s3, s17, 2
	v_readlane_b32 s1, v255, 46
	s_add_u32 s36, s1, s3
	v_readlane_b32 s1, v255, 48
	s_addc_u32 s37, s1, 0
	s_ashr_i32 s3, s2, 31
	s_add_i32 s18, s17, s0
	v_lshl_add_u64 v[2:3], s[2:3], 2, v[48:49]
	v_mad_u64_u32 v[4:5], s[2:3], s18, v198, v[2:3]
	s_or_b32 s2, s18, 1
	s_nop 0
	v_mad_u64_u32 v[6:7], s[2:3], s2, v198, v[2:3]
	s_or_b32 s2, s18, 2
	global_load_dwordx4 v[22:25], v[4:5], off nt
	global_load_dwordx4 v[26:29], v[6:7], off nt
	v_mad_u64_u32 v[4:5], s[2:3], s2, v198, v[2:3]
	s_or_b32 s2, s18, 3
	s_nop 0
	v_mad_u64_u32 v[6:7], s[2:3], s2, v198, v[2:3]
	s_or_b32 s2, s18, 4
	global_load_dwordx4 v[30:33], v[4:5], off nt
	global_load_dwordx4 v[18:21], v[6:7], off nt
	v_mad_u64_u32 v[4:5], s[2:3], s2, v198, v[2:3]
	s_or_b32 s2, s18, 5
	s_nop 0
	v_mad_u64_u32 v[10:11], s[2:3], s2, v198, v[2:3]
	s_or_b32 s2, s18, 6
	global_load_dwordx4 v[6:9], v[4:5], off nt
	global_load_dwordx4 v[10:13], v[10:11], off nt
	v_mad_u64_u32 v[4:5], s[2:3], s2, v198, v[2:3]
	s_or_b32 s2, s18, 7
	s_nop 0
	v_mad_u64_u32 v[2:3], s[2:3], s2, v198, v[2:3]
	global_load_dwordx4 v[14:17], v[4:5], off nt
	global_load_dwordx4 v[2:5], v[2:3], off nt
	v_lshl_add_u32 v98, v141, 2, s96
	v_readlane_b32 s18, v254, 49
	v_cndmask_b32_e64 v34, 0, 1, s[52:53]
	v_cmp_ne_u32_e64 s[2:3], 1, v34
	v_add_u32_e32 v147, s18, v98
	v_readlane_b32 s18, v252, 25
	s_andn2_b64 vcc, exec, s[52:53]
	s_nop 0
	v_add_u32_e32 v148, s18, v98
	s_cbranch_vccnz .LBB0_347
	s_lshl_b32 s18, s0, 2
	v_mov_b32_e32 v34, s18
	global_load_dwordx4 v[150:153], v34, s[36:37]
	s_waitcnt vmcnt(0)
	v_pk_mul_f32 v[36:37], v[24:25], v[150:151] op_sel_hi:[1,0]
	v_pk_mul_f32 v[34:35], v[22:23], v[150:151] op_sel_hi:[1,0]
	ds_write_b128 v147, v[34:37]
	v_pk_mul_f32 v[36:37], v[28:29], v[150:151] op_sel:[0,1]
	v_pk_mul_f32 v[34:35], v[26:27], v[150:151] op_sel:[0,1]
	ds_write_b128 v148, v[34:37]
	v_pk_mul_f32 v[36:37], v[32:33], v[152:153] op_sel_hi:[1,0]
	v_pk_mul_f32 v[34:35], v[30:31], v[152:153] op_sel_hi:[1,0]
	v_mov_b32_e32 v84, v153
	s_cbranch_execnz .LBB0_97

; #define LAS __attribute__((address_space(3)))
; __device__ __forceinline__ void transpose_item_wg(const float* W, int K, int N, bf16* WT, int mode, const float* g0, const float* g1, int item, LAS float* scr, int tid, int lane, int wave) {
;     const int nblk = (N + 255) >> 8, kb = item / nblk, nb = item - kb * nblk, k0 = 64 * kb, n0 = 256 * nb, nw = min(256, N - n0);
;     const float* gk = g0 ? ((g1 && k0 >= 512) ? g1 + (k0 - 512) : g0 + k0) : nullptr;
;     if (4 * lane < nw) {
;         f32x4 v[8];
; #pragma unroll
;         for (int j = 0; j < 8; ++j) v[j] = __builtin_nontemporal_load((const f32x4*)(W + (size_t)(k0 + 8 * wave + j) * N + n0 + 4 * lane));
; #pragma unroll
;         for (int j = 0; j < 8; ++j) { const float gv = gk ? gk[8 * wave + j] : 1.0f; *(LAS f32x4*)(scr + (8 * wave + j) * 260 + 4 * lane) = v[j] * gv; }
.LBB0_111:
	s_andn2_b64 vcc, exec, s[2:3]
	s_cbranch_vccnz .LBB0_123
	s_lshl_b32 s2, s79, 8
	s_and_b32 s4, s2, 0xfffffc00
	s_lshl_b32 s2, s97, 4
	s_addk_i32 s2, 0x2200
	s_and_b32 s18, s2, 0xffffffc0
	s_add_i32 s2, s40, s4
	s_add_i32 s2, s2, 0xfffde000
	s_min_i32 s16, s2, 0x100
	v_cmp_gt_i32_e32 vcc, s16, v141
	s_and_saveexec_b64 s[2:3], vcc
	s_cbranch_execz .LBB0_114
	s_sub_i32 s17, s65, s4
	v_readlane_b32 s1, v254, 27
	s_add_i32 s30, s1, s17
	s_add_i32 s34, s18, s0
	s_ashr_i32 s31, s30, 31
	s_mov_b32 s35, s19
	v_lshl_add_u64 v[26:27], s[30:31], 2, v[50:51]
	s_lshl_b64 s[30:31], s[34:35], 12
	v_lshl_add_u64 v[2:3], v[26:27], 0, s[30:31]
	s_or_b32 s30, s34, 1
	s_mov_b32 s31, s19
	s_lshl_b64 s[30:31], s[30:31], 12
	v_lshl_add_u64 v[6:7], v[26:27], 0, s[30:31]
	s_or_b32 s30, s34, 2
	s_mov_b32 s31, s19
	s_lshl_b64 s[30:31], s[30:31], 12
	v_lshl_add_u64 v[10:11], v[26:27], 0, s[30:31]
	s_or_b32 s30, s34, 3
	s_mov_b32 s31, s19
	s_lshl_b64 s[30:31], s[30:31], 12
	v_lshl_add_u64 v[14:15], v[26:27], 0, s[30:31]
	s_or_b32 s30, s34, 4
	s_mov_b32 s31, s19
	s_lshl_b64 s[30:31], s[30:31], 12
	v_lshl_add_u64 v[18:19], v[26:27], 0, s[30:31]
	s_or_b32 s30, s34, 5
	s_mov_b32 s31, s19
	s_lshl_b64 s[30:31], s[30:31], 12
	v_lshl_add_u64 v[22:23], v[26:27], 0, s[30:31]
	s_or_b32 s30, s34, 6
	s_mov_b32 s31, s19
	s_lshl_b64 s[30:31], s[30:31], 12
	v_lshl_add_u64 v[28:29], v[26:27], 0, s[30:31]
	s_or_b32 s30, s34, 7
	s_mov_b32 s31, s19
	s_lshl_b64 s[30:31], s[30:31], 12
	v_lshl_add_u64 v[30:31], v[26:27], 0, s[30:31]
	global_load_dwordx4 v[2:5], v[2:3], off nt
	global_load_dwordx4 v[6:9], v[6:7], off nt
	global_load_dwordx4 v[10:13], v[10:11], off nt
	global_load_dwordx4 v[14:17], v[14:15], off nt
	global_load_dwordx4 v[18:21], v[18:19], off nt
	global_load_dwordx4 v[22:25], v[22:23], off nt
	global_load_dwordx4 v[26:29], v[28:29], off nt
	global_load_dwordx4 v[30:33], v[30:31], off nt
	v_readlane_b32 s1, v254, 49
	s_add_i32 s17, s1, s96
	v_lshl_add_u32 v34, v141, 2, s17
	s_waitcnt vmcnt(7)
	ds_write_b128 v34, v[2:5]
	s_waitcnt vmcnt(6)
	ds_write_b128 v34, v[6:9] offset:1040
	s_waitcnt vmcnt(5)
	ds_write_b128 v34, v[10:13] offset:2080
	s_waitcnt vmcnt(4)
	ds_write_b128 v34, v[14:17] offset:3120
	s_waitcnt vmcnt(3)
	ds_write_b128 v34, v[18:21] offset:4160
	s_waitcnt vmcnt(2)
	ds_write_b128 v34, v[22:25] offset:5200
	s_waitcnt vmcnt(1)
	ds_write_b128 v34, v[26:29] offset:6240
	s_waitcnt vmcnt(0)
	ds_write_b128 v34, v[30:33] offset:7280

; #define LAS __attribute__((address_space(3)))
; __device__ __forceinline__ void transpose_item_wg(const float* W, int K, int N, bf16* WT, int mode, const float* g0, const float* g1, int item, LAS float* scr, int tid, int lane, int wave) {
;     const int nblk = (N + 255) >> 8, kb = item / nblk, nb = item - kb * nblk, k0 = 64 * kb, n0 = 256 * nb, nw = min(256, N - n0);
;     const float* gk = g0 ? ((g1 && k0 >= 512) ? g1 + (k0 - 512) : g0 + k0) : nullptr;
;     if (4 * lane < nw) {
;         f32x4 v[8];
; #pragma unroll
;         for (int j = 0; j < 8; ++j) v[j] = __builtin_nontemporal_load((const f32x4*)(W + (size_t)(k0 + 8 * wave + j) * N + n0 + 4 * lane));
; #pragma unroll
;         for (int j = 0; j < 8; ++j) { const float gv = gk ? gk[8 * wave + j] : 1.0f; *(LAS f32x4*)(scr + (8 * wave + j) * 260 + 4 * lane) = v[j] * gv; }
.LBB0_131:
	s_lshl_b32 s2, s78, 8
	s_and_b32 s4, s2, 0xfffffc00
	s_add_i32 s2, s40, s4
	s_add_i32 s2, s2, 0xfffda000
	s_min_i32 s16, s2, 0x100
	v_cmp_gt_i32_e32 vcc, s16, v141
	s_and_saveexec_b64 s[2:3], vcc
	s_cbranch_execz .LBB0_139
	s_sub_i32 s17, s66, s4
	v_readlane_b32 s1, v254, 27
	s_add_i32 s30, s1, s17
	s_add_i32 s36, s18, s0
	s_ashr_i32 s31, s30, 31
	s_mov_b32 s37, s19
	v_lshl_add_u64 v[10:11], s[30:31], 2, v[52:53]
	s_lshl_b64 s[30:31], s[36:37], 12
	v_lshl_add_u64 v[2:3], v[10:11], 0, s[30:31]
	s_or_b32 s30, s36, 1
	s_mov_b32 s31, s19
	s_lshl_b64 s[30:31], s[30:31], 12
	v_lshl_add_u64 v[4:5], v[10:11], 0, s[30:31]
	s_or_b32 s30, s36, 2
	s_mov_b32 s31, s19
	s_lshl_b64 s[30:31], s[30:31], 12
	global_load_dwordx4 v[22:25], v[2:3], off nt
	global_load_dwordx4 v[26:29], v[4:5], off nt
	v_lshl_add_u64 v[2:3], v[10:11], 0, s[30:31]
	s_or_b32 s30, s36, 3
	s_mov_b32 s31, s19
	s_lshl_b64 s[30:31], s[30:31], 12
	v_lshl_add_u64 v[4:5], v[10:11], 0, s[30:31]
	s_or_b32 s30, s36, 4
	s_mov_b32 s31, s19
	s_lshl_b64 s[30:31], s[30:31], 12
	global_load_dwordx4 v[30:33], v[2:3], off nt
	global_load_dwordx4 v[18:21], v[4:5], off nt
	v_lshl_add_u64 v[2:3], v[10:11], 0, s[30:31]
	s_or_b32 s30, s36, 5
	s_mov_b32 s31, s19
	s_lshl_b64 s[30:31], s[30:31], 12
	v_lshl_add_u64 v[6:7], v[10:11], 0, s[30:31]
	s_or_b32 s30, s36, 6
	s_mov_b32 s31, s19
	s_lshl_b64 s[30:31], s[30:31], 12
	v_lshl_add_u64 v[12:13], v[10:11], 0, s[30:31]
	s_or_b32 s30, s36, 7
	s_mov_b32 s31, s19
	s_lshl_b64 s[30:31], s[30:31], 12
	v_lshl_add_u64 v[10:11], v[10:11], 0, s[30:31]
	global_load_dwordx4 v[2:5], v[2:3], off nt
	global_load_dwordx4 v[6:9], v[6:7], off nt
	global_load_dwordx4 v[14:17], v[12:13], off nt
	global_load_dwordx4 v[10:13], v[10:11], off nt
	v_lshl_add_u32 v98, v141, 2, s96
	v_readlane_b32 s17, v254, 49
	s_cmp_lg_u64 s[34:35], 0
	s_cselect_b64 s[36:37], -1, 0
	v_add_u32_e32 v147, s17, v98
	v_readlane_b32 s17, v252, 25
	s_cmp_eq_u64 s[34:35], 0
	s_nop 0
	v_add_u32_e32 v148, s17, v98
	s_cbranch_scc1 .LBB0_345
	s_lshl_b32 s17, s0, 2
	v_mov_b32_e32 v34, s17
	global_load_dwordx4 v[150:153], v34, s[34:35]
	s_waitcnt vmcnt(0)
	v_pk_mul_f32 v[36:37], v[24:25], v[150:151] op_sel_hi:[1,0]
	v_pk_mul_f32 v[34:35], v[22:23], v[150:151] op_sel_hi:[1,0]
	ds_write_b128 v147, v[34:37]
	v_pk_mul_f32 v[36:37], v[28:29], v[150:151] op_sel:[0,1]
	v_pk_mul_f32 v[34:35], v[26:27], v[150:151] op_sel:[0,1]
	ds_write_b128 v148, v[34:37]
	v_pk_mul_f32 v[36:37], v[32:33], v[152:153] op_sel_hi:[1,0]
	v_pk_mul_f32 v[34:35], v[30:31], v[152:153] op_sel_hi:[1,0]
	v_mov_b32_e32 v84, v153
	s_cbranch_execnz .LBB0_135

; #define LAS __attribute__((address_space(3)))
; __device__ __forceinline__ void transpose_item_wg(const float* W, int K, int N, bf16* WT, int mode, const float* g0, const float* g1, int item, LAS float* scr, int tid, int lane, int wave) {
;     const int nblk = (N + 255) >> 8, kb = item / nblk, nb = item - kb * nblk, k0 = 64 * kb, n0 = 256 * nb, nw = min(256, N - n0);
;     const float* gk = g0 ? ((g1 && k0 >= 512) ? g1 + (k0 - 512) : g0 + k0) : nullptr;
;     if (4 * lane < nw) {
;         f32x4 v[8];
; #pragma unroll
;         for (int j = 0; j < 8; ++j) v[j] = __builtin_nontemporal_load((const f32x4*)(W + (size_t)(k0 + 8 * wave + j) * N + n0 + 4 * lane));
; #pragma unroll
;         for (int j = 0; j < 8; ++j) { const float gv = gk ? gk[8 * wave + j] : 1.0f; *(LAS f32x4*)(scr + (8 * wave + j) * 260 + 4 * lane) = v[j] * gv; }
.LBB0_149:
	s_andn2_b64 vcc, exec, s[2:3]
	s_cbranch_vccnz .LBB0_167
	s_add_i32 s2, s97, 0x268
	s_cmp_gt_u32 s2, 3
	s_cselect_b32 s2, -4, 0
	s_cselect_b32 s16, 64, 0
	s_add_i32 s2, s2, s97
	s_lshl_b32 s2, s2, 8
	s_add_i32 s34, s2, 0x26800
	s_sub_i32 s2, 0xfffd9c00, s2
	s_min_i32 s4, s2, 0x100
	v_cmp_gt_i32_e32 vcc, s4, v141
	s_and_saveexec_b64 s[36:37], vcc
	s_cbranch_execz .LBB0_158
	s_lshl_b32 s2, s16, 2
	s_add_u32 s60, s89, s2
	s_addc_u32 s61, s90, 0
	s_add_i32 s18, s16, s0
	s_ashr_i32 s35, s34, 31
	v_lshl_add_u64 v[10:11], s[34:35], 2, v[58:59]
	s_lshl_b64 s[2:3], s[18:19], 12
	v_lshl_add_u64 v[2:3], v[10:11], 0, s[2:3]
	s_or_b32 s2, s18, 1
	s_mov_b32 s3, s19
	s_lshl_b64 s[2:3], s[2:3], 12
	v_lshl_add_u64 v[4:5], v[10:11], 0, s[2:3]
	s_or_b32 s2, s18, 2
	s_mov_b32 s3, s19
	s_lshl_b64 s[2:3], s[2:3], 12
	global_load_dwordx4 v[22:25], v[2:3], off nt
	global_load_dwordx4 v[26:29], v[4:5], off nt
	v_lshl_add_u64 v[2:3], v[10:11], 0, s[2:3]
	s_or_b32 s2, s18, 3
	s_mov_b32 s3, s19
	s_lshl_b64 s[2:3], s[2:3], 12
	v_lshl_add_u64 v[4:5], v[10:11], 0, s[2:3]
	s_or_b32 s2, s18, 4
	s_mov_b32 s3, s19
	s_lshl_b64 s[2:3], s[2:3], 12
	global_load_dwordx4 v[30:33], v[2:3], off nt
	global_load_dwordx4 v[18:21], v[4:5], off nt
	v_lshl_add_u64 v[2:3], v[10:11], 0, s[2:3]
	s_or_b32 s2, s18, 5
	s_mov_b32 s3, s19
	s_lshl_b64 s[2:3], s[2:3], 12
	v_lshl_add_u64 v[6:7], v[10:11], 0, s[2:3]
	s_or_b32 s2, s18, 6
	s_mov_b32 s3, s19
	s_lshl_b64 s[2:3], s[2:3], 12
	s_or_b32 s18, s18, 7
	v_lshl_add_u64 v[12:13], v[10:11], 0, s[2:3]
	s_lshl_b64 s[2:3], s[18:19], 12
	v_lshl_add_u64 v[10:11], v[10:11], 0, s[2:3]
	global_load_dwordx4 v[2:5], v[2:3], off nt
	global_load_dwordx4 v[6:9], v[6:7], off nt
	global_load_dwordx4 v[14:17], v[12:13], off nt
	global_load_dwordx4 v[10:13], v[10:11], off nt
	v_lshl_add_u32 v98, v141, 2, s96
	v_readlane_b32 s17, v254, 49
	v_cndmask_b32_e64 v34, 0, 1, s[10:11]
	v_cmp_ne_u32_e64 s[2:3], 1, v34
	v_add_u32_e32 v147, s17, v98
	v_readlane_b32 s17, v252, 25
	s_andn2_b64 vcc, exec, s[10:11]
	s_nop 0
	v_add_u32_e32 v148, s17, v98
	s_cbranch_vccnz .LBB0_343
	s_lshl_b32 s17, s0, 2
	v_mov_b32_e32 v34, s17
	global_load_dwordx4 v[150:153], v34, s[60:61]
	s_waitcnt vmcnt(0)
	v_pk_mul_f32 v[36:37], v[24:25], v[150:151] op_sel_hi:[1,0]
	v_pk_mul_f32 v[34:35], v[22:23], v[150:151] op_sel_hi:[1,0]
	ds_write_b128 v147, v[34:37]
	v_pk_mul_f32 v[36:37], v[28:29], v[150:151] op_sel:[0,1]
	v_pk_mul_f32 v[34:35], v[26:27], v[150:151] op_sel:[0,1]
	ds_write_b128 v148, v[34:37]
	v_pk_mul_f32 v[36:37], v[32:33], v[152:153] op_sel_hi:[1,0]
	v_pk_mul_f32 v[34:35], v[30:31], v[152:153] op_sel_hi:[1,0]
	v_mov_b32_e32 v84, v153
	s_cbranch_execnz .LBB0_154

; #define LAS __attribute__((address_space(3)))
; __device__ __forceinline__ void transpose_item_wg(const float* W, int K, int N, bf16* WT, int mode, const float* g0, const float* g1, int item, LAS float* scr, int tid, int lane, int wave) {
;     const int nblk = (N + 255) >> 8, kb = item / nblk, nb = item - kb * nblk, k0 = 64 * kb, n0 = 256 * nb, nw = min(256, N - n0);
;     const float* gk = g0 ? ((g1 && k0 >= 512) ? g1 + (k0 - 512) : g0 + k0) : nullptr;
;     if (4 * lane < nw) {
;         f32x4 v[8];
; #pragma unroll
;         for (int j = 0; j < 8; ++j) v[j] = __builtin_nontemporal_load((const f32x4*)(W + (size_t)(k0 + 8 * wave + j) * N + n0 + 4 * lane));
; #pragma unroll
;         for (int j = 0; j < 8; ++j) { const float gv = gk ? gk[8 * wave + j] : 1.0f; *(LAS f32x4*)(scr + (8 * wave + j) * 260 + 4 * lane) = v[j] * gv; }
.LBB0_168:
	s_andn2_b64 vcc, exec, s[2:3]
	s_cbranch_vccnz .LBB0_210
	s_and_b32 s2, s77, 0xff
	s_mul_hi_u32 s4, s2, 0x55555556
	s_mul_i32 s2, s97, 0xab
	s_mulk_i32 s4, 0x300
	s_add_i32 s2, s2, 0xa37c
	s_bfe_u32 s17, s2, 0x70009
	s_add_i32 s2, s40, s4
	s_add_i32 s2, s2, 0xfffd8b00
	s_min_i32 s16, s2, 0x100
	s_lshl_b32 s18, s17, 6
	v_cmp_gt_i32_e32 vcc, s16, v141
	s_and_saveexec_b64 s[34:35], vcc
	s_cbranch_execz .LBB0_177
	s_sub_i32 s2, s67, s4
	v_readlane_b32 s1, v254, 27
	s_add_i32 s2, s1, s2
	s_lshl_b32 s3, s18, 2
	s_add_u32 s36, s87, s3
	s_addc_u32 s37, s88, 0
	s_ashr_i32 s3, s2, 31
	s_add_i32 s22, s18, s0
	v_lshl_add_u64 v[2:3], s[2:3], 2, v[62:63]
	v_mad_u64_u32 v[4:5], s[2:3], s22, v199, v[2:3]
	s_or_b32 s2, s22, 1
	s_nop 0
	v_mad_u64_u32 v[6:7], s[2:3], s2, v199, v[2:3]
	s_or_b32 s2, s22, 2
	global_load_dwordx4 v[22:25], v[4:5], off nt
	global_load_dwordx4 v[26:29], v[6:7], off nt
	v_mad_u64_u32 v[4:5], s[2:3], s2, v199, v[2:3]
	s_or_b32 s2, s22, 3
	s_nop 0
	v_mad_u64_u32 v[6:7], s[2:3], s2, v199, v[2:3]
	s_or_b32 s2, s22, 4
	global_load_dwordx4 v[30:33], v[4:5], off nt
	global_load_dwordx4 v[18:21], v[6:7], off nt
	v_mad_u64_u32 v[4:5], s[2:3], s2, v199, v[2:3]
	s_or_b32 s2, s22, 5
	s_nop 0
	v_mad_u64_u32 v[10:11], s[2:3], s2, v199, v[2:3]
	s_or_b32 s2, s22, 6
	global_load_dwordx4 v[6:9], v[4:5], off nt
	global_load_dwordx4 v[10:13], v[10:11], off nt
	v_mad_u64_u32 v[4:5], s[2:3], s2, v199, v[2:3]
	s_or_b32 s2, s22, 7
	s_nop 0
	v_mad_u64_u32 v[2:3], s[2:3], s2, v199, v[2:3]
	global_load_dwordx4 v[14:17], v[4:5], off nt
	global_load_dwordx4 v[2:5], v[2:3], off nt
	v_lshl_add_u32 v98, v141, 2, s96
	v_readlane_b32 s22, v254, 49
	v_cndmask_b32_e64 v34, 0, 1, s[50:51]
	v_cmp_ne_u32_e64 s[2:3], 1, v34
	v_add_u32_e32 v147, s22, v98
	v_readlane_b32 s22, v252, 25
	s_andn2_b64 vcc, exec, s[50:51]
	s_nop 0
	v_add_u32_e32 v148, s22, v98
	s_cbranch_vccnz .LBB0_341
	s_lshl_b32 s22, s0, 2
	v_mov_b32_e32 v34, s22
	global_load_dwordx4 v[150:153], v34, s[36:37]
	s_waitcnt vmcnt(0)
	v_pk_mul_f32 v[36:37], v[24:25], v[150:151] op_sel_hi:[1,0]
	v_pk_mul_f32 v[34:35], v[22:23], v[150:151] op_sel_hi:[1,0]
	ds_write_b128 v147, v[34:37]
	v_pk_mul_f32 v[36:37], v[28:29], v[150:151] op_sel:[0,1]
	v_pk_mul_f32 v[34:35], v[26:27], v[150:151] op_sel:[0,1]
	ds_write_b128 v148, v[34:37]
	v_pk_mul_f32 v[36:37], v[32:33], v[152:153] op_sel_hi:[1,0]
	v_pk_mul_f32 v[34:35], v[30:31], v[152:153] op_sel_hi:[1,0]
	v_mov_b32_e32 v84, v153
	s_cbranch_execnz .LBB0_173

; #define LAS __attribute__((address_space(3)))
; __device__ __forceinline__ void transpose_item_wg(const float* W, int K, int N, bf16* WT, int mode, const float* g0, const float* g1, int item, LAS float* scr, int tid, int lane, int wave) {
;     const int nblk = (N + 255) >> 8, kb = item / nblk, nb = item - kb * nblk, k0 = 64 * kb, n0 = 256 * nb, nw = min(256, N - n0);
;     const float* gk = g0 ? ((g1 && k0 >= 512) ? g1 + (k0 - 512) : g0 + k0) : nullptr;
;     if (4 * lane < nw) {
;         f32x4 v[8];
; #pragma unroll
;         for (int j = 0; j < 8; ++j) v[j] = __builtin_nontemporal_load((const f32x4*)(W + (size_t)(k0 + 8 * wave + j) * N + n0 + 4 * lane));
; #pragma unroll
;         for (int j = 0; j < 8; ++j) { const float gv = gk ? gk[8 * wave + j] : 1.0f; *(LAS f32x4*)(scr + (8 * wave + j) * 260 + 4 * lane) = v[j] * gv; }
.LBB0_211:
	s_andn2_b64 vcc, exec, s[2:3]
	s_cbranch_vccnz .LBB0_285
	s_lshr_b32 s17, s76, 3
	s_lshl_b32 s2, s17, 11
	s_sub_i32 s4, 0xfffdf000, s2
	s_add_i32 s2, s40, s2
	s_add_i32 s3, s97, 0x2f4
	s_add_i32 s2, s2, 0xfffd0fc0
	s_lshr_b32 s22, s3, 3
	s_min_i32 s16, s2, 0x100
	s_lshl_b32 s18, s22, 6
	v_cmp_gt_i32_e32 vcc, s16, v141
	s_and_saveexec_b64 s[34:35], vcc
	s_cbranch_execz .LBB0_220
	v_readlane_b32 s1, v254, 27
	s_add_i32 s2, s1, s69
	s_add_i32 s2, s2, s4
	s_lshl_b64 s[30:31], s[18:19], 2
	s_add_u32 s36, s85, s30
	s_addc_u32 s37, s86, s31
	s_ashr_i32 s3, s2, 31
	s_add_i32 s28, s18, s0
	v_lshl_add_u64 v[2:3], s[2:3], 2, v[64:65]
	v_mad_u64_u32 v[4:5], s[2:3], s28, v200, v[2:3]
	s_or_b32 s2, s28, 1
	s_nop 0
	v_mad_u64_u32 v[6:7], s[2:3], s2, v200, v[2:3]
	s_or_b32 s2, s28, 2
	global_load_dwordx4 v[22:25], v[4:5], off nt
	global_load_dwordx4 v[26:29], v[6:7], off nt
	v_mad_u64_u32 v[4:5], s[2:3], s2, v200, v[2:3]
	s_or_b32 s2, s28, 3
	s_nop 0
	v_mad_u64_u32 v[6:7], s[2:3], s2, v200, v[2:3]
	s_or_b32 s2, s28, 4
	global_load_dwordx4 v[30:33], v[4:5], off nt
	global_load_dwordx4 v[18:21], v[6:7], off nt
	v_mad_u64_u32 v[4:5], s[2:3], s2, v200, v[2:3]
	s_or_b32 s2, s28, 5
	s_nop 0
	v_mad_u64_u32 v[10:11], s[2:3], s2, v200, v[2:3]
	s_or_b32 s2, s28, 6
	global_load_dwordx4 v[6:9], v[4:5], off nt
	global_load_dwordx4 v[10:13], v[10:11], off nt
	v_mad_u64_u32 v[4:5], s[2:3], s2, v200, v[2:3]
	s_or_b32 s2, s28, 7
	s_nop 0
	v_mad_u64_u32 v[2:3], s[2:3], s2, v200, v[2:3]
	global_load_dwordx4 v[14:17], v[4:5], off nt
	global_load_dwordx4 v[2:5], v[2:3], off nt
	v_lshl_add_u32 v98, v141, 2, s96
	v_readlane_b32 s28, v254, 49
	v_cndmask_b32_e64 v34, 0, 1, s[54:55]
	v_cmp_ne_u32_e64 s[2:3], 1, v34
	v_add_u32_e32 v147, s28, v98
	v_readlane_b32 s28, v252, 25
	s_andn2_b64 vcc, exec, s[54:55]
	s_nop 0
	v_add_u32_e32 v148, s28, v98
	s_cbranch_vccnz .LBB0_339
	s_lshl_b32 s28, s0, 2
	v_mov_b32_e32 v34, s28
	global_load_dwordx4 v[150:153], v34, s[36:37]
	s_waitcnt vmcnt(0)
	v_pk_mul_f32 v[36:37], v[24:25], v[150:151] op_sel_hi:[1,0]
	v_pk_mul_f32 v[34:35], v[22:23], v[150:151] op_sel_hi:[1,0]
	ds_write_b128 v147, v[34:37]
	v_pk_mul_f32 v[36:37], v[28:29], v[150:151] op_sel:[0,1]
	v_pk_mul_f32 v[34:35], v[26:27], v[150:151] op_sel:[0,1]
	ds_write_b128 v148, v[34:37]
	v_pk_mul_f32 v[36:37], v[32:33], v[152:153] op_sel_hi:[1,0]
	v_pk_mul_f32 v[34:35], v[30:31], v[152:153] op_sel_hi:[1,0]
	v_mov_b32_e32 v84, v153
	s_cbranch_execnz .LBB0_216

; #define LAS __attribute__((address_space(3)))
; __device__ __forceinline__ void transpose_item_wg(const float* W, int K, int N, bf16* WT, int mode, const float* g0, const float* g1, int item, LAS float* scr, int tid, int lane, int wave) {
;     const int nblk = (N + 255) >> 8, kb = item / nblk, nb = item - kb * nblk, k0 = 64 * kb, n0 = 256 * nb, nw = min(256, N - n0);
;     const float* gk = g0 ? ((g1 && k0 >= 512) ? g1 + (k0 - 512) : g0 + k0) : nullptr;
;     if (4 * lane < nw) {
;         f32x4 v[8];
; #pragma unroll
;         for (int j = 0; j < 8; ++j) v[j] = __builtin_nontemporal_load((const f32x4*)(W + (size_t)(k0 + 8 * wave + j) * N + n0 + 4 * lane));
; #pragma unroll
;         for (int j = 0; j < 8; ++j) { const float gv = gk ? gk[8 * wave + j] : 1.0f; *(LAS f32x4*)(scr + (8 * wave + j) * 260 + 4 * lane) = v[j] * gv; }
.LBB0_286:
	s_andn2_b64 vcc, exec, s[2:3]
	s_cbranch_vccnz .LBB0_298
	s_lshl_b32 s2, s71, 8
	s_and_b32 s4, s2, 0xfffffc00
	s_lshl_b32 s2, s97, 4
	s_addk_i32 s2, 0x3a40
	s_and_b32 s18, s2, 0xffffffc0
	s_add_i32 s2, s40, s4
	s_add_i32 s2, s2, 0xfffc5c00
	s_min_i32 s16, s2, 0x100
	v_cmp_gt_i32_e32 vcc, s16, v141
	s_and_saveexec_b64 s[2:3], vcc
	s_cbranch_execz .LBB0_289
	s_sub_i32 s17, s68, s4
	v_readlane_b32 s1, v254, 27
	s_add_i32 s30, s1, s17
	s_add_i32 s34, s18, s0
	s_ashr_i32 s31, s30, 31
	s_mov_b32 s35, s19
	v_lshl_add_u64 v[26:27], s[30:31], 2, v[68:69]
	s_lshl_b64 s[30:31], s[34:35], 12
	v_lshl_add_u64 v[2:3], v[26:27], 0, s[30:31]
	s_or_b32 s30, s34, 1
	s_mov_b32 s31, s19
	s_lshl_b64 s[30:31], s[30:31], 12
	v_lshl_add_u64 v[6:7], v[26:27], 0, s[30:31]
	s_or_b32 s30, s34, 2
	s_mov_b32 s31, s19
	s_lshl_b64 s[30:31], s[30:31], 12
	v_lshl_add_u64 v[10:11], v[26:27], 0, s[30:31]
	s_or_b32 s30, s34, 3
	s_mov_b32 s31, s19
	s_lshl_b64 s[30:31], s[30:31], 12
	v_lshl_add_u64 v[14:15], v[26:27], 0, s[30:31]
	s_or_b32 s30, s34, 4
	s_mov_b32 s31, s19
	s_lshl_b64 s[30:31], s[30:31], 12
	v_lshl_add_u64 v[18:19], v[26:27], 0, s[30:31]
	s_or_b32 s30, s34, 5
	s_mov_b32 s31, s19
	s_lshl_b64 s[30:31], s[30:31], 12
	v_lshl_add_u64 v[22:23], v[26:27], 0, s[30:31]
	s_or_b32 s30, s34, 6
	s_mov_b32 s31, s19
	s_lshl_b64 s[30:31], s[30:31], 12
	v_lshl_add_u64 v[28:29], v[26:27], 0, s[30:31]
	s_or_b32 s30, s34, 7
	s_mov_b32 s31, s19
	s_lshl_b64 s[30:31], s[30:31], 12
	v_lshl_add_u64 v[30:31], v[26:27], 0, s[30:31]
	global_load_dwordx4 v[2:5], v[2:3], off nt
	global_load_dwordx4 v[6:9], v[6:7], off nt
	global_load_dwordx4 v[10:13], v[10:11], off nt
	global_load_dwordx4 v[14:17], v[14:15], off nt
	global_load_dwordx4 v[18:21], v[18:19], off nt
	global_load_dwordx4 v[22:25], v[22:23], off nt
	global_load_dwordx4 v[26:29], v[28:29], off nt
	global_load_dwordx4 v[30:33], v[30:31], off nt
	v_readlane_b32 s1, v254, 49
	s_add_i32 s17, s1, s96
	v_lshl_add_u32 v34, v141, 2, s17
	s_waitcnt vmcnt(7)
	ds_write_b128 v34, v[2:5]
	s_waitcnt vmcnt(6)
	ds_write_b128 v34, v[6:9] offset:1040
	s_waitcnt vmcnt(5)
	ds_write_b128 v34, v[10:13] offset:2080
	s_waitcnt vmcnt(4)
	ds_write_b128 v34, v[14:17] offset:3120
	s_waitcnt vmcnt(3)
	ds_write_b128 v34, v[18:21] offset:4160
	s_waitcnt vmcnt(2)
	ds_write_b128 v34, v[22:25] offset:5200
	s_waitcnt vmcnt(1)
	ds_write_b128 v34, v[26:29] offset:6240
	s_waitcnt vmcnt(0)
	ds_write_b128 v34, v[30:33] offset:7280

; #define LAS __attribute__((address_space(3)))
; __device__ __forceinline__ void transpose_item_wg(const float* W, int K, int N, bf16* WT, int mode, const float* g0, const float* g1, int item, LAS float* scr, int tid, int lane, int wave) {
;     const int nblk = (N + 255) >> 8, kb = item / nblk, nb = item - kb * nblk, k0 = 64 * kb, n0 = 256 * nb, nw = min(256, N - n0);
;     const float* gk = g0 ? ((g1 && k0 >= 512) ? g1 + (k0 - 512) : g0 + k0) : nullptr;
;     if (4 * lane < nw) {
;         f32x4 v[8];
; #pragma unroll
;         for (int j = 0; j < 8; ++j) v[j] = __builtin_nontemporal_load((const f32x4*)(W + (size_t)(k0 + 8 * wave + j) * N + n0 + 4 * lane));
; #pragma unroll
;         for (int j = 0; j < 8; ++j) { const float gv = gk ? gk[8 * wave + j] : 1.0f; *(LAS f32x4*)(scr + (8 * wave + j) * 260 + 4 * lane) = v[j] * gv; }
.LBB0_299:
	s_andn2_b64 vcc, exec, s[2:3]
	s_cbranch_vccnz .LBB0_317
	s_add_i32 s3, s97, 0x454
	s_mul_i32 s4, s3, 0x75
	s_lshr_b32 s17, s4, 8
	s_sub_i32 s3, s3, s17
	s_and_b32 s2, s70, 0xff
	s_bfe_u32 s3, s3, 0x70001
	s_bfe_u32 s4, s4, 0x80008
	s_mul_hi_u32 s16, s2, 0x1745d175
	s_add_i32 s3, s3, s4
	s_mul_i32 s2, s16, 0xb00
	s_and_b32 s3, s3, 0xf8
	s_lshl_b32 s17, s3, 3
	s_add_i32 s3, s40, s2
	s_add_i32 s3, s3, 0xfffbb300
	s_min_i32 s4, s3, 0x100
	v_cmp_gt_i32_e32 vcc, s4, v141
	s_and_saveexec_b64 s[34:35], vcc
	s_cbranch_execz .LBB0_308
	v_readlane_b32 s1, v254, 27
	s_add_i32 s3, s1, s69
	s_sub_i32 s2, s3, s2
	s_add_i32 s2, s2, 0xffff5000
	s_lshl_b32 s3, s17, 2
	s_add_u32 s36, s13, s3
	s_addc_u32 s37, s84, 0
	s_ashr_i32 s3, s2, 31
	s_add_i32 s18, s17, s0
	v_lshl_add_u64 v[2:3], s[2:3], 2, v[72:73]
	v_mad_u64_u32 v[4:5], s[2:3], s18, v198, v[2:3]
	s_or_b32 s2, s18, 1
	s_nop 0
	v_mad_u64_u32 v[6:7], s[2:3], s2, v198, v[2:3]
	s_or_b32 s2, s18, 2
	global_load_dwordx4 v[22:25], v[4:5], off nt
	global_load_dwordx4 v[26:29], v[6:7], off nt
	v_mad_u64_u32 v[4:5], s[2:3], s2, v198, v[2:3]
	s_or_b32 s2, s18, 3
	s_nop 0
	v_mad_u64_u32 v[6:7], s[2:3], s2, v198, v[2:3]
	s_or_b32 s2, s18, 4
	global_load_dwordx4 v[30:33], v[4:5], off nt
	global_load_dwordx4 v[18:21], v[6:7], off nt
	v_mad_u64_u32 v[4:5], s[2:3], s2, v198, v[2:3]
	s_or_b32 s2, s18, 5
	s_nop 0
	v_mad_u64_u32 v[10:11], s[2:3], s2, v198, v[2:3]
	s_or_b32 s2, s18, 6
	global_load_dwordx4 v[6:9], v[4:5], off nt
	global_load_dwordx4 v[10:13], v[10:11], off nt
	v_mad_u64_u32 v[4:5], s[2:3], s2, v198, v[2:3]
	s_or_b32 s2, s18, 7
	s_nop 0
	v_mad_u64_u32 v[2:3], s[2:3], s2, v198, v[2:3]
	global_load_dwordx4 v[14:17], v[4:5], off nt
	global_load_dwordx4 v[2:5], v[2:3], off nt
	v_lshl_add_u32 v98, v141, 2, s96
	v_readlane_b32 s18, v254, 49
	v_cndmask_b32_e64 v34, 0, 1, s[56:57]
	v_cmp_ne_u32_e64 s[2:3], 1, v34
	v_add_u32_e32 v147, s18, v98
	v_readlane_b32 s18, v252, 25
	s_andn2_b64 vcc, exec, s[56:57]
	s_nop 0
	v_add_u32_e32 v148, s18, v98
	s_cbranch_vccnz .LBB0_337
	s_lshl_b32 s18, s0, 2
	v_mov_b32_e32 v34, s18
	global_load_dwordx4 v[150:153], v34, s[36:37]
	s_waitcnt vmcnt(0)
	v_pk_mul_f32 v[36:37], v[24:25], v[150:151] op_sel_hi:[1,0]
	v_pk_mul_f32 v[34:35], v[22:23], v[150:151] op_sel_hi:[1,0]
	ds_write_b128 v147, v[34:37]
	v_pk_mul_f32 v[36:37], v[28:29], v[150:151] op_sel:[0,1]
	v_pk_mul_f32 v[34:35], v[26:27], v[150:151] op_sel:[0,1]
	ds_write_b128 v148, v[34:37]
	v_pk_mul_f32 v[36:37], v[32:33], v[152:153] op_sel_hi:[1,0]
	v_pk_mul_f32 v[34:35], v[30:31], v[152:153] op_sel_hi:[1,0]
	v_mov_b32_e32 v84, v153
	s_cbranch_execnz .LBB0_304

; #define LAS __attribute__((address_space(3)))
; __device__ __forceinline__ void transpose_item_wg(const float* W, int K, int N, bf16* WT, int mode, const float* g0, const float* g1, int item, LAS float* scr, int tid, int lane, int wave) {
;     const int nblk = (N + 255) >> 8, kb = item / nblk, nb = item - kb * nblk, k0 = 64 * kb, n0 = 256 * nb, nw = min(256, N - n0);
;     const float* gk = g0 ? ((g1 && k0 >= 512) ? g1 + (k0 - 512) : g0 + k0) : nullptr;
;     if (4 * lane < nw) {
;         f32x4 v[8];
; #pragma unroll
;         for (int j = 0; j < 8; ++j) v[j] = __builtin_nontemporal_load((const f32x4*)(W + (size_t)(k0 + 8 * wave + j) * N + n0 + 4 * lane));
; #pragma unroll
;         for (int j = 0; j < 8; ++j) { const float gv = gk ? gk[8 * wave + j] : 1.0f; *(LAS f32x4*)(scr + (8 * wave + j) * 260 + 4 * lane) = v[j] * gv; }
.LBB0_318:
	s_andn2_b64 vcc, exec, s[2:3]
	s_cbranch_vccnz .LBB0_31
	s_mul_hi_i32 s2, s91, 0x2e8ba2e9
	s_lshr_b32 s3, s2, 31
	s_ashr_i32 s16, s2, 1
	s_add_i32 s16, s16, s3
	s_mul_i32 s2, s16, 0xb00
	s_add_i32 s2, s40, s2
	s_add_i32 s2, s2, 0xfffb0300
	s_lshl_b32 s34, s16, 6
	s_min_i32 s4, s2, 0x100
	s_ashr_i32 s35, s34, 31
	v_cmp_gt_i32_e32 vcc, s4, v141
	s_and_saveexec_b64 s[36:37], vcc
	s_cbranch_execz .LBB0_327
	v_readlane_b32 s3, v254, 27
	s_mul_i32 s2, s16, 0xfffff500
	s_add_i32 s3, s3, s69
	s_add_i32 s2, s3, s2
	s_lshl_b64 s[30:31], s[34:35], 2
	s_add_u32 s60, s13, s30
	s_addc_u32 s61, s84, s31
	s_ashr_i32 s3, s2, 31
	s_add_i32 s17, s34, s0
	v_lshl_add_u64 v[2:3], s[2:3], 2, v[76:77]
	v_mad_i64_i32 v[4:5], s[2:3], s17, v198, v[2:3]
	s_or_b32 s2, s17, 1
	s_nop 0
	v_mad_i64_i32 v[6:7], s[2:3], s2, v198, v[2:3]
	s_or_b32 s2, s17, 2
	global_load_dwordx4 v[22:25], v[4:5], off nt
	global_load_dwordx4 v[26:29], v[6:7], off nt
	v_mad_i64_i32 v[4:5], s[2:3], s2, v198, v[2:3]
	s_or_b32 s2, s17, 3
	s_nop 0
	v_mad_i64_i32 v[6:7], s[2:3], s2, v198, v[2:3]
	s_or_b32 s2, s17, 4
	global_load_dwordx4 v[30:33], v[4:5], off nt
	global_load_dwordx4 v[18:21], v[6:7], off nt
	v_mad_i64_i32 v[4:5], s[2:3], s2, v198, v[2:3]
	s_or_b32 s2, s17, 5
	s_nop 0
	v_mad_i64_i32 v[10:11], s[2:3], s2, v198, v[2:3]
	s_or_b32 s2, s17, 6
	global_load_dwordx4 v[6:9], v[4:5], off nt
	global_load_dwordx4 v[10:13], v[10:11], off nt
	v_mad_i64_i32 v[4:5], s[2:3], s2, v198, v[2:3]
	s_or_b32 s2, s17, 7
	s_nop 0
	v_mad_i64_i32 v[2:3], s[2:3], s2, v198, v[2:3]
	global_load_dwordx4 v[14:17], v[4:5], off nt
	global_load_dwordx4 v[2:5], v[2:3], off nt
	v_lshl_add_u32 v98, v141, 2, s96
	v_readlane_b32 s17, v254, 49
	v_cndmask_b32_e64 v34, 0, 1, s[56:57]
	s_mov_b32 s1, s0
	v_add_u32_e32 v147, s17, v98
	v_readlane_b32 s17, v252, 25
	v_cmp_ne_u32_e64 s[2:3], 1, v34
	s_andn2_b64 vcc, exec, s[56:57]
	v_add_u32_e32 v148, s17, v98
	s_cbranch_vccnz .LBB0_335
	s_lshl_b32 s17, s1, 2
	v_mov_b32_e32 v34, s17
	global_load_dwordx4 v[150:153], v34, s[60:61]
	s_waitcnt vmcnt(0)
	v_pk_mul_f32 v[36:37], v[24:25], v[150:151] op_sel_hi:[1,0]
	v_pk_mul_f32 v[34:35], v[22:23], v[150:151] op_sel_hi:[1,0]
	ds_write_b128 v147, v[34:37]
	v_pk_mul_f32 v[36:37], v[28:29], v[150:151] op_sel:[0,1]
	v_pk_mul_f32 v[34:35], v[26:27], v[150:151] op_sel:[0,1]
	ds_write_b128 v148, v[34:37]
	v_pk_mul_f32 v[36:37], v[32:33], v[152:153] op_sel_hi:[1,0]
	v_pk_mul_f32 v[34:35], v[30:31], v[152:153] op_sel_hi:[1,0]
	v_mov_b32_e32 v84, v153
	s_cbranch_execnz .LBB0_323

; #define LAS __attribute__((address_space(3)))
; __device__ __forceinline__ void transpose_item_wg(const float* W, int K, int N, bf16* WT, int mode, const float* g0, const float* g1, int item, LAS float* scr, int tid, int lane, int wave) {
;     const int nblk = (N + 255) >> 8, kb = item / nblk, nb = item - kb * nblk, k0 = 64 * kb, n0 = 256 * nb, nw = min(256, N - n0);
;     const float* gk = g0 ? ((g1 && k0 >= 512) ? g1 + (k0 - 512) : g0 + k0) : nullptr;
;     if (4 * lane < nw) {
;         f32x4 v[8];
; #pragma unroll
;         for (int j = 0; j < 8; ++j) v[j] = __builtin_nontemporal_load((const f32x4*)(W + (size_t)(k0 + 8 * wave + j) * N + n0 + 4 * lane));
; #pragma unroll
;         for (int j = 0; j < 8; ++j) { const float gv = gk ? gk[8 * wave + j] : 1.0f; *(LAS f32x4*)(scr + (8 * wave + j) * 260 + 4 * lane) = v[j] * gv; }
.LBB0_578:
	s_and_b64 vcc, exec, s[34:35]
	s_cbranch_vccz .LBB0_585
	s_lshl_b32 s4, s61, 8
	s_and_b32 s16, s4, 0xfffffc00
	s_sub_i32 s4, 0xfffea000, s16
	s_lshl_b32 s17, s59, 4
	s_add_i32 s16, s58, s16
	s_addk_i32 s17, 0xb00
	s_add_i32 s16, s16, 0xffff5000
	s_and_b32 s18, s17, 0xffffffc0
	v_cmp_gt_i32_e32 vcc, s16, v1
	s_and_saveexec_b64 s[34:35], vcc
	s_cbranch_execz .LBB0_581
	s_add_i32 s30, s60, s4
	s_add_i32 s36, s18, s87
	s_ashr_i32 s31, s30, 31
	s_mov_b32 s37, s19
	v_lshl_add_u64 v[26:27], s[30:31], 2, v[44:45]
	s_lshl_b64 s[30:31], s[36:37], 12
	v_lshl_add_u64 v[2:3], v[26:27], 0, s[30:31]
	s_or_b32 s30, s36, 1
	s_mov_b32 s31, s19
	s_lshl_b64 s[30:31], s[30:31], 12
	v_lshl_add_u64 v[6:7], v[26:27], 0, s[30:31]
	s_or_b32 s30, s36, 2
	s_mov_b32 s31, s19
	s_lshl_b64 s[30:31], s[30:31], 12
	v_lshl_add_u64 v[10:11], v[26:27], 0, s[30:31]
	s_or_b32 s30, s36, 3
	s_mov_b32 s31, s19
	s_lshl_b64 s[30:31], s[30:31], 12
	v_lshl_add_u64 v[14:15], v[26:27], 0, s[30:31]
	s_or_b32 s30, s36, 4
	s_mov_b32 s31, s19
	s_lshl_b64 s[30:31], s[30:31], 12
	v_lshl_add_u64 v[18:19], v[26:27], 0, s[30:31]
	s_or_b32 s30, s36, 5
	s_mov_b32 s31, s19
	s_lshl_b64 s[30:31], s[30:31], 12
	v_lshl_add_u64 v[22:23], v[26:27], 0, s[30:31]
	s_or_b32 s30, s36, 6
	s_mov_b32 s31, s19
	s_lshl_b64 s[30:31], s[30:31], 12
	v_lshl_add_u64 v[28:29], v[26:27], 0, s[30:31]
	s_or_b32 s30, s36, 7
	s_mov_b32 s31, s19
	s_lshl_b64 s[30:31], s[30:31], 12
	v_lshl_add_u64 v[30:31], v[26:27], 0, s[30:31]
	global_load_dwordx4 v[2:5], v[2:3], off nt
	global_load_dwordx4 v[6:9], v[6:7], off nt
	global_load_dwordx4 v[10:13], v[10:11], off nt
	global_load_dwordx4 v[14:17], v[14:15], off nt
	global_load_dwordx4 v[18:21], v[18:19], off nt
	global_load_dwordx4 v[22:25], v[22:23], off nt
	global_load_dwordx4 v[26:29], v[28:29], off nt
	global_load_dwordx4 v[30:33], v[30:31], off nt
	v_readlane_b32 s1, v254, 49
	s_add_i32 s17, s1, s77
	v_lshl_add_u32 v34, v1, 2, s17
	s_waitcnt vmcnt(0)
	ds_write_b128 v34, v[2:5]
	ds_write_b128 v34, v[6:9] offset:1040
	ds_write_b128 v34, v[10:13] offset:2080
	ds_write_b128 v34, v[14:17] offset:3120
	ds_write_b128 v34, v[18:21] offset:4160
	ds_write_b128 v34, v[22:25] offset:5200
	ds_write_b128 v34, v[26:29] offset:6240
	ds_write_b128 v34, v[30:33] offset:7280

; #define LAS __attribute__((address_space(3)))
; __device__ __forceinline__ void transpose_item_wg(const float* W, int K, int N, bf16* WT, int mode, const float* g0, const float* g1, int item, LAS float* scr, int tid, int lane, int wave) {
;     const int nblk = (N + 255) >> 8, kb = item / nblk, nb = item - kb * nblk, k0 = 64 * kb, n0 = 256 * nb, nw = min(256, N - n0);
;     const float* gk = g0 ? ((g1 && k0 >= 512) ? g1 + (k0 - 512) : g0 + k0) : nullptr;
;     if (4 * lane < nw) {
;         f32x4 v[8];
; #pragma unroll
;         for (int j = 0; j < 8; ++j) v[j] = __builtin_nontemporal_load((const f32x4*)(W + (size_t)(k0 + 8 * wave + j) * N + n0 + 4 * lane));
; #pragma unroll
;         for (int j = 0; j < 8; ++j) { const float gv = gk ? gk[8 * wave + j] : 1.0f; *(LAS f32x4*)(scr + (8 * wave + j) * 260 + 4 * lane) = v[j] * gv; }
.LBB0_617:
	s_andn2_b64 vcc, exec, s[34:35]
	s_cbranch_vccnz .LBB0_629
	s_lshl_b32 s4, s66, 8
	s_and_b32 s16, s4, 0xfffffc00
	s_sub_i32 s4, 0x1000, s16
	s_lshl_b32 s17, s59, 4
	s_add_i32 s16, s58, s16
	s_addk_i32 s17, 0x2200
	s_add_i32 s16, s16, 0xfffde000
	s_and_b32 s18, s17, 0xffffffc0
	v_cmp_gt_i32_e32 vcc, s16, v1
	s_and_saveexec_b64 s[34:35], vcc
	s_cbranch_execz .LBB0_620
	s_add_i32 s30, s60, s4
	s_add_i32 s36, s18, s87
	s_ashr_i32 s31, s30, 31
	s_mov_b32 s37, s19
	v_lshl_add_u64 v[26:27], s[30:31], 2, v[54:55]
	s_lshl_b64 s[30:31], s[36:37], 12
	v_lshl_add_u64 v[2:3], v[26:27], 0, s[30:31]
	s_or_b32 s30, s36, 1
	s_mov_b32 s31, s19
	s_lshl_b64 s[30:31], s[30:31], 12
	v_lshl_add_u64 v[6:7], v[26:27], 0, s[30:31]
	s_or_b32 s30, s36, 2
	s_mov_b32 s31, s19
	s_lshl_b64 s[30:31], s[30:31], 12
	v_lshl_add_u64 v[10:11], v[26:27], 0, s[30:31]
	s_or_b32 s30, s36, 3
	s_mov_b32 s31, s19
	s_lshl_b64 s[30:31], s[30:31], 12
	v_lshl_add_u64 v[14:15], v[26:27], 0, s[30:31]
	s_or_b32 s30, s36, 4
	s_mov_b32 s31, s19
	s_lshl_b64 s[30:31], s[30:31], 12
	v_lshl_add_u64 v[18:19], v[26:27], 0, s[30:31]
	s_or_b32 s30, s36, 5
	s_mov_b32 s31, s19
	s_lshl_b64 s[30:31], s[30:31], 12
	v_lshl_add_u64 v[22:23], v[26:27], 0, s[30:31]
	s_or_b32 s30, s36, 6
	s_mov_b32 s31, s19
	s_lshl_b64 s[30:31], s[30:31], 12
	v_lshl_add_u64 v[28:29], v[26:27], 0, s[30:31]
	s_or_b32 s30, s36, 7
	s_mov_b32 s31, s19
	s_lshl_b64 s[30:31], s[30:31], 12
	v_lshl_add_u64 v[30:31], v[26:27], 0, s[30:31]
	global_load_dwordx4 v[2:5], v[2:3], off nt
	global_load_dwordx4 v[6:9], v[6:7], off nt
	global_load_dwordx4 v[10:13], v[10:11], off nt
	global_load_dwordx4 v[14:17], v[14:15], off nt
	global_load_dwordx4 v[18:21], v[18:19], off nt
	global_load_dwordx4 v[22:25], v[22:23], off nt
	global_load_dwordx4 v[26:29], v[28:29], off nt
	global_load_dwordx4 v[30:33], v[30:31], off nt
	v_readlane_b32 s1, v254, 49
	s_add_i32 s17, s1, s77
	v_lshl_add_u32 v34, v1, 2, s17
	s_waitcnt vmcnt(0)
	ds_write_b128 v34, v[2:5]
	ds_write_b128 v34, v[6:9] offset:1040
	ds_write_b128 v34, v[10:13] offset:2080
	ds_write_b128 v34, v[14:17] offset:3120
	ds_write_b128 v34, v[18:21] offset:4160
	ds_write_b128 v34, v[22:25] offset:5200
	ds_write_b128 v34, v[26:29] offset:6240
	ds_write_b128 v34, v[30:33] offset:7280

; #define LAS __attribute__((address_space(3)))
; __device__ __forceinline__ void transpose_item_wg(const float* W, int K, int N, bf16* WT, int mode, const float* g0, const float* g1, int item, LAS float* scr, int tid, int lane, int wave) {
;     const int nblk = (N + 255) >> 8, kb = item / nblk, nb = item - kb * nblk, k0 = 64 * kb, n0 = 256 * nb, nw = min(256, N - n0);
;     const float* gk = g0 ? ((g1 && k0 >= 512) ? g1 + (k0 - 512) : g0 + k0) : nullptr;
;     if (4 * lane < nw) {
;         f32x4 v[8];
; #pragma unroll
;         for (int j = 0; j < 8; ++j) v[j] = __builtin_nontemporal_load((const f32x4*)(W + (size_t)(k0 + 8 * wave + j) * N + n0 + 4 * lane));
; #pragma unroll
;         for (int j = 0; j < 8; ++j) { const float gv = gk ? gk[8 * wave + j] : 1.0f; *(LAS f32x4*)(scr + (8 * wave + j) * 260 + 4 * lane) = v[j] * gv; }
.LBB0_630:
	s_andn2_b64 vcc, exec, s[34:35]
	s_cbranch_vccnz .LBB0_648
	s_lshl_b32 s4, s62, 8
	s_and_b32 s16, s4, 0xfffffc00
	s_sub_i32 s4, 0, s16
	s_add_i32 s17, s59, 0x260
	s_add_i32 s16, s58, s16
	s_lshl_b32 s18, s17, 4
	s_add_i32 s16, s16, 0xfffda000
	s_andn2_b32 s18, s18, 63
	v_cmp_gt_i32_e32 vcc, s16, v1
	s_and_saveexec_b64 s[34:35], vcc
	s_cbranch_execz .LBB0_639
	s_add_i32 s22, s60, s4
	s_add_i32 s30, s22, 0x5000
	s_cmp_gt_u32 s17, 31
	s_cselect_b32 s17, s11, s73
	s_cselect_b32 s22, s10, s72
	s_lshl_b64 s[36:37], s[18:19], 2
	s_add_u32 s36, s22, s36
	s_addc_u32 s37, s17, s37
	s_add_i32 s40, s18, s87
	s_ashr_i32 s31, s30, 31
	s_mov_b32 s41, s19
	v_lshl_add_u64 v[10:11], s[30:31], 2, v[58:59]
	s_lshl_b64 s[30:31], s[40:41], 12
	v_lshl_add_u64 v[2:3], v[10:11], 0, s[30:31]
	s_or_b32 s30, s40, 1
	s_mov_b32 s31, s19
	s_lshl_b64 s[30:31], s[30:31], 12
	v_lshl_add_u64 v[4:5], v[10:11], 0, s[30:31]
	s_or_b32 s30, s40, 2
	s_mov_b32 s31, s19
	s_lshl_b64 s[30:31], s[30:31], 12
	global_load_dwordx4 v[22:25], v[2:3], off nt
	global_load_dwordx4 v[26:29], v[4:5], off nt
	v_lshl_add_u64 v[2:3], v[10:11], 0, s[30:31]
	s_or_b32 s30, s40, 3
	s_mov_b32 s31, s19
	s_lshl_b64 s[30:31], s[30:31], 12
	v_lshl_add_u64 v[4:5], v[10:11], 0, s[30:31]
	s_or_b32 s30, s40, 4
	s_mov_b32 s31, s19
	s_lshl_b64 s[30:31], s[30:31], 12
	global_load_dwordx4 v[30:33], v[2:3], off nt
	global_load_dwordx4 v[18:21], v[4:5], off nt
	v_lshl_add_u64 v[2:3], v[10:11], 0, s[30:31]
	s_or_b32 s30, s40, 5
	s_mov_b32 s31, s19
	s_lshl_b64 s[30:31], s[30:31], 12
	v_lshl_add_u64 v[6:7], v[10:11], 0, s[30:31]
	s_or_b32 s30, s40, 6
	s_mov_b32 s31, s19
	s_lshl_b64 s[30:31], s[30:31], 12
	v_lshl_add_u64 v[12:13], v[10:11], 0, s[30:31]
	s_or_b32 s30, s40, 7
	s_mov_b32 s31, s19
	s_lshl_b64 s[30:31], s[30:31], 12
	v_lshl_add_u64 v[10:11], v[10:11], 0, s[30:31]
	global_load_dwordx4 v[2:5], v[2:3], off nt
	global_load_dwordx4 v[6:9], v[6:7], off nt
	global_load_dwordx4 v[14:17], v[12:13], off nt
	global_load_dwordx4 v[10:13], v[10:11], off nt
	v_lshl_add_u32 v145, v1, 2, s77
	v_readlane_b32 s1, v254, 49
	s_cmp_lg_u64 s[36:37], 0
	s_cselect_b64 s[40:41], -1, 0
	v_add_u32_e32 v146, s1, v145
	v_readlane_b32 s1, v252, 25
	s_cmp_eq_u64 s[36:37], 0
	s_nop 0
	v_add_u32_e32 v147, s1, v145
	s_cbranch_scc1 .LBB0_805
	v_mov_b32_e32 v34, s74
	global_load_dwordx4 v[148:151], v34, s[36:37]
	s_waitcnt vmcnt(0)
	v_pk_mul_f32 v[36:37], v[24:25], v[148:149] op_sel_hi:[1,0]
	v_pk_mul_f32 v[34:35], v[22:23], v[148:149] op_sel_hi:[1,0]
	ds_write_b128 v146, v[34:37]
	v_pk_mul_f32 v[36:37], v[28:29], v[148:149] op_sel:[0,1]
	v_pk_mul_f32 v[34:35], v[26:27], v[148:149] op_sel:[0,1]
	ds_write_b128 v147, v[34:37]
	v_pk_mul_f32 v[36:37], v[32:33], v[150:151] op_sel_hi:[1,0]
	v_pk_mul_f32 v[34:35], v[30:31], v[150:151] op_sel_hi:[1,0]
	v_mov_b32_e32 v82, v151
	s_cbranch_execnz .LBB0_635

; #define LAS __attribute__((address_space(3)))
; __device__ __forceinline__ void transpose_item_wg(const float* W, int K, int N, bf16* WT, int mode, const float* g0, const float* g1, int item, LAS float* scr, int tid, int lane, int wave) {
;     const int nblk = (N + 255) >> 8, kb = item / nblk, nb = item - kb * nblk, k0 = 64 * kb, n0 = 256 * nb, nw = min(256, N - n0);
;     const float* gk = g0 ? ((g1 && k0 >= 512) ? g1 + (k0 - 512) : g0 + k0) : nullptr;
;     if (4 * lane < nw) {
;         f32x4 v[8];
; #pragma unroll
;         for (int j = 0; j < 8; ++j) v[j] = __builtin_nontemporal_load((const f32x4*)(W + (size_t)(k0 + 8 * wave + j) * N + n0 + 4 * lane));
; #pragma unroll
;         for (int j = 0; j < 8; ++j) { const float gv = gk ? gk[8 * wave + j] : 1.0f; *(LAS f32x4*)(scr + (8 * wave + j) * 260 + 4 * lane) = v[j] * gv; }
.LBB0_699:
	s_andn2_b64 vcc, exec, s[34:35]
	s_cbranch_vccnz .LBB0_767
	s_lshr_b32 s16, s68, 3
	s_lshl_b32 s22, s16, 11
	s_sub_i32 s4, 0, s22
	s_add_i32 s17, s59, 0x2f4
	s_add_i32 s22, s58, s22
	s_lshr_b32 s17, s17, 3
	s_add_i32 s22, s22, 0xfffd0fc0
	s_lshl_b32 s18, s17, 6
	v_cmp_gt_i32_e32 vcc, s22, v1
	s_and_saveexec_b64 s[34:35], vcc
	s_cbranch_execz .LBB0_702
	s_add_i32 s28, s60, s4
	s_add_i32 s30, s28, 0xe400
	s_ashr_i32 s31, s30, 31
	s_add_i32 s28, s18, s87
	v_lshl_add_u64 v[30:31], s[30:31], 2, v[70:71]
	v_mad_u64_u32 v[2:3], s[30:31], s28, v200, v[30:31]
	s_or_b32 s30, s28, 1
	s_nop 0
	v_mad_u64_u32 v[6:7], s[30:31], s30, v200, v[30:31]
	s_or_b32 s30, s28, 2
	s_nop 0
	v_mad_u64_u32 v[10:11], s[30:31], s30, v200, v[30:31]
	s_or_b32 s30, s28, 3
	s_nop 0
	v_mad_u64_u32 v[14:15], s[30:31], s30, v200, v[30:31]
	s_or_b32 s30, s28, 4
	s_nop 0
	v_mad_u64_u32 v[18:19], s[30:31], s30, v200, v[30:31]
	s_or_b32 s30, s28, 5
	s_nop 0
	v_mad_u64_u32 v[22:23], s[30:31], s30, v200, v[30:31]
	s_or_b32 s30, s28, 6
	s_or_b32 s28, s28, 7
	v_mad_u64_u32 v[26:27], s[30:31], s30, v200, v[30:31]
	v_mad_u64_u32 v[30:31], s[30:31], s28, v200, v[30:31]
	s_lshl_b64 s[30:31], s[18:19], 2
	s_add_u32 s30, s54, s30
	s_addc_u32 s31, s55, s31
	global_load_dwordx4 v[2:5], v[2:3], off nt
	v_lshl_add_u32 v82, v1, 2, s77
	global_load_dwordx4 v[6:9], v[6:7], off nt
	v_readlane_b32 s1, v254, 49
	global_load_dwordx4 v[10:13], v[10:11], off nt
	global_load_dwordx4 v[14:17], v[14:15], off nt
	v_add_u32_e32 v145, s1, v82
	global_load_dwordx4 v[18:21], v[18:19], off nt
	v_readlane_b32 s1, v252, 25
	global_load_dwordx4 v[22:25], v[22:23], off nt
	global_load_dwordx4 v[26:29], v[26:27], off nt
	global_load_dwordx4 v[30:33], v[30:31], off nt
	s_nop 0
	global_load_dwordx4 v[34:37], v99, s[30:31] offset:16
	global_load_dwordx4 v[146:149], v99, s[30:31]
	s_waitcnt vmcnt(0)
	v_pk_mul_f32 v[4:5], v[4:5], v[146:147] op_sel_hi:[1,0]
	v_pk_mul_f32 v[2:3], v[2:3], v[146:147] op_sel_hi:[1,0]
	ds_write_b128 v145, v[2:5]
	v_pk_mul_f32 v[4:5], v[8:9], v[146:147] op_sel:[0,1]
	v_pk_mul_f32 v[2:3], v[6:7], v[146:147] op_sel:[0,1]
	v_add_u32_e32 v6, s1, v82
	ds_write_b128 v6, v[2:5]
	v_pk_mul_f32 v[4:5], v[12:13], v[148:149] op_sel_hi:[1,0]
	v_pk_mul_f32 v[2:3], v[10:11], v[148:149] op_sel_hi:[1,0]
	ds_write_b128 v6, v[2:5] offset:1040
	v_mov_b32_e32 v2, v149
	v_pk_mul_f32 v[4:5], v[16:17], v[2:3] op_sel_hi:[1,0]
	v_pk_mul_f32 v[2:3], v[14:15], v[2:3] op_sel_hi:[1,0]
	ds_write_b128 v6, v[2:5] offset:2080
	v_pk_mul_f32 v[4:5], v[20:21], v[34:35] op_sel_hi:[1,0]
	v_pk_mul_f32 v[2:3], v[18:19], v[34:35] op_sel_hi:[1,0]
	ds_write_b128 v6, v[2:5] offset:3120
	v_pk_mul_f32 v[4:5], v[24:25], v[34:35] op_sel:[0,1]
	v_pk_mul_f32 v[2:3], v[22:23], v[34:35] op_sel:[0,1]
	ds_write_b128 v6, v[2:5] offset:4160
	v_pk_mul_f32 v[4:5], v[28:29], v[36:37] op_sel_hi:[1,0]
	v_pk_mul_f32 v[2:3], v[26:27], v[36:37] op_sel_hi:[1,0]
	ds_write_b128 v6, v[2:5] offset:5200
	v_mov_b32_e32 v2, v37
	v_pk_mul_f32 v[4:5], v[32:33], v[2:3] op_sel_hi:[1,0]
	v_pk_mul_f32 v[2:3], v[30:31], v[2:3] op_sel_hi:[1,0]
	ds_write_b128 v6, v[2:5] offset:6240

; #define LAS __attribute__((address_space(3)))
; __device__ __forceinline__ void transpose_item_wg(const float* W, int K, int N, bf16* WT, int mode, const float* g0, const float* g1, int item, LAS float* scr, int tid, int lane, int wave) {
;     const int nblk = (N + 255) >> 8, kb = item / nblk, nb = item - kb * nblk, k0 = 64 * kb, n0 = 256 * nb, nw = min(256, N - n0);
;     const float* gk = g0 ? ((g1 && k0 >= 512) ? g1 + (k0 - 512) : g0 + k0) : nullptr;
;     if (4 * lane < nw) {
;         f32x4 v[8];
; #pragma unroll
;         for (int j = 0; j < 8; ++j) v[j] = __builtin_nontemporal_load((const f32x4*)(W + (size_t)(k0 + 8 * wave + j) * N + n0 + 4 * lane));
; #pragma unroll
;         for (int j = 0; j < 8; ++j) { const float gv = gk ? gk[8 * wave + j] : 1.0f; *(LAS f32x4*)(scr + (8 * wave + j) * 260 + 4 * lane) = v[j] * gv; }
.LBB0_768:
	s_andn2_b64 vcc, exec, s[34:35]
	s_cbranch_vccnz .LBB0_780
	s_lshl_b32 s4, s69, 8
	s_and_b32 s16, s4, 0xfffffc00
	s_sub_i32 s4, 0, s16
	s_lshl_b32 s17, s59, 4
	s_add_i32 s16, s58, s16
	s_addk_i32 s17, 0x3a40
	s_add_i32 s16, s16, 0xfffc5c00
	s_and_b32 s18, s17, 0xffffffc0
	v_cmp_gt_i32_e32 vcc, s16, v1
	s_and_saveexec_b64 s[34:35], vcc
	s_cbranch_execz .LBB0_771
	s_add_i32 s17, s60, s4
	s_add_i32 s30, s17, 0x19400
	s_add_i32 s36, s18, s87
	s_ashr_i32 s31, s30, 31
	s_mov_b32 s37, s19
	v_lshl_add_u64 v[26:27], s[30:31], 2, v[74:75]
	s_lshl_b64 s[30:31], s[36:37], 12
	v_lshl_add_u64 v[2:3], v[26:27], 0, s[30:31]
	s_or_b32 s30, s36, 1
	s_mov_b32 s31, s19
	s_lshl_b64 s[30:31], s[30:31], 12
	v_lshl_add_u64 v[6:7], v[26:27], 0, s[30:31]
	s_or_b32 s30, s36, 2
	s_mov_b32 s31, s19
	s_lshl_b64 s[30:31], s[30:31], 12
	v_lshl_add_u64 v[10:11], v[26:27], 0, s[30:31]
	s_or_b32 s30, s36, 3
	s_mov_b32 s31, s19
	s_lshl_b64 s[30:31], s[30:31], 12
	v_lshl_add_u64 v[14:15], v[26:27], 0, s[30:31]
	s_or_b32 s30, s36, 4
	s_mov_b32 s31, s19
	s_lshl_b64 s[30:31], s[30:31], 12
	v_lshl_add_u64 v[18:19], v[26:27], 0, s[30:31]
	s_or_b32 s30, s36, 5
	s_mov_b32 s31, s19
	s_lshl_b64 s[30:31], s[30:31], 12
	v_lshl_add_u64 v[22:23], v[26:27], 0, s[30:31]
	s_or_b32 s30, s36, 6
	s_mov_b32 s31, s19
	s_lshl_b64 s[30:31], s[30:31], 12
	v_lshl_add_u64 v[28:29], v[26:27], 0, s[30:31]
	s_or_b32 s30, s36, 7
	s_mov_b32 s31, s19
	s_lshl_b64 s[30:31], s[30:31], 12
	v_lshl_add_u64 v[30:31], v[26:27], 0, s[30:31]
	global_load_dwordx4 v[2:5], v[2:3], off nt
	global_load_dwordx4 v[6:9], v[6:7], off nt
	global_load_dwordx4 v[10:13], v[10:11], off nt
	global_load_dwordx4 v[14:17], v[14:15], off nt
	global_load_dwordx4 v[18:21], v[18:19], off nt
	global_load_dwordx4 v[22:25], v[22:23], off nt
	global_load_dwordx4 v[26:29], v[28:29], off nt
	global_load_dwordx4 v[30:33], v[30:31], off nt
	v_readlane_b32 s1, v254, 49
	s_add_i32 s17, s1, s77
	v_lshl_add_u32 v34, v1, 2, s17
	s_waitcnt vmcnt(0)
	ds_write_b128 v34, v[2:5]
	ds_write_b128 v34, v[6:9] offset:1040
	ds_write_b128 v34, v[10:13] offset:2080
	ds_write_b128 v34, v[14:17] offset:3120
	ds_write_b128 v34, v[18:21] offset:4160
	ds_write_b128 v34, v[22:25] offset:5200
	ds_write_b128 v34, v[26:29] offset:6240
	ds_write_b128 v34, v[30:33] offset:7280

; #define LAS __attribute__((address_space(3)))
; __device__ __forceinline__ void transpose_item_wg(const float* W, int K, int N, bf16* WT, int mode, const float* g0, const float* g1, int item, LAS float* scr, int tid, int lane, int wave) {
;     const int nblk = (N + 255) >> 8, kb = item / nblk, nb = item - kb * nblk, k0 = 64 * kb, n0 = 256 * nb, nw = min(256, N - n0);
;     const float* gk = g0 ? ((g1 && k0 >= 512) ? g1 + (k0 - 512) : g0 + k0) : nullptr;
;     if (4 * lane < nw) {
;         f32x4 v[8];
; #pragma unroll
;         for (int j = 0; j < 8; ++j) v[j] = __builtin_nontemporal_load((const f32x4*)(W + (size_t)(k0 + 8 * wave + j) * N + n0 + 4 * lane));
; #pragma unroll
;         for (int j = 0; j < 8; ++j) { const float gv = gk ? gk[8 * wave + j] : 1.0f; *(LAS f32x4*)(scr + (8 * wave + j) * 260 + 4 * lane) = v[j] * gv; }
.LBB0_794:
	s_andn2_b64 vcc, exec, s[34:35]
	s_cbranch_vccnz .LBB0_555
	s_mul_hi_i32 s4, s78, 0x2e8ba2e9
	s_lshr_b32 s16, s4, 31
	s_ashr_i32 s4, s4, 1
	s_add_i32 s4, s4, s16
	s_mul_i32 s16, s4, 0xb00
	s_add_i32 s16, s58, s16
	s_lshl_b32 s34, s4, 6
	s_add_i32 s16, s16, 0xfffb0300
	s_ashr_i32 s35, s34, 31
	v_cmp_gt_i32_e32 vcc, s16, v1
	s_and_saveexec_b64 s[36:37], vcc
	s_cbranch_execz .LBB0_797
	s_mul_i32 s17, s4, 0xfffff500
	s_add_i32 s17, s60, s17
	s_add_i32 s30, s17, 0x2f400
	s_add_i32 s17, s34, s87
	s_ashr_i32 s31, s30, 31
	v_lshl_add_u64 v[30:31], s[30:31], 2, v[80:81]
	s_or_b32 s18, s17, 1
	v_mad_i64_i32 v[6:7], s[30:31], s18, v198, v[30:31]
	s_or_b32 s18, s17, 2
	v_mad_i64_i32 v[10:11], s[30:31], s18, v198, v[30:31]
	s_or_b32 s18, s17, 3
	v_mad_i64_i32 v[14:15], s[30:31], s18, v198, v[30:31]
	s_or_b32 s18, s17, 4
	v_mad_i64_i32 v[18:19], s[30:31], s18, v198, v[30:31]
	s_or_b32 s18, s17, 5
	v_mad_i64_i32 v[2:3], s[30:31], s17, v198, v[30:31]
	v_mad_i64_i32 v[22:23], s[30:31], s18, v198, v[30:31]
	s_or_b32 s18, s17, 6
	s_or_b32 s17, s17, 7
	v_mad_i64_i32 v[26:27], s[30:31], s18, v198, v[30:31]
	v_mad_i64_i32 v[30:31], s[30:31], s17, v198, v[30:31]
	s_lshl_b64 s[30:31], s[34:35], 2
	s_add_u32 s30, s14, s30
	s_addc_u32 s31, s15, s31
	global_load_dwordx4 v[2:5], v[2:3], off nt
	v_lshl_add_u32 v82, v1, 2, s77
	global_load_dwordx4 v[6:9], v[6:7], off nt
	v_readlane_b32 s1, v254, 49
	global_load_dwordx4 v[10:13], v[10:11], off nt
	global_load_dwordx4 v[14:17], v[14:15], off nt
	v_add_u32_e32 v145, s1, v82
	global_load_dwordx4 v[18:21], v[18:19], off nt
	v_readlane_b32 s1, v252, 25
	global_load_dwordx4 v[22:25], v[22:23], off nt
	global_load_dwordx4 v[26:29], v[26:27], off nt
	global_load_dwordx4 v[30:33], v[30:31], off nt
	s_nop 0
	global_load_dwordx4 v[34:37], v99, s[30:31] offset:16
	global_load_dwordx4 v[146:149], v99, s[30:31]
	s_waitcnt vmcnt(0)
	v_pk_mul_f32 v[4:5], v[4:5], v[146:147] op_sel_hi:[1,0]
	v_pk_mul_f32 v[2:3], v[2:3], v[146:147] op_sel_hi:[1,0]
	ds_write_b128 v145, v[2:5]
	v_pk_mul_f32 v[4:5], v[8:9], v[146:147] op_sel:[0,1]
	v_pk_mul_f32 v[2:3], v[6:7], v[146:147] op_sel:[0,1]
	v_add_u32_e32 v6, s1, v82
	ds_write_b128 v6, v[2:5]
	v_pk_mul_f32 v[4:5], v[12:13], v[148:149] op_sel_hi:[1,0]
	v_pk_mul_f32 v[2:3], v[10:11], v[148:149] op_sel_hi:[1,0]
	ds_write_b128 v6, v[2:5] offset:1040
	v_mov_b32_e32 v2, v149
	v_pk_mul_f32 v[4:5], v[16:17], v[2:3] op_sel_hi:[1,0]
	v_pk_mul_f32 v[2:3], v[14:15], v[2:3] op_sel_hi:[1,0]
	ds_write_b128 v6, v[2:5] offset:2080
	v_pk_mul_f32 v[4:5], v[20:21], v[34:35] op_sel_hi:[1,0]
	v_pk_mul_f32 v[2:3], v[18:19], v[34:35] op_sel_hi:[1,0]
	ds_write_b128 v6, v[2:5] offset:3120
	v_pk_mul_f32 v[4:5], v[24:25], v[34:35] op_sel:[0,1]
	v_pk_mul_f32 v[2:3], v[22:23], v[34:35] op_sel:[0,1]
	ds_write_b128 v6, v[2:5] offset:4160
	v_pk_mul_f32 v[4:5], v[28:29], v[36:37] op_sel_hi:[1,0]
	v_pk_mul_f32 v[2:3], v[26:27], v[36:37] op_sel_hi:[1,0]
	ds_write_b128 v6, v[2:5] offset:5200
	v_mov_b32_e32 v2, v37
	v_pk_mul_f32 v[4:5], v[32:33], v[2:3] op_sel_hi:[1,0]
	v_pk_mul_f32 v[2:3], v[30:31], v[2:3] op_sel_hi:[1,0]
	ds_write_b128 v6, v[2:5] offset:6240

; __device__ __forceinline__ unsigned pk2(float lo, float hi) { f32x2 v = {lo, hi}; bf16x2_t b = __builtin_convertvector(v, bf16x2_t); return __builtin_bit_cast(unsigned, b); }
;     __device__ __forceinline__ void operator()(const f32x4 (&acc)[2][2][4][2], const pg8::Unit& u, int wr, int wc, int fr, int fq) const {
;     ...
;                     if (cb < 64) {
;                         const f32x4 a0 = acc[ai][1][m][0] * rr[ai][m], a1 = acc[ai][1][m][1] * rr[ai][m];
;                         const f32x4 c0 = *(const f32x4*)(CS_ + ((size_t)t * 32 + (cb >> 1)) * 2), c1 = *(const f32x4*)(CS_ + ((size_t)t * 32 + (cb >> 1) + 2) * 2);
;                         u32x4 w; w.x = pk2(a0[0] * c0[0] - a0[1] * c0[1], a0[1] * c0[0] + a0[0] * c0[1]); w.y = pk2(a0[2] * c0[2] - a0[3] * c0[3], a0[3] * c0[2] + a0[2] * c0[3]);
;                         w.z = pk2(a1[0] * c1[0] - a1[1] * c1[1], a1[1] * c1[0] + a1[0] * c1[1]); w.w = pk2(a1[2] * c1[2] - a1[3] * c1[3], a1[3] * c1[2] + a1[2] * c1[3]);
; #pragma unroll
;                         for (int hh = 0; hh < 4; ++hh) *(u32x4*)(KM_ + ((size_t)(b * 4 + hh) * S + t) * 192 + 128 + cb) = w;
.LBB0_974:
	s_or_b64 exec, exec, s[34:35]
	v_cndmask_b32_e64 v134, 0, 1, s[56:57]
	v_cmp_ne_u32_e64 s[46:47], 1, v134
	s_andn2_b64 vcc, exec, s[56:57]
	s_lshl_b32 s64, s60, 2
	s_cbranch_vccnz .LBB0_976
	v_mov_b32_e32 v134, v158
	v_mov_b32_e32 v135, v158
	v_lshl_add_u64 v[132:133], v[146:147], 0, v[132:133]
	v_pk_mul_f32 v[176:177], v[122:123], v[134:135]
	v_pk_mul_f32 v[186:187], v[118:119], v[134:135]
	global_load_dwordx4 v[180:183], v[132:133], off offset:16
	global_load_dwordx4 v[132:135], v[132:133], off
	v_mov_b32_e32 v159, v158
	v_pk_mul_f32 v[184:185], v[120:121], v[158:159]
	v_pk_mul_f32 v[188:189], v[116:117], v[158:159]
	s_ashr_i32 s65, s64, 31
	s_lshl_b64 s[16:17], s[64:65], 13
	s_waitcnt vmcnt(0)
	v_pk_mul_f32 v[190:191], v[184:185], v[132:133] op_sel:[1,1] op_sel_hi:[0,1]
	v_pk_fma_f32 v[192:193], v[184:185], v[132:133], v[190:191] neg_lo:[0,0,1] neg_hi:[0,0,1]
	v_pk_fma_f32 v[132:133], v[184:185], v[132:133], v[190:191] op_sel_hi:[1,0,1]
	v_mov_b32_e32 v184, v135
	v_pk_mul_f32 v[184:185], v[176:177], v[184:185] op_sel:[1,0] op_sel_hi:[0,0]
	v_pk_fma_f32 v[190:191], v[176:177], v[134:135], v[184:185] neg_lo:[0,0,1] neg_hi:[0,0,1]
	v_pk_fma_f32 v[134:135], v[176:177], v[134:135], v[184:185] op_sel_hi:[1,0,1]
	v_cvt_pk_bf16_f32 v132, v192, v133
	v_cvt_pk_bf16_f32 v133, v190, v135
	v_pk_mul_f32 v[134:135], v[188:189], v[180:181] op_sel:[1,1] op_sel_hi:[0,1]
	v_pk_fma_f32 v[176:177], v[188:189], v[180:181], v[134:135] neg_lo:[0,0,1] neg_hi:[0,0,1]
	v_pk_fma_f32 v[134:135], v[188:189], v[180:181], v[134:135] op_sel_hi:[1,0,1]
	s_nop 0
	v_cvt_pk_bf16_f32 v134, v176, v135
	v_mov_b32_e32 v176, v183
	v_pk_mul_f32 v[176:177], v[186:187], v[176:177] op_sel:[1,0] op_sel_hi:[0,0]
	v_pk_fma_f32 v[180:181], v[186:187], v[182:183], v[176:177] neg_lo:[0,0,1] neg_hi:[0,0,1]
	v_pk_fma_f32 v[176:177], v[186:187], v[182:183], v[176:177] op_sel_hi:[1,0,1]
	s_nop 0
	v_cvt_pk_bf16_f32 v135, v180, v177
	v_lshl_add_u64 v[176:177], s[16:17], 0, v[156:157]
	v_mad_u64_u32 v[180:181], s[16:17], v176, s5, v[148:149]
	s_or_b32 s16, s64, 1
	s_ashr_i32 s17, s16, 31
	s_lshl_b64 s[16:17], s[16:17], 13
	v_mad_i32_i24 v181, v177, s5, v181
	v_lshl_add_u64 v[176:177], s[16:17], 0, v[156:157]
	global_store_dwordx4 v[180:181], v[132:135], off offset:256
	v_mad_u64_u32 v[180:181], s[16:17], v176, s5, v[148:149]
	s_or_b32 s16, s64, 2
	s_ashr_i32 s17, s16, 31
	s_lshl_b64 s[16:17], s[16:17], 13
	v_mad_i32_i24 v181, v177, s5, v181
	v_lshl_add_u64 v[176:177], s[16:17], 0, v[156:157]
	global_store_dwordx4 v[180:181], v[132:135], off offset:256
	v_mad_u64_u32 v[180:181], s[16:17], v176, s5, v[148:149]
	s_or_b32 s16, s64, 3
	s_ashr_i32 s17, s16, 31
	s_lshl_b64 s[16:17], s[16:17], 13
	v_mad_i32_i24 v181, v177, s5, v181
	v_lshl_add_u64 v[176:177], s[16:17], 0, v[156:157]
	global_store_dwordx4 v[180:181], v[132:135], off offset:256
	v_mad_u64_u32 v[180:181], s[16:17], v176, s5, v[148:149]
	v_mad_i32_i24 v181, v177, s5, v181
	global_store_dwordx4 v[180:181], v[132:135], off offset:256

; __device__ __forceinline__ unsigned pk2(float lo, float hi) { f32x2 v = {lo, hi}; bf16x2_t b = __builtin_convertvector(v, bf16x2_t); return __builtin_bit_cast(unsigned, b); }
;     __device__ __forceinline__ void operator()(const f32x4 (&acc)[2][2][4][2], const pg8::Unit& u, int wr, int wc, int fr, int fq) const {
;     ...
;                     if (cb < 64) {
;                         const f32x4 a0 = acc[ai][1][m][0] * rr[ai][m], a1 = acc[ai][1][m][1] * rr[ai][m];
;                         const f32x4 c0 = *(const f32x4*)(CS_ + ((size_t)t * 32 + (cb >> 1)) * 2), c1 = *(const f32x4*)(CS_ + ((size_t)t * 32 + (cb >> 1) + 2) * 2);
;                         u32x4 w; w.x = pk2(a0[0] * c0[0] - a0[1] * c0[1], a0[1] * c0[0] + a0[0] * c0[1]); w.y = pk2(a0[2] * c0[2] - a0[3] * c0[3], a0[3] * c0[2] + a0[2] * c0[3]);
;                         w.z = pk2(a1[0] * c1[0] - a1[1] * c1[1], a1[1] * c1[0] + a1[0] * c1[1]); w.w = pk2(a1[2] * c1[2] - a1[3] * c1[3], a1[3] * c1[2] + a1[2] * c1[3]);
; #pragma unroll
;                         for (int hh = 0; hh < 4; ++hh) *(u32x4*)(KM_ + ((size_t)(b * 4 + hh) * S + t) * 192 + 128 + cb) = w;
.LBB0_978:
	s_or_b64 exec, exec, s[34:35]
	s_and_b64 vcc, exec, s[46:47]
	s_cbranch_vccnz .LBB0_980
	v_or_b32_e32 v176, 16, v156
	v_mov_b32_e32 v132, v160
	v_mov_b32_e32 v133, v160
	v_ashrrev_i32_e32 v177, 31, v176
	v_pk_mul_f32 v[184:185], v[106:107], v[132:133]
	v_pk_mul_f32 v[188:189], v[102:103], v[132:133]
	v_lshlrev_b64 v[132:133], 8, v[176:177]
	v_lshl_add_u64 v[132:133], v[146:147], 0, v[132:133]
	global_load_dwordx4 v[180:183], v[132:133], off offset:16
	global_load_dwordx4 v[132:135], v[132:133], off
	v_mov_b32_e32 v161, v160
	v_pk_mul_f32 v[186:187], v[104:105], v[160:161]
	v_pk_mul_f32 v[190:191], v[100:101], v[160:161]
	s_ashr_i32 s65, s64, 31
	s_lshl_b64 s[16:17], s[64:65], 13
	s_waitcnt vmcnt(0)
	v_pk_mul_f32 v[192:193], v[186:187], v[132:133] op_sel:[1,1] op_sel_hi:[0,1]
	v_pk_fma_f32 v[208:209], v[186:187], v[132:133], v[192:193] neg_lo:[0,0,1] neg_hi:[0,0,1]
	v_pk_fma_f32 v[132:133], v[186:187], v[132:133], v[192:193] op_sel_hi:[1,0,1]
	v_mov_b32_e32 v186, v135
	v_pk_mul_f32 v[186:187], v[184:185], v[186:187] op_sel:[1,0] op_sel_hi:[0,0]
	v_pk_fma_f32 v[192:193], v[184:185], v[134:135], v[186:187] neg_lo:[0,0,1] neg_hi:[0,0,1]
	v_pk_fma_f32 v[134:135], v[184:185], v[134:135], v[186:187] op_sel_hi:[1,0,1]
	v_cvt_pk_bf16_f32 v132, v208, v133
	v_cvt_pk_bf16_f32 v133, v192, v135
	v_pk_mul_f32 v[134:135], v[190:191], v[180:181] op_sel:[1,1] op_sel_hi:[0,1]
	v_pk_fma_f32 v[184:185], v[190:191], v[180:181], v[134:135] neg_lo:[0,0,1] neg_hi:[0,0,1]
	v_pk_fma_f32 v[134:135], v[190:191], v[180:181], v[134:135] op_sel_hi:[1,0,1]
	v_mov_b32_e32 v180, v183
	v_pk_mul_f32 v[180:181], v[188:189], v[180:181] op_sel:[1,0] op_sel_hi:[0,0]
	v_cvt_pk_bf16_f32 v134, v184, v135
	v_pk_fma_f32 v[184:185], v[188:189], v[182:183], v[180:181] neg_lo:[0,0,1] neg_hi:[0,0,1]
	v_pk_fma_f32 v[180:181], v[188:189], v[182:183], v[180:181] op_sel_hi:[1,0,1]
	s_nop 0
	v_cvt_pk_bf16_f32 v135, v184, v181
	v_lshl_add_u64 v[180:181], s[16:17], 0, v[176:177]
	v_mad_u64_u32 v[182:183], s[16:17], v180, s5, v[148:149]
	s_or_b32 s16, s64, 1
	s_ashr_i32 s17, s16, 31
	s_lshl_b64 s[16:17], s[16:17], 13
	v_mad_i32_i24 v183, v181, s5, v183
	v_lshl_add_u64 v[180:181], s[16:17], 0, v[176:177]
	global_store_dwordx4 v[182:183], v[132:135], off offset:256
	v_mad_u64_u32 v[182:183], s[16:17], v180, s5, v[148:149]
	s_or_b32 s16, s64, 2
	s_ashr_i32 s17, s16, 31
	s_lshl_b64 s[16:17], s[16:17], 13
	v_mad_i32_i24 v183, v181, s5, v183
	v_lshl_add_u64 v[180:181], s[16:17], 0, v[176:177]
	global_store_dwordx4 v[182:183], v[132:135], off offset:256
	v_mad_u64_u32 v[182:183], s[16:17], v180, s5, v[148:149]
	s_or_b32 s16, s64, 3
	s_ashr_i32 s17, s16, 31
	s_lshl_b64 s[16:17], s[16:17], 13
	v_lshl_add_u64 v[176:177], s[16:17], 0, v[176:177]
	v_mad_i32_i24 v183, v181, s5, v183
	v_mad_u64_u32 v[180:181], s[16:17], v176, s5, v[148:149]
	v_mad_i32_i24 v181, v177, s5, v181
	global_store_dwordx4 v[182:183], v[132:135], off offset:256
	global_store_dwordx4 v[180:181], v[132:135], off offset:256

; __device__ __forceinline__ unsigned pk2(float lo, float hi) { f32x2 v = {lo, hi}; bf16x2_t b = __builtin_convertvector(v, bf16x2_t); return __builtin_bit_cast(unsigned, b); }
;     __device__ __forceinline__ void operator()(const f32x4 (&acc)[2][2][4][2], const pg8::Unit& u, int wr, int wc, int fr, int fq) const {
;     ...
;                     if (cb < 64) {
;                         const f32x4 a0 = acc[ai][1][m][0] * rr[ai][m], a1 = acc[ai][1][m][1] * rr[ai][m];
;                         const f32x4 c0 = *(const f32x4*)(CS_ + ((size_t)t * 32 + (cb >> 1)) * 2), c1 = *(const f32x4*)(CS_ + ((size_t)t * 32 + (cb >> 1) + 2) * 2);
;                         u32x4 w; w.x = pk2(a0[0] * c0[0] - a0[1] * c0[1], a0[1] * c0[0] + a0[0] * c0[1]); w.y = pk2(a0[2] * c0[2] - a0[3] * c0[3], a0[3] * c0[2] + a0[2] * c0[3]);
;                         w.z = pk2(a1[0] * c1[0] - a1[1] * c1[1], a1[1] * c1[0] + a1[0] * c1[1]); w.w = pk2(a1[2] * c1[2] - a1[3] * c1[3], a1[3] * c1[2] + a1[2] * c1[3]);
; #pragma unroll
;                         for (int hh = 0; hh < 4; ++hh) *(u32x4*)(KM_ + ((size_t)(b * 4 + hh) * S + t) * 192 + 128 + cb) = w;
.LBB0_982:
	s_or_b64 exec, exec, s[34:35]
	s_and_b64 vcc, exec, s[46:47]
	s_cbranch_vccnz .LBB0_984
	v_or_b32_e32 v176, 32, v156
	v_mov_b32_e32 v132, v162
	v_mov_b32_e32 v133, v162
	v_ashrrev_i32_e32 v177, 31, v176
	v_pk_mul_f32 v[184:185], v[88:89], v[132:133]
	v_pk_mul_f32 v[188:189], v[84:85], v[132:133]
	v_lshlrev_b64 v[132:133], 8, v[176:177]
	v_lshl_add_u64 v[132:133], v[146:147], 0, v[132:133]
	global_load_dwordx4 v[180:183], v[132:133], off offset:16
	global_load_dwordx4 v[132:135], v[132:133], off
	v_mov_b32_e32 v163, v162
	v_pk_mul_f32 v[186:187], v[86:87], v[162:163]
	v_pk_mul_f32 v[190:191], v[82:83], v[162:163]
	s_ashr_i32 s65, s64, 31
	s_lshl_b64 s[16:17], s[64:65], 13
	s_waitcnt vmcnt(0)
	v_pk_mul_f32 v[192:193], v[186:187], v[132:133] op_sel:[1,1] op_sel_hi:[0,1]
	v_pk_fma_f32 v[208:209], v[186:187], v[132:133], v[192:193] neg_lo:[0,0,1] neg_hi:[0,0,1]
	v_pk_fma_f32 v[132:133], v[186:187], v[132:133], v[192:193] op_sel_hi:[1,0,1]
	v_mov_b32_e32 v186, v135
	v_pk_mul_f32 v[186:187], v[184:185], v[186:187] op_sel:[1,0] op_sel_hi:[0,0]
	v_pk_fma_f32 v[192:193], v[184:185], v[134:135], v[186:187] neg_lo:[0,0,1] neg_hi:[0,0,1]
	v_pk_fma_f32 v[134:135], v[184:185], v[134:135], v[186:187] op_sel_hi:[1,0,1]
	v_cvt_pk_bf16_f32 v132, v208, v133
	v_cvt_pk_bf16_f32 v133, v192, v135
	v_pk_mul_f32 v[134:135], v[190:191], v[180:181] op_sel:[1,1] op_sel_hi:[0,1]
	v_pk_fma_f32 v[184:185], v[190:191], v[180:181], v[134:135] neg_lo:[0,0,1] neg_hi:[0,0,1]
	v_pk_fma_f32 v[134:135], v[190:191], v[180:181], v[134:135] op_sel_hi:[1,0,1]
	v_mov_b32_e32 v180, v183
	v_pk_mul_f32 v[180:181], v[188:189], v[180:181] op_sel:[1,0] op_sel_hi:[0,0]
	v_cvt_pk_bf16_f32 v134, v184, v135
	v_pk_fma_f32 v[184:185], v[188:189], v[182:183], v[180:181] neg_lo:[0,0,1] neg_hi:[0,0,1]
	v_pk_fma_f32 v[180:181], v[188:189], v[182:183], v[180:181] op_sel_hi:[1,0,1]
	s_nop 0
	v_cvt_pk_bf16_f32 v135, v184, v181
	v_lshl_add_u64 v[180:181], s[16:17], 0, v[176:177]
	v_mad_u64_u32 v[182:183], s[16:17], v180, s5, v[148:149]
	s_or_b32 s16, s64, 1
	s_ashr_i32 s17, s16, 31
	s_lshl_b64 s[16:17], s[16:17], 13
	v_mad_i32_i24 v183, v181, s5, v183
	v_lshl_add_u64 v[180:181], s[16:17], 0, v[176:177]
	global_store_dwordx4 v[182:183], v[132:135], off offset:256
	v_mad_u64_u32 v[182:183], s[16:17], v180, s5, v[148:149]
	s_or_b32 s16, s64, 2
	s_ashr_i32 s17, s16, 31
	s_lshl_b64 s[16:17], s[16:17], 13
	v_mad_i32_i24 v183, v181, s5, v183
	v_lshl_add_u64 v[180:181], s[16:17], 0, v[176:177]
	global_store_dwordx4 v[182:183], v[132:135], off offset:256
	v_mad_u64_u32 v[182:183], s[16:17], v180, s5, v[148:149]
	s_or_b32 s16, s64, 3
	s_ashr_i32 s17, s16, 31
	s_lshl_b64 s[16:17], s[16:17], 13
	v_lshl_add_u64 v[176:177], s[16:17], 0, v[176:177]
	v_mad_i32_i24 v183, v181, s5, v183
	v_mad_u64_u32 v[180:181], s[16:17], v176, s5, v[148:149]
	v_mad_i32_i24 v181, v177, s5, v181
	global_store_dwordx4 v[182:183], v[132:135], off offset:256
	global_store_dwordx4 v[180:181], v[132:135], off offset:256

; __device__ __forceinline__ unsigned pk2(float lo, float hi) { f32x2 v = {lo, hi}; bf16x2_t b = __builtin_convertvector(v, bf16x2_t); return __builtin_bit_cast(unsigned, b); }
;     __device__ __forceinline__ void operator()(const f32x4 (&acc)[2][2][4][2], const pg8::Unit& u, int wr, int wc, int fr, int fq) const {
;     ...
;                     if (cb < 64) {
;                         const f32x4 a0 = acc[ai][1][m][0] * rr[ai][m], a1 = acc[ai][1][m][1] * rr[ai][m];
;                         const f32x4 c0 = *(const f32x4*)(CS_ + ((size_t)t * 32 + (cb >> 1)) * 2), c1 = *(const f32x4*)(CS_ + ((size_t)t * 32 + (cb >> 1) + 2) * 2);
;                         u32x4 w; w.x = pk2(a0[0] * c0[0] - a0[1] * c0[1], a0[1] * c0[0] + a0[0] * c0[1]); w.y = pk2(a0[2] * c0[2] - a0[3] * c0[3], a0[3] * c0[2] + a0[2] * c0[3]);
;                         w.z = pk2(a1[0] * c1[0] - a1[1] * c1[1], a1[1] * c1[0] + a1[0] * c1[1]); w.w = pk2(a1[2] * c1[2] - a1[3] * c1[3], a1[3] * c1[2] + a1[2] * c1[3]);
; #pragma unroll
;                         for (int hh = 0; hh < 4; ++hh) *(u32x4*)(KM_ + ((size_t)(b * 4 + hh) * S + t) * 192 + 128 + cb) = w;
.LBB0_986:
	s_or_b64 exec, exec, s[34:35]
	s_and_b64 vcc, exec, s[46:47]
	s_cbranch_vccnz .LBB0_988
	v_or_b32_e32 v176, 48, v156
	v_mov_b32_e32 v132, v164
	v_mov_b32_e32 v133, v164
	v_ashrrev_i32_e32 v177, 31, v176
	v_pk_mul_f32 v[184:185], v[72:73], v[132:133]
	v_pk_mul_f32 v[188:189], v[68:69], v[132:133]
	v_lshlrev_b64 v[132:133], 8, v[176:177]
	v_lshl_add_u64 v[132:133], v[146:147], 0, v[132:133]
	global_load_dwordx4 v[180:183], v[132:133], off offset:16
	global_load_dwordx4 v[132:135], v[132:133], off
	v_mov_b32_e32 v165, v164
	v_pk_mul_f32 v[186:187], v[70:71], v[164:165]
	v_pk_mul_f32 v[190:191], v[66:67], v[164:165]
	s_ashr_i32 s65, s64, 31
	s_lshl_b64 s[16:17], s[64:65], 13
	s_waitcnt vmcnt(0)
	v_pk_mul_f32 v[192:193], v[186:187], v[132:133] op_sel:[1,1] op_sel_hi:[0,1]
	v_pk_fma_f32 v[208:209], v[186:187], v[132:133], v[192:193] neg_lo:[0,0,1] neg_hi:[0,0,1]
	v_pk_fma_f32 v[132:133], v[186:187], v[132:133], v[192:193] op_sel_hi:[1,0,1]
	v_mov_b32_e32 v186, v135
	v_pk_mul_f32 v[186:187], v[184:185], v[186:187] op_sel:[1,0] op_sel_hi:[0,0]
	v_pk_fma_f32 v[192:193], v[184:185], v[134:135], v[186:187] neg_lo:[0,0,1] neg_hi:[0,0,1]
	v_pk_fma_f32 v[134:135], v[184:185], v[134:135], v[186:187] op_sel_hi:[1,0,1]
	v_cvt_pk_bf16_f32 v132, v208, v133
	v_cvt_pk_bf16_f32 v133, v192, v135
	v_pk_mul_f32 v[134:135], v[190:191], v[180:181] op_sel:[1,1] op_sel_hi:[0,1]
	v_pk_fma_f32 v[184:185], v[190:191], v[180:181], v[134:135] neg_lo:[0,0,1] neg_hi:[0,0,1]
	v_pk_fma_f32 v[134:135], v[190:191], v[180:181], v[134:135] op_sel_hi:[1,0,1]
	v_mov_b32_e32 v180, v183
	v_pk_mul_f32 v[180:181], v[188:189], v[180:181] op_sel:[1,0] op_sel_hi:[0,0]
	v_cvt_pk_bf16_f32 v134, v184, v135
	v_pk_fma_f32 v[184:185], v[188:189], v[182:183], v[180:181] neg_lo:[0,0,1] neg_hi:[0,0,1]
	v_pk_fma_f32 v[180:181], v[188:189], v[182:183], v[180:181] op_sel_hi:[1,0,1]
	s_nop 0
	v_cvt_pk_bf16_f32 v135, v184, v181
	v_lshl_add_u64 v[180:181], s[16:17], 0, v[176:177]
	v_mad_u64_u32 v[182:183], s[16:17], v180, s5, v[148:149]
	s_or_b32 s16, s64, 1
	s_ashr_i32 s17, s16, 31
	s_lshl_b64 s[16:17], s[16:17], 13
	v_mad_i32_i24 v183, v181, s5, v183
	v_lshl_add_u64 v[180:181], s[16:17], 0, v[176:177]
	global_store_dwordx4 v[182:183], v[132:135], off offset:256
	v_mad_u64_u32 v[182:183], s[16:17], v180, s5, v[148:149]
	s_or_b32 s16, s64, 2
	s_ashr_i32 s17, s16, 31
	s_lshl_b64 s[16:17], s[16:17], 13
	v_mad_i32_i24 v183, v181, s5, v183
	v_lshl_add_u64 v[180:181], s[16:17], 0, v[176:177]
	global_store_dwordx4 v[182:183], v[132:135], off offset:256
	v_mad_u64_u32 v[182:183], s[16:17], v180, s5, v[148:149]
	s_or_b32 s16, s64, 3
	s_ashr_i32 s17, s16, 31
	s_lshl_b64 s[16:17], s[16:17], 13
	v_lshl_add_u64 v[176:177], s[16:17], 0, v[176:177]
	v_mad_i32_i24 v183, v181, s5, v183
	v_mad_u64_u32 v[180:181], s[16:17], v176, s5, v[148:149]
	v_mad_i32_i24 v181, v177, s5, v181
	global_store_dwordx4 v[182:183], v[132:135], off offset:256
	global_store_dwordx4 v[180:181], v[132:135], off offset:256

; __device__ __forceinline__ unsigned pk2(float lo, float hi) { f32x2 v = {lo, hi}; bf16x2_t b = __builtin_convertvector(v, bf16x2_t); return __builtin_bit_cast(unsigned, b); }
;     __device__ __forceinline__ void operator()(const f32x4 (&acc)[2][2][4][2], const pg8::Unit& u, int wr, int wc, int fr, int fq) const {
;     ...
;                     if (cb < 64) {
;                         const f32x4 a0 = acc[ai][1][m][0] * rr[ai][m], a1 = acc[ai][1][m][1] * rr[ai][m];
;                         const f32x4 c0 = *(const f32x4*)(CS_ + ((size_t)t * 32 + (cb >> 1)) * 2), c1 = *(const f32x4*)(CS_ + ((size_t)t * 32 + (cb >> 1) + 2) * 2);
;                         u32x4 w; w.x = pk2(a0[0] * c0[0] - a0[1] * c0[1], a0[1] * c0[0] + a0[0] * c0[1]); w.y = pk2(a0[2] * c0[2] - a0[3] * c0[3], a0[3] * c0[2] + a0[2] * c0[3]);
;                         w.z = pk2(a1[0] * c1[0] - a1[1] * c1[1], a1[1] * c1[0] + a1[0] * c1[1]); w.w = pk2(a1[2] * c1[2] - a1[3] * c1[3], a1[3] * c1[2] + a1[2] * c1[3]);
; #pragma unroll
;                         for (int hh = 0; hh < 4; ++hh) *(u32x4*)(KM_ + ((size_t)(b * 4 + hh) * S + t) * 192 + 128 + cb) = w;
.LBB0_990:
	s_or_b64 exec, exec, s[34:35]
	s_and_b64 vcc, exec, s[46:47]
	s_cbranch_vccnz .LBB0_992
	v_add_u32_e32 v176, 0x80, v156
	v_mov_b32_e32 v132, v166
	v_mov_b32_e32 v133, v166
	v_ashrrev_i32_e32 v177, 31, v176
	v_pk_mul_f32 v[184:185], v[56:57], v[132:133]
	v_pk_mul_f32 v[188:189], v[52:53], v[132:133]
	v_lshlrev_b64 v[132:133], 8, v[176:177]
	v_lshl_add_u64 v[132:133], v[146:147], 0, v[132:133]
	global_load_dwordx4 v[180:183], v[132:133], off offset:16
	global_load_dwordx4 v[132:135], v[132:133], off
	v_mov_b32_e32 v167, v166
	v_pk_mul_f32 v[186:187], v[54:55], v[166:167]
	v_pk_mul_f32 v[190:191], v[50:51], v[166:167]
	s_ashr_i32 s65, s64, 31
	s_lshl_b64 s[16:17], s[64:65], 13
	s_waitcnt vmcnt(0)
	v_pk_mul_f32 v[192:193], v[186:187], v[132:133] op_sel:[1,1] op_sel_hi:[0,1]
	v_pk_fma_f32 v[208:209], v[186:187], v[132:133], v[192:193] neg_lo:[0,0,1] neg_hi:[0,0,1]
	v_pk_fma_f32 v[132:133], v[186:187], v[132:133], v[192:193] op_sel_hi:[1,0,1]
	v_mov_b32_e32 v186, v135
	v_pk_mul_f32 v[186:187], v[184:185], v[186:187] op_sel:[1,0] op_sel_hi:[0,0]
	v_pk_fma_f32 v[192:193], v[184:185], v[134:135], v[186:187] neg_lo:[0,0,1] neg_hi:[0,0,1]
	v_pk_fma_f32 v[134:135], v[184:185], v[134:135], v[186:187] op_sel_hi:[1,0,1]
	v_cvt_pk_bf16_f32 v132, v208, v133
	v_cvt_pk_bf16_f32 v133, v192, v135
	v_pk_mul_f32 v[134:135], v[190:191], v[180:181] op_sel:[1,1] op_sel_hi:[0,1]
	v_pk_fma_f32 v[184:185], v[190:191], v[180:181], v[134:135] neg_lo:[0,0,1] neg_hi:[0,0,1]
	v_pk_fma_f32 v[134:135], v[190:191], v[180:181], v[134:135] op_sel_hi:[1,0,1]
	v_mov_b32_e32 v180, v183
	v_pk_mul_f32 v[180:181], v[188:189], v[180:181] op_sel:[1,0] op_sel_hi:[0,0]
	v_cvt_pk_bf16_f32 v134, v184, v135
	v_pk_fma_f32 v[184:185], v[188:189], v[182:183], v[180:181] neg_lo:[0,0,1] neg_hi:[0,0,1]
	v_pk_fma_f32 v[180:181], v[188:189], v[182:183], v[180:181] op_sel_hi:[1,0,1]
	s_nop 0
	v_cvt_pk_bf16_f32 v135, v184, v181
	v_lshl_add_u64 v[180:181], s[16:17], 0, v[176:177]
	v_mad_u64_u32 v[182:183], s[16:17], v180, s5, v[148:149]
	s_or_b32 s16, s64, 1
	s_ashr_i32 s17, s16, 31
	s_lshl_b64 s[16:17], s[16:17], 13
	v_mad_i32_i24 v183, v181, s5, v183
	v_lshl_add_u64 v[180:181], s[16:17], 0, v[176:177]
	global_store_dwordx4 v[182:183], v[132:135], off offset:256
	v_mad_u64_u32 v[182:183], s[16:17], v180, s5, v[148:149]
	s_or_b32 s16, s64, 2
	s_ashr_i32 s17, s16, 31
	s_lshl_b64 s[16:17], s[16:17], 13
	v_mad_i32_i24 v183, v181, s5, v183
	v_lshl_add_u64 v[180:181], s[16:17], 0, v[176:177]
	global_store_dwordx4 v[182:183], v[132:135], off offset:256
	v_mad_u64_u32 v[182:183], s[16:17], v180, s5, v[148:149]
	s_or_b32 s16, s64, 3
	s_ashr_i32 s17, s16, 31
	s_lshl_b64 s[16:17], s[16:17], 13
	v_lshl_add_u64 v[176:177], s[16:17], 0, v[176:177]
	v_mad_i32_i24 v183, v181, s5, v183
	v_mad_u64_u32 v[180:181], s[16:17], v176, s5, v[148:149]
	v_mad_i32_i24 v181, v177, s5, v181
	global_store_dwordx4 v[182:183], v[132:135], off offset:256
	global_store_dwordx4 v[180:181], v[132:135], off offset:256

; __device__ __forceinline__ unsigned pk2(float lo, float hi) { f32x2 v = {lo, hi}; bf16x2_t b = __builtin_convertvector(v, bf16x2_t); return __builtin_bit_cast(unsigned, b); }
;     __device__ __forceinline__ void operator()(const f32x4 (&acc)[2][2][4][2], const pg8::Unit& u, int wr, int wc, int fr, int fq) const {
;     ...
;                     if (cb < 64) {
;                         const f32x4 a0 = acc[ai][1][m][0] * rr[ai][m], a1 = acc[ai][1][m][1] * rr[ai][m];
;                         const f32x4 c0 = *(const f32x4*)(CS_ + ((size_t)t * 32 + (cb >> 1)) * 2), c1 = *(const f32x4*)(CS_ + ((size_t)t * 32 + (cb >> 1) + 2) * 2);
;                         u32x4 w; w.x = pk2(a0[0] * c0[0] - a0[1] * c0[1], a0[1] * c0[0] + a0[0] * c0[1]); w.y = pk2(a0[2] * c0[2] - a0[3] * c0[3], a0[3] * c0[2] + a0[2] * c0[3]);
;                         w.z = pk2(a1[0] * c1[0] - a1[1] * c1[1], a1[1] * c1[0] + a1[0] * c1[1]); w.w = pk2(a1[2] * c1[2] - a1[3] * c1[3], a1[3] * c1[2] + a1[2] * c1[3]);
; #pragma unroll
;                         for (int hh = 0; hh < 4; ++hh) *(u32x4*)(KM_ + ((size_t)(b * 4 + hh) * S + t) * 192 + 128 + cb) = w;
.LBB0_994:
	s_or_b64 exec, exec, s[34:35]
	s_and_b64 vcc, exec, s[46:47]
	s_cbranch_vccnz .LBB0_996
	v_add_u32_e32 v176, 0x90, v156
	v_mov_b32_e32 v132, v168
	v_mov_b32_e32 v133, v168
	v_ashrrev_i32_e32 v177, 31, v176
	v_pk_mul_f32 v[184:185], v[40:41], v[132:133]
	v_pk_mul_f32 v[188:189], v[36:37], v[132:133]
	v_lshlrev_b64 v[132:133], 8, v[176:177]
	v_lshl_add_u64 v[132:133], v[146:147], 0, v[132:133]
	global_load_dwordx4 v[180:183], v[132:133], off offset:16
	global_load_dwordx4 v[132:135], v[132:133], off
	v_mov_b32_e32 v169, v168
	v_pk_mul_f32 v[186:187], v[38:39], v[168:169]
	v_pk_mul_f32 v[190:191], v[34:35], v[168:169]
	s_ashr_i32 s65, s64, 31
	s_lshl_b64 s[16:17], s[64:65], 13
	s_waitcnt vmcnt(0)
	v_pk_mul_f32 v[192:193], v[186:187], v[132:133] op_sel:[1,1] op_sel_hi:[0,1]
	v_pk_fma_f32 v[208:209], v[186:187], v[132:133], v[192:193] neg_lo:[0,0,1] neg_hi:[0,0,1]
	v_pk_fma_f32 v[132:133], v[186:187], v[132:133], v[192:193] op_sel_hi:[1,0,1]
	v_mov_b32_e32 v186, v135
	v_pk_mul_f32 v[186:187], v[184:185], v[186:187] op_sel:[1,0] op_sel_hi:[0,0]
	v_pk_fma_f32 v[192:193], v[184:185], v[134:135], v[186:187] neg_lo:[0,0,1] neg_hi:[0,0,1]
	v_pk_fma_f32 v[134:135], v[184:185], v[134:135], v[186:187] op_sel_hi:[1,0,1]
	v_cvt_pk_bf16_f32 v132, v208, v133
	v_cvt_pk_bf16_f32 v133, v192, v135
	v_pk_mul_f32 v[134:135], v[190:191], v[180:181] op_sel:[1,1] op_sel_hi:[0,1]
	v_pk_fma_f32 v[184:185], v[190:191], v[180:181], v[134:135] neg_lo:[0,0,1] neg_hi:[0,0,1]
	v_pk_fma_f32 v[134:135], v[190:191], v[180:181], v[134:135] op_sel_hi:[1,0,1]
	v_mov_b32_e32 v180, v183
	v_pk_mul_f32 v[180:181], v[188:189], v[180:181] op_sel:[1,0] op_sel_hi:[0,0]
	v_cvt_pk_bf16_f32 v134, v184, v135
	v_pk_fma_f32 v[184:185], v[188:189], v[182:183], v[180:181] neg_lo:[0,0,1] neg_hi:[0,0,1]
	v_pk_fma_f32 v[180:181], v[188:189], v[182:183], v[180:181] op_sel_hi:[1,0,1]
	s_nop 0
	v_cvt_pk_bf16_f32 v135, v184, v181
	v_lshl_add_u64 v[180:181], s[16:17], 0, v[176:177]
	v_mad_u64_u32 v[182:183], s[16:17], v180, s5, v[148:149]
	s_or_b32 s16, s64, 1
	s_ashr_i32 s17, s16, 31
	s_lshl_b64 s[16:17], s[16:17], 13
	v_mad_i32_i24 v183, v181, s5, v183
	v_lshl_add_u64 v[180:181], s[16:17], 0, v[176:177]
	global_store_dwordx4 v[182:183], v[132:135], off offset:256
	v_mad_u64_u32 v[182:183], s[16:17], v180, s5, v[148:149]
	s_or_b32 s16, s64, 2
	s_ashr_i32 s17, s16, 31
	s_lshl_b64 s[16:17], s[16:17], 13
	v_mad_i32_i24 v183, v181, s5, v183
	v_lshl_add_u64 v[180:181], s[16:17], 0, v[176:177]
	global_store_dwordx4 v[182:183], v[132:135], off offset:256
	v_mad_u64_u32 v[182:183], s[16:17], v180, s5, v[148:149]
	s_or_b32 s16, s64, 3
	s_ashr_i32 s17, s16, 31
	s_lshl_b64 s[16:17], s[16:17], 13
	v_lshl_add_u64 v[176:177], s[16:17], 0, v[176:177]
	v_mad_i32_i24 v183, v181, s5, v183
	v_mad_u64_u32 v[180:181], s[16:17], v176, s5, v[148:149]
	v_mad_i32_i24 v181, v177, s5, v181
	global_store_dwordx4 v[182:183], v[132:135], off offset:256
	global_store_dwordx4 v[180:181], v[132:135], off offset:256

; __device__ __forceinline__ unsigned pk2(float lo, float hi) { f32x2 v = {lo, hi}; bf16x2_t b = __builtin_convertvector(v, bf16x2_t); return __builtin_bit_cast(unsigned, b); }
;     __device__ __forceinline__ void operator()(const f32x4 (&acc)[2][2][4][2], const pg8::Unit& u, int wr, int wc, int fr, int fq) const {
;     ...
;                     if (cb < 64) {
;                         const f32x4 a0 = acc[ai][1][m][0] * rr[ai][m], a1 = acc[ai][1][m][1] * rr[ai][m];
;                         const f32x4 c0 = *(const f32x4*)(CS_ + ((size_t)t * 32 + (cb >> 1)) * 2), c1 = *(const f32x4*)(CS_ + ((size_t)t * 32 + (cb >> 1) + 2) * 2);
;                         u32x4 w; w.x = pk2(a0[0] * c0[0] - a0[1] * c0[1], a0[1] * c0[0] + a0[0] * c0[1]); w.y = pk2(a0[2] * c0[2] - a0[3] * c0[3], a0[3] * c0[2] + a0[2] * c0[3]);
;                         w.z = pk2(a1[0] * c1[0] - a1[1] * c1[1], a1[1] * c1[0] + a1[0] * c1[1]); w.w = pk2(a1[2] * c1[2] - a1[3] * c1[3], a1[3] * c1[2] + a1[2] * c1[3]);
; #pragma unroll
;                         for (int hh = 0; hh < 4; ++hh) *(u32x4*)(KM_ + ((size_t)(b * 4 + hh) * S + t) * 192 + 128 + cb) = w;
.LBB0_998:
	s_or_b64 exec, exec, s[34:35]
	s_and_b64 vcc, exec, s[46:47]
	s_cbranch_vccnz .LBB0_1000
	v_add_u32_e32 v176, 0xa0, v156
	v_mov_b32_e32 v132, v170
	v_mov_b32_e32 v133, v170
	v_ashrrev_i32_e32 v177, 31, v176
	v_pk_mul_f32 v[184:185], v[24:25], v[132:133]
	v_pk_mul_f32 v[188:189], v[20:21], v[132:133]
	v_lshlrev_b64 v[132:133], 8, v[176:177]
	v_lshl_add_u64 v[132:133], v[146:147], 0, v[132:133]
	global_load_dwordx4 v[180:183], v[132:133], off offset:16
	global_load_dwordx4 v[132:135], v[132:133], off
	v_mov_b32_e32 v171, v170
	v_pk_mul_f32 v[186:187], v[22:23], v[170:171]
	v_pk_mul_f32 v[190:191], v[18:19], v[170:171]
	s_ashr_i32 s65, s64, 31
	s_lshl_b64 s[16:17], s[64:65], 13
	s_waitcnt vmcnt(0)
	v_pk_mul_f32 v[192:193], v[186:187], v[132:133] op_sel:[1,1] op_sel_hi:[0,1]
	v_pk_fma_f32 v[208:209], v[186:187], v[132:133], v[192:193] neg_lo:[0,0,1] neg_hi:[0,0,1]
	v_pk_fma_f32 v[132:133], v[186:187], v[132:133], v[192:193] op_sel_hi:[1,0,1]
	v_mov_b32_e32 v186, v135
	v_pk_mul_f32 v[186:187], v[184:185], v[186:187] op_sel:[1,0] op_sel_hi:[0,0]
	v_pk_fma_f32 v[192:193], v[184:185], v[134:135], v[186:187] neg_lo:[0,0,1] neg_hi:[0,0,1]
	v_pk_fma_f32 v[134:135], v[184:185], v[134:135], v[186:187] op_sel_hi:[1,0,1]
	v_cvt_pk_bf16_f32 v132, v208, v133
	v_cvt_pk_bf16_f32 v133, v192, v135
	v_pk_mul_f32 v[134:135], v[190:191], v[180:181] op_sel:[1,1] op_sel_hi:[0,1]
	v_pk_fma_f32 v[184:185], v[190:191], v[180:181], v[134:135] neg_lo:[0,0,1] neg_hi:[0,0,1]
	v_pk_fma_f32 v[134:135], v[190:191], v[180:181], v[134:135] op_sel_hi:[1,0,1]
	v_mov_b32_e32 v180, v183
	v_pk_mul_f32 v[180:181], v[188:189], v[180:181] op_sel:[1,0] op_sel_hi:[0,0]
	v_cvt_pk_bf16_f32 v134, v184, v135
	v_pk_fma_f32 v[184:185], v[188:189], v[182:183], v[180:181] neg_lo:[0,0,1] neg_hi:[0,0,1]
	v_pk_fma_f32 v[180:181], v[188:189], v[182:183], v[180:181] op_sel_hi:[1,0,1]
	s_nop 0
	v_cvt_pk_bf16_f32 v135, v184, v181
	v_lshl_add_u64 v[180:181], s[16:17], 0, v[176:177]
	v_mad_u64_u32 v[182:183], s[16:17], v180, s5, v[148:149]
	s_or_b32 s16, s64, 1
	s_ashr_i32 s17, s16, 31
	s_lshl_b64 s[16:17], s[16:17], 13
	v_mad_i32_i24 v183, v181, s5, v183
	v_lshl_add_u64 v[180:181], s[16:17], 0, v[176:177]
	global_store_dwordx4 v[182:183], v[132:135], off offset:256
	v_mad_u64_u32 v[182:183], s[16:17], v180, s5, v[148:149]
	s_or_b32 s16, s64, 2
	s_ashr_i32 s17, s16, 31
	s_lshl_b64 s[16:17], s[16:17], 13
	v_mad_i32_i24 v183, v181, s5, v183
	v_lshl_add_u64 v[180:181], s[16:17], 0, v[176:177]
	global_store_dwordx4 v[182:183], v[132:135], off offset:256
	v_mad_u64_u32 v[182:183], s[16:17], v180, s5, v[148:149]
	s_or_b32 s16, s64, 3
	s_ashr_i32 s17, s16, 31
	s_lshl_b64 s[16:17], s[16:17], 13
	v_lshl_add_u64 v[176:177], s[16:17], 0, v[176:177]
	v_mad_i32_i24 v183, v181, s5, v183
	v_mad_u64_u32 v[180:181], s[16:17], v176, s5, v[148:149]
	v_mad_i32_i24 v181, v177, s5, v181
	global_store_dwordx4 v[182:183], v[132:135], off offset:256
	global_store_dwordx4 v[180:181], v[132:135], off offset:256

; __device__ __forceinline__ unsigned pk2(float lo, float hi) { f32x2 v = {lo, hi}; bf16x2_t b = __builtin_convertvector(v, bf16x2_t); return __builtin_bit_cast(unsigned, b); }
;     __device__ __forceinline__ void operator()(const f32x4 (&acc)[2][2][4][2], const pg8::Unit& u, int wr, int wc, int fr, int fq) const {
;     ...
;                     if (cb < 64) {
;                         const f32x4 a0 = acc[ai][1][m][0] * rr[ai][m], a1 = acc[ai][1][m][1] * rr[ai][m];
;                         const f32x4 c0 = *(const f32x4*)(CS_ + ((size_t)t * 32 + (cb >> 1)) * 2), c1 = *(const f32x4*)(CS_ + ((size_t)t * 32 + (cb >> 1) + 2) * 2);
;                         u32x4 w; w.x = pk2(a0[0] * c0[0] - a0[1] * c0[1], a0[1] * c0[0] + a0[0] * c0[1]); w.y = pk2(a0[2] * c0[2] - a0[3] * c0[3], a0[3] * c0[2] + a0[2] * c0[3]);
;                         w.z = pk2(a1[0] * c1[0] - a1[1] * c1[1], a1[1] * c1[0] + a1[0] * c1[1]); w.w = pk2(a1[2] * c1[2] - a1[3] * c1[3], a1[3] * c1[2] + a1[2] * c1[3]);
; #pragma unroll
;                         for (int hh = 0; hh < 4; ++hh) *(u32x4*)(KM_ + ((size_t)(b * 4 + hh) * S + t) * 192 + 128 + cb) = w;
.LBB0_1002:
	s_or_b64 exec, exec, s[34:35]
	s_and_b64 vcc, exec, s[46:47]
	s_cbranch_vccnz .LBB0_1004
	v_add_u32_e32 v174, 0xb0, v156
	v_mov_b32_e32 v132, v172
	v_mov_b32_e32 v133, v172
	v_ashrrev_i32_e32 v175, 31, v174
	v_pk_mul_f32 v[176:177], v[8:9], v[132:133]
	v_pk_mul_f32 v[186:187], v[4:5], v[132:133]
	v_lshlrev_b64 v[132:133], 8, v[174:175]
	v_lshl_add_u64 v[132:133], v[146:147], 0, v[132:133]
	global_load_dwordx4 v[180:183], v[132:133], off offset:16
	global_load_dwordx4 v[132:135], v[132:133], off
	v_mov_b32_e32 v173, v172
	v_pk_mul_f32 v[184:185], v[6:7], v[172:173]
	v_pk_mul_f32 v[188:189], v[2:3], v[172:173]
	s_ashr_i32 s65, s64, 31
	s_lshl_b64 s[16:17], s[64:65], 13
	s_waitcnt vmcnt(0)
	v_pk_mul_f32 v[190:191], v[184:185], v[132:133] op_sel:[1,1] op_sel_hi:[0,1]
	v_pk_fma_f32 v[192:193], v[184:185], v[132:133], v[190:191] neg_lo:[0,0,1] neg_hi:[0,0,1]
	v_pk_fma_f32 v[132:133], v[184:185], v[132:133], v[190:191] op_sel_hi:[1,0,1]
	v_mov_b32_e32 v184, v135
	v_pk_mul_f32 v[184:185], v[176:177], v[184:185] op_sel:[1,0] op_sel_hi:[0,0]
	v_pk_fma_f32 v[190:191], v[176:177], v[134:135], v[184:185] neg_lo:[0,0,1] neg_hi:[0,0,1]
	v_pk_fma_f32 v[134:135], v[176:177], v[134:135], v[184:185] op_sel_hi:[1,0,1]
	v_cvt_pk_bf16_f32 v132, v192, v133
	v_cvt_pk_bf16_f32 v133, v190, v135
	v_pk_mul_f32 v[134:135], v[188:189], v[180:181] op_sel:[1,1] op_sel_hi:[0,1]
	v_pk_fma_f32 v[176:177], v[188:189], v[180:181], v[134:135] neg_lo:[0,0,1] neg_hi:[0,0,1]
	v_pk_fma_f32 v[134:135], v[188:189], v[180:181], v[134:135] op_sel_hi:[1,0,1]
	s_nop 0
	v_cvt_pk_bf16_f32 v134, v176, v135
	v_mov_b32_e32 v176, v183
	v_pk_mul_f32 v[176:177], v[186:187], v[176:177] op_sel:[1,0] op_sel_hi:[0,0]
	v_pk_fma_f32 v[180:181], v[186:187], v[182:183], v[176:177] neg_lo:[0,0,1] neg_hi:[0,0,1]
	v_pk_fma_f32 v[176:177], v[186:187], v[182:183], v[176:177] op_sel_hi:[1,0,1]
	s_nop 0
	v_cvt_pk_bf16_f32 v135, v180, v177
	v_lshl_add_u64 v[176:177], s[16:17], 0, v[174:175]
	v_mad_u64_u32 v[180:181], s[16:17], v176, s5, v[148:149]
	s_or_b32 s16, s64, 1
	s_ashr_i32 s17, s16, 31
	s_lshl_b64 s[16:17], s[16:17], 13
	v_mad_i32_i24 v181, v177, s5, v181
	v_lshl_add_u64 v[176:177], s[16:17], 0, v[174:175]
	global_store_dwordx4 v[180:181], v[132:135], off offset:256
	v_mad_u64_u32 v[180:181], s[16:17], v176, s5, v[148:149]
	s_or_b32 s16, s64, 2
	s_ashr_i32 s17, s16, 31
	s_lshl_b64 s[16:17], s[16:17], 13
	v_mad_i32_i24 v181, v177, s5, v181
	v_lshl_add_u64 v[176:177], s[16:17], 0, v[174:175]
	global_store_dwordx4 v[180:181], v[132:135], off offset:256
	v_mad_u64_u32 v[180:181], s[16:17], v176, s5, v[148:149]
	s_or_b32 s16, s64, 3
	s_ashr_i32 s17, s16, 31
	s_lshl_b64 s[16:17], s[16:17], 13
	v_lshl_add_u64 v[174:175], s[16:17], 0, v[174:175]
	v_mad_i32_i24 v181, v177, s5, v181
	v_mad_u64_u32 v[176:177], s[16:17], v174, s5, v[148:149]
	v_mad_i32_i24 v177, v175, s5, v177
	global_store_dwordx4 v[180:181], v[132:135], off offset:256
	global_store_dwordx4 v[176:177], v[132:135], off offset:256

; __device__ __forceinline__ unsigned pk2(float lo, float hi) { f32x2 v = {lo, hi}; bf16x2_t b = __builtin_convertvector(v, bf16x2_t); return __builtin_bit_cast(unsigned, b); }
; __device__ __forceinline__ float ssf(const ssq_t* p) { return (float)(*p) * (1.0f / 1048576.0f); }
;     __device__ __forceinline__ void operator()(const f32x4 (&acc)[2][2][4][2], const pg8::Unit& u, int wr, int wc, int fr, int fq) const {
;     ...
;         for (int bj = 0; bj < 2; ++bj) {
;             const int tok = u.pn * 256 + bj * 128 + wc * 32 + fq * 8, b = tok >> 13, t = tok & (S - 1);
;             float r[8];
; #pragma unroll
;             for (int i = 0; i < 8; ++i) r[i] = rsqrtf(ssf(SSn + tok + i) * invn + EPS);
; #pragma unroll
;             for (int ai = 0; ai < 2; ++ai)
; #pragma unroll
;                 for (int m = 0; m < 4; ++m) {
;                     const int ch = u.pm * 256 + ai * 128 + wr * 64 + m * 16 + fr;
;                     const f32x4 a0 = acc[ai][bj][m][0], a1 = acc[ai][bj][m][1];
;                     u32x4 w; w.x = pk2(a0[0] * r[0], a0[1] * r[1]); w.y = pk2(a0[2] * r[2], a0[3] * r[3]); w.z = pk2(a1[0] * r[4], a1[1] * r[5]); w.w = pk2(a1[2] * r[6], a1[3] * r[7]);
;                     *(u32x4*)(VT + ((size_t)(b * 512 + ch)) * S + t) = w;
;                 }
.LBB0_1055:
	s_lshl_b32 s2, s82, 8
	v_or_b32_e32 v158, s2, v167
	v_ashrrev_i32_e32 v159, 31, v158
	v_lshl_add_u64 v[160:161], v[158:159], 3, s[48:49]
	global_load_dwordx4 v[132:135], v[160:161], off offset:48
	global_load_dwordx4 v[136:139], v[160:161], off offset:32
	global_load_dwordx4 v[140:143], v[160:161], off offset:16
	global_load_dwordx4 v[170:173], v[160:161], off
	s_lshl_b32 s4, s82, 4
	s_lshl_b32 s3, s83, 8
	s_and_b32 s4, s4, 0xfffffe00
	s_add_i32 s4, s4, s3
	v_add_u32_e32 v162, s4, v1
	v_bitop3_b32 v98, s2, v203, v167 bitop3:0xc8
	s_mov_b32 s4, 0x35800000
	s_mov_b32 s2, 0x358637bd
	s_mov_b32 s16, 0x3a800000
	s_mov_b32 s22, 0x45800000
	v_lshlrev_b32_e32 v98, 1, v98
	v_ashrrev_i32_e32 v163, 31, v162
	s_movk_i32 s1, 0x1ff8
	s_waitcnt vmcnt(0)
	v_ffbh_u32_e32 v156, v173
	v_min_u32_e32 v159, 32, v156
	v_lshlrev_b64 v[156:157], v159, v[172:173]
	v_min_u32_e32 v156, 1, v156
	v_or_b32_e32 v156, v157, v156
	v_cvt_f32_u32_e32 v156, v156
	v_sub_u32_e32 v157, 32, v159
	v_ldexp_f32 v157, v156, v157
	v_ffbh_u32_e32 v156, v171
	v_min_u32_e32 v156, 32, v156
	v_lshlrev_b64 v[164:165], v156, v[170:171]
	v_min_u32_e32 v159, 1, v164
	v_or_b32_e32 v159, v165, v159
	v_cvt_f32_u32_e32 v159, v159
	v_sub_u32_e32 v156, 32, v156
	v_ldexp_f32 v156, v159, v156
	v_pk_mul_f32 v[164:165], v[156:157], s[4:5] op_sel_hi:[1,0]
	v_mov_b64_e32 v[156:157], s[2:3]
	v_pk_fma_f32 v[164:165], v[164:165], s[16:17], v[156:157] op_sel_hi:[1,0,0]
	s_nop 0
	v_mul_f32_e32 v159, 0x4b800000, v164
	v_cmp_gt_f32_e64 s[2:3], s23, v164
	v_cmp_gt_f32_e32 vcc, s23, v165
	s_nop 0
	v_cndmask_b32_e64 v159, v164, v159, s[2:3]
	v_rsq_f32_e32 v164, v159
	v_mul_f32_e32 v159, 0x4b800000, v165
	v_cndmask_b32_e32 v159, v165, v159, vcc
	v_rsq_f32_e32 v165, v159
	s_nop 0
	v_pk_mul_f32 v[170:171], v[164:165], s[22:23] op_sel_hi:[1,0]
	s_nop 0
	v_cndmask_b32_e32 v165, v165, v171, vcc
	v_cndmask_b32_e64 v164, v164, v170, s[2:3]
	v_pk_mul_f32 v[128:129], v[128:129], v[164:165]
	v_pk_mul_f32 v[78:79], v[78:79], v[164:165]
	v_cvt_pk_bf16_f32 v128, v128, v129
	v_ffbh_u32_e32 v129, v143
	v_min_u32_e32 v129, 32, v129
	v_lshlrev_b64 v[142:143], v129, v[142:143]
	v_min_u32_e32 v142, 1, v142
	v_or_b32_e32 v142, v143, v142
	v_cvt_f32_u32_e32 v142, v142
	v_sub_u32_e32 v129, 32, v129
	v_pk_mul_f32 v[104:105], v[104:105], v[164:165]
	v_cvt_pk_bf16_f32 v78, v78, v79
	v_ldexp_f32 v143, v142, v129
	v_ffbh_u32_e32 v129, v141
	v_min_u32_e32 v129, 32, v129
	v_lshlrev_b64 v[140:141], v129, v[140:141]
	v_min_u32_e32 v140, 1, v140
	v_or_b32_e32 v140, v141, v140
	v_cvt_f32_u32_e32 v140, v140
	v_sub_u32_e32 v129, 32, v129
	v_cvt_pk_bf16_f32 v104, v104, v105
	v_pk_mul_f32 v[120:121], v[120:121], v[164:165]
	v_ldexp_f32 v142, v140, v129
	v_pk_mul_f32 v[140:141], v[142:143], s[4:5] op_sel_hi:[1,0]
	v_pk_mul_f32 v[112:113], v[112:113], v[164:165]
	v_pk_fma_f32 v[140:141], v[140:141], s[16:17], v[156:157] op_sel_hi:[1,0,0]
	v_pk_mul_f32 v[86:87], v[86:87], v[164:165]
	v_mul_f32_e32 v129, 0x4b800000, v140
	v_cmp_gt_f32_e64 s[2:3], s23, v140
	v_cmp_gt_f32_e32 vcc, s23, v141
	v_cvt_pk_bf16_f32 v120, v120, v121
	v_cndmask_b32_e64 v129, v140, v129, s[2:3]
	v_rsq_f32_e32 v140, v129
	v_mul_f32_e32 v129, 0x4b800000, v141
	v_cndmask_b32_e32 v129, v141, v129, vcc
	v_rsq_f32_e32 v141, v129
	v_cvt_pk_bf16_f32 v112, v112, v113
	v_cvt_pk_bf16_f32 v86, v86, v87
	v_pk_mul_f32 v[94:95], v[94:95], v[164:165]
	v_pk_mul_f32 v[142:143], v[140:141], s[22:23] op_sel_hi:[1,0]
	v_cvt_pk_bf16_f32 v94, v94, v95
	v_cndmask_b32_e32 v141, v141, v143, vcc
	v_cndmask_b32_e64 v140, v140, v142, s[2:3]
	v_pk_mul_f32 v[130:131], v[130:131], v[140:141]
	v_pk_mul_f32 v[80:81], v[80:81], v[140:141]
	v_cvt_pk_bf16_f32 v129, v130, v131
	v_ffbh_u32_e32 v130, v139
	v_min_u32_e32 v142, 32, v130
	v_lshlrev_b64 v[130:131], v142, v[138:139]
	v_min_u32_e32 v130, 1, v130
	v_or_b32_e32 v130, v131, v130
	v_cvt_f32_u32_e32 v130, v130
	v_sub_u32_e32 v131, 32, v142
	v_pk_mul_f32 v[106:107], v[106:107], v[140:141]
	v_cvt_pk_bf16_f32 v79, v80, v81
	v_ldexp_f32 v131, v130, v131
	v_ffbh_u32_e32 v130, v137
	v_min_u32_e32 v130, 32, v130
	v_lshlrev_b64 v[136:137], v130, v[136:137]
	v_min_u32_e32 v136, 1, v136
	v_or_b32_e32 v136, v137, v136
	v_cvt_f32_u32_e32 v136, v136
	v_sub_u32_e32 v130, 32, v130
	v_cvt_pk_bf16_f32 v105, v106, v107
	v_pk_mul_f32 v[122:123], v[122:123], v[140:141]
	v_ldexp_f32 v130, v136, v130
	v_pk_mul_f32 v[130:131], v[130:131], s[4:5] op_sel_hi:[1,0]
	v_pk_mul_f32 v[114:115], v[114:115], v[140:141]
	v_pk_fma_f32 v[130:131], v[130:131], s[16:17], v[156:157] op_sel_hi:[1,0,0]
	v_pk_mul_f32 v[88:89], v[88:89], v[140:141]
	v_mul_f32_e32 v136, 0x4b800000, v130
	v_cmp_gt_f32_e64 s[2:3], s23, v130
	v_cmp_gt_f32_e32 vcc, s23, v131
	v_cvt_pk_bf16_f32 v121, v122, v123
	v_cndmask_b32_e64 v130, v130, v136, s[2:3]
	v_mul_f32_e32 v136, 0x4b800000, v131
	v_cndmask_b32_e32 v131, v131, v136, vcc
	v_rsq_f32_e32 v130, v130
	v_rsq_f32_e32 v131, v131
	v_cvt_pk_bf16_f32 v113, v114, v115
	v_cvt_pk_bf16_f32 v87, v88, v89
	v_pk_mul_f32 v[96:97], v[96:97], v[140:141]
	v_pk_mul_f32 v[136:137], v[130:131], s[22:23] op_sel_hi:[1,0]
	v_cvt_pk_bf16_f32 v95, v96, v97
	v_cndmask_b32_e32 v137, v131, v137, vcc
	v_cndmask_b32_e64 v136, v130, v136, s[2:3]
	v_pk_mul_f32 v[124:125], v[124:125], v[136:137]
	v_pk_mul_f32 v[74:75], v[74:75], v[136:137]
	v_cvt_pk_bf16_f32 v130, v124, v125
	v_ffbh_u32_e32 v124, v135
	v_min_u32_e32 v131, 32, v124
	v_lshlrev_b64 v[124:125], v131, v[134:135]
	v_min_u32_e32 v124, 1, v124
	v_or_b32_e32 v124, v125, v124
	v_cvt_f32_u32_e32 v124, v124
	v_sub_u32_e32 v125, 32, v131
	v_pk_mul_f32 v[100:101], v[100:101], v[136:137]
	v_cvt_pk_bf16_f32 v80, v74, v75
	v_ldexp_f32 v125, v124, v125
; __device__ __forceinline__ unsigned pk2(float lo, float hi) { f32x2 v = {lo, hi}; bf16x2_t b = __builtin_convertvector(v, bf16x2_t); return __builtin_bit_cast(unsigned, b); }
; __device__ __forceinline__ float ssf(const ssq_t* p) { return (float)(*p) * (1.0f / 1048576.0f); }
;     __device__ __forceinline__ void operator()(const f32x4 (&acc)[2][2][4][2], const pg8::Unit& u, int wr, int wc, int fr, int fq) const {
;     ...
;         for (int bj = 0; bj < 2; ++bj) {
;             const int tok = u.pn * 256 + bj * 128 + wc * 32 + fq * 8, b = tok >> 13, t = tok & (S - 1);
;             float r[8];
; #pragma unroll
;             for (int i = 0; i < 8; ++i) r[i] = rsqrtf(ssf(SSn + tok + i) * invn + EPS);
; #pragma unroll
;             for (int ai = 0; ai < 2; ++ai)
; #pragma unroll
;                 for (int m = 0; m < 4; ++m) {
;                     const int ch = u.pm * 256 + ai * 128 + wr * 64 + m * 16 + fr;
;                     const f32x4 a0 = acc[ai][bj][m][0], a1 = acc[ai][bj][m][1];
;                     u32x4 w; w.x = pk2(a0[0] * r[0], a0[1] * r[1]); w.y = pk2(a0[2] * r[2], a0[3] * r[3]); w.z = pk2(a1[0] * r[4], a1[1] * r[5]); w.w = pk2(a1[2] * r[6], a1[3] * r[7]);
;                     *(u32x4*)(VT + ((size_t)(b * 512 + ch)) * S + t) = w;
;                 }
	v_ffbh_u32_e32 v124, v133
	v_min_u32_e32 v124, 32, v124
	v_lshlrev_b64 v[132:133], v124, v[132:133]
	v_min_u32_e32 v131, 1, v132
	v_or_b32_e32 v131, v133, v131
	v_cvt_f32_u32_e32 v131, v131
	v_sub_u32_e32 v124, 32, v124
	v_cvt_pk_bf16_f32 v106, v100, v101
	v_pk_mul_f32 v[116:117], v[116:117], v[136:137]
	v_ldexp_f32 v124, v131, v124
	v_pk_mul_f32 v[124:125], v[124:125], s[4:5] op_sel_hi:[1,0]
	v_pk_mul_f32 v[108:109], v[108:109], v[136:137]
	v_pk_fma_f32 v[124:125], v[124:125], s[16:17], v[156:157] op_sel_hi:[1,0,0]
	v_pk_mul_f32 v[82:83], v[82:83], v[136:137]
	v_mul_f32_e32 v131, 0x4b800000, v124
	v_cmp_gt_f32_e64 s[2:3], s23, v124
	v_cmp_gt_f32_e32 vcc, s23, v125
	v_pk_mul_f32 v[66:67], v[66:67], v[136:137]
	v_cndmask_b32_e64 v124, v124, v131, s[2:3]
	v_mul_f32_e32 v131, 0x4b800000, v125
	v_cndmask_b32_e32 v125, v125, v131, vcc
	v_rsq_f32_e32 v124, v124
	v_rsq_f32_e32 v125, v125
	v_cvt_pk_bf16_f32 v122, v116, v117
	v_cvt_pk_bf16_f32 v114, v108, v109
	v_cvt_pk_bf16_f32 v88, v82, v83
	v_pk_mul_f32 v[132:133], v[124:125], s[22:23] op_sel_hi:[1,0]
	v_pk_mul_f32 v[90:91], v[90:91], v[136:137]
	v_cndmask_b32_e32 v133, v125, v133, vcc
	v_cndmask_b32_e64 v132, v124, v132, s[2:3]
	v_pk_mul_f32 v[74:75], v[76:77], v[132:133]
	v_pk_mul_f32 v[100:101], v[102:103], v[132:133]
	v_cvt_pk_bf16_f32 v81, v74, v75
	v_add_u32_e32 v74, 0xa0, v162
	v_cvt_pk_bf16_f32 v107, v100, v101
	v_or_b32_e32 v100, 48, v162
	v_ashrrev_i32_e32 v75, 31, v74
	v_ashrrev_i32_e32 v101, 31, v100
	v_lshlrev_b64 v[74:75], 14, v[74:75]
	v_lshlrev_b64 v[100:101], 14, v[100:101]
	v_lshl_add_u64 v[74:75], s[46:47], 0, v[74:75]
	v_lshl_add_u64 v[100:101], s[46:47], 0, v[100:101]
	v_lshl_add_u64 v[76:77], v[74:75], 0, v[98:99]
	v_pk_mul_f32 v[116:117], v[118:119], v[132:133]
	v_pk_mul_f32 v[108:109], v[110:111], v[132:133]
	v_lshl_add_u64 v[102:103], v[100:101], 0, v[98:99]
	v_pk_mul_f32 v[82:83], v[84:85], v[132:133]
	global_store_dwordx4 v[76:77], v[78:81], off
	v_cvt_pk_bf16_f32 v123, v116, v117
	v_or_b32_e32 v116, 16, v162
	v_cvt_pk_bf16_f32 v78, v66, v67
	v_pk_mul_f32 v[66:67], v[68:69], v[132:133]
	v_cvt_pk_bf16_f32 v115, v108, v109
	v_or_b32_e32 v108, 32, v162
	global_store_dwordx4 v[102:103], v[104:107], off
	v_add_u32_e32 v102, 0x80, v162
	v_cvt_pk_bf16_f32 v89, v82, v83
	v_add_u32_e32 v82, 0x90, v162
	v_cvt_pk_bf16_f32 v79, v66, v67
	v_add_u32_e32 v66, 0xb0, v162
	v_pk_mul_f32 v[124:125], v[126:127], v[132:133]
	v_ashrrev_i32_e32 v117, 31, v116
	v_ashrrev_i32_e32 v109, 31, v108
	v_cvt_pk_bf16_f32 v96, v90, v91
	v_pk_mul_f32 v[90:91], v[92:93], v[132:133]
	v_ashrrev_i32_e32 v103, 31, v102
	v_ashrrev_i32_e32 v83, 31, v82
	v_pk_mul_f32 v[70:71], v[70:71], v[164:165]
	v_ashrrev_i32_e32 v67, 31, v66
	v_cvt_pk_bf16_f32 v131, v124, v125
	v_lshlrev_b64 v[124:125], 14, v[162:163]
	v_lshlrev_b64 v[116:117], 14, v[116:117]
	v_lshlrev_b64 v[108:109], 14, v[108:109]
	v_cvt_pk_bf16_f32 v97, v90, v91
	v_lshlrev_b64 v[90:91], 14, v[102:103]
	v_lshlrev_b64 v[82:83], 14, v[82:83]
	v_cvt_pk_bf16_f32 v76, v70, v71
	v_pk_mul_f32 v[70:71], v[72:73], v[140:141]
	v_lshlrev_b64 v[66:67], 14, v[66:67]
	v_lshl_add_u64 v[124:125], s[46:47], 0, v[124:125]
	v_lshl_add_u64 v[116:117], s[46:47], 0, v[116:117]
	v_lshl_add_u64 v[108:109], s[46:47], 0, v[108:109]
	v_lshl_add_u64 v[90:91], s[46:47], 0, v[90:91]
	v_lshl_add_u64 v[82:83], s[46:47], 0, v[82:83]
	v_cvt_pk_bf16_f32 v77, v70, v71
	v_lshl_add_u64 v[70:71], s[46:47], 0, v[66:67]
	v_lshl_add_u64 v[126:127], v[124:125], 0, v[98:99]
	v_lshl_add_u64 v[118:119], v[116:117], 0, v[98:99]
	v_lshl_add_u64 v[110:111], v[108:109], 0, v[98:99]
	v_lshl_add_u64 v[92:93], v[90:91], 0, v[98:99]
	v_lshl_add_u64 v[84:85], v[82:83], 0, v[98:99]
	v_lshl_add_u64 v[66:67], v[70:71], 0, v[98:99]
	global_store_dwordx4 v[126:127], v[128:131], off
	global_store_dwordx4 v[118:119], v[120:123], off
	global_store_dwordx4 v[110:111], v[112:115], off
	global_store_dwordx4 v[92:93], v[94:97], off
	global_store_dwordx4 v[84:85], v[86:89], off
	global_store_dwordx4 v[66:67], v[76:79], off
	global_load_dwordx4 v[66:69], v[160:161], off offset:1072
	global_load_dwordx4 v[78:81], v[160:161], off offset:1056
	global_load_dwordx4 v[84:87], v[160:161], off offset:1040
	global_load_dwordx4 v[92:95], v[160:161], off offset:1024
	v_bitop3_b32 v88, v158, s1, v204 bitop3:0xc8
	v_lshlrev_b32_e32 v98, 1, v88
	s_waitcnt vmcnt(0)
; __device__ __forceinline__ unsigned pk2(float lo, float hi) { f32x2 v = {lo, hi}; bf16x2_t b = __builtin_convertvector(v, bf16x2_t); return __builtin_bit_cast(unsigned, b); }
; __device__ __forceinline__ float ssf(const ssq_t* p) { return (float)(*p) * (1.0f / 1048576.0f); }
;     __device__ __forceinline__ void operator()(const f32x4 (&acc)[2][2][4][2], const pg8::Unit& u, int wr, int wc, int fr, int fq) const {
;     ...
;         for (int bj = 0; bj < 2; ++bj) {
;             const int tok = u.pn * 256 + bj * 128 + wc * 32 + fq * 8, b = tok >> 13, t = tok & (S - 1);
;             float r[8];
; #pragma unroll
;             for (int i = 0; i < 8; ++i) r[i] = rsqrtf(ssf(SSn + tok + i) * invn + EPS);
; #pragma unroll
;             for (int ai = 0; ai < 2; ++ai)
; #pragma unroll
;                 for (int m = 0; m < 4; ++m) {
;                     const int ch = u.pm * 256 + ai * 128 + wr * 64 + m * 16 + fr;
;                     const f32x4 a0 = acc[ai][bj][m][0], a1 = acc[ai][bj][m][1];
;                     u32x4 w; w.x = pk2(a0[0] * r[0], a0[1] * r[1]); w.y = pk2(a0[2] * r[2], a0[3] * r[3]); w.z = pk2(a1[0] * r[4], a1[1] * r[5]); w.w = pk2(a1[2] * r[6], a1[3] * r[7]);
;                     *(u32x4*)(VT + ((size_t)(b * 512 + ch)) * S + t) = w;
;                 }
	v_ffbh_u32_e32 v72, v95
	v_min_u32_e32 v76, 32, v72
	v_lshlrev_b64 v[72:73], v76, v[94:95]
	v_min_u32_e32 v72, 1, v72
	v_or_b32_e32 v72, v73, v72
	v_cvt_f32_u32_e32 v72, v72
	v_sub_u32_e32 v73, 32, v76
	v_ldexp_f32 v73, v72, v73
	v_ffbh_u32_e32 v72, v93
	v_min_u32_e32 v72, 32, v72
	v_lshlrev_b64 v[76:77], v72, v[92:93]
	v_min_u32_e32 v76, 1, v76
	v_or_b32_e32 v76, v77, v76
	v_cvt_f32_u32_e32 v76, v76
	v_sub_u32_e32 v72, 32, v72
	v_ldexp_f32 v72, v76, v72
	v_pk_mul_f32 v[72:73], v[72:73], s[4:5] op_sel_hi:[1,0]
	s_nop 0
	v_pk_fma_f32 v[72:73], v[72:73], s[16:17], v[156:157] op_sel_hi:[1,0,0]
	s_nop 0
	v_mul_f32_e32 v76, 0x4b800000, v72
	v_cmp_gt_f32_e64 s[2:3], s23, v72
	v_cmp_gt_f32_e32 vcc, s23, v73
	s_nop 0
	v_cndmask_b32_e64 v72, v72, v76, s[2:3]
	v_mul_f32_e32 v76, 0x4b800000, v73
	v_cndmask_b32_e32 v73, v73, v76, vcc
	v_rsq_f32_e32 v72, v72
	v_rsq_f32_e32 v73, v73
	s_nop 0
	v_pk_mul_f32 v[76:77], v[72:73], s[22:23] op_sel_hi:[1,0]
	s_nop 0
	v_cndmask_b32_e32 v73, v73, v77, vcc
	v_cndmask_b32_e64 v72, v72, v76, s[2:3]
	v_pk_mul_f32 v[62:63], v[62:63], v[72:73]
	v_pk_mul_f32 v[54:55], v[54:55], v[72:73]
	v_cvt_pk_bf16_f32 v62, v62, v63
	v_ffbh_u32_e32 v63, v87
	v_min_u32_e32 v63, 32, v63
	v_lshlrev_b64 v[76:77], v63, v[86:87]
	v_min_u32_e32 v76, 1, v76
	v_or_b32_e32 v76, v77, v76
	v_cvt_f32_u32_e32 v76, v76
	v_sub_u32_e32 v63, 32, v63
	v_pk_mul_f32 v[46:47], v[46:47], v[72:73]
	v_pk_mul_f32 v[38:39], v[38:39], v[72:73]
	v_ldexp_f32 v77, v76, v63
	v_ffbh_u32_e32 v63, v85
	v_min_u32_e32 v63, 32, v63
	v_lshlrev_b64 v[84:85], v63, v[84:85]
	v_min_u32_e32 v76, 1, v84
	v_or_b32_e32 v76, v85, v76
	v_cvt_f32_u32_e32 v76, v76
	v_sub_u32_e32 v63, 32, v63
	v_pk_mul_f32 v[30:31], v[30:31], v[72:73]
	v_pk_mul_f32 v[22:23], v[22:23], v[72:73]
	v_ldexp_f32 v76, v76, v63
	v_pk_mul_f32 v[76:77], v[76:77], s[4:5] op_sel_hi:[1,0]
	v_pk_mul_f32 v[14:15], v[14:15], v[72:73]
	v_pk_fma_f32 v[76:77], v[76:77], s[16:17], v[156:157] op_sel_hi:[1,0,0]
	v_pk_mul_f32 v[6:7], v[6:7], v[72:73]
	v_mul_f32_e32 v63, 0x4b800000, v76
	v_cmp_gt_f32_e64 s[2:3], s23, v76
	v_cmp_gt_f32_e32 vcc, s23, v77
	v_cvt_pk_bf16_f32 v54, v54, v55
	v_cndmask_b32_e64 v63, v76, v63, s[2:3]
	v_rsq_f32_e32 v76, v63
	v_mul_f32_e32 v63, 0x4b800000, v77
	v_cndmask_b32_e32 v63, v77, v63, vcc
	v_rsq_f32_e32 v77, v63
	v_cvt_pk_bf16_f32 v46, v46, v47
	v_cvt_pk_bf16_f32 v38, v38, v39
	v_cvt_pk_bf16_f32 v30, v30, v31
	v_pk_mul_f32 v[84:85], v[76:77], s[22:23] op_sel_hi:[1,0]
	v_cvt_pk_bf16_f32 v22, v22, v23
	v_cndmask_b32_e32 v77, v77, v85, vcc
	v_cndmask_b32_e64 v76, v76, v84, s[2:3]
	v_pk_mul_f32 v[64:65], v[64:65], v[76:77]
	v_pk_mul_f32 v[56:57], v[56:57], v[76:77]
	v_cvt_pk_bf16_f32 v63, v64, v65
	v_ffbh_u32_e32 v64, v81
	v_min_u32_e32 v84, 32, v64
	v_lshlrev_b64 v[64:65], v84, v[80:81]
	v_min_u32_e32 v64, 1, v64
	v_or_b32_e32 v64, v65, v64
	v_cvt_f32_u32_e32 v64, v64
	v_sub_u32_e32 v65, 32, v84
	v_pk_mul_f32 v[48:49], v[48:49], v[76:77]
	v_pk_mul_f32 v[40:41], v[40:41], v[76:77]
	v_ldexp_f32 v65, v64, v65
	v_ffbh_u32_e32 v64, v79
	v_min_u32_e32 v64, 32, v64
	v_lshlrev_b64 v[78:79], v64, v[78:79]
	v_min_u32_e32 v78, 1, v78
	v_or_b32_e32 v78, v79, v78
	v_cvt_f32_u32_e32 v78, v78
	v_sub_u32_e32 v64, 32, v64
	v_pk_mul_f32 v[32:33], v[32:33], v[76:77]
	v_pk_mul_f32 v[24:25], v[24:25], v[76:77]
	v_ldexp_f32 v64, v78, v64
	v_pk_mul_f32 v[64:65], v[64:65], s[4:5] op_sel_hi:[1,0]
	v_pk_mul_f32 v[16:17], v[16:17], v[76:77]
	v_pk_fma_f32 v[64:65], v[64:65], s[16:17], v[156:157] op_sel_hi:[1,0,0]
	v_pk_mul_f32 v[8:9], v[8:9], v[76:77]
	v_mul_f32_e32 v78, 0x4b800000, v64
	v_cmp_gt_f32_e64 s[2:3], s23, v64
	v_cmp_gt_f32_e32 vcc, s23, v65
	v_cvt_pk_bf16_f32 v55, v56, v57
; #define PG8_BAR __builtin_amdgcn_s_barrier()
; __device__ __forceinline__ unsigned pk2(float lo, float hi) { f32x2 v = {lo, hi}; bf16x2_t b = __builtin_convertvector(v, bf16x2_t); return __builtin_bit_cast(unsigned, b); }
; template <class Epi, class Sched, bool ALIGN_EPI = false, bool SP2 = false>
; __device__ __forceinline__ void gemm_phase(PG8_LAS unsigned char* lds, const Gemm g, const Sched& S, const Epi& E) {
;     ...
;         if constexpr (ALIGN_EPI) { if (wr == 0) PG8_BAR; }
;         if constexpr (!Epi::AFTER_DRAIN) { E(acc, cur, wr, wc, fr, fq); S.done(cur); }
;         if (!has_next) break;
; #pragma unroll
;         for (int a = 0; a < 2; ++a)
; #pragma unroll
;             for (int b = 0; b < 2; ++b)
; #pragma unroll
;                 for (int m = 0; m < 4; ++m)
; #pragma unroll
;                     for (int n = 0; n < 2; ++n) acc[a][b][m][n] = (f32x4){0.f, 0.f, 0.f, 0.f};
;         cur = nxt; cA = nA; cB = nB; ++ui;
;         if constexpr (Epi::MID) E.begin(cur, lds, tid);
;         if constexpr (ALIGN_EPI) { if (wr == 1) PG8_BAR; }
;     __device__ __forceinline__ void operator()(const f32x4 (&acc)[2][2][4][2], const pg8::Unit& u, int wr, int wc, int fr, int fq) const {
;     ...
;             for (int ai = 0; ai < 2; ++ai)
; #pragma unroll
;                 for (int m = 0; m < 4; ++m) {
;                     const int ch = u.pm * 256 + ai * 128 + wr * 64 + m * 16 + fr;
;                     const f32x4 a0 = acc[ai][bj][m][0], a1 = acc[ai][bj][m][1];
;                     u32x4 w; w.x = pk2(a0[0] * r[0], a0[1] * r[1]); w.y = pk2(a0[2] * r[2], a0[3] * r[3]); w.z = pk2(a1[0] * r[4], a1[1] * r[5]); w.w = pk2(a1[2] * r[6], a1[3] * r[7]);
;                     *(u32x4*)(VT + ((size_t)(b * 512 + ch)) * S + t) = w;
;                 }
	v_cndmask_b32_e64 v64, v64, v78, s[2:3]
	v_mul_f32_e32 v78, 0x4b800000, v65
	v_cndmask_b32_e32 v65, v65, v78, vcc
	v_rsq_f32_e32 v64, v64
	v_rsq_f32_e32 v65, v65
	v_cvt_pk_bf16_f32 v47, v48, v49
	v_cvt_pk_bf16_f32 v39, v40, v41
	v_cvt_pk_bf16_f32 v31, v32, v33
	v_pk_mul_f32 v[78:79], v[64:65], s[22:23] op_sel_hi:[1,0]
	v_cvt_pk_bf16_f32 v23, v24, v25
	v_cndmask_b32_e32 v79, v65, v79, vcc
	v_cndmask_b32_e64 v78, v64, v78, s[2:3]
	v_pk_mul_f32 v[58:59], v[58:59], v[78:79]
	v_pk_mul_f32 v[50:51], v[50:51], v[78:79]
	v_cvt_pk_bf16_f32 v64, v58, v59
	v_ffbh_u32_e32 v58, v69
	v_min_u32_e32 v65, 32, v58
	v_lshlrev_b64 v[58:59], v65, v[68:69]
	v_min_u32_e32 v58, 1, v58
	v_or_b32_e32 v58, v59, v58
	v_cvt_f32_u32_e32 v58, v58
	v_sub_u32_e32 v59, 32, v65
	v_pk_mul_f32 v[42:43], v[42:43], v[78:79]
	v_pk_mul_f32 v[34:35], v[34:35], v[78:79]
	v_ldexp_f32 v59, v58, v59
	v_ffbh_u32_e32 v58, v67
	v_min_u32_e32 v58, 32, v58
	v_lshlrev_b64 v[66:67], v58, v[66:67]
	v_min_u32_e32 v65, 1, v66
	v_or_b32_e32 v65, v67, v65
	v_cvt_f32_u32_e32 v65, v65
	v_sub_u32_e32 v58, 32, v58
	v_pk_mul_f32 v[26:27], v[26:27], v[78:79]
	v_pk_mul_f32 v[18:19], v[18:19], v[78:79]
	v_ldexp_f32 v58, v65, v58
	v_pk_mul_f32 v[58:59], v[58:59], s[4:5] op_sel_hi:[1,0]
	v_pk_mul_f32 v[10:11], v[10:11], v[78:79]
	v_pk_fma_f32 v[58:59], v[58:59], s[16:17], v[156:157] op_sel_hi:[1,0,0]
	v_pk_mul_f32 v[2:3], v[2:3], v[78:79]
	v_mul_f32_e32 v65, 0x4b800000, v58
	v_cmp_gt_f32_e64 s[2:3], s23, v58
	v_cmp_gt_f32_e32 vcc, s23, v59
	v_cvt_pk_bf16_f32 v56, v50, v51
	v_cndmask_b32_e64 v58, v58, v65, s[2:3]
	v_mul_f32_e32 v65, 0x4b800000, v59
	v_cndmask_b32_e32 v59, v59, v65, vcc
	v_rsq_f32_e32 v58, v58
	v_rsq_f32_e32 v59, v59
	v_cvt_pk_bf16_f32 v48, v42, v43
	v_cvt_pk_bf16_f32 v40, v34, v35
	v_cvt_pk_bf16_f32 v32, v26, v27
	v_pk_mul_f32 v[66:67], v[58:59], s[22:23] op_sel_hi:[1,0]
	v_cvt_pk_bf16_f32 v24, v18, v19
	v_cndmask_b32_e32 v59, v59, v67, vcc
	v_cndmask_b32_e64 v58, v58, v66, s[2:3]
	v_pk_mul_f32 v[60:61], v[60:61], v[58:59]
	v_pk_mul_f32 v[50:51], v[52:53], v[58:59]
	v_pk_mul_f32 v[42:43], v[44:45], v[58:59]
	v_pk_mul_f32 v[34:35], v[36:37], v[58:59]
	v_pk_mul_f32 v[26:27], v[28:29], v[58:59]
	v_pk_mul_f32 v[18:19], v[20:21], v[58:59]
	v_cvt_pk_bf16_f32 v14, v14, v15
	v_cvt_pk_bf16_f32 v15, v16, v17
	v_cvt_pk_bf16_f32 v16, v10, v11
	v_pk_mul_f32 v[10:11], v[12:13], v[58:59]
	v_cvt_pk_bf16_f32 v6, v6, v7
	v_cvt_pk_bf16_f32 v7, v8, v9
	v_cvt_pk_bf16_f32 v8, v2, v3
	v_pk_mul_f32 v[2:3], v[4:5], v[58:59]
	v_cvt_pk_bf16_f32 v65, v60, v61
	v_lshl_add_u64 v[60:61], v[124:125], 0, v[98:99]
	v_cvt_pk_bf16_f32 v57, v50, v51
	v_lshl_add_u64 v[50:51], v[116:117], 0, v[98:99]
	v_cvt_pk_bf16_f32 v49, v42, v43
	v_lshl_add_u64 v[42:43], v[108:109], 0, v[98:99]
	v_cvt_pk_bf16_f32 v41, v34, v35
	v_lshl_add_u64 v[34:35], v[100:101], 0, v[98:99]
	v_cvt_pk_bf16_f32 v33, v26, v27
	v_lshl_add_u64 v[26:27], v[90:91], 0, v[98:99]
	v_cvt_pk_bf16_f32 v25, v18, v19
	v_lshl_add_u64 v[18:19], v[82:83], 0, v[98:99]
	v_cvt_pk_bf16_f32 v17, v10, v11
	v_lshl_add_u64 v[10:11], v[74:75], 0, v[98:99]
	v_cvt_pk_bf16_f32 v9, v2, v3
	v_lshl_add_u64 v[2:3], v[70:71], 0, v[98:99]
	s_mov_b64 s[2:3], -1
	s_and_b64 vcc, exec, s[42:43]
	global_store_dwordx4 v[60:61], v[62:65], off
	global_store_dwordx4 v[50:51], v[54:57], off
	global_store_dwordx4 v[42:43], v[46:49], off
	global_store_dwordx4 v[34:35], v[38:41], off
	global_store_dwordx4 v[26:27], v[30:33], off
	global_store_dwordx4 v[18:19], v[22:25], off
	global_store_dwordx4 v[10:11], v[14:17], off
	global_store_dwordx4 v[2:3], v[6:9], off
	s_cbranch_vccnz .LBB0_1039
	s_andn2_b64 vcc, exec, s[44:45]
	s_cbranch_vccnz .LBB0_1038
	s_barrier
	s_branch .LBB0_1038

; __device__ __forceinline__ float ssf(const ssq_t* p) { return (float)(*p) * (1.0f / 1048576.0f); }
;     __device__ __forceinline__ void operator()(const f32x4 (&acc)[2][2][4][2], const pg8::Unit& u, int wr, int wc, int fr, int fq) const {
;     ...
;             for (int m = 0; m < 4; ++m) {
;                 const int b = (u.pm * 256) >> 13, t = ((u.pm * 256) & (S - 1)) + ai * 128 + wr * 64 + m * 16 + fr, row = b * S + t;
;                 const float r = rsqrtf(ssf(SSq + row) * (1.0f / QL) + EPS) * QS_MLA;
; #pragma unroll
;                 for (int bj = 0; bj < 2; ++bj) {
;                     const int c = u.pn * 256 + bj * 128 + wc * 32 + fq * 8;
;                     const int head = (c >= 576) ? 3 : (c >= 384) ? 2 : (c >= 192) ? 1 : 0, j = c - 192 * head;
;                     f32x4 a0 = acc[ai][bj][m][0] * r, a1 = acc[ai][bj][m][1] * r;
;                     if (j >= 128) {
;                         const f32x4 c0 = *(const f32x4*)(CS_ + ((size_t)t * 32 + ((j - 128) >> 1)) * 2), c1 = *(const f32x4*)(CS_ + ((size_t)t * 32 + ((j - 128) >> 1) + 2) * 2);
;                         const float y0 = a0[0] * c0[0] - a0[1] * c0[1], y1 = a0[1] * c0[0] + a0[0] * c0[1], y2 = a0[2] * c0[2] - a0[3] * c0[3], y3 = a0[3] * c0[2] + a0[2] * c0[3];
;                         const float y4 = a1[0] * c1[0] - a1[1] * c1[1], y5 = a1[1] * c1[0] + a1[0] * c1[1], y6 = a1[2] * c1[2] - a1[3] * c1[3], y7 = a1[3] * c1[2] + a1[2] * c1[3];
;                         a0[0] = y0; a0[1] = y1; a0[2] = y2; a0[3] = y3; a1[0] = y4; a1[1] = y5; a1[2] = y6; a1[3] = y7;
;                     }
.LBB0_1130:
	s_lshl_b32 s2, s45, 8
	s_and_b32 s2, s2, 0x1f00
	s_ashr_i32 s4, s45, 5
	v_add_u32_e32 v146, s2, v1
	v_lshl_add_u32 v144, s4, 13, v146
	v_ashrrev_i32_e32 v145, 31, v144
	v_lshl_add_u64 v[148:149], v[144:145], 3, s[8:9]
	global_load_dwordx2 v[144:145], v[148:149], off
	v_lshl_or_b32 v157, s44, 8, v155
	s_movk_i32 s1, 0xbf
	v_ashrrev_i32_e32 v147, 31, v146
	v_lshlrev_b64 v[158:159], 8, v[146:147]
	s_waitcnt vmcnt(0)
	v_ffbh_u32_e32 v98, v145
	v_min_u32_e32 v98, 32, v98
	v_lshlrev_b64 v[144:145], v98, v[144:145]
	v_min_u32_e32 v144, 1, v144
	v_or_b32_e32 v144, v145, v144
	v_cvt_f32_u32_e32 v144, v144
	v_sub_u32_e32 v98, 32, v98
	v_ldexp_f32 v98, v144, v98
	v_mul_f32_e32 v98, 0x35800000, v98
	v_fmamk_f32 v98, v98, 0x3b800000, v196
	v_cmp_gt_f32_e32 vcc, s23, v98
	v_mul_f32_e32 v144, 0x4b800000, v98
	s_nop 0
	v_cndmask_b32_e32 v98, v98, v144, vcc
	v_rsq_f32_e32 v98, v98
	s_nop 0
	v_mul_f32_e32 v144, 0x45800000, v98
	v_cndmask_b32_e32 v98, v98, v144, vcc
	v_cmp_lt_i32_e32 vcc, s1, v157
	v_mul_f32_e32 v150, 0x3dd53b94, v98
	s_movk_i32 s1, 0x240
	v_cndmask_b32_e64 v98, 0, 1, vcc
	v_cmp_gt_i32_e32 vcc, s5, v157
	v_pk_mul_f32 v[152:153], v[126:127], v[150:151] op_sel_hi:[1,0]
	v_pk_mul_f32 v[126:127], v[124:125], v[150:151] op_sel_hi:[1,0]
	v_cndmask_b32_e32 v98, 2, v98, vcc
	v_cmp_gt_i32_e32 vcc, s1, v157
	s_movk_i32 s1, 0xff40
	v_pk_mul_f32 v[130:131], v[130:131], v[150:151] op_sel_hi:[1,0]
	v_cndmask_b32_e32 v145, 3, v98, vcc
	v_mad_i32_i24 v144, v145, s1, v157
	s_movk_i32 s1, 0x7f
	v_add_u32_e32 v98, 0xffffff80, v144
	v_pk_mul_f32 v[124:125], v[128:129], v[150:151] op_sel_hi:[1,0]
	v_cmp_lt_i32_e32 vcc, s1, v144
	v_lshl_add_u64 v[128:129], s[50:51], 0, v[158:159]
	v_lshrrev_b32_e32 v98, 1, v98
	s_and_saveexec_b64 s[2:3], vcc
	s_cbranch_execz .LBB0_1132
	v_lshl_add_u64 v[162:163], v[98:99], 3, v[128:129]
	global_load_dwordx4 v[158:161], v[162:163], off offset:16
	global_load_dwordx4 v[162:165], v[162:163], off
	s_waitcnt vmcnt(0)
	v_pk_mul_f32 v[170:171], v[124:125], v[158:159] op_sel:[1,1] op_sel_hi:[0,1]
	v_pk_mul_f32 v[168:169], v[126:127], v[162:163] op_sel:[1,1] op_sel_hi:[0,1]
	v_pk_mul_f32 v[166:167], v[126:127], v[162:163]
	v_pk_fma_f32 v[126:127], v[126:127], v[162:163], v[168:169] op_sel_hi:[1,0,1]
	s_nop 0
	v_mul_f32_e32 v126, v153, v165
	v_pk_fma_f32 v[162:163], v[152:153], v[164:165], v[126:127] op_sel_hi:[1,1,0] neg_lo:[0,0,1] neg_hi:[0,0,1]
	v_mul_f32_e32 v126, v152, v165
	v_pk_fma_f32 v[164:165], v[152:153], v[164:165], v[126:127] op_sel:[1,0,0] op_sel_hi:[0,1,0]
	v_pk_mul_f32 v[152:153], v[124:125], v[158:159]
	v_pk_fma_f32 v[124:125], v[124:125], v[158:159], v[170:171] op_sel_hi:[1,0,1]
	v_sub_f32_e32 v126, v166, v168
	v_mul_f32_e32 v124, v131, v161
	v_pk_fma_f32 v[158:159], v[130:131], v[160:161], v[124:125] op_sel_hi:[1,1,0] neg_lo:[0,0,1] neg_hi:[0,0,1]
	v_mul_f32_e32 v124, v130, v161
	v_pk_fma_f32 v[160:161], v[130:131], v[160:161], v[124:125] op_sel:[1,0,0] op_sel_hi:[0,1,0]
	v_sub_f32_e32 v124, v152, v170
	v_mov_b32_e32 v130, v158
	v_mov_b32_e32 v131, v160
	v_mov_b32_e32 v152, v162
	v_mov_b32_e32 v153, v164

; __device__ __forceinline__ unsigned pk2(float lo, float hi) { f32x2 v = {lo, hi}; bf16x2_t b = __builtin_convertvector(v, bf16x2_t); return __builtin_bit_cast(unsigned, b); }
; __device__ __forceinline__ float ssf(const ssq_t* p) { return (float)(*p) * (1.0f / 1048576.0f); }
;     __device__ __forceinline__ void operator()(const f32x4 (&acc)[2][2][4][2], const pg8::Unit& u, int wr, int wc, int fr, int fq) const {
;     ...
;         for (int ai = 0; ai < 2; ++ai)
; #pragma unroll
;             for (int m = 0; m < 4; ++m) {
;                 const int b = (u.pm * 256) >> 13, t = ((u.pm * 256) & (S - 1)) + ai * 128 + wr * 64 + m * 16 + fr, row = b * S + t;
;                 const float r = rsqrtf(ssf(SSq + row) * (1.0f / QL) + EPS) * QS_MLA;
; #pragma unroll
;                 for (int bj = 0; bj < 2; ++bj) {
;                     const int c = u.pn * 256 + bj * 128 + wc * 32 + fq * 8;
;                     const int head = (c >= 576) ? 3 : (c >= 384) ? 2 : (c >= 192) ? 1 : 0, j = c - 192 * head;
;                     f32x4 a0 = acc[ai][bj][m][0] * r, a1 = acc[ai][bj][m][1] * r;
;                     if (j >= 128) {
;                         const f32x4 c0 = *(const f32x4*)(CS_ + ((size_t)t * 32 + ((j - 128) >> 1)) * 2), c1 = *(const f32x4*)(CS_ + ((size_t)t * 32 + ((j - 128) >> 1) + 2) * 2);
;                         const float y0 = a0[0] * c0[0] - a0[1] * c0[1], y1 = a0[1] * c0[0] + a0[0] * c0[1], y2 = a0[2] * c0[2] - a0[3] * c0[3], y3 = a0[3] * c0[2] + a0[2] * c0[3];
;                         const float y4 = a1[0] * c1[0] - a1[1] * c1[1], y5 = a1[1] * c1[0] + a1[0] * c1[1], y6 = a1[2] * c1[2] - a1[3] * c1[3], y7 = a1[3] * c1[2] + a1[2] * c1[3];
;                         a0[0] = y0; a0[1] = y1; a0[2] = y2; a0[3] = y3; a1[0] = y4; a1[1] = y5; a1[2] = y6; a1[3] = y7;
;                     }
;                     u32x4 w; w.x = pk2(a0[0], a0[1]); w.y = pk2(a0[2], a0[3]); w.z = pk2(a1[0], a1[1]); w.w = pk2(a1[2], a1[3]);
;                     *(u32x4*)(QM_ + ((size_t)(b * 4 + head) * S + t) * 192 + j) = w;
;                 }
.LBB0_1136:
	s_or_b64 exec, exec, s[2:3]
	v_cvt_pk_bf16_f32 v150, v112, v113
	v_cvt_pk_bf16_f32 v152, v110, v111
	v_lshl_add_u64 v[110:111], v[126:127], 0, v[120:121]
	v_mov_b64_e32 v[112:113], s[48:49]
	v_mad_u64_u32 v[112:113], s[2:3], v110, s5, v[112:113]
	v_mad_i32_i24 v113, v111, s5, v113
	v_cvt_pk_bf16_f32 v151, v128, v129
	v_cvt_pk_bf16_f32 v153, v114, v115
	v_lshl_add_u64 v[110:111], v[144:145], 1, v[112:113]
	v_mov_b32_e32 v123, v122
	global_store_dwordx4 v[110:111], v[150:153], off
	v_mov_b32_e32 v110, v122
	v_mov_b32_e32 v111, v122
	v_pk_mul_f32 v[106:107], v[106:107], v[110:111]
	v_pk_mul_f32 v[104:105], v[104:105], v[122:123]
	v_pk_mul_f32 v[102:103], v[102:103], v[110:111]
	v_pk_mul_f32 v[100:101], v[100:101], v[122:123]
	s_and_saveexec_b64 s[2:3], s[44:45]
	s_cbranch_execz .LBB0_1138
	v_mov_b32_e32 v117, v99
	v_lshl_add_u64 v[112:113], v[116:117], 3, v[108:109]
	global_load_dwordx4 v[108:111], v[112:113], off offset:16
	global_load_dwordx4 v[112:115], v[112:113], off
	s_waitcnt vmcnt(0)
	v_pk_mul_f32 v[130:131], v[100:101], v[108:109] op_sel:[1,1] op_sel_hi:[0,1]
	v_pk_mul_f32 v[128:129], v[104:105], v[112:113] op_sel:[1,1] op_sel_hi:[0,1]
	v_pk_mul_f32 v[122:123], v[104:105], v[112:113]
	v_pk_fma_f32 v[104:105], v[104:105], v[112:113], v[128:129] op_sel_hi:[1,0,1]
	s_nop 0
	v_mul_f32_e32 v104, v107, v115
	v_pk_fma_f32 v[112:113], v[106:107], v[114:115], v[104:105] op_sel_hi:[1,1,0] neg_lo:[0,0,1] neg_hi:[0,0,1]
	v_mul_f32_e32 v104, v106, v115
	v_pk_fma_f32 v[114:115], v[106:107], v[114:115], v[104:105] op_sel:[1,0,0] op_sel_hi:[0,1,0]
	v_pk_mul_f32 v[106:107], v[100:101], v[108:109]
	v_pk_fma_f32 v[100:101], v[100:101], v[108:109], v[130:131] op_sel_hi:[1,0,1]
	v_sub_f32_e32 v104, v122, v128
	v_mul_f32_e32 v100, v103, v111
	v_pk_fma_f32 v[108:109], v[102:103], v[110:111], v[100:101] op_sel_hi:[1,1,0] neg_lo:[0,0,1] neg_hi:[0,0,1]
	v_mul_f32_e32 v100, v102, v111
	v_pk_fma_f32 v[110:111], v[102:103], v[110:111], v[100:101] op_sel:[1,0,0] op_sel_hi:[0,1,0]
	v_sub_f32_e32 v100, v106, v130
	v_mov_b32_e32 v102, v108
	v_mov_b32_e32 v103, v110
	v_mov_b32_e32 v106, v112
	v_mov_b32_e32 v107, v114
.LBB0_1138:
	s_or_b64 exec, exec, s[2:3]
	v_cvt_pk_bf16_f32 v104, v104, v105
	v_cvt_pk_bf16_f32 v105, v106, v107
	v_cvt_pk_bf16_f32 v106, v100, v101
	v_cvt_pk_bf16_f32 v107, v102, v103
	v_lshl_add_u64 v[100:101], v[118:119], 0, v[120:121]
	v_mov_b64_e32 v[102:103], s[48:49]
	v_mad_u64_u32 v[102:103], s[2:3], v100, s5, v[102:103]
	v_mad_i32_i24 v103, v101, s5, v103
	v_lshl_add_u64 v[100:101], v[124:125], 1, v[102:103]
	global_store_dwordx4 v[100:101], v[104:107], off
	global_load_dwordx2 v[100:101], v[148:149], off offset:256
	s_waitcnt vmcnt(0)
	v_ffbh_u32_e32 v102, v101
	v_min_u32_e32 v102, 32, v102
	v_lshlrev_b64 v[100:101], v102, v[100:101]
	v_min_u32_e32 v100, 1, v100
	v_or_b32_e32 v100, v101, v100
	v_cvt_f32_u32_e32 v100, v100
	v_sub_u32_e32 v101, 32, v102
	v_ldexp_f32 v100, v100, v101
	v_mul_f32_e32 v100, 0x35800000, v100
	v_fmamk_f32 v100, v100, 0x3b800000, v196
	v_mul_f32_e32 v101, 0x4b800000, v100
	v_cmp_gt_f32_e64 s[2:3], s23, v100
	s_nop 1
	v_cndmask_b32_e64 v100, v100, v101, s[2:3]
	v_rsq_f32_e32 v102, v100
	v_or_b32_e32 v100, 32, v146
	v_ashrrev_i32_e32 v101, 31, v100
	v_lshlrev_b64 v[106:107], 8, v[100:101]
	v_mul_f32_e32 v103, 0x45800000, v102
	v_cndmask_b32_e64 v102, v102, v103, s[2:3]
	v_mul_f32_e32 v102, 0x3dd53b94, v102
	v_pk_mul_f32 v[104:105], v[96:97], v[102:103] op_sel_hi:[1,0]
	v_pk_mul_f32 v[94:95], v[94:95], v[102:103] op_sel_hi:[1,0]
	v_pk_mul_f32 v[96:97], v[92:93], v[102:103] op_sel_hi:[1,0]
	v_pk_mul_f32 v[92:93], v[90:91], v[102:103] op_sel_hi:[1,0]
	v_lshl_add_u64 v[90:91], s[50:51], 0, v[106:107]
	s_and_saveexec_b64 s[2:3], vcc
	s_cbranch_execz .LBB0_1140
	v_lshl_add_u64 v[110:111], v[98:99], 3, v[90:91]
	global_load_dwordx4 v[106:109], v[110:111], off offset:16
	global_load_dwordx4 v[110:113], v[110:111], off
	s_waitcnt vmcnt(0)
	v_pk_mul_f32 v[122:123], v[92:93], v[106:107] op_sel:[1,1] op_sel_hi:[0,1]
	v_pk_mul_f32 v[120:121], v[94:95], v[110:111] op_sel:[1,1] op_sel_hi:[0,1]
	v_pk_mul_f32 v[114:115], v[94:95], v[110:111]
	v_pk_fma_f32 v[94:95], v[94:95], v[110:111], v[120:121] op_sel_hi:[1,0,1]
	s_nop 0
	v_mul_f32_e32 v94, v105, v113
	v_pk_fma_f32 v[110:111], v[104:105], v[112:113], v[94:95] op_sel_hi:[1,1,0] neg_lo:[0,0,1] neg_hi:[0,0,1]
	v_mul_f32_e32 v94, v104, v113
	v_pk_fma_f32 v[112:113], v[104:105], v[112:113], v[94:95] op_sel:[1,0,0] op_sel_hi:[0,1,0]
	v_pk_mul_f32 v[104:105], v[92:93], v[106:107]
	v_pk_fma_f32 v[92:93], v[92:93], v[106:107], v[122:123] op_sel_hi:[1,0,1]
	v_sub_f32_e32 v94, v114, v120
	v_mul_f32_e32 v92, v97, v109
	v_pk_fma_f32 v[106:107], v[96:97], v[108:109], v[92:93] op_sel_hi:[1,1,0] neg_lo:[0,0,1] neg_hi:[0,0,1]
	v_mul_f32_e32 v92, v96, v109
	v_pk_fma_f32 v[108:109], v[96:97], v[108:109], v[92:93] op_sel:[1,0,0] op_sel_hi:[0,1,0]
	v_sub_f32_e32 v92, v104, v122
	v_mov_b32_e32 v96, v106
	v_mov_b32_e32 v97, v108
	v_mov_b32_e32 v104, v110
	v_mov_b32_e32 v105, v112
; __device__ __forceinline__ unsigned pk2(float lo, float hi) { f32x2 v = {lo, hi}; bf16x2_t b = __builtin_convertvector(v, bf16x2_t); return __builtin_bit_cast(unsigned, b); }
; __device__ __forceinline__ float ssf(const ssq_t* p) { return (float)(*p) * (1.0f / 1048576.0f); }
;     __device__ __forceinline__ void operator()(const f32x4 (&acc)[2][2][4][2], const pg8::Unit& u, int wr, int wc, int fr, int fq) const {
;     ...
;         for (int ai = 0; ai < 2; ++ai)
; #pragma unroll
;             for (int m = 0; m < 4; ++m) {
;                 const int b = (u.pm * 256) >> 13, t = ((u.pm * 256) & (S - 1)) + ai * 128 + wr * 64 + m * 16 + fr, row = b * S + t;
;                 const float r = rsqrtf(ssf(SSq + row) * (1.0f / QL) + EPS) * QS_MLA;
; #pragma unroll
;                 for (int bj = 0; bj < 2; ++bj) {
;                     const int c = u.pn * 256 + bj * 128 + wc * 32 + fq * 8;
;                     const int head = (c >= 576) ? 3 : (c >= 384) ? 2 : (c >= 192) ? 1 : 0, j = c - 192 * head;
;                     f32x4 a0 = acc[ai][bj][m][0] * r, a1 = acc[ai][bj][m][1] * r;
;                     if (j >= 128) {
;                         const f32x4 c0 = *(const f32x4*)(CS_ + ((size_t)t * 32 + ((j - 128) >> 1)) * 2), c1 = *(const f32x4*)(CS_ + ((size_t)t * 32 + ((j - 128) >> 1) + 2) * 2);
;                         const float y0 = a0[0] * c0[0] - a0[1] * c0[1], y1 = a0[1] * c0[0] + a0[0] * c0[1], y2 = a0[2] * c0[2] - a0[3] * c0[3], y3 = a0[3] * c0[2] + a0[2] * c0[3];
;                         const float y4 = a1[0] * c1[0] - a1[1] * c1[1], y5 = a1[1] * c1[0] + a1[0] * c1[1], y6 = a1[2] * c1[2] - a1[3] * c1[3], y7 = a1[3] * c1[2] + a1[2] * c1[3];
;                         a0[0] = y0; a0[1] = y1; a0[2] = y2; a0[3] = y3; a1[0] = y4; a1[1] = y5; a1[2] = y6; a1[3] = y7;
;                     }
;                     u32x4 w; w.x = pk2(a0[0], a0[1]); w.y = pk2(a0[2], a0[3]); w.z = pk2(a1[0], a1[1]); w.w = pk2(a1[2], a1[3]);
;                     *(u32x4*)(QM_ + ((size_t)(b * 4 + head) * S + t) * 192 + j) = w;
;                 }
.LBB0_1140:
	s_or_b64 exec, exec, s[2:3]
	v_cvt_pk_bf16_f32 v106, v94, v95
	v_cvt_pk_bf16_f32 v108, v92, v93
	v_lshl_add_u64 v[92:93], v[126:127], 0, v[100:101]
	v_mov_b64_e32 v[94:95], s[48:49]
	v_mad_u64_u32 v[94:95], s[2:3], v92, s5, v[94:95]
	v_mad_i32_i24 v95, v93, s5, v95
	v_cvt_pk_bf16_f32 v107, v104, v105
	v_cvt_pk_bf16_f32 v109, v96, v97
	v_lshl_add_u64 v[92:93], v[144:145], 1, v[94:95]
	v_mov_b32_e32 v103, v102
	global_store_dwordx4 v[92:93], v[106:109], off
	v_mov_b32_e32 v92, v102
	v_mov_b32_e32 v93, v102
	v_pk_mul_f32 v[88:89], v[88:89], v[92:93]
	v_pk_mul_f32 v[86:87], v[86:87], v[102:103]
	v_pk_mul_f32 v[84:85], v[84:85], v[92:93]
	v_pk_mul_f32 v[82:83], v[82:83], v[102:103]
	s_and_saveexec_b64 s[2:3], s[44:45]
	s_cbranch_execz .LBB0_1142
	v_mov_b32_e32 v117, v99
	v_lshl_add_u64 v[94:95], v[116:117], 3, v[90:91]
	global_load_dwordx4 v[90:93], v[94:95], off offset:16
	global_load_dwordx4 v[94:97], v[94:95], off
	s_waitcnt vmcnt(0)
	v_pk_mul_f32 v[106:107], v[82:83], v[90:91] op_sel:[1,1] op_sel_hi:[0,1]
	v_pk_mul_f32 v[104:105], v[86:87], v[94:95] op_sel:[1,1] op_sel_hi:[0,1]
	v_pk_mul_f32 v[102:103], v[86:87], v[94:95]
	v_pk_fma_f32 v[86:87], v[86:87], v[94:95], v[104:105] op_sel_hi:[1,0,1]
	s_nop 0
	v_mul_f32_e32 v86, v89, v97
	v_pk_fma_f32 v[94:95], v[88:89], v[96:97], v[86:87] op_sel_hi:[1,1,0] neg_lo:[0,0,1] neg_hi:[0,0,1]
	v_mul_f32_e32 v86, v88, v97
	v_pk_fma_f32 v[96:97], v[88:89], v[96:97], v[86:87] op_sel:[1,0,0] op_sel_hi:[0,1,0]
	v_pk_mul_f32 v[88:89], v[82:83], v[90:91]
	v_pk_fma_f32 v[82:83], v[82:83], v[90:91], v[106:107] op_sel_hi:[1,0,1]
	v_sub_f32_e32 v86, v102, v104
	v_mul_f32_e32 v82, v85, v93
	v_pk_fma_f32 v[90:91], v[84:85], v[92:93], v[82:83] op_sel_hi:[1,1,0] neg_lo:[0,0,1] neg_hi:[0,0,1]
	v_mul_f32_e32 v82, v84, v93
	v_pk_fma_f32 v[92:93], v[84:85], v[92:93], v[82:83] op_sel:[1,0,0] op_sel_hi:[0,1,0]
	v_sub_f32_e32 v82, v88, v106
	v_mov_b32_e32 v84, v90
	v_mov_b32_e32 v85, v92
	v_mov_b32_e32 v88, v94
	v_mov_b32_e32 v89, v96
.LBB0_1142:
	s_or_b64 exec, exec, s[2:3]
	v_cvt_pk_bf16_f32 v86, v86, v87
	v_cvt_pk_bf16_f32 v87, v88, v89
	v_cvt_pk_bf16_f32 v88, v82, v83
	v_cvt_pk_bf16_f32 v89, v84, v85
	v_lshl_add_u64 v[82:83], v[118:119], 0, v[100:101]
	v_mov_b64_e32 v[84:85], s[48:49]
	v_mad_u64_u32 v[84:85], s[2:3], v82, s5, v[84:85]
	v_mad_i32_i24 v85, v83, s5, v85
	v_lshl_add_u64 v[82:83], v[124:125], 1, v[84:85]
	global_store_dwordx4 v[82:83], v[86:89], off
	global_load_dwordx2 v[82:83], v[148:149], off offset:384
	s_waitcnt vmcnt(0)
	v_ffbh_u32_e32 v84, v83
	v_min_u32_e32 v84, 32, v84
	v_lshlrev_b64 v[82:83], v84, v[82:83]
	v_min_u32_e32 v82, 1, v82
	v_or_b32_e32 v82, v83, v82
	v_cvt_f32_u32_e32 v82, v82
	v_sub_u32_e32 v83, 32, v84
	v_ldexp_f32 v82, v82, v83
	v_mul_f32_e32 v82, 0x35800000, v82
	v_fmamk_f32 v82, v82, 0x3b800000, v196
	v_mul_f32_e32 v83, 0x4b800000, v82
	v_cmp_gt_f32_e64 s[2:3], s23, v82
	s_nop 1
	v_cndmask_b32_e64 v82, v82, v83, s[2:3]
	v_rsq_f32_e32 v84, v82
	v_or_b32_e32 v82, 48, v146
	v_ashrrev_i32_e32 v83, 31, v82
	v_lshlrev_b64 v[88:89], 8, v[82:83]
	v_mul_f32_e32 v85, 0x45800000, v84
	v_cndmask_b32_e64 v84, v84, v85, s[2:3]
	v_mul_f32_e32 v84, 0x3dd53b94, v84
	v_pk_mul_f32 v[86:87], v[80:81], v[84:85] op_sel_hi:[1,0]
	v_pk_mul_f32 v[78:79], v[78:79], v[84:85] op_sel_hi:[1,0]
	v_pk_mul_f32 v[80:81], v[76:77], v[84:85] op_sel_hi:[1,0]
	v_pk_mul_f32 v[76:77], v[74:75], v[84:85] op_sel_hi:[1,0]
	v_lshl_add_u64 v[74:75], s[50:51], 0, v[88:89]
	s_and_saveexec_b64 s[2:3], vcc
	s_cbranch_execz .LBB0_1144
	v_lshl_add_u64 v[92:93], v[98:99], 3, v[74:75]
	global_load_dwordx4 v[88:91], v[92:93], off offset:16
	global_load_dwordx4 v[92:95], v[92:93], off
	s_waitcnt vmcnt(0)
	v_pk_mul_f32 v[102:103], v[76:77], v[88:89] op_sel:[1,1] op_sel_hi:[0,1]
	v_pk_mul_f32 v[100:101], v[78:79], v[92:93] op_sel:[1,1] op_sel_hi:[0,1]
	v_pk_mul_f32 v[96:97], v[78:79], v[92:93]
	v_pk_fma_f32 v[78:79], v[78:79], v[92:93], v[100:101] op_sel_hi:[1,0,1]
	s_nop 0
	v_mul_f32_e32 v78, v87, v95
	v_pk_fma_f32 v[92:93], v[86:87], v[94:95], v[78:79] op_sel_hi:[1,1,0] neg_lo:[0,0,1] neg_hi:[0,0,1]
	v_mul_f32_e32 v78, v86, v95
	v_pk_fma_f32 v[94:95], v[86:87], v[94:95], v[78:79] op_sel:[1,0,0] op_sel_hi:[0,1,0]
	v_pk_mul_f32 v[86:87], v[76:77], v[88:89]
	v_pk_fma_f32 v[76:77], v[76:77], v[88:89], v[102:103] op_sel_hi:[1,0,1]
	v_sub_f32_e32 v78, v96, v100
	v_mul_f32_e32 v76, v81, v91
	v_pk_fma_f32 v[88:89], v[80:81], v[90:91], v[76:77] op_sel_hi:[1,1,0] neg_lo:[0,0,1] neg_hi:[0,0,1]
	v_mul_f32_e32 v76, v80, v91
	v_pk_fma_f32 v[90:91], v[80:81], v[90:91], v[76:77] op_sel:[1,0,0] op_sel_hi:[0,1,0]
	v_sub_f32_e32 v76, v86, v102
	v_mov_b32_e32 v80, v88
	v_mov_b32_e32 v81, v90
	v_mov_b32_e32 v86, v92
	v_mov_b32_e32 v87, v94
; __device__ __forceinline__ unsigned pk2(float lo, float hi) { f32x2 v = {lo, hi}; bf16x2_t b = __builtin_convertvector(v, bf16x2_t); return __builtin_bit_cast(unsigned, b); }
; __device__ __forceinline__ float ssf(const ssq_t* p) { return (float)(*p) * (1.0f / 1048576.0f); }
;     __device__ __forceinline__ void operator()(const f32x4 (&acc)[2][2][4][2], const pg8::Unit& u, int wr, int wc, int fr, int fq) const {
;     ...
;         for (int ai = 0; ai < 2; ++ai)
; #pragma unroll
;             for (int m = 0; m < 4; ++m) {
;                 const int b = (u.pm * 256) >> 13, t = ((u.pm * 256) & (S - 1)) + ai * 128 + wr * 64 + m * 16 + fr, row = b * S + t;
;                 const float r = rsqrtf(ssf(SSq + row) * (1.0f / QL) + EPS) * QS_MLA;
; #pragma unroll
;                 for (int bj = 0; bj < 2; ++bj) {
;                     const int c = u.pn * 256 + bj * 128 + wc * 32 + fq * 8;
;                     const int head = (c >= 576) ? 3 : (c >= 384) ? 2 : (c >= 192) ? 1 : 0, j = c - 192 * head;
;                     f32x4 a0 = acc[ai][bj][m][0] * r, a1 = acc[ai][bj][m][1] * r;
;                     if (j >= 128) {
;                         const f32x4 c0 = *(const f32x4*)(CS_ + ((size_t)t * 32 + ((j - 128) >> 1)) * 2), c1 = *(const f32x4*)(CS_ + ((size_t)t * 32 + ((j - 128) >> 1) + 2) * 2);
;                         const float y0 = a0[0] * c0[0] - a0[1] * c0[1], y1 = a0[1] * c0[0] + a0[0] * c0[1], y2 = a0[2] * c0[2] - a0[3] * c0[3], y3 = a0[3] * c0[2] + a0[2] * c0[3];
;                         const float y4 = a1[0] * c1[0] - a1[1] * c1[1], y5 = a1[1] * c1[0] + a1[0] * c1[1], y6 = a1[2] * c1[2] - a1[3] * c1[3], y7 = a1[3] * c1[2] + a1[2] * c1[3];
;                         a0[0] = y0; a0[1] = y1; a0[2] = y2; a0[3] = y3; a1[0] = y4; a1[1] = y5; a1[2] = y6; a1[3] = y7;
;                     }
;                     u32x4 w; w.x = pk2(a0[0], a0[1]); w.y = pk2(a0[2], a0[3]); w.z = pk2(a1[0], a1[1]); w.w = pk2(a1[2], a1[3]);
;                     *(u32x4*)(QM_ + ((size_t)(b * 4 + head) * S + t) * 192 + j) = w;
;                 }
.LBB0_1144:
	s_or_b64 exec, exec, s[2:3]
	v_cvt_pk_bf16_f32 v88, v78, v79
	v_cvt_pk_bf16_f32 v90, v76, v77
	v_lshl_add_u64 v[76:77], v[126:127], 0, v[82:83]
	v_mov_b64_e32 v[78:79], s[48:49]
	v_mad_u64_u32 v[78:79], s[2:3], v76, s5, v[78:79]
	v_mad_i32_i24 v79, v77, s5, v79
	v_cvt_pk_bf16_f32 v89, v86, v87
	v_cvt_pk_bf16_f32 v91, v80, v81
	v_lshl_add_u64 v[76:77], v[144:145], 1, v[78:79]
	v_mov_b32_e32 v85, v84
	global_store_dwordx4 v[76:77], v[88:91], off
	v_mov_b32_e32 v76, v84
	v_mov_b32_e32 v77, v84
	v_pk_mul_f32 v[72:73], v[72:73], v[76:77]
	v_pk_mul_f32 v[70:71], v[70:71], v[84:85]
	v_pk_mul_f32 v[68:69], v[68:69], v[76:77]
	v_pk_mul_f32 v[66:67], v[66:67], v[84:85]
	s_and_saveexec_b64 s[2:3], s[44:45]
	s_cbranch_execz .LBB0_1146
	v_mov_b32_e32 v117, v99
	v_lshl_add_u64 v[78:79], v[116:117], 3, v[74:75]
	global_load_dwordx4 v[74:77], v[78:79], off offset:16
	global_load_dwordx4 v[78:81], v[78:79], off
	s_waitcnt vmcnt(0)
	v_pk_mul_f32 v[88:89], v[66:67], v[74:75] op_sel:[1,1] op_sel_hi:[0,1]
	v_pk_mul_f32 v[86:87], v[70:71], v[78:79] op_sel:[1,1] op_sel_hi:[0,1]
	v_pk_mul_f32 v[84:85], v[70:71], v[78:79]
	v_pk_fma_f32 v[70:71], v[70:71], v[78:79], v[86:87] op_sel_hi:[1,0,1]
	s_nop 0
	v_mul_f32_e32 v70, v73, v81
	v_pk_fma_f32 v[78:79], v[72:73], v[80:81], v[70:71] op_sel_hi:[1,1,0] neg_lo:[0,0,1] neg_hi:[0,0,1]
	v_mul_f32_e32 v70, v72, v81
	v_pk_fma_f32 v[80:81], v[72:73], v[80:81], v[70:71] op_sel:[1,0,0] op_sel_hi:[0,1,0]
	v_pk_mul_f32 v[72:73], v[66:67], v[74:75]
	v_pk_fma_f32 v[66:67], v[66:67], v[74:75], v[88:89] op_sel_hi:[1,0,1]
	v_sub_f32_e32 v70, v84, v86
	v_mul_f32_e32 v66, v69, v77
	v_pk_fma_f32 v[74:75], v[68:69], v[76:77], v[66:67] op_sel_hi:[1,1,0] neg_lo:[0,0,1] neg_hi:[0,0,1]
	v_mul_f32_e32 v66, v68, v77
	v_pk_fma_f32 v[76:77], v[68:69], v[76:77], v[66:67] op_sel:[1,0,0] op_sel_hi:[0,1,0]
	v_sub_f32_e32 v66, v72, v88
	v_mov_b32_e32 v68, v74
	v_mov_b32_e32 v69, v76
	v_mov_b32_e32 v72, v78
	v_mov_b32_e32 v73, v80
.LBB0_1146:
	s_or_b64 exec, exec, s[2:3]
	v_cvt_pk_bf16_f32 v70, v70, v71
	v_cvt_pk_bf16_f32 v71, v72, v73
	v_cvt_pk_bf16_f32 v72, v66, v67
	v_cvt_pk_bf16_f32 v73, v68, v69
	v_lshl_add_u64 v[66:67], v[118:119], 0, v[82:83]
	v_mov_b64_e32 v[68:69], s[48:49]
	v_mad_u64_u32 v[68:69], s[2:3], v66, s5, v[68:69]
	v_mad_i32_i24 v69, v67, s5, v69
	v_lshl_add_u64 v[66:67], v[124:125], 1, v[68:69]
	global_store_dwordx4 v[66:67], v[70:73], off
	global_load_dwordx2 v[66:67], v[148:149], off offset:1024
	s_waitcnt vmcnt(0)
	v_ffbh_u32_e32 v68, v67
	v_min_u32_e32 v68, 32, v68
	v_lshlrev_b64 v[66:67], v68, v[66:67]
	v_min_u32_e32 v66, 1, v66
	v_or_b32_e32 v66, v67, v66
	v_cvt_f32_u32_e32 v66, v66
	v_sub_u32_e32 v67, 32, v68
	v_ldexp_f32 v66, v66, v67
	v_mul_f32_e32 v66, 0x35800000, v66
	v_fmamk_f32 v66, v66, 0x3b800000, v196
	v_mul_f32_e32 v67, 0x4b800000, v66
	v_cmp_gt_f32_e64 s[2:3], s23, v66
	s_nop 1
	v_cndmask_b32_e64 v66, v66, v67, s[2:3]
	v_rsq_f32_e32 v68, v66
	v_add_u32_e32 v66, 0x80, v146
	v_ashrrev_i32_e32 v67, 31, v66
	v_lshlrev_b64 v[72:73], 8, v[66:67]
	v_mul_f32_e32 v69, 0x45800000, v68
	v_cndmask_b32_e64 v68, v68, v69, s[2:3]
	v_mul_f32_e32 v68, 0x3dd53b94, v68
	v_pk_mul_f32 v[70:71], v[64:65], v[68:69] op_sel_hi:[1,0]
	v_pk_mul_f32 v[62:63], v[62:63], v[68:69] op_sel_hi:[1,0]
	v_pk_mul_f32 v[64:65], v[60:61], v[68:69] op_sel_hi:[1,0]
	v_pk_mul_f32 v[60:61], v[58:59], v[68:69] op_sel_hi:[1,0]
	v_lshl_add_u64 v[58:59], s[50:51], 0, v[72:73]
	s_and_saveexec_b64 s[2:3], vcc
	s_cbranch_execz .LBB0_1148
	v_lshl_add_u64 v[76:77], v[98:99], 3, v[58:59]
	global_load_dwordx4 v[72:75], v[76:77], off offset:16
	global_load_dwordx4 v[76:79], v[76:77], off
	s_waitcnt vmcnt(0)
	v_pk_mul_f32 v[84:85], v[60:61], v[72:73] op_sel:[1,1] op_sel_hi:[0,1]
	v_pk_mul_f32 v[82:83], v[62:63], v[76:77] op_sel:[1,1] op_sel_hi:[0,1]
	v_pk_mul_f32 v[80:81], v[62:63], v[76:77]
	v_pk_fma_f32 v[62:63], v[62:63], v[76:77], v[82:83] op_sel_hi:[1,0,1]
	s_nop 0
	v_mul_f32_e32 v62, v71, v79
	v_pk_fma_f32 v[76:77], v[70:71], v[78:79], v[62:63] op_sel_hi:[1,1,0] neg_lo:[0,0,1] neg_hi:[0,0,1]
	v_mul_f32_e32 v62, v70, v79
	v_pk_fma_f32 v[78:79], v[70:71], v[78:79], v[62:63] op_sel:[1,0,0] op_sel_hi:[0,1,0]
	v_pk_mul_f32 v[70:71], v[60:61], v[72:73]
	v_pk_fma_f32 v[60:61], v[60:61], v[72:73], v[84:85] op_sel_hi:[1,0,1]
	v_sub_f32_e32 v62, v80, v82
	v_mul_f32_e32 v60, v65, v75
	v_pk_fma_f32 v[72:73], v[64:65], v[74:75], v[60:61] op_sel_hi:[1,1,0] neg_lo:[0,0,1] neg_hi:[0,0,1]
	v_mul_f32_e32 v60, v64, v75
	v_pk_fma_f32 v[74:75], v[64:65], v[74:75], v[60:61] op_sel:[1,0,0] op_sel_hi:[0,1,0]
	v_sub_f32_e32 v60, v70, v84
	v_mov_b32_e32 v64, v72
	v_mov_b32_e32 v65, v74
	v_mov_b32_e32 v70, v76
	v_mov_b32_e32 v71, v78
; __device__ __forceinline__ unsigned pk2(float lo, float hi) { f32x2 v = {lo, hi}; bf16x2_t b = __builtin_convertvector(v, bf16x2_t); return __builtin_bit_cast(unsigned, b); }
; __device__ __forceinline__ float ssf(const ssq_t* p) { return (float)(*p) * (1.0f / 1048576.0f); }
;     __device__ __forceinline__ void operator()(const f32x4 (&acc)[2][2][4][2], const pg8::Unit& u, int wr, int wc, int fr, int fq) const {
;     ...
;         for (int ai = 0; ai < 2; ++ai)
; #pragma unroll
;             for (int m = 0; m < 4; ++m) {
;                 const int b = (u.pm * 256) >> 13, t = ((u.pm * 256) & (S - 1)) + ai * 128 + wr * 64 + m * 16 + fr, row = b * S + t;
;                 const float r = rsqrtf(ssf(SSq + row) * (1.0f / QL) + EPS) * QS_MLA;
; #pragma unroll
;                 for (int bj = 0; bj < 2; ++bj) {
;                     const int c = u.pn * 256 + bj * 128 + wc * 32 + fq * 8;
;                     const int head = (c >= 576) ? 3 : (c >= 384) ? 2 : (c >= 192) ? 1 : 0, j = c - 192 * head;
;                     f32x4 a0 = acc[ai][bj][m][0] * r, a1 = acc[ai][bj][m][1] * r;
;                     if (j >= 128) {
;                         const f32x4 c0 = *(const f32x4*)(CS_ + ((size_t)t * 32 + ((j - 128) >> 1)) * 2), c1 = *(const f32x4*)(CS_ + ((size_t)t * 32 + ((j - 128) >> 1) + 2) * 2);
;                         const float y0 = a0[0] * c0[0] - a0[1] * c0[1], y1 = a0[1] * c0[0] + a0[0] * c0[1], y2 = a0[2] * c0[2] - a0[3] * c0[3], y3 = a0[3] * c0[2] + a0[2] * c0[3];
;                         const float y4 = a1[0] * c1[0] - a1[1] * c1[1], y5 = a1[1] * c1[0] + a1[0] * c1[1], y6 = a1[2] * c1[2] - a1[3] * c1[3], y7 = a1[3] * c1[2] + a1[2] * c1[3];
;                         a0[0] = y0; a0[1] = y1; a0[2] = y2; a0[3] = y3; a1[0] = y4; a1[1] = y5; a1[2] = y6; a1[3] = y7;
;                     }
;                     u32x4 w; w.x = pk2(a0[0], a0[1]); w.y = pk2(a0[2], a0[3]); w.z = pk2(a1[0], a1[1]); w.w = pk2(a1[2], a1[3]);
;                     *(u32x4*)(QM_ + ((size_t)(b * 4 + head) * S + t) * 192 + j) = w;
;                 }
.LBB0_1148:
	s_or_b64 exec, exec, s[2:3]
	v_cvt_pk_bf16_f32 v72, v62, v63
	v_cvt_pk_bf16_f32 v74, v60, v61
	v_lshl_add_u64 v[60:61], v[126:127], 0, v[66:67]
	v_mov_b64_e32 v[62:63], s[48:49]
	v_mad_u64_u32 v[62:63], s[2:3], v60, s5, v[62:63]
	v_mad_i32_i24 v63, v61, s5, v63
	v_cvt_pk_bf16_f32 v73, v70, v71
	v_cvt_pk_bf16_f32 v75, v64, v65
	v_lshl_add_u64 v[60:61], v[144:145], 1, v[62:63]
	v_mov_b32_e32 v69, v68
	global_store_dwordx4 v[60:61], v[72:75], off
	v_mov_b32_e32 v60, v68
	v_mov_b32_e32 v61, v68
	v_pk_mul_f32 v[56:57], v[56:57], v[60:61]
	v_pk_mul_f32 v[54:55], v[54:55], v[68:69]
	v_pk_mul_f32 v[52:53], v[52:53], v[60:61]
	v_pk_mul_f32 v[50:51], v[50:51], v[68:69]
	s_and_saveexec_b64 s[2:3], s[44:45]
	s_cbranch_execz .LBB0_1150
	v_mov_b32_e32 v117, v99
	v_lshl_add_u64 v[62:63], v[116:117], 3, v[58:59]
	global_load_dwordx4 v[58:61], v[62:63], off offset:16
	global_load_dwordx4 v[62:65], v[62:63], off
	s_waitcnt vmcnt(0)
	v_pk_mul_f32 v[72:73], v[50:51], v[58:59] op_sel:[1,1] op_sel_hi:[0,1]
	v_pk_mul_f32 v[70:71], v[54:55], v[62:63] op_sel:[1,1] op_sel_hi:[0,1]
	v_pk_mul_f32 v[68:69], v[54:55], v[62:63]
	v_pk_fma_f32 v[54:55], v[54:55], v[62:63], v[70:71] op_sel_hi:[1,0,1]
	s_nop 0
	v_mul_f32_e32 v54, v57, v65
	v_pk_fma_f32 v[62:63], v[56:57], v[64:65], v[54:55] op_sel_hi:[1,1,0] neg_lo:[0,0,1] neg_hi:[0,0,1]
	v_mul_f32_e32 v54, v56, v65
	v_pk_fma_f32 v[64:65], v[56:57], v[64:65], v[54:55] op_sel:[1,0,0] op_sel_hi:[0,1,0]
	v_pk_mul_f32 v[56:57], v[50:51], v[58:59]
	v_pk_fma_f32 v[50:51], v[50:51], v[58:59], v[72:73] op_sel_hi:[1,0,1]
	v_sub_f32_e32 v54, v68, v70
	v_mul_f32_e32 v50, v53, v61
	v_pk_fma_f32 v[58:59], v[52:53], v[60:61], v[50:51] op_sel_hi:[1,1,0] neg_lo:[0,0,1] neg_hi:[0,0,1]
	v_mul_f32_e32 v50, v52, v61
	v_pk_fma_f32 v[60:61], v[52:53], v[60:61], v[50:51] op_sel:[1,0,0] op_sel_hi:[0,1,0]
	v_sub_f32_e32 v50, v56, v72
	v_mov_b32_e32 v52, v58
	v_mov_b32_e32 v53, v60
	v_mov_b32_e32 v56, v62
	v_mov_b32_e32 v57, v64
.LBB0_1150:
	s_or_b64 exec, exec, s[2:3]
	v_cvt_pk_bf16_f32 v54, v54, v55
	v_cvt_pk_bf16_f32 v55, v56, v57
	v_cvt_pk_bf16_f32 v56, v50, v51
	v_cvt_pk_bf16_f32 v57, v52, v53
	v_lshl_add_u64 v[50:51], v[118:119], 0, v[66:67]
	v_mov_b64_e32 v[52:53], s[48:49]
	v_mad_u64_u32 v[52:53], s[2:3], v50, s5, v[52:53]
	v_mad_i32_i24 v53, v51, s5, v53
	v_lshl_add_u64 v[50:51], v[124:125], 1, v[52:53]
	global_store_dwordx4 v[50:51], v[54:57], off
	global_load_dwordx2 v[50:51], v[148:149], off offset:1152
	s_waitcnt vmcnt(0)
	v_ffbh_u32_e32 v52, v51
	v_min_u32_e32 v52, 32, v52
	v_lshlrev_b64 v[50:51], v52, v[50:51]
	v_min_u32_e32 v50, 1, v50
	v_or_b32_e32 v50, v51, v50
	v_cvt_f32_u32_e32 v50, v50
	v_sub_u32_e32 v51, 32, v52
	v_ldexp_f32 v50, v50, v51
	v_mul_f32_e32 v50, 0x35800000, v50
	v_fmamk_f32 v50, v50, 0x3b800000, v196
	v_mul_f32_e32 v51, 0x4b800000, v50
	v_cmp_gt_f32_e64 s[2:3], s23, v50
	s_nop 1
	v_cndmask_b32_e64 v50, v50, v51, s[2:3]
	v_rsq_f32_e32 v52, v50
	v_add_u32_e32 v50, 0x90, v146
	v_ashrrev_i32_e32 v51, 31, v50
	v_lshlrev_b64 v[56:57], 8, v[50:51]
	v_mul_f32_e32 v53, 0x45800000, v52
	v_cndmask_b32_e64 v52, v52, v53, s[2:3]
	v_mul_f32_e32 v52, 0x3dd53b94, v52
	v_pk_mul_f32 v[54:55], v[48:49], v[52:53] op_sel_hi:[1,0]
	v_pk_mul_f32 v[46:47], v[46:47], v[52:53] op_sel_hi:[1,0]
	v_pk_mul_f32 v[48:49], v[44:45], v[52:53] op_sel_hi:[1,0]
	v_pk_mul_f32 v[44:45], v[42:43], v[52:53] op_sel_hi:[1,0]
	v_lshl_add_u64 v[42:43], s[50:51], 0, v[56:57]
	s_and_saveexec_b64 s[2:3], vcc
	s_cbranch_execz .LBB0_1152
	v_lshl_add_u64 v[60:61], v[98:99], 3, v[42:43]
	global_load_dwordx4 v[56:59], v[60:61], off offset:16
	global_load_dwordx4 v[60:63], v[60:61], off
	s_waitcnt vmcnt(0)
	v_pk_mul_f32 v[68:69], v[44:45], v[56:57] op_sel:[1,1] op_sel_hi:[0,1]
	v_pk_mul_f32 v[66:67], v[46:47], v[60:61] op_sel:[1,1] op_sel_hi:[0,1]
	v_pk_mul_f32 v[64:65], v[46:47], v[60:61]
	v_pk_fma_f32 v[46:47], v[46:47], v[60:61], v[66:67] op_sel_hi:[1,0,1]
	s_nop 0
	v_mul_f32_e32 v46, v55, v63
	v_pk_fma_f32 v[60:61], v[54:55], v[62:63], v[46:47] op_sel_hi:[1,1,0] neg_lo:[0,0,1] neg_hi:[0,0,1]
	v_mul_f32_e32 v46, v54, v63
	v_pk_fma_f32 v[62:63], v[54:55], v[62:63], v[46:47] op_sel:[1,0,0] op_sel_hi:[0,1,0]
	v_pk_mul_f32 v[54:55], v[44:45], v[56:57]
	v_pk_fma_f32 v[44:45], v[44:45], v[56:57], v[68:69] op_sel_hi:[1,0,1]
	v_sub_f32_e32 v46, v64, v66
	v_mul_f32_e32 v44, v49, v59
	v_pk_fma_f32 v[56:57], v[48:49], v[58:59], v[44:45] op_sel_hi:[1,1,0] neg_lo:[0,0,1] neg_hi:[0,0,1]
	v_mul_f32_e32 v44, v48, v59
	v_pk_fma_f32 v[58:59], v[48:49], v[58:59], v[44:45] op_sel:[1,0,0] op_sel_hi:[0,1,0]
	v_sub_f32_e32 v44, v54, v68
	v_mov_b32_e32 v48, v56
	v_mov_b32_e32 v49, v58
	v_mov_b32_e32 v54, v60
	v_mov_b32_e32 v55, v62
; __device__ __forceinline__ unsigned pk2(float lo, float hi) { f32x2 v = {lo, hi}; bf16x2_t b = __builtin_convertvector(v, bf16x2_t); return __builtin_bit_cast(unsigned, b); }
; __device__ __forceinline__ float ssf(const ssq_t* p) { return (float)(*p) * (1.0f / 1048576.0f); }
;     __device__ __forceinline__ void operator()(const f32x4 (&acc)[2][2][4][2], const pg8::Unit& u, int wr, int wc, int fr, int fq) const {
;     ...
;         for (int ai = 0; ai < 2; ++ai)
; #pragma unroll
;             for (int m = 0; m < 4; ++m) {
;                 const int b = (u.pm * 256) >> 13, t = ((u.pm * 256) & (S - 1)) + ai * 128 + wr * 64 + m * 16 + fr, row = b * S + t;
;                 const float r = rsqrtf(ssf(SSq + row) * (1.0f / QL) + EPS) * QS_MLA;
; #pragma unroll
;                 for (int bj = 0; bj < 2; ++bj) {
;                     const int c = u.pn * 256 + bj * 128 + wc * 32 + fq * 8;
;                     const int head = (c >= 576) ? 3 : (c >= 384) ? 2 : (c >= 192) ? 1 : 0, j = c - 192 * head;
;                     f32x4 a0 = acc[ai][bj][m][0] * r, a1 = acc[ai][bj][m][1] * r;
;                     if (j >= 128) {
;                         const f32x4 c0 = *(const f32x4*)(CS_ + ((size_t)t * 32 + ((j - 128) >> 1)) * 2), c1 = *(const f32x4*)(CS_ + ((size_t)t * 32 + ((j - 128) >> 1) + 2) * 2);
;                         const float y0 = a0[0] * c0[0] - a0[1] * c0[1], y1 = a0[1] * c0[0] + a0[0] * c0[1], y2 = a0[2] * c0[2] - a0[3] * c0[3], y3 = a0[3] * c0[2] + a0[2] * c0[3];
;                         const float y4 = a1[0] * c1[0] - a1[1] * c1[1], y5 = a1[1] * c1[0] + a1[0] * c1[1], y6 = a1[2] * c1[2] - a1[3] * c1[3], y7 = a1[3] * c1[2] + a1[2] * c1[3];
;                         a0[0] = y0; a0[1] = y1; a0[2] = y2; a0[3] = y3; a1[0] = y4; a1[1] = y5; a1[2] = y6; a1[3] = y7;
;                     }
;                     u32x4 w; w.x = pk2(a0[0], a0[1]); w.y = pk2(a0[2], a0[3]); w.z = pk2(a1[0], a1[1]); w.w = pk2(a1[2], a1[3]);
;                     *(u32x4*)(QM_ + ((size_t)(b * 4 + head) * S + t) * 192 + j) = w;
;                 }
.LBB0_1152:
	s_or_b64 exec, exec, s[2:3]
	v_cvt_pk_bf16_f32 v56, v46, v47
	v_cvt_pk_bf16_f32 v58, v44, v45
	v_lshl_add_u64 v[44:45], v[126:127], 0, v[50:51]
	v_mov_b64_e32 v[46:47], s[48:49]
	v_mad_u64_u32 v[46:47], s[2:3], v44, s5, v[46:47]
	v_mad_i32_i24 v47, v45, s5, v47
	v_cvt_pk_bf16_f32 v57, v54, v55
	v_cvt_pk_bf16_f32 v59, v48, v49
	v_lshl_add_u64 v[44:45], v[144:145], 1, v[46:47]
	v_mov_b32_e32 v53, v52
	global_store_dwordx4 v[44:45], v[56:59], off
	v_mov_b32_e32 v44, v52
	v_mov_b32_e32 v45, v52
	v_pk_mul_f32 v[40:41], v[40:41], v[44:45]
	v_pk_mul_f32 v[38:39], v[38:39], v[52:53]
	v_pk_mul_f32 v[36:37], v[36:37], v[44:45]
	v_pk_mul_f32 v[34:35], v[34:35], v[52:53]
	s_and_saveexec_b64 s[2:3], s[44:45]
	s_cbranch_execz .LBB0_1154
	v_mov_b32_e32 v117, v99
	v_lshl_add_u64 v[46:47], v[116:117], 3, v[42:43]
	global_load_dwordx4 v[42:45], v[46:47], off offset:16
	global_load_dwordx4 v[46:49], v[46:47], off
	s_waitcnt vmcnt(0)
	v_pk_mul_f32 v[56:57], v[34:35], v[42:43] op_sel:[1,1] op_sel_hi:[0,1]
	v_pk_mul_f32 v[54:55], v[38:39], v[46:47] op_sel:[1,1] op_sel_hi:[0,1]
	v_pk_mul_f32 v[52:53], v[38:39], v[46:47]
	v_pk_fma_f32 v[38:39], v[38:39], v[46:47], v[54:55] op_sel_hi:[1,0,1]
	s_nop 0
	v_mul_f32_e32 v38, v41, v49
	v_pk_fma_f32 v[46:47], v[40:41], v[48:49], v[38:39] op_sel_hi:[1,1,0] neg_lo:[0,0,1] neg_hi:[0,0,1]
	v_mul_f32_e32 v38, v40, v49
	v_pk_fma_f32 v[48:49], v[40:41], v[48:49], v[38:39] op_sel:[1,0,0] op_sel_hi:[0,1,0]
	v_pk_mul_f32 v[40:41], v[34:35], v[42:43]
	v_pk_fma_f32 v[34:35], v[34:35], v[42:43], v[56:57] op_sel_hi:[1,0,1]
	v_sub_f32_e32 v38, v52, v54
	v_mul_f32_e32 v34, v37, v45
	v_pk_fma_f32 v[42:43], v[36:37], v[44:45], v[34:35] op_sel_hi:[1,1,0] neg_lo:[0,0,1] neg_hi:[0,0,1]
	v_mul_f32_e32 v34, v36, v45
	v_pk_fma_f32 v[44:45], v[36:37], v[44:45], v[34:35] op_sel:[1,0,0] op_sel_hi:[0,1,0]
	v_sub_f32_e32 v34, v40, v56
	v_mov_b32_e32 v36, v42
	v_mov_b32_e32 v37, v44
	v_mov_b32_e32 v40, v46
	v_mov_b32_e32 v41, v48
.LBB0_1154:
	s_or_b64 exec, exec, s[2:3]
	v_cvt_pk_bf16_f32 v38, v38, v39
	v_cvt_pk_bf16_f32 v39, v40, v41
	v_cvt_pk_bf16_f32 v40, v34, v35
	v_cvt_pk_bf16_f32 v41, v36, v37
	v_lshl_add_u64 v[34:35], v[118:119], 0, v[50:51]
	v_mov_b64_e32 v[36:37], s[48:49]
	v_mad_u64_u32 v[36:37], s[2:3], v34, s5, v[36:37]
	v_mad_i32_i24 v37, v35, s5, v37
	v_lshl_add_u64 v[34:35], v[124:125], 1, v[36:37]
	global_store_dwordx4 v[34:35], v[38:41], off
	global_load_dwordx2 v[34:35], v[148:149], off offset:1280
	s_waitcnt vmcnt(0)
	v_ffbh_u32_e32 v36, v35
	v_min_u32_e32 v36, 32, v36
	v_lshlrev_b64 v[34:35], v36, v[34:35]
	v_min_u32_e32 v34, 1, v34
	v_or_b32_e32 v34, v35, v34
	v_cvt_f32_u32_e32 v34, v34
	v_sub_u32_e32 v35, 32, v36
	v_ldexp_f32 v34, v34, v35
	v_mul_f32_e32 v34, 0x35800000, v34
	v_fmamk_f32 v34, v34, 0x3b800000, v196
	v_mul_f32_e32 v35, 0x4b800000, v34
	v_cmp_gt_f32_e64 s[2:3], s23, v34
	s_nop 1
	v_cndmask_b32_e64 v34, v34, v35, s[2:3]
	v_rsq_f32_e32 v36, v34
	v_add_u32_e32 v34, 0xa0, v146
	v_ashrrev_i32_e32 v35, 31, v34
	v_lshlrev_b64 v[40:41], 8, v[34:35]
	v_mul_f32_e32 v37, 0x45800000, v36
	v_cndmask_b32_e64 v36, v36, v37, s[2:3]
	v_mul_f32_e32 v36, 0x3dd53b94, v36
	v_pk_mul_f32 v[38:39], v[32:33], v[36:37] op_sel_hi:[1,0]
	v_pk_mul_f32 v[30:31], v[30:31], v[36:37] op_sel_hi:[1,0]
	v_pk_mul_f32 v[32:33], v[28:29], v[36:37] op_sel_hi:[1,0]
	v_pk_mul_f32 v[28:29], v[26:27], v[36:37] op_sel_hi:[1,0]
	v_lshl_add_u64 v[26:27], s[50:51], 0, v[40:41]
	s_and_saveexec_b64 s[2:3], vcc
	s_cbranch_execz .LBB0_1156
	v_lshl_add_u64 v[44:45], v[98:99], 3, v[26:27]
	global_load_dwordx4 v[40:43], v[44:45], off offset:16
	global_load_dwordx4 v[44:47], v[44:45], off
	s_waitcnt vmcnt(0)
	v_pk_mul_f32 v[52:53], v[28:29], v[40:41] op_sel:[1,1] op_sel_hi:[0,1]
	v_pk_mul_f32 v[50:51], v[30:31], v[44:45] op_sel:[1,1] op_sel_hi:[0,1]
	v_pk_mul_f32 v[48:49], v[30:31], v[44:45]
	v_pk_fma_f32 v[30:31], v[30:31], v[44:45], v[50:51] op_sel_hi:[1,0,1]
	s_nop 0
	v_mul_f32_e32 v30, v39, v47
	v_pk_fma_f32 v[44:45], v[38:39], v[46:47], v[30:31] op_sel_hi:[1,1,0] neg_lo:[0,0,1] neg_hi:[0,0,1]
	v_mul_f32_e32 v30, v38, v47
	v_pk_fma_f32 v[46:47], v[38:39], v[46:47], v[30:31] op_sel:[1,0,0] op_sel_hi:[0,1,0]
	v_pk_mul_f32 v[38:39], v[28:29], v[40:41]
	v_pk_fma_f32 v[28:29], v[28:29], v[40:41], v[52:53] op_sel_hi:[1,0,1]
	v_sub_f32_e32 v30, v48, v50
	v_mul_f32_e32 v28, v33, v43
	v_pk_fma_f32 v[40:41], v[32:33], v[42:43], v[28:29] op_sel_hi:[1,1,0] neg_lo:[0,0,1] neg_hi:[0,0,1]
	v_mul_f32_e32 v28, v32, v43
	v_pk_fma_f32 v[42:43], v[32:33], v[42:43], v[28:29] op_sel:[1,0,0] op_sel_hi:[0,1,0]
	v_sub_f32_e32 v28, v38, v52
	v_mov_b32_e32 v32, v40
	v_mov_b32_e32 v33, v42
	v_mov_b32_e32 v38, v44
	v_mov_b32_e32 v39, v46
; __device__ __forceinline__ unsigned pk2(float lo, float hi) { f32x2 v = {lo, hi}; bf16x2_t b = __builtin_convertvector(v, bf16x2_t); return __builtin_bit_cast(unsigned, b); }
; __device__ __forceinline__ float ssf(const ssq_t* p) { return (float)(*p) * (1.0f / 1048576.0f); }
;     __device__ __forceinline__ void operator()(const f32x4 (&acc)[2][2][4][2], const pg8::Unit& u, int wr, int wc, int fr, int fq) const {
;     ...
;         for (int ai = 0; ai < 2; ++ai)
; #pragma unroll
;             for (int m = 0; m < 4; ++m) {
;                 const int b = (u.pm * 256) >> 13, t = ((u.pm * 256) & (S - 1)) + ai * 128 + wr * 64 + m * 16 + fr, row = b * S + t;
;                 const float r = rsqrtf(ssf(SSq + row) * (1.0f / QL) + EPS) * QS_MLA;
; #pragma unroll
;                 for (int bj = 0; bj < 2; ++bj) {
;                     const int c = u.pn * 256 + bj * 128 + wc * 32 + fq * 8;
;                     const int head = (c >= 576) ? 3 : (c >= 384) ? 2 : (c >= 192) ? 1 : 0, j = c - 192 * head;
;                     f32x4 a0 = acc[ai][bj][m][0] * r, a1 = acc[ai][bj][m][1] * r;
;                     if (j >= 128) {
;                         const f32x4 c0 = *(const f32x4*)(CS_ + ((size_t)t * 32 + ((j - 128) >> 1)) * 2), c1 = *(const f32x4*)(CS_ + ((size_t)t * 32 + ((j - 128) >> 1) + 2) * 2);
;                         const float y0 = a0[0] * c0[0] - a0[1] * c0[1], y1 = a0[1] * c0[0] + a0[0] * c0[1], y2 = a0[2] * c0[2] - a0[3] * c0[3], y3 = a0[3] * c0[2] + a0[2] * c0[3];
;                         const float y4 = a1[0] * c1[0] - a1[1] * c1[1], y5 = a1[1] * c1[0] + a1[0] * c1[1], y6 = a1[2] * c1[2] - a1[3] * c1[3], y7 = a1[3] * c1[2] + a1[2] * c1[3];
;                         a0[0] = y0; a0[1] = y1; a0[2] = y2; a0[3] = y3; a1[0] = y4; a1[1] = y5; a1[2] = y6; a1[3] = y7;
;                     }
;                     u32x4 w; w.x = pk2(a0[0], a0[1]); w.y = pk2(a0[2], a0[3]); w.z = pk2(a1[0], a1[1]); w.w = pk2(a1[2], a1[3]);
;                     *(u32x4*)(QM_ + ((size_t)(b * 4 + head) * S + t) * 192 + j) = w;
;                 }
.LBB0_1156:
	s_or_b64 exec, exec, s[2:3]
	v_cvt_pk_bf16_f32 v40, v30, v31
	v_cvt_pk_bf16_f32 v42, v28, v29
	v_lshl_add_u64 v[28:29], v[126:127], 0, v[34:35]
	v_mov_b64_e32 v[30:31], s[48:49]
	v_mad_u64_u32 v[30:31], s[2:3], v28, s5, v[30:31]
	v_mad_i32_i24 v31, v29, s5, v31
	v_cvt_pk_bf16_f32 v41, v38, v39
	v_cvt_pk_bf16_f32 v43, v32, v33
	v_lshl_add_u64 v[28:29], v[144:145], 1, v[30:31]
	v_mov_b32_e32 v37, v36
	global_store_dwordx4 v[28:29], v[40:43], off
	v_mov_b32_e32 v28, v36
	v_mov_b32_e32 v29, v36
	v_pk_mul_f32 v[24:25], v[24:25], v[28:29]
	v_pk_mul_f32 v[22:23], v[22:23], v[36:37]
	v_pk_mul_f32 v[20:21], v[20:21], v[28:29]
	v_pk_mul_f32 v[18:19], v[18:19], v[36:37]
	s_and_saveexec_b64 s[2:3], s[44:45]
	s_cbranch_execz .LBB0_1158
	v_mov_b32_e32 v117, v99
	v_lshl_add_u64 v[30:31], v[116:117], 3, v[26:27]
	global_load_dwordx4 v[26:29], v[30:31], off offset:16
	global_load_dwordx4 v[30:33], v[30:31], off
	s_waitcnt vmcnt(0)
	v_pk_mul_f32 v[40:41], v[18:19], v[26:27] op_sel:[1,1] op_sel_hi:[0,1]
	v_pk_mul_f32 v[38:39], v[22:23], v[30:31] op_sel:[1,1] op_sel_hi:[0,1]
	v_pk_mul_f32 v[36:37], v[22:23], v[30:31]
	v_pk_fma_f32 v[22:23], v[22:23], v[30:31], v[38:39] op_sel_hi:[1,0,1]
	s_nop 0
	v_mul_f32_e32 v22, v25, v33
	v_pk_fma_f32 v[30:31], v[24:25], v[32:33], v[22:23] op_sel_hi:[1,1,0] neg_lo:[0,0,1] neg_hi:[0,0,1]
	v_mul_f32_e32 v22, v24, v33
	v_pk_fma_f32 v[32:33], v[24:25], v[32:33], v[22:23] op_sel:[1,0,0] op_sel_hi:[0,1,0]
	v_pk_mul_f32 v[24:25], v[18:19], v[26:27]
	v_pk_fma_f32 v[18:19], v[18:19], v[26:27], v[40:41] op_sel_hi:[1,0,1]
	v_sub_f32_e32 v22, v36, v38
	v_mul_f32_e32 v18, v21, v29
	v_pk_fma_f32 v[26:27], v[20:21], v[28:29], v[18:19] op_sel_hi:[1,1,0] neg_lo:[0,0,1] neg_hi:[0,0,1]
	v_mul_f32_e32 v18, v20, v29
	v_pk_fma_f32 v[28:29], v[20:21], v[28:29], v[18:19] op_sel:[1,0,0] op_sel_hi:[0,1,0]
	v_sub_f32_e32 v18, v24, v40
	v_mov_b32_e32 v20, v26
	v_mov_b32_e32 v21, v28
	v_mov_b32_e32 v24, v30
	v_mov_b32_e32 v25, v32
.LBB0_1158:
	s_or_b64 exec, exec, s[2:3]
	v_cvt_pk_bf16_f32 v22, v22, v23
	v_cvt_pk_bf16_f32 v23, v24, v25
	v_cvt_pk_bf16_f32 v24, v18, v19
	v_cvt_pk_bf16_f32 v25, v20, v21
	v_lshl_add_u64 v[18:19], v[118:119], 0, v[34:35]
	v_mov_b64_e32 v[20:21], s[48:49]
	v_mad_u64_u32 v[20:21], s[2:3], v18, s5, v[20:21]
	v_mad_i32_i24 v21, v19, s5, v21
	v_lshl_add_u64 v[18:19], v[124:125], 1, v[20:21]
	global_store_dwordx4 v[18:19], v[22:25], off
	global_load_dwordx2 v[18:19], v[148:149], off offset:1408
	s_waitcnt vmcnt(0)
	v_ffbh_u32_e32 v20, v19
	v_min_u32_e32 v20, 32, v20
	v_lshlrev_b64 v[18:19], v20, v[18:19]
	v_min_u32_e32 v18, 1, v18
	v_or_b32_e32 v18, v19, v18
	v_cvt_f32_u32_e32 v18, v18
	v_sub_u32_e32 v19, 32, v20
	v_ldexp_f32 v18, v18, v19
	v_mul_f32_e32 v18, 0x35800000, v18
	v_fmamk_f32 v18, v18, 0x3b800000, v196
	v_mul_f32_e32 v19, 0x4b800000, v18
	v_cmp_gt_f32_e64 s[2:3], s23, v18
	s_nop 1
	v_cndmask_b32_e64 v18, v18, v19, s[2:3]
	v_rsq_f32_e32 v20, v18
	v_add_u32_e32 v18, 0xb0, v146
	v_ashrrev_i32_e32 v19, 31, v18
	v_lshlrev_b64 v[24:25], 8, v[18:19]
	v_mul_f32_e32 v21, 0x45800000, v20
	v_cndmask_b32_e64 v20, v20, v21, s[2:3]
	v_mul_f32_e32 v20, 0x3dd53b94, v20
	v_pk_mul_f32 v[22:23], v[16:17], v[20:21] op_sel_hi:[1,0]
	v_pk_mul_f32 v[14:15], v[14:15], v[20:21] op_sel_hi:[1,0]
	v_pk_mul_f32 v[16:17], v[12:13], v[20:21] op_sel_hi:[1,0]
	v_pk_mul_f32 v[12:13], v[10:11], v[20:21] op_sel_hi:[1,0]
	v_lshl_add_u64 v[10:11], s[50:51], 0, v[24:25]
	s_and_saveexec_b64 s[2:3], vcc
	s_cbranch_execz .LBB0_1160
	v_lshl_add_u64 v[28:29], v[98:99], 3, v[10:11]
	global_load_dwordx4 v[24:27], v[28:29], off offset:16
	global_load_dwordx4 v[28:31], v[28:29], off
	s_waitcnt vmcnt(0)
	v_pk_mul_f32 v[36:37], v[12:13], v[24:25] op_sel:[1,1] op_sel_hi:[0,1]
	v_pk_mul_f32 v[34:35], v[14:15], v[28:29] op_sel:[1,1] op_sel_hi:[0,1]
	v_pk_mul_f32 v[32:33], v[14:15], v[28:29]
	v_pk_fma_f32 v[14:15], v[14:15], v[28:29], v[34:35] op_sel_hi:[1,0,1]
	s_nop 0
	v_mul_f32_e32 v14, v23, v31
	v_pk_fma_f32 v[28:29], v[22:23], v[30:31], v[14:15] op_sel_hi:[1,1,0] neg_lo:[0,0,1] neg_hi:[0,0,1]
	v_mul_f32_e32 v14, v22, v31
	v_pk_fma_f32 v[30:31], v[22:23], v[30:31], v[14:15] op_sel:[1,0,0] op_sel_hi:[0,1,0]
	v_pk_mul_f32 v[22:23], v[12:13], v[24:25]
	v_pk_fma_f32 v[12:13], v[12:13], v[24:25], v[36:37] op_sel_hi:[1,0,1]
	v_sub_f32_e32 v14, v32, v34
	v_mul_f32_e32 v12, v17, v27
	v_pk_fma_f32 v[24:25], v[16:17], v[26:27], v[12:13] op_sel_hi:[1,1,0] neg_lo:[0,0,1] neg_hi:[0,0,1]
	v_mul_f32_e32 v12, v16, v27
	v_pk_fma_f32 v[26:27], v[16:17], v[26:27], v[12:13] op_sel:[1,0,0] op_sel_hi:[0,1,0]
	v_sub_f32_e32 v12, v22, v36
	v_mov_b32_e32 v16, v24
	v_mov_b32_e32 v17, v26
	v_mov_b32_e32 v22, v28
	v_mov_b32_e32 v23, v30
.LBB0_1160:
	s_or_b64 exec, exec, s[2:3]
	v_cvt_pk_bf16_f32 v24, v14, v15
	v_cvt_pk_bf16_f32 v26, v12, v13
	v_lshl_add_u64 v[12:13], v[126:127], 0, v[18:19]
	v_mov_b64_e32 v[14:15], s[48:49]
	v_mad_u64_u32 v[14:15], s[2:3], v12, s5, v[14:15]
	v_mad_i32_i24 v15, v13, s5, v15
	v_cvt_pk_bf16_f32 v25, v22, v23
	v_cvt_pk_bf16_f32 v27, v16, v17
	v_lshl_add_u64 v[12:13], v[144:145], 1, v[14:15]
	v_mov_b32_e32 v21, v20
	global_store_dwordx4 v[12:13], v[24:27], off
	v_mov_b32_e32 v12, v20
	v_mov_b32_e32 v13, v20
	v_pk_mul_f32 v[8:9], v[8:9], v[12:13]
	v_pk_mul_f32 v[6:7], v[6:7], v[20:21]
	v_pk_mul_f32 v[4:5], v[4:5], v[12:13]
	v_pk_mul_f32 v[2:3], v[2:3], v[20:21]
	s_and_saveexec_b64 s[2:3], s[44:45]
	s_cbranch_execz .LBB0_1162
	v_mov_b32_e32 v117, v99
	v_lshl_add_u64 v[14:15], v[116:117], 3, v[10:11]
	global_load_dwordx4 v[10:13], v[14:15], off offset:16
	global_load_dwordx4 v[14:17], v[14:15], off
	s_waitcnt vmcnt(0)
	v_pk_mul_f32 v[24:25], v[2:3], v[10:11] op_sel:[1,1] op_sel_hi:[0,1]
	v_pk_mul_f32 v[22:23], v[6:7], v[14:15] op_sel:[1,1] op_sel_hi:[0,1]
	v_pk_mul_f32 v[20:21], v[6:7], v[14:15]
	v_pk_fma_f32 v[6:7], v[6:7], v[14:15], v[22:23] op_sel_hi:[1,0,1]
	s_nop 0
	v_mul_f32_e32 v6, v9, v17
	v_pk_fma_f32 v[14:15], v[8:9], v[16:17], v[6:7] op_sel_hi:[1,1,0] neg_lo:[0,0,1] neg_hi:[0,0,1]
	v_mul_f32_e32 v6, v8, v17
	v_pk_fma_f32 v[16:17], v[8:9], v[16:17], v[6:7] op_sel:[1,0,0] op_sel_hi:[0,1,0]
	v_pk_mul_f32 v[8:9], v[2:3], v[10:11]
	v_pk_fma_f32 v[2:3], v[2:3], v[10:11], v[24:25] op_sel_hi:[1,0,1]
	v_sub_f32_e32 v6, v20, v22
	v_mul_f32_e32 v2, v5, v13
	v_pk_fma_f32 v[10:11], v[4:5], v[12:13], v[2:3] op_sel_hi:[1,1,0] neg_lo:[0,0,1] neg_hi:[0,0,1]
	v_mul_f32_e32 v2, v4, v13
	v_pk_fma_f32 v[12:13], v[4:5], v[12:13], v[2:3] op_sel:[1,0,0] op_sel_hi:[0,1,0]
	v_sub_f32_e32 v2, v8, v24
	v_mov_b32_e32 v4, v10
	v_mov_b32_e32 v5, v12
	v_mov_b32_e32 v8, v14
	v_mov_b32_e32 v9, v16

; __device__ __forceinline__ unsigned pk2(float lo, float hi) { f32x2 v = {lo, hi}; bf16x2_t b = __builtin_convertvector(v, bf16x2_t); return __builtin_bit_cast(unsigned, b); }
; __device__ __forceinline__ float ssf(const ssq_t* p) { return (float)(*p) * (1.0f / 1048576.0f); }
;     __device__ __forceinline__ void operator()(const f32x4 (&acc)[2][2][4][2], const pg8::Unit& u, int wr, int wc, int fr, int fq) const {
;     ...
;         for (int bj = 0; bj < 2; ++bj) {
;             const int tok = u.pn * 256 + bj * 128 + wc * 32 + fq * 8, b = tok >> 13, t = tok & (S - 1);
;             float r[8];
; #pragma unroll
;             for (int i = 0; i < 8; ++i) r[i] = rsqrtf(ssf(SSn + tok + i) * invn + EPS);
; #pragma unroll
;             for (int ai = 0; ai < 2; ++ai)
; #pragma unroll
;                 for (int m = 0; m < 4; ++m) {
;                     const int ch = u.pm * 256 + ai * 128 + wr * 64 + m * 16 + fr;
;                     const f32x4 a0 = acc[ai][bj][m][0], a1 = acc[ai][bj][m][1];
;                     u32x4 w; w.x = pk2(a0[0] * r[0], a0[1] * r[1]); w.y = pk2(a0[2] * r[2], a0[3] * r[3]); w.z = pk2(a1[0] * r[4], a1[1] * r[5]); w.w = pk2(a1[2] * r[6], a1[3] * r[7]);
;                     *(u32x4*)(VT + ((size_t)(b * 512 + ch)) * S + t) = w;
;                 }
.LBB0_1212:
	s_lshl_b32 s2, s78, 8
	v_or_b32_e32 v158, s2, v167
	v_ashrrev_i32_e32 v159, 31, v158
	v_lshl_add_u64 v[160:161], v[158:159], 3, s[6:7]
	global_load_dwordx4 v[132:135], v[160:161], off offset:48
	global_load_dwordx4 v[136:139], v[160:161], off offset:32
	global_load_dwordx4 v[140:143], v[160:161], off offset:16
	global_load_dwordx4 v[170:173], v[160:161], off
	s_lshl_b32 s4, s78, 4
	s_lshl_b32 s3, s79, 8
	s_and_b32 s4, s4, 0xfffffe00
	s_add_i32 s4, s4, s3
	v_add_u32_e32 v162, s4, v1
	v_bitop3_b32 v98, s2, v203, v167 bitop3:0xc8
	s_mov_b32 s4, 0x35800000
	s_mov_b32 s2, 0x358637bd
	s_brev_b32 s22, 60
	s_mov_b32 s16, 0x45800000
	v_lshlrev_b32_e32 v98, 1, v98
	v_ashrrev_i32_e32 v163, 31, v162
	s_movk_i32 s1, 0x1ff8
	s_waitcnt vmcnt(0)
	v_ffbh_u32_e32 v156, v173
	v_min_u32_e32 v159, 32, v156
	v_lshlrev_b64 v[156:157], v159, v[172:173]
	v_min_u32_e32 v156, 1, v156
	v_or_b32_e32 v156, v157, v156
	v_cvt_f32_u32_e32 v156, v156
	v_sub_u32_e32 v157, 32, v159
	v_ldexp_f32 v157, v156, v157
	v_ffbh_u32_e32 v156, v171
	v_min_u32_e32 v156, 32, v156
	v_lshlrev_b64 v[164:165], v156, v[170:171]
	v_min_u32_e32 v159, 1, v164
	v_or_b32_e32 v159, v165, v159
	v_cvt_f32_u32_e32 v159, v159
	v_sub_u32_e32 v156, 32, v156
	v_ldexp_f32 v156, v159, v156
	v_pk_mul_f32 v[164:165], v[156:157], s[4:5] op_sel_hi:[1,0]
	v_mov_b64_e32 v[156:157], s[2:3]
	v_pk_fma_f32 v[164:165], v[164:165], s[22:23], v[156:157] op_sel_hi:[1,0,0]
	s_nop 0
	v_mul_f32_e32 v159, 0x4b800000, v164
	v_cmp_gt_f32_e64 s[2:3], s23, v164
	v_cmp_gt_f32_e32 vcc, s23, v165
	s_nop 0
	v_cndmask_b32_e64 v159, v164, v159, s[2:3]
	v_rsq_f32_e32 v164, v159
	v_mul_f32_e32 v159, 0x4b800000, v165
	v_cndmask_b32_e32 v159, v165, v159, vcc
	v_rsq_f32_e32 v165, v159
	s_nop 0
	v_pk_mul_f32 v[170:171], v[164:165], s[16:17] op_sel_hi:[1,0]
	s_nop 0
	v_cndmask_b32_e32 v165, v165, v171, vcc
	v_cndmask_b32_e64 v164, v164, v170, s[2:3]
	v_pk_mul_f32 v[128:129], v[128:129], v[164:165]
	v_pk_mul_f32 v[78:79], v[78:79], v[164:165]
	v_cvt_pk_bf16_f32 v128, v128, v129
	v_ffbh_u32_e32 v129, v143
	v_min_u32_e32 v129, 32, v129
	v_lshlrev_b64 v[142:143], v129, v[142:143]
	v_min_u32_e32 v142, 1, v142
	v_or_b32_e32 v142, v143, v142
	v_cvt_f32_u32_e32 v142, v142
	v_sub_u32_e32 v129, 32, v129
	v_pk_mul_f32 v[104:105], v[104:105], v[164:165]
	v_cvt_pk_bf16_f32 v78, v78, v79
	v_ldexp_f32 v143, v142, v129
	v_ffbh_u32_e32 v129, v141
	v_min_u32_e32 v129, 32, v129
	v_lshlrev_b64 v[140:141], v129, v[140:141]
	v_min_u32_e32 v140, 1, v140
	v_or_b32_e32 v140, v141, v140
	v_cvt_f32_u32_e32 v140, v140
	v_sub_u32_e32 v129, 32, v129
	v_cvt_pk_bf16_f32 v104, v104, v105
	v_pk_mul_f32 v[120:121], v[120:121], v[164:165]
	v_ldexp_f32 v142, v140, v129
	v_pk_mul_f32 v[140:141], v[142:143], s[4:5] op_sel_hi:[1,0]
	v_pk_mul_f32 v[112:113], v[112:113], v[164:165]
	v_pk_fma_f32 v[140:141], v[140:141], s[22:23], v[156:157] op_sel_hi:[1,0,0]
	v_pk_mul_f32 v[86:87], v[86:87], v[164:165]
	v_mul_f32_e32 v129, 0x4b800000, v140
	v_cmp_gt_f32_e64 s[2:3], s23, v140
	v_cmp_gt_f32_e32 vcc, s23, v141
	v_cvt_pk_bf16_f32 v120, v120, v121
	v_cndmask_b32_e64 v129, v140, v129, s[2:3]
	v_rsq_f32_e32 v140, v129
	v_mul_f32_e32 v129, 0x4b800000, v141
	v_cndmask_b32_e32 v129, v141, v129, vcc
	v_rsq_f32_e32 v141, v129
	v_cvt_pk_bf16_f32 v112, v112, v113
	v_cvt_pk_bf16_f32 v86, v86, v87
	v_pk_mul_f32 v[94:95], v[94:95], v[164:165]
	v_pk_mul_f32 v[142:143], v[140:141], s[16:17] op_sel_hi:[1,0]
	v_cvt_pk_bf16_f32 v94, v94, v95
	v_cndmask_b32_e32 v141, v141, v143, vcc
	v_cndmask_b32_e64 v140, v140, v142, s[2:3]
	v_pk_mul_f32 v[130:131], v[130:131], v[140:141]
	v_pk_mul_f32 v[80:81], v[80:81], v[140:141]
	v_cvt_pk_bf16_f32 v129, v130, v131
	v_ffbh_u32_e32 v130, v139
	v_min_u32_e32 v142, 32, v130
	v_lshlrev_b64 v[130:131], v142, v[138:139]
	v_min_u32_e32 v130, 1, v130
	v_or_b32_e32 v130, v131, v130
	v_cvt_f32_u32_e32 v130, v130
	v_sub_u32_e32 v131, 32, v142
	v_pk_mul_f32 v[106:107], v[106:107], v[140:141]
	v_cvt_pk_bf16_f32 v79, v80, v81
	v_ldexp_f32 v131, v130, v131
	v_ffbh_u32_e32 v130, v137
	v_min_u32_e32 v130, 32, v130
	v_lshlrev_b64 v[136:137], v130, v[136:137]
	v_min_u32_e32 v136, 1, v136
	v_or_b32_e32 v136, v137, v136
	v_cvt_f32_u32_e32 v136, v136
	v_sub_u32_e32 v130, 32, v130
	v_cvt_pk_bf16_f32 v105, v106, v107
	v_pk_mul_f32 v[122:123], v[122:123], v[140:141]
	v_ldexp_f32 v130, v136, v130
	v_pk_mul_f32 v[130:131], v[130:131], s[4:5] op_sel_hi:[1,0]
	v_pk_mul_f32 v[114:115], v[114:115], v[140:141]
	v_pk_fma_f32 v[130:131], v[130:131], s[22:23], v[156:157] op_sel_hi:[1,0,0]
	v_pk_mul_f32 v[88:89], v[88:89], v[140:141]
	v_mul_f32_e32 v136, 0x4b800000, v130
	v_cmp_gt_f32_e64 s[2:3], s23, v130
	v_cmp_gt_f32_e32 vcc, s23, v131
	v_cvt_pk_bf16_f32 v121, v122, v123
	v_cndmask_b32_e64 v130, v130, v136, s[2:3]
	v_mul_f32_e32 v136, 0x4b800000, v131
	v_cndmask_b32_e32 v131, v131, v136, vcc
	v_rsq_f32_e32 v130, v130
	v_rsq_f32_e32 v131, v131
	v_cvt_pk_bf16_f32 v113, v114, v115
	v_cvt_pk_bf16_f32 v87, v88, v89
	v_pk_mul_f32 v[96:97], v[96:97], v[140:141]
	v_pk_mul_f32 v[136:137], v[130:131], s[16:17] op_sel_hi:[1,0]
	v_cvt_pk_bf16_f32 v95, v96, v97
	v_cndmask_b32_e32 v137, v131, v137, vcc
	v_cndmask_b32_e64 v136, v130, v136, s[2:3]
	v_pk_mul_f32 v[124:125], v[124:125], v[136:137]
	v_pk_mul_f32 v[74:75], v[74:75], v[136:137]
	v_cvt_pk_bf16_f32 v130, v124, v125
	v_ffbh_u32_e32 v124, v135
	v_min_u32_e32 v131, 32, v124
	v_lshlrev_b64 v[124:125], v131, v[134:135]
	v_min_u32_e32 v124, 1, v124
	v_or_b32_e32 v124, v125, v124
	v_cvt_f32_u32_e32 v124, v124
	v_sub_u32_e32 v125, 32, v131
	v_pk_mul_f32 v[100:101], v[100:101], v[136:137]
	v_cvt_pk_bf16_f32 v80, v74, v75
	v_ldexp_f32 v125, v124, v125
; __device__ __forceinline__ unsigned pk2(float lo, float hi) { f32x2 v = {lo, hi}; bf16x2_t b = __builtin_convertvector(v, bf16x2_t); return __builtin_bit_cast(unsigned, b); }
; __device__ __forceinline__ float ssf(const ssq_t* p) { return (float)(*p) * (1.0f / 1048576.0f); }
;     __device__ __forceinline__ void operator()(const f32x4 (&acc)[2][2][4][2], const pg8::Unit& u, int wr, int wc, int fr, int fq) const {
;     ...
;         for (int bj = 0; bj < 2; ++bj) {
;             const int tok = u.pn * 256 + bj * 128 + wc * 32 + fq * 8, b = tok >> 13, t = tok & (S - 1);
;             float r[8];
; #pragma unroll
;             for (int i = 0; i < 8; ++i) r[i] = rsqrtf(ssf(SSn + tok + i) * invn + EPS);
; #pragma unroll
;             for (int ai = 0; ai < 2; ++ai)
; #pragma unroll
;                 for (int m = 0; m < 4; ++m) {
;                     const int ch = u.pm * 256 + ai * 128 + wr * 64 + m * 16 + fr;
;                     const f32x4 a0 = acc[ai][bj][m][0], a1 = acc[ai][bj][m][1];
;                     u32x4 w; w.x = pk2(a0[0] * r[0], a0[1] * r[1]); w.y = pk2(a0[2] * r[2], a0[3] * r[3]); w.z = pk2(a1[0] * r[4], a1[1] * r[5]); w.w = pk2(a1[2] * r[6], a1[3] * r[7]);
;                     *(u32x4*)(VT + ((size_t)(b * 512 + ch)) * S + t) = w;
;                 }
	v_ffbh_u32_e32 v124, v133
	v_min_u32_e32 v124, 32, v124
	v_lshlrev_b64 v[132:133], v124, v[132:133]
	v_min_u32_e32 v131, 1, v132
	v_or_b32_e32 v131, v133, v131
	v_cvt_f32_u32_e32 v131, v131
	v_sub_u32_e32 v124, 32, v124
	v_cvt_pk_bf16_f32 v106, v100, v101
	v_pk_mul_f32 v[116:117], v[116:117], v[136:137]
	v_ldexp_f32 v124, v131, v124
	v_pk_mul_f32 v[124:125], v[124:125], s[4:5] op_sel_hi:[1,0]
	v_pk_mul_f32 v[108:109], v[108:109], v[136:137]
	v_pk_fma_f32 v[124:125], v[124:125], s[22:23], v[156:157] op_sel_hi:[1,0,0]
	v_pk_mul_f32 v[82:83], v[82:83], v[136:137]
	v_mul_f32_e32 v131, 0x4b800000, v124
	v_cmp_gt_f32_e64 s[2:3], s23, v124
	v_cmp_gt_f32_e32 vcc, s23, v125
	v_pk_mul_f32 v[66:67], v[66:67], v[136:137]
	v_cndmask_b32_e64 v124, v124, v131, s[2:3]
	v_mul_f32_e32 v131, 0x4b800000, v125
	v_cndmask_b32_e32 v125, v125, v131, vcc
	v_rsq_f32_e32 v124, v124
	v_rsq_f32_e32 v125, v125
	v_cvt_pk_bf16_f32 v122, v116, v117
	v_cvt_pk_bf16_f32 v114, v108, v109
	v_cvt_pk_bf16_f32 v88, v82, v83
	v_pk_mul_f32 v[132:133], v[124:125], s[16:17] op_sel_hi:[1,0]
	v_pk_mul_f32 v[90:91], v[90:91], v[136:137]
	v_cndmask_b32_e32 v133, v125, v133, vcc
	v_cndmask_b32_e64 v132, v124, v132, s[2:3]
	v_pk_mul_f32 v[74:75], v[76:77], v[132:133]
	v_pk_mul_f32 v[100:101], v[102:103], v[132:133]
	v_cvt_pk_bf16_f32 v81, v74, v75
	v_add_u32_e32 v74, 0xa0, v162
	v_cvt_pk_bf16_f32 v107, v100, v101
	v_or_b32_e32 v100, 48, v162
	v_ashrrev_i32_e32 v75, 31, v74
	v_ashrrev_i32_e32 v101, 31, v100
	v_lshlrev_b64 v[74:75], 14, v[74:75]
	v_lshlrev_b64 v[100:101], 14, v[100:101]
	v_lshl_add_u64 v[74:75], s[44:45], 0, v[74:75]
	v_lshl_add_u64 v[100:101], s[44:45], 0, v[100:101]
	v_lshl_add_u64 v[76:77], v[74:75], 0, v[98:99]
	v_pk_mul_f32 v[116:117], v[118:119], v[132:133]
	v_pk_mul_f32 v[108:109], v[110:111], v[132:133]
	v_lshl_add_u64 v[102:103], v[100:101], 0, v[98:99]
	v_pk_mul_f32 v[82:83], v[84:85], v[132:133]
	global_store_dwordx4 v[76:77], v[78:81], off
	v_cvt_pk_bf16_f32 v123, v116, v117
	v_or_b32_e32 v116, 16, v162
	v_cvt_pk_bf16_f32 v78, v66, v67
	v_pk_mul_f32 v[66:67], v[68:69], v[132:133]
	v_cvt_pk_bf16_f32 v115, v108, v109
	v_or_b32_e32 v108, 32, v162
	global_store_dwordx4 v[102:103], v[104:107], off
	v_add_u32_e32 v102, 0x80, v162
	v_cvt_pk_bf16_f32 v89, v82, v83
	v_add_u32_e32 v82, 0x90, v162
	v_cvt_pk_bf16_f32 v79, v66, v67
	v_add_u32_e32 v66, 0xb0, v162
	v_pk_mul_f32 v[124:125], v[126:127], v[132:133]
	v_ashrrev_i32_e32 v117, 31, v116
	v_ashrrev_i32_e32 v109, 31, v108
	v_cvt_pk_bf16_f32 v96, v90, v91
	v_pk_mul_f32 v[90:91], v[92:93], v[132:133]
	v_ashrrev_i32_e32 v103, 31, v102
	v_ashrrev_i32_e32 v83, 31, v82
	v_pk_mul_f32 v[70:71], v[70:71], v[164:165]
	v_ashrrev_i32_e32 v67, 31, v66
	v_cvt_pk_bf16_f32 v131, v124, v125
	v_lshlrev_b64 v[124:125], 14, v[162:163]
	v_lshlrev_b64 v[116:117], 14, v[116:117]
	v_lshlrev_b64 v[108:109], 14, v[108:109]
	v_cvt_pk_bf16_f32 v97, v90, v91
	v_lshlrev_b64 v[90:91], 14, v[102:103]
	v_lshlrev_b64 v[82:83], 14, v[82:83]
	v_cvt_pk_bf16_f32 v76, v70, v71
	v_pk_mul_f32 v[70:71], v[72:73], v[140:141]
	v_lshlrev_b64 v[66:67], 14, v[66:67]
	v_lshl_add_u64 v[124:125], s[44:45], 0, v[124:125]
	v_lshl_add_u64 v[116:117], s[44:45], 0, v[116:117]
	v_lshl_add_u64 v[108:109], s[44:45], 0, v[108:109]
	v_lshl_add_u64 v[90:91], s[44:45], 0, v[90:91]
	v_lshl_add_u64 v[82:83], s[44:45], 0, v[82:83]
	v_cvt_pk_bf16_f32 v77, v70, v71
	v_lshl_add_u64 v[70:71], s[44:45], 0, v[66:67]
	v_lshl_add_u64 v[126:127], v[124:125], 0, v[98:99]
	v_lshl_add_u64 v[118:119], v[116:117], 0, v[98:99]
	v_lshl_add_u64 v[110:111], v[108:109], 0, v[98:99]
	v_lshl_add_u64 v[92:93], v[90:91], 0, v[98:99]
	v_lshl_add_u64 v[84:85], v[82:83], 0, v[98:99]
	v_lshl_add_u64 v[66:67], v[70:71], 0, v[98:99]
	global_store_dwordx4 v[126:127], v[128:131], off
	global_store_dwordx4 v[118:119], v[120:123], off
	global_store_dwordx4 v[110:111], v[112:115], off
	global_store_dwordx4 v[92:93], v[94:97], off
	global_store_dwordx4 v[84:85], v[86:89], off
	global_store_dwordx4 v[66:67], v[76:79], off
	global_load_dwordx4 v[66:69], v[160:161], off offset:1072
	global_load_dwordx4 v[78:81], v[160:161], off offset:1056
	global_load_dwordx4 v[84:87], v[160:161], off offset:1040
	global_load_dwordx4 v[92:95], v[160:161], off offset:1024
	v_bitop3_b32 v88, v158, s1, v204 bitop3:0xc8
	v_lshlrev_b32_e32 v98, 1, v88
	s_waitcnt vmcnt(0)
; __device__ __forceinline__ unsigned pk2(float lo, float hi) { f32x2 v = {lo, hi}; bf16x2_t b = __builtin_convertvector(v, bf16x2_t); return __builtin_bit_cast(unsigned, b); }
; __device__ __forceinline__ float ssf(const ssq_t* p) { return (float)(*p) * (1.0f / 1048576.0f); }
;     __device__ __forceinline__ void operator()(const f32x4 (&acc)[2][2][4][2], const pg8::Unit& u, int wr, int wc, int fr, int fq) const {
;     ...
;         for (int bj = 0; bj < 2; ++bj) {
;             const int tok = u.pn * 256 + bj * 128 + wc * 32 + fq * 8, b = tok >> 13, t = tok & (S - 1);
;             float r[8];
; #pragma unroll
;             for (int i = 0; i < 8; ++i) r[i] = rsqrtf(ssf(SSn + tok + i) * invn + EPS);
; #pragma unroll
;             for (int ai = 0; ai < 2; ++ai)
; #pragma unroll
;                 for (int m = 0; m < 4; ++m) {
;                     const int ch = u.pm * 256 + ai * 128 + wr * 64 + m * 16 + fr;
;                     const f32x4 a0 = acc[ai][bj][m][0], a1 = acc[ai][bj][m][1];
;                     u32x4 w; w.x = pk2(a0[0] * r[0], a0[1] * r[1]); w.y = pk2(a0[2] * r[2], a0[3] * r[3]); w.z = pk2(a1[0] * r[4], a1[1] * r[5]); w.w = pk2(a1[2] * r[6], a1[3] * r[7]);
;                     *(u32x4*)(VT + ((size_t)(b * 512 + ch)) * S + t) = w;
;                 }
	v_ffbh_u32_e32 v72, v95
	v_min_u32_e32 v76, 32, v72
	v_lshlrev_b64 v[72:73], v76, v[94:95]
	v_min_u32_e32 v72, 1, v72
	v_or_b32_e32 v72, v73, v72
	v_cvt_f32_u32_e32 v72, v72
	v_sub_u32_e32 v73, 32, v76
	v_ldexp_f32 v73, v72, v73
	v_ffbh_u32_e32 v72, v93
	v_min_u32_e32 v72, 32, v72
	v_lshlrev_b64 v[76:77], v72, v[92:93]
	v_min_u32_e32 v76, 1, v76
	v_or_b32_e32 v76, v77, v76
	v_cvt_f32_u32_e32 v76, v76
	v_sub_u32_e32 v72, 32, v72
	v_ldexp_f32 v72, v76, v72
	v_pk_mul_f32 v[72:73], v[72:73], s[4:5] op_sel_hi:[1,0]
	s_nop 0
	v_pk_fma_f32 v[72:73], v[72:73], s[22:23], v[156:157] op_sel_hi:[1,0,0]
	s_nop 0
	v_mul_f32_e32 v76, 0x4b800000, v72
	v_cmp_gt_f32_e64 s[2:3], s23, v72
	v_cmp_gt_f32_e32 vcc, s23, v73
	s_nop 0
	v_cndmask_b32_e64 v72, v72, v76, s[2:3]
	v_mul_f32_e32 v76, 0x4b800000, v73
	v_cndmask_b32_e32 v73, v73, v76, vcc
	v_rsq_f32_e32 v72, v72
	v_rsq_f32_e32 v73, v73
	s_nop 0
	v_pk_mul_f32 v[76:77], v[72:73], s[16:17] op_sel_hi:[1,0]
	s_nop 0
	v_cndmask_b32_e32 v73, v73, v77, vcc
	v_cndmask_b32_e64 v72, v72, v76, s[2:3]
	v_pk_mul_f32 v[62:63], v[62:63], v[72:73]
	v_pk_mul_f32 v[54:55], v[54:55], v[72:73]
	v_cvt_pk_bf16_f32 v62, v62, v63
	v_ffbh_u32_e32 v63, v87
	v_min_u32_e32 v63, 32, v63
	v_lshlrev_b64 v[76:77], v63, v[86:87]
	v_min_u32_e32 v76, 1, v76
	v_or_b32_e32 v76, v77, v76
	v_cvt_f32_u32_e32 v76, v76
	v_sub_u32_e32 v63, 32, v63
	v_pk_mul_f32 v[46:47], v[46:47], v[72:73]
	v_pk_mul_f32 v[38:39], v[38:39], v[72:73]
	v_ldexp_f32 v77, v76, v63
	v_ffbh_u32_e32 v63, v85
	v_min_u32_e32 v63, 32, v63
	v_lshlrev_b64 v[84:85], v63, v[84:85]
	v_min_u32_e32 v76, 1, v84
	v_or_b32_e32 v76, v85, v76
	v_cvt_f32_u32_e32 v76, v76
	v_sub_u32_e32 v63, 32, v63
	v_pk_mul_f32 v[30:31], v[30:31], v[72:73]
	v_pk_mul_f32 v[22:23], v[22:23], v[72:73]
	v_ldexp_f32 v76, v76, v63
	v_pk_mul_f32 v[76:77], v[76:77], s[4:5] op_sel_hi:[1,0]
	v_pk_mul_f32 v[14:15], v[14:15], v[72:73]
	v_pk_fma_f32 v[76:77], v[76:77], s[22:23], v[156:157] op_sel_hi:[1,0,0]
	v_pk_mul_f32 v[6:7], v[6:7], v[72:73]
	v_mul_f32_e32 v63, 0x4b800000, v76
	v_cmp_gt_f32_e64 s[2:3], s23, v76
	v_cmp_gt_f32_e32 vcc, s23, v77
	v_cvt_pk_bf16_f32 v54, v54, v55
	v_cndmask_b32_e64 v63, v76, v63, s[2:3]
	v_rsq_f32_e32 v76, v63
	v_mul_f32_e32 v63, 0x4b800000, v77
	v_cndmask_b32_e32 v63, v77, v63, vcc
	v_rsq_f32_e32 v77, v63
	v_cvt_pk_bf16_f32 v46, v46, v47
	v_cvt_pk_bf16_f32 v38, v38, v39
	v_cvt_pk_bf16_f32 v30, v30, v31
	v_pk_mul_f32 v[84:85], v[76:77], s[16:17] op_sel_hi:[1,0]
	v_cvt_pk_bf16_f32 v22, v22, v23
	v_cndmask_b32_e32 v77, v77, v85, vcc
	v_cndmask_b32_e64 v76, v76, v84, s[2:3]
	v_pk_mul_f32 v[64:65], v[64:65], v[76:77]
	v_pk_mul_f32 v[56:57], v[56:57], v[76:77]
	v_cvt_pk_bf16_f32 v63, v64, v65
	v_ffbh_u32_e32 v64, v81
	v_min_u32_e32 v84, 32, v64
	v_lshlrev_b64 v[64:65], v84, v[80:81]
	v_min_u32_e32 v64, 1, v64
	v_or_b32_e32 v64, v65, v64
	v_cvt_f32_u32_e32 v64, v64
	v_sub_u32_e32 v65, 32, v84
	v_pk_mul_f32 v[48:49], v[48:49], v[76:77]
	v_pk_mul_f32 v[40:41], v[40:41], v[76:77]
	v_ldexp_f32 v65, v64, v65
	v_ffbh_u32_e32 v64, v79
	v_min_u32_e32 v64, 32, v64
	v_lshlrev_b64 v[78:79], v64, v[78:79]
	v_min_u32_e32 v78, 1, v78
	v_or_b32_e32 v78, v79, v78
	v_cvt_f32_u32_e32 v78, v78
	v_sub_u32_e32 v64, 32, v64
	v_pk_mul_f32 v[32:33], v[32:33], v[76:77]
	v_pk_mul_f32 v[24:25], v[24:25], v[76:77]
	v_ldexp_f32 v64, v78, v64
	v_pk_mul_f32 v[64:65], v[64:65], s[4:5] op_sel_hi:[1,0]
	v_pk_mul_f32 v[16:17], v[16:17], v[76:77]
	v_pk_fma_f32 v[64:65], v[64:65], s[22:23], v[156:157] op_sel_hi:[1,0,0]
	v_pk_mul_f32 v[8:9], v[8:9], v[76:77]
	v_mul_f32_e32 v78, 0x4b800000, v64
	v_cmp_gt_f32_e64 s[2:3], s23, v64
	v_cmp_gt_f32_e32 vcc, s23, v65
	v_cvt_pk_bf16_f32 v55, v56, v57
; #define PG8_BAR __builtin_amdgcn_s_barrier()
; __device__ __forceinline__ unsigned pk2(float lo, float hi) { f32x2 v = {lo, hi}; bf16x2_t b = __builtin_convertvector(v, bf16x2_t); return __builtin_bit_cast(unsigned, b); }
; template <class Epi, class Sched, bool ALIGN_EPI = false, bool SP2 = false>
; __device__ __forceinline__ void gemm_phase(PG8_LAS unsigned char* lds, const Gemm g, const Sched& S, const Epi& E) {
;     ...
;         if constexpr (ALIGN_EPI) { if (wr == 0) PG8_BAR; }
;         if constexpr (!Epi::AFTER_DRAIN) { E(acc, cur, wr, wc, fr, fq); S.done(cur); }
;         if (!has_next) break;
; #pragma unroll
;         for (int a = 0; a < 2; ++a)
; #pragma unroll
;             for (int b = 0; b < 2; ++b)
; #pragma unroll
;                 for (int m = 0; m < 4; ++m)
; #pragma unroll
;                     for (int n = 0; n < 2; ++n) acc[a][b][m][n] = (f32x4){0.f, 0.f, 0.f, 0.f};
;         cur = nxt; cA = nA; cB = nB; ++ui;
;         if constexpr (Epi::MID) E.begin(cur, lds, tid);
;         if constexpr (ALIGN_EPI) { if (wr == 1) PG8_BAR; }
;     __device__ __forceinline__ void operator()(const f32x4 (&acc)[2][2][4][2], const pg8::Unit& u, int wr, int wc, int fr, int fq) const {
;     ...
;             for (int ai = 0; ai < 2; ++ai)
; #pragma unroll
;                 for (int m = 0; m < 4; ++m) {
;                     const int ch = u.pm * 256 + ai * 128 + wr * 64 + m * 16 + fr;
;                     const f32x4 a0 = acc[ai][bj][m][0], a1 = acc[ai][bj][m][1];
;                     u32x4 w; w.x = pk2(a0[0] * r[0], a0[1] * r[1]); w.y = pk2(a0[2] * r[2], a0[3] * r[3]); w.z = pk2(a1[0] * r[4], a1[1] * r[5]); w.w = pk2(a1[2] * r[6], a1[3] * r[7]);
;                     *(u32x4*)(VT + ((size_t)(b * 512 + ch)) * S + t) = w;
;                 }
	v_cndmask_b32_e64 v64, v64, v78, s[2:3]
	v_mul_f32_e32 v78, 0x4b800000, v65
	v_cndmask_b32_e32 v65, v65, v78, vcc
	v_rsq_f32_e32 v64, v64
	v_rsq_f32_e32 v65, v65
	v_cvt_pk_bf16_f32 v47, v48, v49
	v_cvt_pk_bf16_f32 v39, v40, v41
	v_cvt_pk_bf16_f32 v31, v32, v33
	v_pk_mul_f32 v[78:79], v[64:65], s[16:17] op_sel_hi:[1,0]
	v_cvt_pk_bf16_f32 v23, v24, v25
	v_cndmask_b32_e32 v79, v65, v79, vcc
	v_cndmask_b32_e64 v78, v64, v78, s[2:3]
	v_pk_mul_f32 v[58:59], v[58:59], v[78:79]
	v_pk_mul_f32 v[50:51], v[50:51], v[78:79]
	v_cvt_pk_bf16_f32 v64, v58, v59
	v_ffbh_u32_e32 v58, v69
	v_min_u32_e32 v65, 32, v58
	v_lshlrev_b64 v[58:59], v65, v[68:69]
	v_min_u32_e32 v58, 1, v58
	v_or_b32_e32 v58, v59, v58
	v_cvt_f32_u32_e32 v58, v58
	v_sub_u32_e32 v59, 32, v65
	v_pk_mul_f32 v[42:43], v[42:43], v[78:79]
	v_pk_mul_f32 v[34:35], v[34:35], v[78:79]
	v_ldexp_f32 v59, v58, v59
	v_ffbh_u32_e32 v58, v67
	v_min_u32_e32 v58, 32, v58
	v_lshlrev_b64 v[66:67], v58, v[66:67]
	v_min_u32_e32 v65, 1, v66
	v_or_b32_e32 v65, v67, v65
	v_cvt_f32_u32_e32 v65, v65
	v_sub_u32_e32 v58, 32, v58
	v_pk_mul_f32 v[26:27], v[26:27], v[78:79]
	v_pk_mul_f32 v[18:19], v[18:19], v[78:79]
	v_ldexp_f32 v58, v65, v58
	v_pk_mul_f32 v[58:59], v[58:59], s[4:5] op_sel_hi:[1,0]
	v_pk_mul_f32 v[10:11], v[10:11], v[78:79]
	v_pk_fma_f32 v[58:59], v[58:59], s[22:23], v[156:157] op_sel_hi:[1,0,0]
	v_pk_mul_f32 v[2:3], v[2:3], v[78:79]
	v_mul_f32_e32 v65, 0x4b800000, v58
	v_cmp_gt_f32_e64 s[2:3], s23, v58
	v_cmp_gt_f32_e32 vcc, s23, v59
	v_cvt_pk_bf16_f32 v56, v50, v51
	v_cndmask_b32_e64 v58, v58, v65, s[2:3]
	v_mul_f32_e32 v65, 0x4b800000, v59
	v_cndmask_b32_e32 v59, v59, v65, vcc
	v_rsq_f32_e32 v58, v58
	v_rsq_f32_e32 v59, v59
	v_cvt_pk_bf16_f32 v48, v42, v43
	v_cvt_pk_bf16_f32 v40, v34, v35
	v_cvt_pk_bf16_f32 v32, v26, v27
	v_pk_mul_f32 v[66:67], v[58:59], s[16:17] op_sel_hi:[1,0]
	v_cvt_pk_bf16_f32 v24, v18, v19
	v_cndmask_b32_e32 v59, v59, v67, vcc
	v_cndmask_b32_e64 v58, v58, v66, s[2:3]
	v_pk_mul_f32 v[60:61], v[60:61], v[58:59]
	v_pk_mul_f32 v[50:51], v[52:53], v[58:59]
	v_pk_mul_f32 v[42:43], v[44:45], v[58:59]
	v_pk_mul_f32 v[34:35], v[36:37], v[58:59]
	v_pk_mul_f32 v[26:27], v[28:29], v[58:59]
	v_pk_mul_f32 v[18:19], v[20:21], v[58:59]
	v_cvt_pk_bf16_f32 v14, v14, v15
	v_cvt_pk_bf16_f32 v15, v16, v17
	v_cvt_pk_bf16_f32 v16, v10, v11
	v_pk_mul_f32 v[10:11], v[12:13], v[58:59]
	v_cvt_pk_bf16_f32 v6, v6, v7
	v_cvt_pk_bf16_f32 v7, v8, v9
	v_cvt_pk_bf16_f32 v8, v2, v3
	v_pk_mul_f32 v[2:3], v[4:5], v[58:59]
	v_cvt_pk_bf16_f32 v65, v60, v61
	v_lshl_add_u64 v[60:61], v[124:125], 0, v[98:99]
	v_cvt_pk_bf16_f32 v57, v50, v51
	v_lshl_add_u64 v[50:51], v[116:117], 0, v[98:99]
	v_cvt_pk_bf16_f32 v49, v42, v43
	v_lshl_add_u64 v[42:43], v[108:109], 0, v[98:99]
	v_cvt_pk_bf16_f32 v41, v34, v35
	v_lshl_add_u64 v[34:35], v[100:101], 0, v[98:99]
	v_cvt_pk_bf16_f32 v33, v26, v27
	v_lshl_add_u64 v[26:27], v[90:91], 0, v[98:99]
	v_cvt_pk_bf16_f32 v25, v18, v19
	v_lshl_add_u64 v[18:19], v[82:83], 0, v[98:99]
	v_cvt_pk_bf16_f32 v17, v10, v11
	v_lshl_add_u64 v[10:11], v[74:75], 0, v[98:99]
	v_cvt_pk_bf16_f32 v9, v2, v3
	v_lshl_add_u64 v[2:3], v[70:71], 0, v[98:99]
	s_mov_b64 s[2:3], -1
	s_and_b64 vcc, exec, s[42:43]
	global_store_dwordx4 v[60:61], v[62:65], off
	global_store_dwordx4 v[50:51], v[54:57], off
	global_store_dwordx4 v[42:43], v[46:49], off
	global_store_dwordx4 v[34:35], v[38:41], off
	global_store_dwordx4 v[26:27], v[30:33], off
	global_store_dwordx4 v[18:19], v[22:25], off
	global_store_dwordx4 v[10:11], v[14:17], off
	global_store_dwordx4 v[2:3], v[6:9], off
	s_cbranch_vccnz .LBB0_1196
	s_andn2_b64 vcc, exec, s[40:41]
	s_cbranch_vccnz .LBB0_1195
	s_barrier
	s_branch .LBB0_1195

; #define LAS __attribute__((address_space(3)))
; __device__ __forceinline__ void transpose_item_wg(const float* W, int K, int N, bf16* WT, int mode, const float* g0, const float* g1, int item, LAS float* scr, int tid, int lane, int wave) {
;     const int nblk = (N + 255) >> 8, kb = item / nblk, nb = item - kb * nblk, k0 = 64 * kb, n0 = 256 * nb, nw = min(256, N - n0);
;     const float* gk = g0 ? ((g1 && k0 >= 512) ? g1 + (k0 - 512) : g0 + k0) : nullptr;
;     if (4 * lane < nw) {
;         f32x4 v[8];
; #pragma unroll
;         for (int j = 0; j < 8; ++j) v[j] = __builtin_nontemporal_load((const f32x4*)(W + (size_t)(k0 + 8 * wave + j) * N + n0 + 4 * lane));
; #pragma unroll
;         for (int j = 0; j < 8; ++j) { const float gv = gk ? gk[8 * wave + j] : 1.0f; *(LAS f32x4*)(scr + (8 * wave + j) * 260 + 4 * lane) = v[j] * gv; }
.LBB0_1495:
	s_xor_b32 s75, s75, 1
	s_mul_i32 s4, s75, 0x10400
	s_add_i32 s77, s62, 0x2e4
	s_add_i32 s76, s4, 0
	s_cmpk_gt_i32 s77, 0xaf
	s_mov_b64 s[34:35], -1
	s_cbranch_scc0 .LBB0_1677
	s_cmpk_gt_u32 s77, 0x15f
	s_cbranch_scc0 .LBB0_1664
	s_cmpk_gt_u32 s77, 0x20f
	s_cbranch_scc0 .LBB0_1651
	s_cmpk_gt_u32 s77, 0x28f
	s_cbranch_scc0 .LBB0_1582
	s_cmpk_gt_u32 s77, 0x29b
	s_cbranch_scc0 .LBB0_1545
	s_cmpk_gt_u32 s77, 0x2a3
	s_cbranch_scc0 .LBB0_1532
	s_cmpk_gt_u32 s77, 0x2e3
	s_cbranch_scc0 .LBB0_1513
	s_lshr_b32 s4, s62, 2
	s_lshl_b32 s16, s4, 10
	s_add_i32 s17, s61, s16
	s_lshl_b32 s22, s4, 6
	s_add_i32 s4, s63, s73
	v_cmp_gt_i32_e32 vcc, s17, v1
	s_and_saveexec_b64 s[34:35], vcc
	s_cbranch_execz .LBB0_1504
	s_sub_i32 s18, s4, s16
	s_add_i32 s30, s18, 0xfffd1c00
	s_add_i32 s18, s22, s87
	s_ashr_i32 s31, s30, 31
	v_lshl_add_u64 v[26:27], s[30:31], 2, v[40:41]
	s_lshl_b64 s[30:31], s[18:19], 12
	v_lshl_add_u64 v[2:3], v[26:27], 0, s[30:31]
	s_or_b32 s30, s18, 1
	s_mov_b32 s31, s19
	s_lshl_b64 s[30:31], s[30:31], 12
	v_lshl_add_u64 v[6:7], v[26:27], 0, s[30:31]
	s_or_b32 s30, s18, 2
	s_mov_b32 s31, s19
	s_lshl_b64 s[30:31], s[30:31], 12
	v_lshl_add_u64 v[10:11], v[26:27], 0, s[30:31]
	s_or_b32 s30, s18, 3
	s_mov_b32 s31, s19
	s_lshl_b64 s[30:31], s[30:31], 12
	v_lshl_add_u64 v[14:15], v[26:27], 0, s[30:31]
	s_or_b32 s30, s18, 4
	s_mov_b32 s31, s19
	s_lshl_b64 s[30:31], s[30:31], 12
	v_lshl_add_u64 v[18:19], v[26:27], 0, s[30:31]
	s_or_b32 s30, s18, 5
	s_mov_b32 s31, s19
	s_lshl_b64 s[30:31], s[30:31], 12
	v_lshl_add_u64 v[22:23], v[26:27], 0, s[30:31]
	s_or_b32 s30, s18, 6
	s_mov_b32 s31, s19
	s_lshl_b64 s[30:31], s[30:31], 12
	s_or_b32 s18, s18, 7
	v_lshl_add_u64 v[28:29], v[26:27], 0, s[30:31]
	s_lshl_b64 s[30:31], s[18:19], 12
	v_lshl_add_u64 v[30:31], v[26:27], 0, s[30:31]
	global_load_dwordx4 v[2:5], v[2:3], off nt
	global_load_dwordx4 v[6:9], v[6:7], off nt
	global_load_dwordx4 v[10:13], v[10:11], off nt
	global_load_dwordx4 v[14:17], v[14:15], off nt
	global_load_dwordx4 v[18:21], v[18:19], off nt
	global_load_dwordx4 v[22:25], v[22:23], off nt
	global_load_dwordx4 v[26:29], v[28:29], off nt
	global_load_dwordx4 v[30:33], v[30:31], off nt
	v_readlane_b32 s1, v254, 49
	s_add_i32 s18, s1, s76
	v_lshl_add_u32 v34, v1, 2, s18
	s_waitcnt vmcnt(7)
	ds_write_b128 v34, v[2:5]
	s_waitcnt vmcnt(6)
	ds_write_b128 v34, v[6:9] offset:1040
	s_waitcnt vmcnt(5)
	ds_write_b128 v34, v[10:13] offset:2080
	s_waitcnt vmcnt(4)
	ds_write_b128 v34, v[14:17] offset:3120
	s_waitcnt vmcnt(3)
	ds_write_b128 v34, v[18:21] offset:4160
	s_waitcnt vmcnt(2)
	ds_write_b128 v34, v[22:25] offset:5200
	s_waitcnt vmcnt(1)
	ds_write_b128 v34, v[26:29] offset:6240
	s_waitcnt vmcnt(0)
	ds_write_b128 v34, v[30:33] offset:7280

; #define LAS __attribute__((address_space(3)))
; __device__ __forceinline__ void transpose_item_wg(const float* W, int K, int N, bf16* WT, int mode, const float* g0, const float* g1, int item, LAS float* scr, int tid, int lane, int wave) {
;     const int nblk = (N + 255) >> 8, kb = item / nblk, nb = item - kb * nblk, k0 = 64 * kb, n0 = 256 * nb, nw = min(256, N - n0);
;     const float* gk = g0 ? ((g1 && k0 >= 512) ? g1 + (k0 - 512) : g0 + k0) : nullptr;
;     if (4 * lane < nw) {
;         f32x4 v[8];
; #pragma unroll
;         for (int j = 0; j < 8; ++j) v[j] = __builtin_nontemporal_load((const f32x4*)(W + (size_t)(k0 + 8 * wave + j) * N + n0 + 4 * lane));
; #pragma unroll
;         for (int j = 0; j < 8; ++j) { const float gv = gk ? gk[8 * wave + j] : 1.0f; *(LAS f32x4*)(scr + (8 * wave + j) * 260 + 4 * lane) = v[j] * gv; }
.LBB0_1513:
	s_and_b64 vcc, exec, s[34:35]
	s_cbranch_vccz .LBB0_1526
	s_lshl_b32 s4, s64, 8
	s_add_i32 s17, s62, 64
	s_and_b32 s4, s4, 0xfffffc00
	s_lshl_b32 s16, s17, 4
	s_and_b32 s18, s16, 0xffffffc0
	s_add_i32 s16, s61, s4
	s_addk_i32 s16, 0xc000
	v_cmp_gt_i32_e32 vcc, s16, v1
	s_and_saveexec_b64 s[34:35], vcc
	s_cbranch_execz .LBB0_1522
	s_sub_i32 s22, s65, s4
	s_add_i32 s30, s73, s22
	s_cmp_gt_u32 s17, 31
	s_cselect_b32 s17, s11, s15
	s_cselect_b32 s22, s10, s13
	s_lshl_b64 s[36:37], s[18:19], 2
	s_add_u32 s36, s22, s36
	s_addc_u32 s37, s17, s37
	s_add_i32 s52, s18, s87
	s_ashr_i32 s31, s30, 31
	s_mov_b32 s53, s19
	v_lshl_add_u64 v[10:11], s[30:31], 2, v[46:47]
	s_lshl_b64 s[30:31], s[52:53], 12
	v_lshl_add_u64 v[2:3], v[10:11], 0, s[30:31]
	s_or_b32 s30, s52, 1
	s_mov_b32 s31, s19
	s_lshl_b64 s[30:31], s[30:31], 12
	v_lshl_add_u64 v[4:5], v[10:11], 0, s[30:31]
	s_or_b32 s30, s52, 2
	s_mov_b32 s31, s19
	s_lshl_b64 s[30:31], s[30:31], 12
	global_load_dwordx4 v[22:25], v[2:3], off nt
	global_load_dwordx4 v[26:29], v[4:5], off nt
	v_lshl_add_u64 v[2:3], v[10:11], 0, s[30:31]
	s_or_b32 s30, s52, 3
	s_mov_b32 s31, s19
	s_lshl_b64 s[30:31], s[30:31], 12
	v_lshl_add_u64 v[4:5], v[10:11], 0, s[30:31]
	s_or_b32 s30, s52, 4
	s_mov_b32 s31, s19
	s_lshl_b64 s[30:31], s[30:31], 12
	global_load_dwordx4 v[30:33], v[2:3], off nt
	global_load_dwordx4 v[18:21], v[4:5], off nt
	v_lshl_add_u64 v[2:3], v[10:11], 0, s[30:31]
	s_or_b32 s30, s52, 5
	s_mov_b32 s31, s19
	s_lshl_b64 s[30:31], s[30:31], 12
	v_lshl_add_u64 v[6:7], v[10:11], 0, s[30:31]
	s_or_b32 s30, s52, 6
	s_mov_b32 s31, s19
	s_lshl_b64 s[30:31], s[30:31], 12
	v_lshl_add_u64 v[12:13], v[10:11], 0, s[30:31]
	s_or_b32 s30, s52, 7
	s_mov_b32 s31, s19
	s_lshl_b64 s[30:31], s[30:31], 12
	v_lshl_add_u64 v[10:11], v[10:11], 0, s[30:31]
	global_load_dwordx4 v[2:5], v[2:3], off nt
	global_load_dwordx4 v[6:9], v[6:7], off nt
	global_load_dwordx4 v[14:17], v[12:13], off nt
	global_load_dwordx4 v[10:13], v[10:11], off nt
	v_lshl_add_u32 v120, v1, 2, s76
	v_readlane_b32 s1, v254, 49
	s_cmp_lg_u64 s[36:37], 0
	s_cselect_b64 s[52:53], -1, 0
	v_add_u32_e32 v121, s1, v120
	v_readlane_b32 s1, v252, 25
	s_cmp_eq_u64 s[36:37], 0
	s_nop 0
	v_add_u32_e32 v122, s1, v120
	s_cbranch_scc1 .LBB0_1688
	v_mov_b32_e32 v34, s60
	global_load_dwordx4 v[124:127], v34, s[36:37]
	s_waitcnt vmcnt(0)
	v_pk_mul_f32 v[36:37], v[24:25], v[124:125] op_sel_hi:[1,0]
	v_pk_mul_f32 v[34:35], v[22:23], v[124:125] op_sel_hi:[1,0]
	ds_write_b128 v121, v[34:37]
	v_pk_mul_f32 v[36:37], v[28:29], v[124:125] op_sel:[0,1]
	v_pk_mul_f32 v[34:35], v[26:27], v[124:125] op_sel:[0,1]
	ds_write_b128 v122, v[34:37]
	v_pk_mul_f32 v[36:37], v[32:33], v[126:127] op_sel_hi:[1,0]
	v_pk_mul_f32 v[34:35], v[30:31], v[126:127] op_sel_hi:[1,0]
	v_mov_b32_e32 v70, v127
	s_cbranch_execnz .LBB0_1518

; #define LAS __attribute__((address_space(3)))
; __device__ __forceinline__ void transpose_item_wg(const float* W, int K, int N, bf16* WT, int mode, const float* g0, const float* g1, int item, LAS float* scr, int tid, int lane, int wave) {
;     const int nblk = (N + 255) >> 8, kb = item / nblk, nb = item - kb * nblk, k0 = 64 * kb, n0 = 256 * nb, nw = min(256, N - n0);
;     const float* gk = g0 ? ((g1 && k0 >= 512) ? g1 + (k0 - 512) : g0 + k0) : nullptr;
;     if (4 * lane < nw) {
;         f32x4 v[8];
; #pragma unroll
;         for (int j = 0; j < 8; ++j) v[j] = __builtin_nontemporal_load((const f32x4*)(W + (size_t)(k0 + 8 * wave + j) * N + n0 + 4 * lane));
; #pragma unroll
;         for (int j = 0; j < 8; ++j) { const float gv = gk ? gk[8 * wave + j] : 1.0f; *(LAS f32x4*)(scr + (8 * wave + j) * 260 + 4 * lane) = v[j] * gv; }
.LBB0_1582:
	s_andn2_b64 vcc, exec, s[34:35]
	s_cbranch_vccnz .LBB0_1650
	s_lshr_b32 s16, s68, 3
	s_lshl_b32 s4, s16, 11
	s_add_i32 s17, s62, 0xd4
	s_add_i32 s22, s61, s4
	s_lshr_b32 s17, s17, 3
	s_add_i32 s22, s22, 0xffff2fc0
	s_lshl_b32 s18, s17, 6
	v_cmp_gt_i32_e32 vcc, s22, v1
	s_and_saveexec_b64 s[34:35], vcc
	s_cbranch_execz .LBB0_1585
	s_sub_i32 s28, s70, s4
	s_add_i32 s30, s73, s28
	s_ashr_i32 s31, s30, 31
	s_add_i32 s28, s18, s87
	v_lshl_add_u64 v[30:31], s[30:31], 2, v[58:59]
	v_mad_u64_u32 v[2:3], s[30:31], s28, v200, v[30:31]
	s_or_b32 s30, s28, 1
	s_nop 0
	v_mad_u64_u32 v[6:7], s[30:31], s30, v200, v[30:31]
	s_or_b32 s30, s28, 2
	s_nop 0
	v_mad_u64_u32 v[10:11], s[30:31], s30, v200, v[30:31]
	s_or_b32 s30, s28, 3
	s_nop 0
	v_mad_u64_u32 v[14:15], s[30:31], s30, v200, v[30:31]
	s_or_b32 s30, s28, 4
	s_nop 0
	v_mad_u64_u32 v[18:19], s[30:31], s30, v200, v[30:31]
	s_or_b32 s30, s28, 5
	s_nop 0
	v_mad_u64_u32 v[22:23], s[30:31], s30, v200, v[30:31]
	s_or_b32 s30, s28, 6
	s_or_b32 s28, s28, 7
	v_mad_u64_u32 v[26:27], s[30:31], s30, v200, v[30:31]
	v_mad_u64_u32 v[30:31], s[30:31], s28, v200, v[30:31]
	s_lshl_b64 s[30:31], s[18:19], 2
	s_add_u32 s30, s58, s30
	s_addc_u32 s31, s59, s31
	global_load_dwordx4 v[2:5], v[2:3], off nt
	v_lshl_add_u32 v70, v1, 2, s76
	global_load_dwordx4 v[6:9], v[6:7], off nt
	v_readlane_b32 s1, v254, 49
	global_load_dwordx4 v[10:13], v[10:11], off nt
	global_load_dwordx4 v[14:17], v[14:15], off nt
	s_waitcnt vmcnt(13)
	v_add_u32_e32 v124, s1, v70
	global_load_dwordx4 v[18:21], v[18:19], off nt
	v_readlane_b32 s1, v252, 25
	global_load_dwordx4 v[22:25], v[22:23], off nt
	global_load_dwordx4 v[26:29], v[26:27], off nt
	global_load_dwordx4 v[30:33], v[30:31], off nt
	s_nop 0
	global_load_dwordx4 v[34:37], v99, s[30:31] offset:16
	global_load_dwordx4 v[120:123], v99, s[30:31]
	s_waitcnt vmcnt(0)
	v_pk_mul_f32 v[4:5], v[4:5], v[120:121] op_sel_hi:[1,0]
	v_pk_mul_f32 v[2:3], v[2:3], v[120:121] op_sel_hi:[1,0]
	ds_write_b128 v124, v[2:5]
	v_pk_mul_f32 v[4:5], v[8:9], v[120:121] op_sel:[0,1]
	v_pk_mul_f32 v[2:3], v[6:7], v[120:121] op_sel:[0,1]
	v_add_u32_e32 v6, s1, v70
	ds_write_b128 v6, v[2:5]
	v_pk_mul_f32 v[4:5], v[12:13], v[122:123] op_sel_hi:[1,0]
	v_pk_mul_f32 v[2:3], v[10:11], v[122:123] op_sel_hi:[1,0]
	ds_write_b128 v6, v[2:5] offset:1040
	v_mov_b32_e32 v2, v123
	v_pk_mul_f32 v[4:5], v[16:17], v[2:3] op_sel_hi:[1,0]
	v_pk_mul_f32 v[2:3], v[14:15], v[2:3] op_sel_hi:[1,0]
	ds_write_b128 v6, v[2:5] offset:2080
	v_pk_mul_f32 v[4:5], v[20:21], v[34:35] op_sel_hi:[1,0]
	v_pk_mul_f32 v[2:3], v[18:19], v[34:35] op_sel_hi:[1,0]
	ds_write_b128 v6, v[2:5] offset:3120
	v_pk_mul_f32 v[4:5], v[24:25], v[34:35] op_sel:[0,1]
	v_pk_mul_f32 v[2:3], v[22:23], v[34:35] op_sel:[0,1]
	ds_write_b128 v6, v[2:5] offset:4160
	v_pk_mul_f32 v[4:5], v[28:29], v[36:37] op_sel_hi:[1,0]
	v_pk_mul_f32 v[2:3], v[26:27], v[36:37] op_sel_hi:[1,0]
	ds_write_b128 v6, v[2:5] offset:5200
	v_mov_b32_e32 v2, v37
	v_pk_mul_f32 v[4:5], v[32:33], v[2:3] op_sel_hi:[1,0]
	v_pk_mul_f32 v[2:3], v[30:31], v[2:3] op_sel_hi:[1,0]
	ds_write_b128 v6, v[2:5] offset:6240

; #define LAS __attribute__((address_space(3)))
; __device__ __forceinline__ void transpose_item_wg(const float* W, int K, int N, bf16* WT, int mode, const float* g0, const float* g1, int item, LAS float* scr, int tid, int lane, int wave) {
;     const int nblk = (N + 255) >> 8, kb = item / nblk, nb = item - kb * nblk, k0 = 64 * kb, n0 = 256 * nb, nw = min(256, N - n0);
;     const float* gk = g0 ? ((g1 && k0 >= 512) ? g1 + (k0 - 512) : g0 + k0) : nullptr;
;     if (4 * lane < nw) {
;         f32x4 v[8];
; #pragma unroll
;         for (int j = 0; j < 8; ++j) v[j] = __builtin_nontemporal_load((const f32x4*)(W + (size_t)(k0 + 8 * wave + j) * N + n0 + 4 * lane));
; #pragma unroll
;         for (int j = 0; j < 8; ++j) { const float gv = gk ? gk[8 * wave + j] : 1.0f; *(LAS f32x4*)(scr + (8 * wave + j) * 260 + 4 * lane) = v[j] * gv; }
.LBB0_1651:
	s_andn2_b64 vcc, exec, s[34:35]
	s_cbranch_vccnz .LBB0_1663
	s_lshl_b32 s4, s71, 8
	s_and_b32 s16, s4, 0xfffffc00
	s_lshl_b32 s4, s62, 4
	s_add_i32 s17, s61, s16
	s_addk_i32 s4, 0x1840
	s_add_i32 s17, s17, 0xfffe7c00
	s_and_b32 s18, s4, 0xffffffc0
	s_add_i32 s4, s63, s73
	v_cmp_gt_i32_e32 vcc, s17, v1
	s_and_saveexec_b64 s[34:35], vcc
	s_cbranch_execz .LBB0_1654
	s_sub_i32 s22, s4, s16
	s_add_i32 s30, s22, 0xfffea000
	s_add_i32 s36, s18, s87
	s_ashr_i32 s31, s30, 31
	s_mov_b32 s37, s19
	v_lshl_add_u64 v[26:27], s[30:31], 2, v[62:63]
	s_lshl_b64 s[30:31], s[36:37], 12
	v_lshl_add_u64 v[2:3], v[26:27], 0, s[30:31]
	s_or_b32 s30, s36, 1
	s_mov_b32 s31, s19
	s_lshl_b64 s[30:31], s[30:31], 12
	v_lshl_add_u64 v[6:7], v[26:27], 0, s[30:31]
	s_or_b32 s30, s36, 2
	s_mov_b32 s31, s19
	s_lshl_b64 s[30:31], s[30:31], 12
	v_lshl_add_u64 v[10:11], v[26:27], 0, s[30:31]
	s_or_b32 s30, s36, 3
	s_mov_b32 s31, s19
	s_lshl_b64 s[30:31], s[30:31], 12
	v_lshl_add_u64 v[14:15], v[26:27], 0, s[30:31]
	s_or_b32 s30, s36, 4
	s_mov_b32 s31, s19
	s_lshl_b64 s[30:31], s[30:31], 12
	v_lshl_add_u64 v[18:19], v[26:27], 0, s[30:31]
	s_or_b32 s30, s36, 5
	s_mov_b32 s31, s19
	s_lshl_b64 s[30:31], s[30:31], 12
	v_lshl_add_u64 v[22:23], v[26:27], 0, s[30:31]
	s_or_b32 s30, s36, 6
	s_mov_b32 s31, s19
	s_lshl_b64 s[30:31], s[30:31], 12
	v_lshl_add_u64 v[28:29], v[26:27], 0, s[30:31]
	s_or_b32 s30, s36, 7
	s_mov_b32 s31, s19
	s_lshl_b64 s[30:31], s[30:31], 12
	v_lshl_add_u64 v[30:31], v[26:27], 0, s[30:31]
	global_load_dwordx4 v[2:5], v[2:3], off nt
	global_load_dwordx4 v[6:9], v[6:7], off nt
	global_load_dwordx4 v[10:13], v[10:11], off nt
	global_load_dwordx4 v[14:17], v[14:15], off nt
	global_load_dwordx4 v[18:21], v[18:19], off nt
	global_load_dwordx4 v[22:25], v[22:23], off nt
	global_load_dwordx4 v[26:29], v[28:29], off nt
	global_load_dwordx4 v[30:33], v[30:31], off nt
	v_readlane_b32 s1, v254, 49
	s_add_i32 s22, s1, s76
	v_lshl_add_u32 v34, v1, 2, s22
	s_waitcnt vmcnt(7)
	ds_write_b128 v34, v[2:5]
	s_waitcnt vmcnt(6)
	ds_write_b128 v34, v[6:9] offset:1040
	s_waitcnt vmcnt(5)
	ds_write_b128 v34, v[10:13] offset:2080
	s_waitcnt vmcnt(4)
	ds_write_b128 v34, v[14:17] offset:3120
	s_waitcnt vmcnt(3)
	ds_write_b128 v34, v[18:21] offset:4160
	s_waitcnt vmcnt(2)
	ds_write_b128 v34, v[22:25] offset:5200
	s_waitcnt vmcnt(1)
	ds_write_b128 v34, v[26:29] offset:6240
	s_waitcnt vmcnt(0)
	ds_write_b128 v34, v[30:33] offset:7280

; #define LAS __attribute__((address_space(3)))
; __device__ __forceinline__ void transpose_item_wg(const float* W, int K, int N, bf16* WT, int mode, const float* g0, const float* g1, int item, LAS float* scr, int tid, int lane, int wave) {
;     const int nblk = (N + 255) >> 8, kb = item / nblk, nb = item - kb * nblk, k0 = 64 * kb, n0 = 256 * nb, nw = min(256, N - n0);
;     const float* gk = g0 ? ((g1 && k0 >= 512) ? g1 + (k0 - 512) : g0 + k0) : nullptr;
;     if (4 * lane < nw) {
;         f32x4 v[8];
; #pragma unroll
;         for (int j = 0; j < 8; ++j) v[j] = __builtin_nontemporal_load((const f32x4*)(W + (size_t)(k0 + 8 * wave + j) * N + n0 + 4 * lane));
; #pragma unroll
;         for (int j = 0; j < 8; ++j) { const float gv = gk ? gk[8 * wave + j] : 1.0f; *(LAS f32x4*)(scr + (8 * wave + j) * 260 + 4 * lane) = v[j] * gv; }
.LBB0_1677:
	s_andn2_b64 vcc, exec, s[34:35]
	s_cbranch_vccnz .LBB0_1494
	s_mul_hi_i32 s4, s77, 0x2e8ba2e9
	s_lshr_b32 s16, s4, 31
	s_ashr_i32 s4, s4, 1
	s_add_i32 s4, s4, s16
	s_mul_i32 s16, s4, 0xb00
	s_add_i32 s16, s61, s16
	s_lshl_b32 s34, s4, 6
	s_add_i32 s16, s16, 0xfffd2300
	s_ashr_i32 s35, s34, 31
	v_cmp_gt_i32_e32 vcc, s16, v1
	s_and_saveexec_b64 s[36:37], vcc
	s_cbranch_execz .LBB0_1680
	s_mul_i32 s17, s4, 0xfffff500
	s_add_i32 s18, s63, s73
	s_add_i32 s30, s18, s17
	s_add_i32 s17, s34, s87
	s_ashr_i32 s31, s30, 31
	v_lshl_add_u64 v[30:31], s[30:31], 2, v[68:69]
	s_or_b32 s18, s17, 1
	v_mad_i64_i32 v[6:7], s[30:31], s18, v198, v[30:31]
	s_or_b32 s18, s17, 2
	v_mad_i64_i32 v[10:11], s[30:31], s18, v198, v[30:31]
	s_or_b32 s18, s17, 3
	v_mad_i64_i32 v[14:15], s[30:31], s18, v198, v[30:31]
	s_or_b32 s18, s17, 4
	v_mad_i64_i32 v[18:19], s[30:31], s18, v198, v[30:31]
	s_or_b32 s18, s17, 5
	v_mad_i64_i32 v[2:3], s[30:31], s17, v198, v[30:31]
	v_mad_i64_i32 v[22:23], s[30:31], s18, v198, v[30:31]
	s_or_b32 s18, s17, 6
	s_or_b32 s17, s17, 7
	v_mad_i64_i32 v[26:27], s[30:31], s18, v198, v[30:31]
	v_mad_i64_i32 v[30:31], s[30:31], s17, v198, v[30:31]
	s_lshl_b64 s[30:31], s[34:35], 2
	s_add_u32 s30, s50, s30
	s_addc_u32 s31, s51, s31
	global_load_dwordx4 v[2:5], v[2:3], off nt
	v_lshl_add_u32 v70, v1, 2, s76
	global_load_dwordx4 v[6:9], v[6:7], off nt
	v_readlane_b32 s1, v254, 49
	global_load_dwordx4 v[10:13], v[10:11], off nt
	global_load_dwordx4 v[14:17], v[14:15], off nt
	s_waitcnt vmcnt(13)
	v_add_u32_e32 v124, s1, v70
	global_load_dwordx4 v[18:21], v[18:19], off nt
	v_readlane_b32 s1, v252, 25
	global_load_dwordx4 v[22:25], v[22:23], off nt
	global_load_dwordx4 v[26:29], v[26:27], off nt
	global_load_dwordx4 v[30:33], v[30:31], off nt
	s_nop 0
	global_load_dwordx4 v[34:37], v99, s[30:31] offset:16
	global_load_dwordx4 v[120:123], v99, s[30:31]
	s_waitcnt vmcnt(0)
	v_pk_mul_f32 v[4:5], v[4:5], v[120:121] op_sel_hi:[1,0]
	v_pk_mul_f32 v[2:3], v[2:3], v[120:121] op_sel_hi:[1,0]
	ds_write_b128 v124, v[2:5]
	v_pk_mul_f32 v[4:5], v[8:9], v[120:121] op_sel:[0,1]
	v_pk_mul_f32 v[2:3], v[6:7], v[120:121] op_sel:[0,1]
	v_add_u32_e32 v6, s1, v70
	ds_write_b128 v6, v[2:5]
	v_pk_mul_f32 v[4:5], v[12:13], v[122:123] op_sel_hi:[1,0]
	v_pk_mul_f32 v[2:3], v[10:11], v[122:123] op_sel_hi:[1,0]
	ds_write_b128 v6, v[2:5] offset:1040
	v_mov_b32_e32 v2, v123
	v_pk_mul_f32 v[4:5], v[16:17], v[2:3] op_sel_hi:[1,0]
	v_pk_mul_f32 v[2:3], v[14:15], v[2:3] op_sel_hi:[1,0]
	ds_write_b128 v6, v[2:5] offset:2080
	v_pk_mul_f32 v[4:5], v[20:21], v[34:35] op_sel_hi:[1,0]
	v_pk_mul_f32 v[2:3], v[18:19], v[34:35] op_sel_hi:[1,0]
	ds_write_b128 v6, v[2:5] offset:3120
	v_pk_mul_f32 v[4:5], v[24:25], v[34:35] op_sel:[0,1]
	v_pk_mul_f32 v[2:3], v[22:23], v[34:35] op_sel:[0,1]
	ds_write_b128 v6, v[2:5] offset:4160
	v_pk_mul_f32 v[4:5], v[28:29], v[36:37] op_sel_hi:[1,0]
	v_pk_mul_f32 v[2:3], v[26:27], v[36:37] op_sel_hi:[1,0]
	ds_write_b128 v6, v[2:5] offset:5200
	v_mov_b32_e32 v2, v37
	v_pk_mul_f32 v[4:5], v[32:33], v[2:3] op_sel_hi:[1,0]
	v_pk_mul_f32 v[2:3], v[30:31], v[2:3] op_sel_hi:[1,0]
	ds_write_b128 v6, v[2:5] offset:6240

; __device__ __forceinline__ unsigned pk2(float lo, float hi) { f32x2 v = {lo, hi}; bf16x2_t b = __builtin_convertvector(v, bf16x2_t); return __builtin_bit_cast(unsigned, b); }
; __device__ __forceinline__ float bflo(unsigned u) { return __uint_as_float(u << 16); }
; __device__ __forceinline__ float bfhi(unsigned u) { return __uint_as_float(u & 0xffff0000u); }
; __device__ __forceinline__ float ex2(float x) { return __builtin_amdgcn_exp2f(x); }
; __device__ __forceinline__ float rcpf_(float x) { return __builtin_amdgcn_rcpf(x); }
;     __device__ __forceinline__ void operator()(const f32x4 (&acc)[2][2][4][2], const pg8::Unit& u, int wr, int wc, int fr, int fq) const {
;     ...
;             for (int m = 0; m < 4; ++m) {
;                 const int row = u.pm * 256 + ai * 128 + wr * 64 + m * 16 + fr;
;                 const float r = rsqrtf(ssf(SSin + row) * (1.0f / D) + EPS) * LOG2E;
;                 float ss = 0.f;
; #pragma unroll
;                 for (int bj = 0; bj < 2; ++bj) {
;                     const int col = u.pn * 256 + bj * 128 + wc * 32 + fq * 8;
;                     const u32x4 hw = *(const u32x4*)(Hin + (size_t)row * D + col);
;                     const u32x4 pw = *(const u32x4*)(PP_ + (size_t)row * D + col);
;                     const f32x4 a0 = acc[ai][bj][m][0] * r, a1 = acc[ai][bj][m][1] * r;
;                     float h[8];
;                     h[0] = bflo(hw.x) + rcpf_(1.0f + ex2(-a0[0])) * bflo(pw.x); h[1] = bfhi(hw.x) + rcpf_(1.0f + ex2(-a0[1])) * bfhi(pw.x);
;                     h[2] = bflo(hw.y) + rcpf_(1.0f + ex2(-a0[2])) * bflo(pw.y); h[3] = bfhi(hw.y) + rcpf_(1.0f + ex2(-a0[3])) * bfhi(pw.y);
;                     h[4] = bflo(hw.z) + rcpf_(1.0f + ex2(-a1[0])) * bflo(pw.z); h[5] = bfhi(hw.z) + rcpf_(1.0f + ex2(-a1[1])) * bfhi(pw.z);
;                     h[6] = bflo(hw.w) + rcpf_(1.0f + ex2(-a1[2])) * bflo(pw.w); h[7] = bfhi(hw.w) + rcpf_(1.0f + ex2(-a1[3])) * bfhi(pw.w);
; #pragma unroll
;                     for (int i = 0; i < 8; ++i) ss += h[i] * h[i];
;                     u32x4 w; w.x = pk2(h[0], h[1]); w.y = pk2(h[2], h[3]); w.z = pk2(h[4], h[5]); w.w = pk2(h[6], h[7]);
;                     *(u32x4*)(Hout + (size_t)row * D + col) = w;
;                 }
;                 ss = xor16_sum(ss); ss = xor32_sum(ss);
;                 if (fq == 0) atomic_addf(SSout + row, ss);
.LBB0_1856:
	v_lshl_add_u32 v146, s78, 8, v1
	v_ashrrev_i32_e32 v147, 31, v146
	v_lshl_add_u64 v[144:145], v[146:147], 3, s[50:51]
	global_load_dwordx2 v[148:149], v[144:145], off
	v_lshl_or_b32 v142, s77, 8, v158
	v_lshlrev_b64 v[164:165], 11, v[146:147]
	v_lshl_add_u64 v[156:157], s[48:49], 0, v[164:165]
	s_waitcnt vmcnt(0)
	v_ffbh_u32_e32 v143, v149
	v_min_u32_e32 v143, 32, v143
	v_lshlrev_b64 v[148:149], v143, v[148:149]
	v_min_u32_e32 v148, 1, v148
	v_or_b32_e32 v148, v149, v148
	v_cvt_f32_u32_e32 v148, v148
	v_sub_u32_e32 v143, 32, v143
	v_ldexp_f32 v143, v148, v143
	v_mul_f32_e32 v143, 0x35800000, v143
	v_fmamk_f32 v143, v143, 0x3a800000, v196
	v_cmp_gt_f32_e32 vcc, s23, v143
	v_mul_f32_e32 v148, 0x4b800000, v143
	s_nop 0
	v_cndmask_b32_e32 v143, v143, v148, vcc
	v_rsq_f32_e32 v143, v143
	s_nop 0
	v_mul_f32_e32 v148, 0x45800000, v143
	v_cndmask_b32_e32 v143, v143, v148, vcc
	v_mul_f32_e32 v152, 0x3fb8aa3b, v143
	v_ashrrev_i32_e32 v143, 31, v142
	v_lshl_add_u64 v[148:149], s[8:9], 0, v[164:165]
	v_lshlrev_b64 v[142:143], 1, v[142:143]
	v_lshl_add_u64 v[154:155], v[148:149], 0, v[142:143]
	v_lshl_add_u64 v[156:157], v[156:157], 0, v[142:143]
	global_load_dwordx4 v[148:151], v[154:155], off
	global_load_dwordx4 v[160:163], v[156:157], off
	v_pk_mul_f32 v[126:127], v[126:127], v[152:153] op_sel_hi:[1,0]
	v_pk_mul_f32 v[124:125], v[124:125], v[152:153] op_sel_hi:[1,0]
	v_pk_mul_f32 v[128:129], v[128:129], v[152:153] op_sel_hi:[1,0]
	v_exp_f32_e64 v126, -v126
	v_exp_f32_e64 v127, -v127
	v_pk_mul_f32 v[130:131], v[130:131], v[152:153] op_sel_hi:[1,0]
	v_exp_f32_e64 v124, -v124
	v_exp_f32_e64 v125, -v125
	v_exp_f32_e64 v128, -v128
	v_exp_f32_e64 v129, -v129
	v_exp_f32_e64 v130, -v130
	v_exp_f32_e64 v131, -v131
	v_add_f32_e32 v126, 1.0, v126
	v_add_f32_e32 v127, 1.0, v127
	v_add_f32_e32 v124, 1.0, v124
	v_add_f32_e32 v125, 1.0, v125
	v_rcp_f32_e32 v126, v126
	v_rcp_f32_e32 v127, v127
	v_add_f32_e32 v128, 1.0, v128
	v_add_f32_e32 v129, 1.0, v129
	v_rcp_f32_e32 v124, v124
	v_rcp_f32_e32 v125, v125
	v_rcp_f32_e32 v128, v128
	v_rcp_f32_e32 v129, v129
	v_add_f32_e32 v130, 1.0, v130
	v_add_f32_e32 v131, 1.0, v131
	v_rcp_f32_e32 v130, v130
	v_rcp_f32_e32 v131, v131
	v_pk_mul_f32 v[122:123], v[122:123], v[152:153] op_sel_hi:[1,0]
	v_pk_mul_f32 v[116:117], v[116:117], v[152:153] op_sel_hi:[1,0]
	v_exp_f32_e64 v122, -v122
	v_exp_f32_e64 v123, -v123
	v_exp_f32_e64 v116, -v116
	v_exp_f32_e64 v117, -v117
	v_add_f32_e32 v122, 1.0, v122
	v_add_f32_e32 v123, 1.0, v123
	v_rcp_f32_e32 v122, v122
	v_rcp_f32_e32 v123, v123
	v_add_f32_e32 v116, 1.0, v116
	v_add_f32_e32 v117, 1.0, v117
	v_rcp_f32_e32 v116, v116
	v_rcp_f32_e32 v117, v117
	v_pk_mul_f32 v[120:121], v[120:121], v[152:153] op_sel_hi:[1,0]
	v_pk_mul_f32 v[118:119], v[118:119], v[152:153] op_sel_hi:[1,0]
	v_exp_f32_e64 v120, -v120
	v_exp_f32_e64 v121, -v121
	v_add_f32_e32 v120, 1.0, v120
	v_add_f32_e32 v121, 1.0, v121
	v_rcp_f32_e32 v120, v120
	v_rcp_f32_e32 v121, v121
	s_waitcnt vmcnt(0)
	v_lshlrev_b32_e32 v166, 16, v148
	v_and_b32_e32 v167, 0xffff0000, v148
	v_lshlrev_b32_e32 v168, 16, v160
	v_and_b32_e32 v169, 0xffff0000, v160
	v_lshlrev_b32_e32 v148, 16, v149
	v_and_b32_e32 v149, 0xffff0000, v149
	v_lshlrev_b32_e32 v160, 16, v161
	v_and_b32_e32 v161, 0xffff0000, v161
	v_pk_fma_f32 v[126:127], v[126:127], v[160:161], v[148:149]
	v_lshlrev_b32_e32 v148, 16, v150
	v_and_b32_e32 v149, 0xffff0000, v150
	v_lshlrev_b32_e32 v160, 16, v162
	v_and_b32_e32 v161, 0xffff0000, v162
	v_pk_fma_f32 v[124:125], v[124:125], v[168:169], v[166:167]
	v_pk_fma_f32 v[128:129], v[128:129], v[160:161], v[148:149]
	v_lshlrev_b32_e32 v148, 16, v151
	v_and_b32_e32 v149, 0xffff0000, v151
	v_lshlrev_b32_e32 v150, 16, v163
	v_and_b32_e32 v151, 0xffff0000, v163
	v_pk_fma_f32 v[130:131], v[130:131], v[150:151], v[148:149]
	v_mul_f32_e32 v148, v125, v125
	v_pk_fma_f32 v[148:149], v[124:125], v[124:125], v[148:149] op_sel_hi:[1,1,0]
	v_mul_f32_e32 v150, v127, v127
	v_pk_fma_f32 v[148:149], v[126:127], v[126:127], v[148:149]
	v_cvt_pk_bf16_f32 v124, v124, v125
	v_pk_add_f32 v[148:149], v[150:151], v[148:149] op_sel_hi:[0,1]
	v_pk_fma_f32 v[148:149], v[128:129], v[128:129], v[148:149]
	v_mul_f32_e32 v150, v129, v129
	v_pk_add_f32 v[148:149], v[150:151], v[148:149] op_sel_hi:[0,1]
	v_pk_fma_f32 v[148:149], v[130:131], v[130:131], v[148:149]
	v_mul_f32_e32 v150, v131, v131
	v_cvt_pk_bf16_f32 v125, v126, v127
	v_cvt_pk_bf16_f32 v126, v128, v129
	v_lshl_add_u64 v[128:129], s[46:47], 0, v[164:165]
	v_pk_add_f32 v[150:151], v[150:151], v[148:149] op_sel_hi:[0,1]
	v_cvt_pk_bf16_f32 v127, v130, v131
	v_lshl_add_u64 v[148:149], v[128:129], 0, v[142:143]
	global_store_dwordx4 v[148:149], v[124:127], off
	global_load_dwordx4 v[128:131], v[154:155], off offset:256
	global_load_dwordx4 v[124:127], v[156:157], off offset:256
	s_waitcnt vmcnt(0)
	v_lshlrev_b32_e32 v154, 16, v128
	v_and_b32_e32 v155, 0xffff0000, v128
	v_lshlrev_b32_e32 v156, 16, v124
	v_and_b32_e32 v157, 0xffff0000, v124
	v_lshlrev_b32_e32 v128, 16, v129
	v_and_b32_e32 v129, 0xffff0000, v129
	v_lshlrev_b32_e32 v124, 16, v125
	v_and_b32_e32 v125, 0xffff0000, v125
	v_pk_fma_f32 v[122:123], v[122:123], v[124:125], v[128:129]
	v_lshlrev_b32_e32 v124, 16, v130
	v_and_b32_e32 v125, 0xffff0000, v130
	v_lshlrev_b32_e32 v128, 16, v126
	v_and_b32_e32 v129, 0xffff0000, v126
	v_pk_fma_f32 v[124:125], v[116:117], v[128:129], v[124:125]
	v_exp_f32_e64 v116, -v118
	v_exp_f32_e64 v117, -v119
	v_pk_fma_f32 v[120:121], v[120:121], v[156:157], v[154:155]
	v_lshlrev_b32_e32 v118, 16, v131
	v_add_f32_e32 v116, 1.0, v116
	v_add_f32_e32 v117, 1.0, v117
	v_rcp_f32_e32 v116, v116
	v_rcp_f32_e32 v117, v117
	v_and_b32_e32 v119, 0xffff0000, v131
	v_lshlrev_b32_e32 v126, 16, v127
	v_and_b32_e32 v127, 0xffff0000, v127
	v_pk_fma_f32 v[126:127], v[116:117], v[126:127], v[118:119]
	v_pk_fma_f32 v[116:117], v[120:121], v[120:121], v[150:151]
	v_mul_f32_e32 v118, v121, v121
	v_pk_add_f32 v[116:117], v[118:119], v[116:117] op_sel_hi:[0,1]
	v_pk_fma_f32 v[116:117], v[122:123], v[122:123], v[116:117]
	v_mul_f32_e32 v118, v123, v123
	v_pk_add_f32 v[116:117], v[118:119], v[116:117] op_sel_hi:[0,1]
	v_pk_fma_f32 v[116:117], v[124:125], v[124:125], v[116:117]
	v_mul_f32_e32 v118, v125, v125
	v_pk_add_f32 v[116:117], v[118:119], v[116:117] op_sel_hi:[0,1]
	v_pk_fma_f32 v[116:117], v[126:127], v[126:127], v[116:117]
	v_mul_f32_e32 v118, v127, v127
	v_pk_add_f32 v[128:129], v[118:119], v[116:117] op_sel_hi:[0,1]
	v_cvt_pk_bf16_f32 v116, v120, v121
	v_cvt_pk_bf16_f32 v117, v122, v123
	v_cvt_pk_bf16_f32 v118, v124, v125
	v_cvt_pk_bf16_f32 v119, v126, v127
	global_store_dwordx4 v[148:149], v[116:119], off offset:256
	s_nop 1
	v_mov_b32_e32 v116, v128
	s_nop 1
	v_permlane16_swap_b32_e32 v128, v116
	v_add_f32_e32 v116, v128, v116
	v_mov_b32_e32 v117, v116
	s_nop 1
	v_permlane32_swap_b32_e32 v116, v117
	s_and_saveexec_b64 s[34:35], s[42:43]
	s_cbranch_execz .LBB0_1858
; __device__ __forceinline__ unsigned pk2(float lo, float hi) { f32x2 v = {lo, hi}; bf16x2_t b = __builtin_convertvector(v, bf16x2_t); return __builtin_bit_cast(unsigned, b); }
; __device__ __forceinline__ float bflo(unsigned u) { return __uint_as_float(u << 16); }
; __device__ __forceinline__ float bfhi(unsigned u) { return __uint_as_float(u & 0xffff0000u); }
; __device__ __forceinline__ float ex2(float x) { return __builtin_amdgcn_exp2f(x); }
; __device__ __forceinline__ float rcpf_(float x) { return __builtin_amdgcn_rcpf(x); }
;     __device__ __forceinline__ void operator()(const f32x4 (&acc)[2][2][4][2], const pg8::Unit& u, int wr, int wc, int fr, int fq) const {
;     ...
;             for (int m = 0; m < 4; ++m) {
;                 const int row = u.pm * 256 + ai * 128 + wr * 64 + m * 16 + fr;
;                 const float r = rsqrtf(ssf(SSin + row) * (1.0f / D) + EPS) * LOG2E;
;                 float ss = 0.f;
; #pragma unroll
;                 for (int bj = 0; bj < 2; ++bj) {
;                     const int col = u.pn * 256 + bj * 128 + wc * 32 + fq * 8;
;                     const u32x4 hw = *(const u32x4*)(Hin + (size_t)row * D + col);
;                     const u32x4 pw = *(const u32x4*)(PP_ + (size_t)row * D + col);
;                     const f32x4 a0 = acc[ai][bj][m][0] * r, a1 = acc[ai][bj][m][1] * r;
;                     float h[8];
;                     h[0] = bflo(hw.x) + rcpf_(1.0f + ex2(-a0[0])) * bflo(pw.x); h[1] = bfhi(hw.x) + rcpf_(1.0f + ex2(-a0[1])) * bfhi(pw.x);
;                     h[2] = bflo(hw.y) + rcpf_(1.0f + ex2(-a0[2])) * bflo(pw.y); h[3] = bfhi(hw.y) + rcpf_(1.0f + ex2(-a0[3])) * bfhi(pw.y);
;                     h[4] = bflo(hw.z) + rcpf_(1.0f + ex2(-a1[0])) * bflo(pw.z); h[5] = bfhi(hw.z) + rcpf_(1.0f + ex2(-a1[1])) * bfhi(pw.z);
;                     h[6] = bflo(hw.w) + rcpf_(1.0f + ex2(-a1[2])) * bflo(pw.w); h[7] = bfhi(hw.w) + rcpf_(1.0f + ex2(-a1[3])) * bfhi(pw.w);
; #pragma unroll
;                     for (int i = 0; i < 8; ++i) ss += h[i] * h[i];
;                     u32x4 w; w.x = pk2(h[0], h[1]); w.y = pk2(h[2], h[3]); w.z = pk2(h[4], h[5]); w.w = pk2(h[6], h[7]);
;                     *(u32x4*)(Hout + (size_t)row * D + col) = w;
;                 }
;                 ss = xor16_sum(ss); ss = xor32_sum(ss);
;                 if (fq == 0) atomic_addf(SSout + row, ss);
	v_add_f32_e32 v116, v116, v117
	s_mov_b32 s1, 0x49800000
	v_fma_f32 v116, v116, s1, 0.5
	v_trunc_f32_e32 v116, v116
	v_mul_f32_e32 v117, 0x2f800000, v116
	v_floor_f32_e32 v117, v117
	v_fmac_f32_e32 v116, 0xcf800000, v117
	v_cvt_u32_f32_e32 v116, v116
	v_cvt_u32_f32_e32 v117, v117
	v_lshl_add_u64 v[118:119], v[146:147], 3, s[52:53]
	global_atomic_add_x2 v[118:119], v[116:117], off
.LBB0_1858:
	s_or_b64 exec, exec, s[34:35]
	global_load_dwordx2 v[118:119], v[144:145], off offset:128
	v_or_b32_e32 v116, 16, v146
	v_ashrrev_i32_e32 v117, 31, v116
	v_lshlrev_b64 v[148:149], 11, v[116:117]
	v_lshl_add_u64 v[126:127], s[48:49], 0, v[148:149]
	v_lshl_add_u64 v[126:127], v[126:127], 0, v[142:143]
	global_load_dwordx4 v[128:131], v[126:127], off
	s_waitcnt vmcnt(0)
	v_ffbh_u32_e32 v120, v119
	v_min_u32_e32 v120, 32, v120
	v_lshlrev_b64 v[118:119], v120, v[118:119]
	v_min_u32_e32 v118, 1, v118
	v_or_b32_e32 v118, v119, v118
	v_cvt_f32_u32_e32 v118, v118
	v_sub_u32_e32 v119, 32, v120
	v_lshlrev_b32_e32 v154, 16, v128
	v_and_b32_e32 v155, 0xffff0000, v128
	v_ldexp_f32 v118, v118, v119
	v_mul_f32_e32 v118, 0x35800000, v118
	v_fmamk_f32 v118, v118, 0x3a800000, v196
	v_cmp_gt_f32_e32 vcc, s23, v118
	v_mul_f32_e32 v119, 0x4b800000, v118
	v_lshlrev_b32_e32 v128, 16, v129
	v_cndmask_b32_e32 v118, v118, v119, vcc
	v_rsq_f32_e32 v118, v118
	v_and_b32_e32 v129, 0xffff0000, v129
	v_mul_f32_e32 v119, 0x45800000, v118
	v_cndmask_b32_e32 v118, v118, v119, vcc
	v_mul_f32_e32 v122, 0x3fb8aa3b, v118
	v_lshl_add_u64 v[118:119], s[8:9], 0, v[148:149]
	v_lshl_add_u64 v[124:125], v[118:119], 0, v[142:143]
	global_load_dwordx4 v[118:121], v[124:125], off
	v_pk_mul_f32 v[114:115], v[114:115], v[122:123] op_sel_hi:[1,0]
	v_pk_mul_f32 v[108:109], v[108:109], v[122:123] op_sel_hi:[1,0]
	v_exp_f32_e64 v114, -v114
	v_exp_f32_e64 v115, -v115
	v_exp_f32_e64 v108, -v108
	v_exp_f32_e64 v109, -v109
	v_add_f32_e32 v114, 1.0, v114
	v_add_f32_e32 v115, 1.0, v115
	v_rcp_f32_e32 v114, v114
	v_rcp_f32_e32 v115, v115
	v_add_f32_e32 v108, 1.0, v108
	v_add_f32_e32 v109, 1.0, v109
	v_rcp_f32_e32 v108, v108
	v_rcp_f32_e32 v109, v109
	v_pk_mul_f32 v[112:113], v[112:113], v[122:123] op_sel_hi:[1,0]
	v_pk_mul_f32 v[110:111], v[110:111], v[122:123] op_sel_hi:[1,0]
	v_exp_f32_e64 v112, -v112
	v_exp_f32_e64 v113, -v113
	v_pk_mul_f32 v[106:107], v[106:107], v[122:123] op_sel_hi:[1,0]
	v_pk_mul_f32 v[100:101], v[100:101], v[122:123] op_sel_hi:[1,0]
	v_add_f32_e32 v112, 1.0, v112
	v_add_f32_e32 v113, 1.0, v113
	v_rcp_f32_e32 v112, v112
	v_rcp_f32_e32 v113, v113
	v_exp_f32_e64 v106, -v106
	v_exp_f32_e64 v107, -v107
	v_exp_f32_e64 v100, -v100
	v_exp_f32_e64 v101, -v101
	v_add_f32_e32 v106, 1.0, v106
	v_add_f32_e32 v107, 1.0, v107
	v_rcp_f32_e32 v106, v106
	v_rcp_f32_e32 v107, v107
	v_add_f32_e32 v100, 1.0, v100
	v_add_f32_e32 v101, 1.0, v101
	v_rcp_f32_e32 v100, v100
	v_rcp_f32_e32 v101, v101
	v_pk_mul_f32 v[104:105], v[104:105], v[122:123] op_sel_hi:[1,0]
	v_pk_mul_f32 v[102:103], v[102:103], v[122:123] op_sel_hi:[1,0]
	v_exp_f32_e64 v104, -v104
	v_exp_f32_e64 v105, -v105
	v_add_f32_e32 v104, 1.0, v104
	v_add_f32_e32 v105, 1.0, v105
	v_rcp_f32_e32 v104, v104
	v_rcp_f32_e32 v105, v105
	s_waitcnt vmcnt(0)
	v_lshlrev_b32_e32 v150, 16, v118
	v_and_b32_e32 v151, 0xffff0000, v118
	v_lshlrev_b32_e32 v118, 16, v119
	v_and_b32_e32 v119, 0xffff0000, v119
	v_pk_fma_f32 v[114:115], v[114:115], v[128:129], v[118:119]
	v_lshlrev_b32_e32 v118, 16, v120
	v_and_b32_e32 v119, 0xffff0000, v120
	v_lshlrev_b32_e32 v128, 16, v130
	v_and_b32_e32 v129, 0xffff0000, v130
	v_pk_fma_f32 v[118:119], v[108:109], v[128:129], v[118:119]
	v_exp_f32_e64 v108, -v110
	v_exp_f32_e64 v109, -v111
	v_pk_fma_f32 v[112:113], v[112:113], v[154:155], v[150:151]
	v_lshlrev_b32_e32 v110, 16, v121
	v_add_f32_e32 v108, 1.0, v108
	v_add_f32_e32 v109, 1.0, v109
	v_rcp_f32_e32 v108, v108
	v_rcp_f32_e32 v109, v109
	v_and_b32_e32 v111, 0xffff0000, v121
	v_lshlrev_b32_e32 v120, 16, v131
	v_and_b32_e32 v121, 0xffff0000, v131
	v_pk_fma_f32 v[128:129], v[108:109], v[120:121], v[110:111]
	v_mul_f32_e32 v108, v113, v113
	v_pk_fma_f32 v[108:109], v[112:113], v[112:113], v[108:109] op_sel_hi:[1,1,0]
	v_mul_f32_e32 v110, v115, v115
	v_pk_fma_f32 v[108:109], v[114:115], v[114:115], v[108:109]
	s_nop 0
	v_pk_add_f32 v[108:109], v[110:111], v[108:109] op_sel_hi:[0,1]
	v_pk_fma_f32 v[108:109], v[118:119], v[118:119], v[108:109]
	v_mul_f32_e32 v110, v119, v119
	v_pk_add_f32 v[108:109], v[110:111], v[108:109] op_sel_hi:[0,1]
	v_pk_fma_f32 v[108:109], v[128:129], v[128:129], v[108:109]
	v_mul_f32_e32 v110, v129, v129
	v_pk_add_f32 v[120:121], v[110:111], v[108:109] op_sel_hi:[0,1]
	v_cvt_pk_bf16_f32 v108, v112, v113
	v_lshl_add_u64 v[112:113], s[46:47], 0, v[148:149]
	v_cvt_pk_bf16_f32 v109, v114, v115
	v_cvt_pk_bf16_f32 v110, v118, v119
	v_cvt_pk_bf16_f32 v111, v128, v129
	v_lshl_add_u64 v[118:119], v[112:113], 0, v[142:143]
	global_store_dwordx4 v[118:119], v[108:111], off
	global_load_dwordx4 v[112:115], v[124:125], off offset:256
	global_load_dwordx4 v[108:111], v[126:127], off offset:256
	s_waitcnt vmcnt(0)
; __device__ __forceinline__ unsigned pk2(float lo, float hi) { f32x2 v = {lo, hi}; bf16x2_t b = __builtin_convertvector(v, bf16x2_t); return __builtin_bit_cast(unsigned, b); }
; __device__ __forceinline__ float bflo(unsigned u) { return __uint_as_float(u << 16); }
; __device__ __forceinline__ float bfhi(unsigned u) { return __uint_as_float(u & 0xffff0000u); }
; __device__ __forceinline__ float ex2(float x) { return __builtin_amdgcn_exp2f(x); }
; __device__ __forceinline__ float rcpf_(float x) { return __builtin_amdgcn_rcpf(x); }
;     __device__ __forceinline__ void operator()(const f32x4 (&acc)[2][2][4][2], const pg8::Unit& u, int wr, int wc, int fr, int fq) const {
;     ...
;             for (int m = 0; m < 4; ++m) {
;                 const int row = u.pm * 256 + ai * 128 + wr * 64 + m * 16 + fr;
;                 const float r = rsqrtf(ssf(SSin + row) * (1.0f / D) + EPS) * LOG2E;
;                 float ss = 0.f;
; #pragma unroll
;                 for (int bj = 0; bj < 2; ++bj) {
;                     const int col = u.pn * 256 + bj * 128 + wc * 32 + fq * 8;
;                     const u32x4 hw = *(const u32x4*)(Hin + (size_t)row * D + col);
;                     const u32x4 pw = *(const u32x4*)(PP_ + (size_t)row * D + col);
;                     const f32x4 a0 = acc[ai][bj][m][0] * r, a1 = acc[ai][bj][m][1] * r;
;                     float h[8];
;                     h[0] = bflo(hw.x) + rcpf_(1.0f + ex2(-a0[0])) * bflo(pw.x); h[1] = bfhi(hw.x) + rcpf_(1.0f + ex2(-a0[1])) * bfhi(pw.x);
;                     h[2] = bflo(hw.y) + rcpf_(1.0f + ex2(-a0[2])) * bflo(pw.y); h[3] = bfhi(hw.y) + rcpf_(1.0f + ex2(-a0[3])) * bfhi(pw.y);
;                     h[4] = bflo(hw.z) + rcpf_(1.0f + ex2(-a1[0])) * bflo(pw.z); h[5] = bfhi(hw.z) + rcpf_(1.0f + ex2(-a1[1])) * bfhi(pw.z);
;                     h[6] = bflo(hw.w) + rcpf_(1.0f + ex2(-a1[2])) * bflo(pw.w); h[7] = bfhi(hw.w) + rcpf_(1.0f + ex2(-a1[3])) * bfhi(pw.w);
; #pragma unroll
;                     for (int i = 0; i < 8; ++i) ss += h[i] * h[i];
;                     u32x4 w; w.x = pk2(h[0], h[1]); w.y = pk2(h[2], h[3]); w.z = pk2(h[4], h[5]); w.w = pk2(h[6], h[7]);
;                     *(u32x4*)(Hout + (size_t)row * D + col) = w;
;                 }
;                 ss = xor16_sum(ss); ss = xor32_sum(ss);
;                 if (fq == 0) atomic_addf(SSout + row, ss);
	v_lshlrev_b32_e32 v122, 16, v112
	v_and_b32_e32 v123, 0xffff0000, v112
	v_lshlrev_b32_e32 v124, 16, v108
	v_and_b32_e32 v125, 0xffff0000, v108
	v_lshlrev_b32_e32 v112, 16, v113
	v_and_b32_e32 v113, 0xffff0000, v113
	v_lshlrev_b32_e32 v108, 16, v109
	v_and_b32_e32 v109, 0xffff0000, v109
	v_pk_fma_f32 v[106:107], v[106:107], v[108:109], v[112:113]
	v_lshlrev_b32_e32 v108, 16, v114
	v_and_b32_e32 v109, 0xffff0000, v114
	v_lshlrev_b32_e32 v112, 16, v110
	v_and_b32_e32 v113, 0xffff0000, v110
	v_pk_fma_f32 v[108:109], v[100:101], v[112:113], v[108:109]
	v_exp_f32_e64 v100, -v102
	v_exp_f32_e64 v101, -v103
	v_pk_fma_f32 v[104:105], v[104:105], v[124:125], v[122:123]
	v_lshlrev_b32_e32 v102, 16, v115
	v_add_f32_e32 v100, 1.0, v100
	v_add_f32_e32 v101, 1.0, v101
	v_rcp_f32_e32 v100, v100
	v_rcp_f32_e32 v101, v101
	v_and_b32_e32 v103, 0xffff0000, v115
	v_lshlrev_b32_e32 v110, 16, v111
	v_and_b32_e32 v111, 0xffff0000, v111
	v_pk_fma_f32 v[110:111], v[100:101], v[110:111], v[102:103]
	v_pk_fma_f32 v[100:101], v[104:105], v[104:105], v[120:121]
	v_mul_f32_e32 v102, v105, v105
	v_pk_add_f32 v[100:101], v[102:103], v[100:101] op_sel_hi:[0,1]
	v_pk_fma_f32 v[100:101], v[106:107], v[106:107], v[100:101]
	v_mul_f32_e32 v102, v107, v107
	v_pk_add_f32 v[100:101], v[102:103], v[100:101] op_sel_hi:[0,1]
	v_pk_fma_f32 v[100:101], v[108:109], v[108:109], v[100:101]
	v_mul_f32_e32 v102, v109, v109
	v_pk_add_f32 v[100:101], v[102:103], v[100:101] op_sel_hi:[0,1]
	v_pk_fma_f32 v[100:101], v[110:111], v[110:111], v[100:101]
	v_mul_f32_e32 v102, v111, v111
	v_pk_add_f32 v[112:113], v[102:103], v[100:101] op_sel_hi:[0,1]
	v_cvt_pk_bf16_f32 v100, v104, v105
	v_cvt_pk_bf16_f32 v101, v106, v107
	v_cvt_pk_bf16_f32 v102, v108, v109
	v_cvt_pk_bf16_f32 v103, v110, v111
	global_store_dwordx4 v[118:119], v[100:103], off offset:256
	s_nop 1
	v_mov_b32_e32 v100, v112
	s_nop 1
	v_permlane16_swap_b32_e32 v112, v100
	v_add_f32_e32 v100, v112, v100
	v_mov_b32_e32 v101, v100
	s_nop 1
	v_permlane32_swap_b32_e32 v100, v101
	s_and_saveexec_b64 s[34:35], s[42:43]
	s_cbranch_execz .LBB0_1860
	v_add_f32_e32 v100, v100, v101
	s_mov_b32 s1, 0x49800000
	v_fma_f32 v100, v100, s1, 0.5
	v_trunc_f32_e32 v100, v100
	v_mul_f32_e32 v101, 0x2f800000, v100
	v_floor_f32_e32 v101, v101
	v_fmac_f32_e32 v100, 0xcf800000, v101
	v_cvt_u32_f32_e32 v100, v100
	v_cvt_u32_f32_e32 v101, v101
	v_lshl_add_u64 v[102:103], v[116:117], 3, s[52:53]
	global_atomic_add_x2 v[102:103], v[100:101], off
.LBB0_1860:
	s_or_b64 exec, exec, s[34:35]
	global_load_dwordx2 v[102:103], v[144:145], off offset:256
	v_or_b32_e32 v100, 32, v146
	v_ashrrev_i32_e32 v101, 31, v100
	v_lshlrev_b64 v[116:117], 11, v[100:101]
	v_lshl_add_u64 v[110:111], s[48:49], 0, v[116:117]
	v_lshl_add_u64 v[110:111], v[110:111], 0, v[142:143]
	global_load_dwordx4 v[112:115], v[110:111], off
	s_waitcnt vmcnt(0)
	v_ffbh_u32_e32 v104, v103
	v_min_u32_e32 v104, 32, v104
	v_lshlrev_b64 v[102:103], v104, v[102:103]
	v_min_u32_e32 v102, 1, v102
	v_or_b32_e32 v102, v103, v102
	v_cvt_f32_u32_e32 v102, v102
	v_sub_u32_e32 v103, 32, v104
	v_lshlrev_b32_e32 v120, 16, v112
	v_and_b32_e32 v121, 0xffff0000, v112
	v_ldexp_f32 v102, v102, v103
	v_mul_f32_e32 v102, 0x35800000, v102
	v_fmamk_f32 v102, v102, 0x3a800000, v196
	v_cmp_gt_f32_e32 vcc, s23, v102
	v_mul_f32_e32 v103, 0x4b800000, v102
	v_lshlrev_b32_e32 v112, 16, v113
	v_cndmask_b32_e32 v102, v102, v103, vcc
	v_rsq_f32_e32 v102, v102
	v_and_b32_e32 v113, 0xffff0000, v113
	v_mul_f32_e32 v103, 0x45800000, v102
	v_cndmask_b32_e32 v102, v102, v103, vcc
	v_mul_f32_e32 v106, 0x3fb8aa3b, v102
	v_lshl_add_u64 v[102:103], s[8:9], 0, v[116:117]
	v_lshl_add_u64 v[108:109], v[102:103], 0, v[142:143]
	global_load_dwordx4 v[102:105], v[108:109], off
	v_pk_mul_f32 v[96:97], v[96:97], v[106:107] op_sel_hi:[1,0]
	v_pk_mul_f32 v[90:91], v[90:91], v[106:107] op_sel_hi:[1,0]
	v_exp_f32_e64 v96, -v96
	v_exp_f32_e64 v97, -v97
	v_exp_f32_e64 v90, -v90
	v_exp_f32_e64 v91, -v91
	v_add_f32_e32 v96, 1.0, v96
	v_add_f32_e32 v97, 1.0, v97
	v_rcp_f32_e32 v96, v96
	v_rcp_f32_e32 v97, v97
	v_add_f32_e32 v90, 1.0, v90
	v_add_f32_e32 v91, 1.0, v91
	v_rcp_f32_e32 v90, v90
	v_rcp_f32_e32 v91, v91
	v_pk_mul_f32 v[94:95], v[94:95], v[106:107] op_sel_hi:[1,0]
	v_pk_mul_f32 v[92:93], v[92:93], v[106:107] op_sel_hi:[1,0]
	v_exp_f32_e64 v94, -v94
	v_exp_f32_e64 v95, -v95
	v_pk_mul_f32 v[88:89], v[88:89], v[106:107] op_sel_hi:[1,0]
	v_pk_mul_f32 v[82:83], v[82:83], v[106:107] op_sel_hi:[1,0]
	v_add_f32_e32 v94, 1.0, v94
	v_add_f32_e32 v95, 1.0, v95
	v_rcp_f32_e32 v94, v94
	v_rcp_f32_e32 v95, v95
	v_exp_f32_e64 v88, -v88
	v_exp_f32_e64 v89, -v89
	v_exp_f32_e64 v82, -v82
	v_exp_f32_e64 v83, -v83
	v_add_f32_e32 v88, 1.0, v88
	v_add_f32_e32 v89, 1.0, v89
	v_rcp_f32_e32 v88, v88
	v_rcp_f32_e32 v89, v89
	v_add_f32_e32 v82, 1.0, v82
	v_add_f32_e32 v83, 1.0, v83
	v_rcp_f32_e32 v82, v82
	v_rcp_f32_e32 v83, v83
	v_pk_mul_f32 v[86:87], v[86:87], v[106:107] op_sel_hi:[1,0]
	v_pk_mul_f32 v[84:85], v[84:85], v[106:107] op_sel_hi:[1,0]
	v_exp_f32_e64 v86, -v86
	v_exp_f32_e64 v87, -v87
	v_add_f32_e32 v86, 1.0, v86
	v_add_f32_e32 v87, 1.0, v87
	v_rcp_f32_e32 v86, v86
	v_rcp_f32_e32 v87, v87
	s_waitcnt vmcnt(0)
; __device__ __forceinline__ unsigned pk2(float lo, float hi) { f32x2 v = {lo, hi}; bf16x2_t b = __builtin_convertvector(v, bf16x2_t); return __builtin_bit_cast(unsigned, b); }
; __device__ __forceinline__ float bflo(unsigned u) { return __uint_as_float(u << 16); }
; __device__ __forceinline__ float bfhi(unsigned u) { return __uint_as_float(u & 0xffff0000u); }
; __device__ __forceinline__ float ex2(float x) { return __builtin_amdgcn_exp2f(x); }
; __device__ __forceinline__ float rcpf_(float x) { return __builtin_amdgcn_rcpf(x); }
;     __device__ __forceinline__ void operator()(const f32x4 (&acc)[2][2][4][2], const pg8::Unit& u, int wr, int wc, int fr, int fq) const {
;     ...
;             for (int m = 0; m < 4; ++m) {
;                 const int row = u.pm * 256 + ai * 128 + wr * 64 + m * 16 + fr;
;                 const float r = rsqrtf(ssf(SSin + row) * (1.0f / D) + EPS) * LOG2E;
;                 float ss = 0.f;
; #pragma unroll
;                 for (int bj = 0; bj < 2; ++bj) {
;                     const int col = u.pn * 256 + bj * 128 + wc * 32 + fq * 8;
;                     const u32x4 hw = *(const u32x4*)(Hin + (size_t)row * D + col);
;                     const u32x4 pw = *(const u32x4*)(PP_ + (size_t)row * D + col);
;                     const f32x4 a0 = acc[ai][bj][m][0] * r, a1 = acc[ai][bj][m][1] * r;
;                     float h[8];
;                     h[0] = bflo(hw.x) + rcpf_(1.0f + ex2(-a0[0])) * bflo(pw.x); h[1] = bfhi(hw.x) + rcpf_(1.0f + ex2(-a0[1])) * bfhi(pw.x);
;                     h[2] = bflo(hw.y) + rcpf_(1.0f + ex2(-a0[2])) * bflo(pw.y); h[3] = bfhi(hw.y) + rcpf_(1.0f + ex2(-a0[3])) * bfhi(pw.y);
;                     h[4] = bflo(hw.z) + rcpf_(1.0f + ex2(-a1[0])) * bflo(pw.z); h[5] = bfhi(hw.z) + rcpf_(1.0f + ex2(-a1[1])) * bfhi(pw.z);
;                     h[6] = bflo(hw.w) + rcpf_(1.0f + ex2(-a1[2])) * bflo(pw.w); h[7] = bfhi(hw.w) + rcpf_(1.0f + ex2(-a1[3])) * bfhi(pw.w);
; #pragma unroll
;                     for (int i = 0; i < 8; ++i) ss += h[i] * h[i];
;                     u32x4 w; w.x = pk2(h[0], h[1]); w.y = pk2(h[2], h[3]); w.z = pk2(h[4], h[5]); w.w = pk2(h[6], h[7]);
;                     *(u32x4*)(Hout + (size_t)row * D + col) = w;
;                 }
;                 ss = xor16_sum(ss); ss = xor32_sum(ss);
;                 if (fq == 0) atomic_addf(SSout + row, ss);
	v_lshlrev_b32_e32 v118, 16, v102
	v_and_b32_e32 v119, 0xffff0000, v102
	v_lshlrev_b32_e32 v102, 16, v103
	v_and_b32_e32 v103, 0xffff0000, v103
	v_pk_fma_f32 v[96:97], v[96:97], v[112:113], v[102:103]
	v_lshlrev_b32_e32 v102, 16, v104
	v_and_b32_e32 v103, 0xffff0000, v104
	v_lshlrev_b32_e32 v112, 16, v114
	v_and_b32_e32 v113, 0xffff0000, v114
	v_pk_fma_f32 v[102:103], v[90:91], v[112:113], v[102:103]
	v_exp_f32_e64 v90, -v92
	v_exp_f32_e64 v91, -v93
	v_pk_fma_f32 v[94:95], v[94:95], v[120:121], v[118:119]
	v_lshlrev_b32_e32 v92, 16, v105
	v_add_f32_e32 v90, 1.0, v90
	v_add_f32_e32 v91, 1.0, v91
	v_rcp_f32_e32 v90, v90
	v_rcp_f32_e32 v91, v91
	v_and_b32_e32 v93, 0xffff0000, v105
	v_lshlrev_b32_e32 v104, 16, v115
	v_and_b32_e32 v105, 0xffff0000, v115
	v_pk_fma_f32 v[112:113], v[90:91], v[104:105], v[92:93]
	v_mul_f32_e32 v90, v95, v95
	v_pk_fma_f32 v[90:91], v[94:95], v[94:95], v[90:91] op_sel_hi:[1,1,0]
	v_mul_f32_e32 v92, v97, v97
	v_pk_fma_f32 v[90:91], v[96:97], v[96:97], v[90:91]
	s_nop 0
	v_pk_add_f32 v[90:91], v[92:93], v[90:91] op_sel_hi:[0,1]
	v_pk_fma_f32 v[90:91], v[102:103], v[102:103], v[90:91]
	v_mul_f32_e32 v92, v103, v103
	v_pk_add_f32 v[90:91], v[92:93], v[90:91] op_sel_hi:[0,1]
	v_pk_fma_f32 v[90:91], v[112:113], v[112:113], v[90:91]
	v_mul_f32_e32 v92, v113, v113
	v_pk_add_f32 v[104:105], v[92:93], v[90:91] op_sel_hi:[0,1]
	v_cvt_pk_bf16_f32 v90, v94, v95
	v_lshl_add_u64 v[94:95], s[46:47], 0, v[116:117]
	v_cvt_pk_bf16_f32 v91, v96, v97
	v_cvt_pk_bf16_f32 v92, v102, v103
	v_cvt_pk_bf16_f32 v93, v112, v113
	v_lshl_add_u64 v[102:103], v[94:95], 0, v[142:143]
	global_store_dwordx4 v[102:103], v[90:93], off
	global_load_dwordx4 v[94:97], v[108:109], off offset:256
	global_load_dwordx4 v[90:93], v[110:111], off offset:256
	s_waitcnt vmcnt(0)
	v_lshlrev_b32_e32 v106, 16, v94
	v_and_b32_e32 v107, 0xffff0000, v94
	v_lshlrev_b32_e32 v108, 16, v90
	v_and_b32_e32 v109, 0xffff0000, v90
	v_lshlrev_b32_e32 v94, 16, v95
	v_and_b32_e32 v95, 0xffff0000, v95
	v_lshlrev_b32_e32 v90, 16, v91
	v_and_b32_e32 v91, 0xffff0000, v91
	v_pk_fma_f32 v[88:89], v[88:89], v[90:91], v[94:95]
	v_lshlrev_b32_e32 v90, 16, v96
	v_and_b32_e32 v91, 0xffff0000, v96
	v_lshlrev_b32_e32 v94, 16, v92
	v_and_b32_e32 v95, 0xffff0000, v92
	v_pk_fma_f32 v[90:91], v[82:83], v[94:95], v[90:91]
	v_exp_f32_e64 v82, -v84
	v_exp_f32_e64 v83, -v85
	v_pk_fma_f32 v[86:87], v[86:87], v[108:109], v[106:107]
	v_lshlrev_b32_e32 v84, 16, v97
	v_add_f32_e32 v82, 1.0, v82
	v_add_f32_e32 v83, 1.0, v83
	v_rcp_f32_e32 v82, v82
	v_rcp_f32_e32 v83, v83
	v_and_b32_e32 v85, 0xffff0000, v97
	v_lshlrev_b32_e32 v92, 16, v93
	v_and_b32_e32 v93, 0xffff0000, v93
	v_pk_fma_f32 v[92:93], v[82:83], v[92:93], v[84:85]
	v_pk_fma_f32 v[82:83], v[86:87], v[86:87], v[104:105]
	v_mul_f32_e32 v84, v87, v87
	v_pk_add_f32 v[82:83], v[84:85], v[82:83] op_sel_hi:[0,1]
	v_pk_fma_f32 v[82:83], v[88:89], v[88:89], v[82:83]
	v_mul_f32_e32 v84, v89, v89
	v_pk_add_f32 v[82:83], v[84:85], v[82:83] op_sel_hi:[0,1]
	v_pk_fma_f32 v[82:83], v[90:91], v[90:91], v[82:83]
	v_mul_f32_e32 v84, v91, v91
	v_pk_add_f32 v[82:83], v[84:85], v[82:83] op_sel_hi:[0,1]
	v_pk_fma_f32 v[82:83], v[92:93], v[92:93], v[82:83]
	v_mul_f32_e32 v84, v93, v93
	v_pk_add_f32 v[94:95], v[84:85], v[82:83] op_sel_hi:[0,1]
	v_cvt_pk_bf16_f32 v82, v86, v87
	v_cvt_pk_bf16_f32 v83, v88, v89
	v_cvt_pk_bf16_f32 v84, v90, v91
	v_cvt_pk_bf16_f32 v85, v92, v93
	global_store_dwordx4 v[102:103], v[82:85], off offset:256
	s_nop 1
	v_mov_b32_e32 v82, v94
	s_nop 1
	v_permlane16_swap_b32_e32 v94, v82
	v_add_f32_e32 v82, v94, v82
	v_mov_b32_e32 v83, v82
	s_nop 1
	v_permlane32_swap_b32_e32 v82, v83
	s_and_saveexec_b64 s[34:35], s[42:43]
	s_cbranch_execz .LBB0_1862
	v_add_f32_e32 v82, v82, v83
	s_mov_b32 s1, 0x49800000
	v_fma_f32 v82, v82, s1, 0.5
	v_trunc_f32_e32 v82, v82
	v_mul_f32_e32 v83, 0x2f800000, v82
	v_floor_f32_e32 v83, v83
	v_fmac_f32_e32 v82, 0xcf800000, v83
	v_cvt_u32_f32_e32 v82, v82
	v_cvt_u32_f32_e32 v83, v83
	v_lshl_add_u64 v[84:85], v[100:101], 3, s[52:53]
	global_atomic_add_x2 v[84:85], v[82:83], off
.LBB0_1862:
	s_or_b64 exec, exec, s[34:35]
	global_load_dwordx2 v[84:85], v[144:145], off offset:384
	v_or_b32_e32 v82, 48, v146
	v_ashrrev_i32_e32 v83, 31, v82
	v_lshlrev_b64 v[100:101], 11, v[82:83]
	v_lshl_add_u64 v[92:93], s[48:49], 0, v[100:101]
	v_lshl_add_u64 v[92:93], v[92:93], 0, v[142:143]
	global_load_dwordx4 v[94:97], v[92:93], off
	s_waitcnt vmcnt(0)
	v_ffbh_u32_e32 v86, v85
	v_min_u32_e32 v86, 32, v86
	v_lshlrev_b64 v[84:85], v86, v[84:85]
	v_min_u32_e32 v84, 1, v84
	v_or_b32_e32 v84, v85, v84
	v_cvt_f32_u32_e32 v84, v84
	v_sub_u32_e32 v85, 32, v86
	v_lshlrev_b32_e32 v104, 16, v94
	v_and_b32_e32 v105, 0xffff0000, v94
	v_ldexp_f32 v84, v84, v85
	v_mul_f32_e32 v84, 0x35800000, v84
	v_fmamk_f32 v84, v84, 0x3a800000, v196
	v_cmp_gt_f32_e32 vcc, s23, v84
	v_mul_f32_e32 v85, 0x4b800000, v84
	v_lshlrev_b32_e32 v94, 16, v95
	v_cndmask_b32_e32 v84, v84, v85, vcc
	v_rsq_f32_e32 v84, v84
	v_and_b32_e32 v95, 0xffff0000, v95
	v_mul_f32_e32 v85, 0x45800000, v84
	v_cndmask_b32_e32 v84, v84, v85, vcc
	v_mul_f32_e32 v88, 0x3fb8aa3b, v84
	v_lshl_add_u64 v[84:85], s[8:9], 0, v[100:101]
	v_lshl_add_u64 v[90:91], v[84:85], 0, v[142:143]
	global_load_dwordx4 v[84:87], v[90:91], off
	v_pk_mul_f32 v[80:81], v[80:81], v[88:89] op_sel_hi:[1,0]
	v_pk_mul_f32 v[74:75], v[74:75], v[88:89] op_sel_hi:[1,0]
	v_exp_f32_e64 v80, -v80
	v_exp_f32_e64 v81, -v81
	v_exp_f32_e64 v74, -v74
	v_exp_f32_e64 v75, -v75
	v_add_f32_e32 v80, 1.0, v80
	v_add_f32_e32 v81, 1.0, v81
	v_rcp_f32_e32 v80, v80
	v_rcp_f32_e32 v81, v81
	v_add_f32_e32 v74, 1.0, v74
	v_add_f32_e32 v75, 1.0, v75
	v_rcp_f32_e32 v74, v74
	v_rcp_f32_e32 v75, v75
	v_pk_mul_f32 v[78:79], v[78:79], v[88:89] op_sel_hi:[1,0]
	v_pk_mul_f32 v[76:77], v[76:77], v[88:89] op_sel_hi:[1,0]
	v_exp_f32_e64 v78, -v78
	v_exp_f32_e64 v79, -v79
	v_pk_mul_f32 v[72:73], v[72:73], v[88:89] op_sel_hi:[1,0]
	v_pk_mul_f32 v[66:67], v[66:67], v[88:89] op_sel_hi:[1,0]
	v_add_f32_e32 v78, 1.0, v78
	v_add_f32_e32 v79, 1.0, v79
	v_rcp_f32_e32 v78, v78
	v_rcp_f32_e32 v79, v79
	v_exp_f32_e64 v72, -v72
	v_exp_f32_e64 v73, -v73
	v_exp_f32_e64 v66, -v66
	v_exp_f32_e64 v67, -v67
	v_add_f32_e32 v72, 1.0, v72
	v_add_f32_e32 v73, 1.0, v73
	v_rcp_f32_e32 v72, v72
	v_rcp_f32_e32 v73, v73
	v_add_f32_e32 v66, 1.0, v66
	v_add_f32_e32 v67, 1.0, v67
	v_rcp_f32_e32 v66, v66
	v_rcp_f32_e32 v67, v67
	v_pk_mul_f32 v[70:71], v[70:71], v[88:89] op_sel_hi:[1,0]
	v_pk_mul_f32 v[68:69], v[68:69], v[88:89] op_sel_hi:[1,0]
	v_exp_f32_e64 v70, -v70
	v_exp_f32_e64 v71, -v71
	v_add_f32_e32 v70, 1.0, v70
	v_add_f32_e32 v71, 1.0, v71
	v_rcp_f32_e32 v70, v70
	v_rcp_f32_e32 v71, v71
	s_waitcnt vmcnt(0)
; __device__ __forceinline__ unsigned pk2(float lo, float hi) { f32x2 v = {lo, hi}; bf16x2_t b = __builtin_convertvector(v, bf16x2_t); return __builtin_bit_cast(unsigned, b); }
; __device__ __forceinline__ float bflo(unsigned u) { return __uint_as_float(u << 16); }
; __device__ __forceinline__ float bfhi(unsigned u) { return __uint_as_float(u & 0xffff0000u); }
; __device__ __forceinline__ float ex2(float x) { return __builtin_amdgcn_exp2f(x); }
; __device__ __forceinline__ float rcpf_(float x) { return __builtin_amdgcn_rcpf(x); }
;     __device__ __forceinline__ void operator()(const f32x4 (&acc)[2][2][4][2], const pg8::Unit& u, int wr, int wc, int fr, int fq) const {
;     ...
;             for (int m = 0; m < 4; ++m) {
;                 const int row = u.pm * 256 + ai * 128 + wr * 64 + m * 16 + fr;
;                 const float r = rsqrtf(ssf(SSin + row) * (1.0f / D) + EPS) * LOG2E;
;                 float ss = 0.f;
; #pragma unroll
;                 for (int bj = 0; bj < 2; ++bj) {
;                     const int col = u.pn * 256 + bj * 128 + wc * 32 + fq * 8;
;                     const u32x4 hw = *(const u32x4*)(Hin + (size_t)row * D + col);
;                     const u32x4 pw = *(const u32x4*)(PP_ + (size_t)row * D + col);
;                     const f32x4 a0 = acc[ai][bj][m][0] * r, a1 = acc[ai][bj][m][1] * r;
;                     float h[8];
;                     h[0] = bflo(hw.x) + rcpf_(1.0f + ex2(-a0[0])) * bflo(pw.x); h[1] = bfhi(hw.x) + rcpf_(1.0f + ex2(-a0[1])) * bfhi(pw.x);
;                     h[2] = bflo(hw.y) + rcpf_(1.0f + ex2(-a0[2])) * bflo(pw.y); h[3] = bfhi(hw.y) + rcpf_(1.0f + ex2(-a0[3])) * bfhi(pw.y);
;                     h[4] = bflo(hw.z) + rcpf_(1.0f + ex2(-a1[0])) * bflo(pw.z); h[5] = bfhi(hw.z) + rcpf_(1.0f + ex2(-a1[1])) * bfhi(pw.z);
;                     h[6] = bflo(hw.w) + rcpf_(1.0f + ex2(-a1[2])) * bflo(pw.w); h[7] = bfhi(hw.w) + rcpf_(1.0f + ex2(-a1[3])) * bfhi(pw.w);
; #pragma unroll
;                     for (int i = 0; i < 8; ++i) ss += h[i] * h[i];
;                     u32x4 w; w.x = pk2(h[0], h[1]); w.y = pk2(h[2], h[3]); w.z = pk2(h[4], h[5]); w.w = pk2(h[6], h[7]);
;                     *(u32x4*)(Hout + (size_t)row * D + col) = w;
;                 }
;                 ss = xor16_sum(ss); ss = xor32_sum(ss);
;                 if (fq == 0) atomic_addf(SSout + row, ss);
	v_lshlrev_b32_e32 v102, 16, v84
	v_and_b32_e32 v103, 0xffff0000, v84
	v_lshlrev_b32_e32 v84, 16, v85
	v_and_b32_e32 v85, 0xffff0000, v85
	v_pk_fma_f32 v[80:81], v[80:81], v[94:95], v[84:85]
	v_lshlrev_b32_e32 v84, 16, v86
	v_and_b32_e32 v85, 0xffff0000, v86
	v_lshlrev_b32_e32 v94, 16, v96
	v_and_b32_e32 v95, 0xffff0000, v96
	v_pk_fma_f32 v[84:85], v[74:75], v[94:95], v[84:85]
	v_exp_f32_e64 v74, -v76
	v_exp_f32_e64 v75, -v77
	v_pk_fma_f32 v[78:79], v[78:79], v[104:105], v[102:103]
	v_lshlrev_b32_e32 v76, 16, v87
	v_add_f32_e32 v74, 1.0, v74
	v_add_f32_e32 v75, 1.0, v75
	v_rcp_f32_e32 v74, v74
	v_rcp_f32_e32 v75, v75
	v_and_b32_e32 v77, 0xffff0000, v87
	v_lshlrev_b32_e32 v86, 16, v97
	v_and_b32_e32 v87, 0xffff0000, v97
	v_pk_fma_f32 v[94:95], v[74:75], v[86:87], v[76:77]
	v_mul_f32_e32 v74, v79, v79
	v_pk_fma_f32 v[74:75], v[78:79], v[78:79], v[74:75] op_sel_hi:[1,1,0]
	v_mul_f32_e32 v76, v81, v81
	v_pk_fma_f32 v[74:75], v[80:81], v[80:81], v[74:75]
	s_nop 0
	v_pk_add_f32 v[74:75], v[76:77], v[74:75] op_sel_hi:[0,1]
	v_pk_fma_f32 v[74:75], v[84:85], v[84:85], v[74:75]
	v_mul_f32_e32 v76, v85, v85
	v_pk_add_f32 v[74:75], v[76:77], v[74:75] op_sel_hi:[0,1]
	v_pk_fma_f32 v[74:75], v[94:95], v[94:95], v[74:75]
	v_mul_f32_e32 v76, v95, v95
	v_pk_add_f32 v[86:87], v[76:77], v[74:75] op_sel_hi:[0,1]
	v_cvt_pk_bf16_f32 v74, v78, v79
	v_lshl_add_u64 v[78:79], s[46:47], 0, v[100:101]
	v_cvt_pk_bf16_f32 v75, v80, v81
	v_cvt_pk_bf16_f32 v76, v84, v85
	v_cvt_pk_bf16_f32 v77, v94, v95
	v_lshl_add_u64 v[84:85], v[78:79], 0, v[142:143]
	global_store_dwordx4 v[84:85], v[74:77], off
	global_load_dwordx4 v[78:81], v[90:91], off offset:256
	global_load_dwordx4 v[74:77], v[92:93], off offset:256
	s_waitcnt vmcnt(0)
	v_lshlrev_b32_e32 v88, 16, v78
	v_and_b32_e32 v89, 0xffff0000, v78
	v_lshlrev_b32_e32 v90, 16, v74
	v_and_b32_e32 v91, 0xffff0000, v74
	v_lshlrev_b32_e32 v78, 16, v79
	v_and_b32_e32 v79, 0xffff0000, v79
	v_lshlrev_b32_e32 v74, 16, v75
	v_and_b32_e32 v75, 0xffff0000, v75
	v_pk_fma_f32 v[72:73], v[72:73], v[74:75], v[78:79]
	v_lshlrev_b32_e32 v74, 16, v80
	v_and_b32_e32 v75, 0xffff0000, v80
	v_lshlrev_b32_e32 v78, 16, v76
	v_and_b32_e32 v79, 0xffff0000, v76
	v_pk_fma_f32 v[74:75], v[66:67], v[78:79], v[74:75]
	v_exp_f32_e64 v66, -v68
	v_exp_f32_e64 v67, -v69
	v_pk_fma_f32 v[70:71], v[70:71], v[90:91], v[88:89]
	v_lshlrev_b32_e32 v68, 16, v81
	v_add_f32_e32 v66, 1.0, v66
	v_add_f32_e32 v67, 1.0, v67
	v_rcp_f32_e32 v66, v66
	v_rcp_f32_e32 v67, v67
	v_and_b32_e32 v69, 0xffff0000, v81
	v_lshlrev_b32_e32 v76, 16, v77
	v_and_b32_e32 v77, 0xffff0000, v77
	v_pk_fma_f32 v[76:77], v[66:67], v[76:77], v[68:69]
	v_pk_fma_f32 v[66:67], v[70:71], v[70:71], v[86:87]
	v_mul_f32_e32 v68, v71, v71
	v_pk_add_f32 v[66:67], v[68:69], v[66:67] op_sel_hi:[0,1]
	v_pk_fma_f32 v[66:67], v[72:73], v[72:73], v[66:67]
	v_mul_f32_e32 v68, v73, v73
	v_pk_add_f32 v[66:67], v[68:69], v[66:67] op_sel_hi:[0,1]
	v_pk_fma_f32 v[66:67], v[74:75], v[74:75], v[66:67]
	v_mul_f32_e32 v68, v75, v75
	v_pk_add_f32 v[66:67], v[68:69], v[66:67] op_sel_hi:[0,1]
	v_pk_fma_f32 v[66:67], v[76:77], v[76:77], v[66:67]
	v_mul_f32_e32 v68, v77, v77
	v_pk_add_f32 v[78:79], v[68:69], v[66:67] op_sel_hi:[0,1]
	v_cvt_pk_bf16_f32 v66, v70, v71
	v_cvt_pk_bf16_f32 v67, v72, v73
	v_cvt_pk_bf16_f32 v68, v74, v75
	v_cvt_pk_bf16_f32 v69, v76, v77
	global_store_dwordx4 v[84:85], v[66:69], off offset:256
	s_nop 1
	v_mov_b32_e32 v66, v78
	s_nop 1
	v_permlane16_swap_b32_e32 v78, v66
	v_add_f32_e32 v66, v78, v66
	v_mov_b32_e32 v67, v66
	s_nop 1
	v_permlane32_swap_b32_e32 v66, v67
	s_and_saveexec_b64 s[34:35], s[42:43]
	s_cbranch_execz .LBB0_1864
	v_add_f32_e32 v66, v66, v67
	s_mov_b32 s1, 0x49800000
	v_fma_f32 v66, v66, s1, 0.5
	v_trunc_f32_e32 v66, v66
	v_mul_f32_e32 v67, 0x2f800000, v66
	v_floor_f32_e32 v67, v67
	v_fmac_f32_e32 v66, 0xcf800000, v67
	v_cvt_u32_f32_e32 v66, v66
	v_cvt_u32_f32_e32 v67, v67
	v_lshl_add_u64 v[68:69], v[82:83], 3, s[52:53]
	global_atomic_add_x2 v[68:69], v[66:67], off
.LBB0_1864:
	s_or_b64 exec, exec, s[34:35]
	global_load_dwordx2 v[68:69], v[144:145], off offset:1024
	v_add_u32_e32 v66, 0x80, v146
	v_ashrrev_i32_e32 v67, 31, v66
	v_lshlrev_b64 v[82:83], 11, v[66:67]
	v_lshl_add_u64 v[76:77], s[48:49], 0, v[82:83]
	v_lshl_add_u64 v[76:77], v[76:77], 0, v[142:143]
	global_load_dwordx4 v[78:81], v[76:77], off
	s_waitcnt vmcnt(0)
	v_ffbh_u32_e32 v70, v69
	v_min_u32_e32 v70, 32, v70
	v_lshlrev_b64 v[68:69], v70, v[68:69]
	v_min_u32_e32 v68, 1, v68
	v_or_b32_e32 v68, v69, v68
	v_cvt_f32_u32_e32 v68, v68
	v_sub_u32_e32 v69, 32, v70
	v_lshlrev_b32_e32 v86, 16, v78
	v_and_b32_e32 v87, 0xffff0000, v78
	v_ldexp_f32 v68, v68, v69
	v_mul_f32_e32 v68, 0x35800000, v68
	v_fmamk_f32 v68, v68, 0x3a800000, v196
	v_cmp_gt_f32_e32 vcc, s23, v68
	v_mul_f32_e32 v69, 0x4b800000, v68
	v_lshlrev_b32_e32 v78, 16, v79
	v_cndmask_b32_e32 v68, v68, v69, vcc
	v_rsq_f32_e32 v68, v68
	v_and_b32_e32 v79, 0xffff0000, v79
	v_mul_f32_e32 v69, 0x45800000, v68
	v_cndmask_b32_e32 v68, v68, v69, vcc
	v_mul_f32_e32 v72, 0x3fb8aa3b, v68
	v_lshl_add_u64 v[68:69], s[8:9], 0, v[82:83]
	v_lshl_add_u64 v[74:75], v[68:69], 0, v[142:143]
	global_load_dwordx4 v[68:71], v[74:75], off
	v_pk_mul_f32 v[64:65], v[64:65], v[72:73] op_sel_hi:[1,0]
	v_pk_mul_f32 v[58:59], v[58:59], v[72:73] op_sel_hi:[1,0]
	v_exp_f32_e64 v64, -v64
	v_exp_f32_e64 v65, -v65
	v_exp_f32_e64 v58, -v58
	v_exp_f32_e64 v59, -v59
	v_add_f32_e32 v64, 1.0, v64
	v_add_f32_e32 v65, 1.0, v65
	v_rcp_f32_e32 v64, v64
	v_rcp_f32_e32 v65, v65
	v_add_f32_e32 v58, 1.0, v58
	v_add_f32_e32 v59, 1.0, v59
	v_rcp_f32_e32 v58, v58
	v_rcp_f32_e32 v59, v59
	v_pk_mul_f32 v[62:63], v[62:63], v[72:73] op_sel_hi:[1,0]
	v_pk_mul_f32 v[60:61], v[60:61], v[72:73] op_sel_hi:[1,0]
	v_exp_f32_e64 v62, -v62
	v_exp_f32_e64 v63, -v63
	v_pk_mul_f32 v[56:57], v[56:57], v[72:73] op_sel_hi:[1,0]
	v_pk_mul_f32 v[50:51], v[50:51], v[72:73] op_sel_hi:[1,0]
	v_add_f32_e32 v62, 1.0, v62
	v_add_f32_e32 v63, 1.0, v63
	v_rcp_f32_e32 v62, v62
	v_rcp_f32_e32 v63, v63
	v_exp_f32_e64 v56, -v56
	v_exp_f32_e64 v57, -v57
	v_exp_f32_e64 v50, -v50
	v_exp_f32_e64 v51, -v51
	v_add_f32_e32 v56, 1.0, v56
	v_add_f32_e32 v57, 1.0, v57
	v_rcp_f32_e32 v56, v56
	v_rcp_f32_e32 v57, v57
	v_add_f32_e32 v50, 1.0, v50
	v_add_f32_e32 v51, 1.0, v51
	v_rcp_f32_e32 v50, v50
	v_rcp_f32_e32 v51, v51
	v_pk_mul_f32 v[54:55], v[54:55], v[72:73] op_sel_hi:[1,0]
	v_pk_mul_f32 v[52:53], v[52:53], v[72:73] op_sel_hi:[1,0]
	v_exp_f32_e64 v54, -v54
	v_exp_f32_e64 v55, -v55
	v_add_f32_e32 v54, 1.0, v54
	v_add_f32_e32 v55, 1.0, v55
	v_rcp_f32_e32 v54, v54
	v_rcp_f32_e32 v55, v55
	s_waitcnt vmcnt(0)
; __device__ __forceinline__ unsigned pk2(float lo, float hi) { f32x2 v = {lo, hi}; bf16x2_t b = __builtin_convertvector(v, bf16x2_t); return __builtin_bit_cast(unsigned, b); }
; __device__ __forceinline__ float bflo(unsigned u) { return __uint_as_float(u << 16); }
; __device__ __forceinline__ float bfhi(unsigned u) { return __uint_as_float(u & 0xffff0000u); }
; __device__ __forceinline__ float ex2(float x) { return __builtin_amdgcn_exp2f(x); }
; __device__ __forceinline__ float rcpf_(float x) { return __builtin_amdgcn_rcpf(x); }
;     __device__ __forceinline__ void operator()(const f32x4 (&acc)[2][2][4][2], const pg8::Unit& u, int wr, int wc, int fr, int fq) const {
;     ...
;             for (int m = 0; m < 4; ++m) {
;                 const int row = u.pm * 256 + ai * 128 + wr * 64 + m * 16 + fr;
;                 const float r = rsqrtf(ssf(SSin + row) * (1.0f / D) + EPS) * LOG2E;
;                 float ss = 0.f;
; #pragma unroll
;                 for (int bj = 0; bj < 2; ++bj) {
;                     const int col = u.pn * 256 + bj * 128 + wc * 32 + fq * 8;
;                     const u32x4 hw = *(const u32x4*)(Hin + (size_t)row * D + col);
;                     const u32x4 pw = *(const u32x4*)(PP_ + (size_t)row * D + col);
;                     const f32x4 a0 = acc[ai][bj][m][0] * r, a1 = acc[ai][bj][m][1] * r;
;                     float h[8];
;                     h[0] = bflo(hw.x) + rcpf_(1.0f + ex2(-a0[0])) * bflo(pw.x); h[1] = bfhi(hw.x) + rcpf_(1.0f + ex2(-a0[1])) * bfhi(pw.x);
;                     h[2] = bflo(hw.y) + rcpf_(1.0f + ex2(-a0[2])) * bflo(pw.y); h[3] = bfhi(hw.y) + rcpf_(1.0f + ex2(-a0[3])) * bfhi(pw.y);
;                     h[4] = bflo(hw.z) + rcpf_(1.0f + ex2(-a1[0])) * bflo(pw.z); h[5] = bfhi(hw.z) + rcpf_(1.0f + ex2(-a1[1])) * bfhi(pw.z);
;                     h[6] = bflo(hw.w) + rcpf_(1.0f + ex2(-a1[2])) * bflo(pw.w); h[7] = bfhi(hw.w) + rcpf_(1.0f + ex2(-a1[3])) * bfhi(pw.w);
; #pragma unroll
;                     for (int i = 0; i < 8; ++i) ss += h[i] * h[i];
;                     u32x4 w; w.x = pk2(h[0], h[1]); w.y = pk2(h[2], h[3]); w.z = pk2(h[4], h[5]); w.w = pk2(h[6], h[7]);
;                     *(u32x4*)(Hout + (size_t)row * D + col) = w;
;                 }
;                 ss = xor16_sum(ss); ss = xor32_sum(ss);
;                 if (fq == 0) atomic_addf(SSout + row, ss);
	v_lshlrev_b32_e32 v84, 16, v68
	v_and_b32_e32 v85, 0xffff0000, v68
	v_lshlrev_b32_e32 v68, 16, v69
	v_and_b32_e32 v69, 0xffff0000, v69
	v_pk_fma_f32 v[64:65], v[64:65], v[78:79], v[68:69]
	v_lshlrev_b32_e32 v68, 16, v70
	v_and_b32_e32 v69, 0xffff0000, v70
	v_lshlrev_b32_e32 v78, 16, v80
	v_and_b32_e32 v79, 0xffff0000, v80
	v_pk_fma_f32 v[68:69], v[58:59], v[78:79], v[68:69]
	v_exp_f32_e64 v58, -v60
	v_exp_f32_e64 v59, -v61
	v_pk_fma_f32 v[62:63], v[62:63], v[86:87], v[84:85]
	v_lshlrev_b32_e32 v60, 16, v71
	v_add_f32_e32 v58, 1.0, v58
	v_add_f32_e32 v59, 1.0, v59
	v_rcp_f32_e32 v58, v58
	v_rcp_f32_e32 v59, v59
	v_and_b32_e32 v61, 0xffff0000, v71
	v_lshlrev_b32_e32 v70, 16, v81
	v_and_b32_e32 v71, 0xffff0000, v81
	v_pk_fma_f32 v[78:79], v[58:59], v[70:71], v[60:61]
	v_mul_f32_e32 v58, v63, v63
	v_pk_fma_f32 v[58:59], v[62:63], v[62:63], v[58:59] op_sel_hi:[1,1,0]
	v_mul_f32_e32 v60, v65, v65
	v_pk_fma_f32 v[58:59], v[64:65], v[64:65], v[58:59]
	s_nop 0
	v_pk_add_f32 v[58:59], v[60:61], v[58:59] op_sel_hi:[0,1]
	v_pk_fma_f32 v[58:59], v[68:69], v[68:69], v[58:59]
	v_mul_f32_e32 v60, v69, v69
	v_pk_add_f32 v[58:59], v[60:61], v[58:59] op_sel_hi:[0,1]
	v_pk_fma_f32 v[58:59], v[78:79], v[78:79], v[58:59]
	v_mul_f32_e32 v60, v79, v79
	v_pk_add_f32 v[70:71], v[60:61], v[58:59] op_sel_hi:[0,1]
	v_cvt_pk_bf16_f32 v58, v62, v63
	v_lshl_add_u64 v[62:63], s[46:47], 0, v[82:83]
	v_cvt_pk_bf16_f32 v59, v64, v65
	v_cvt_pk_bf16_f32 v60, v68, v69
	v_cvt_pk_bf16_f32 v61, v78, v79
	v_lshl_add_u64 v[68:69], v[62:63], 0, v[142:143]
	global_store_dwordx4 v[68:69], v[58:61], off
	global_load_dwordx4 v[62:65], v[74:75], off offset:256
	global_load_dwordx4 v[58:61], v[76:77], off offset:256
	s_waitcnt vmcnt(0)
	v_lshlrev_b32_e32 v72, 16, v62
	v_and_b32_e32 v73, 0xffff0000, v62
	v_lshlrev_b32_e32 v74, 16, v58
	v_and_b32_e32 v75, 0xffff0000, v58
	v_lshlrev_b32_e32 v62, 16, v63
	v_and_b32_e32 v63, 0xffff0000, v63
	v_lshlrev_b32_e32 v58, 16, v59
	v_and_b32_e32 v59, 0xffff0000, v59
	v_pk_fma_f32 v[56:57], v[56:57], v[58:59], v[62:63]
	v_lshlrev_b32_e32 v58, 16, v64
	v_and_b32_e32 v59, 0xffff0000, v64
	v_lshlrev_b32_e32 v62, 16, v60
	v_and_b32_e32 v63, 0xffff0000, v60
	v_pk_fma_f32 v[58:59], v[50:51], v[62:63], v[58:59]
	v_exp_f32_e64 v50, -v52
	v_exp_f32_e64 v51, -v53
	v_pk_fma_f32 v[54:55], v[54:55], v[74:75], v[72:73]
	v_lshlrev_b32_e32 v52, 16, v65
	v_add_f32_e32 v50, 1.0, v50
	v_add_f32_e32 v51, 1.0, v51
	v_rcp_f32_e32 v50, v50
	v_rcp_f32_e32 v51, v51
	v_and_b32_e32 v53, 0xffff0000, v65
	v_lshlrev_b32_e32 v60, 16, v61
	v_and_b32_e32 v61, 0xffff0000, v61
	v_pk_fma_f32 v[60:61], v[50:51], v[60:61], v[52:53]
	v_pk_fma_f32 v[50:51], v[54:55], v[54:55], v[70:71]
	v_mul_f32_e32 v52, v55, v55
	v_pk_add_f32 v[50:51], v[52:53], v[50:51] op_sel_hi:[0,1]
	v_pk_fma_f32 v[50:51], v[56:57], v[56:57], v[50:51]
	v_mul_f32_e32 v52, v57, v57
	v_pk_add_f32 v[50:51], v[52:53], v[50:51] op_sel_hi:[0,1]
	v_pk_fma_f32 v[50:51], v[58:59], v[58:59], v[50:51]
	v_mul_f32_e32 v52, v59, v59
	v_pk_add_f32 v[50:51], v[52:53], v[50:51] op_sel_hi:[0,1]
	v_pk_fma_f32 v[50:51], v[60:61], v[60:61], v[50:51]
	v_mul_f32_e32 v52, v61, v61
	v_pk_add_f32 v[62:63], v[52:53], v[50:51] op_sel_hi:[0,1]
	v_cvt_pk_bf16_f32 v50, v54, v55
	v_cvt_pk_bf16_f32 v51, v56, v57
	v_cvt_pk_bf16_f32 v52, v58, v59
	v_cvt_pk_bf16_f32 v53, v60, v61
	global_store_dwordx4 v[68:69], v[50:53], off offset:256
	s_nop 1
	v_mov_b32_e32 v50, v62
	s_nop 1
	v_permlane16_swap_b32_e32 v62, v50
	v_add_f32_e32 v50, v62, v50
	v_mov_b32_e32 v51, v50
	s_nop 1
	v_permlane32_swap_b32_e32 v50, v51
	s_and_saveexec_b64 s[34:35], s[42:43]
	s_cbranch_execz .LBB0_1866
	v_add_f32_e32 v50, v50, v51
	s_mov_b32 s1, 0x49800000
	v_fma_f32 v50, v50, s1, 0.5
	v_trunc_f32_e32 v50, v50
	v_mul_f32_e32 v51, 0x2f800000, v50
	v_floor_f32_e32 v51, v51
	v_fmac_f32_e32 v50, 0xcf800000, v51
	v_cvt_u32_f32_e32 v50, v50
	v_cvt_u32_f32_e32 v51, v51
	v_lshl_add_u64 v[52:53], v[66:67], 3, s[52:53]
	global_atomic_add_x2 v[52:53], v[50:51], off
.LBB0_1866:
	s_or_b64 exec, exec, s[34:35]
	global_load_dwordx2 v[52:53], v[144:145], off offset:1152
	v_add_u32_e32 v50, 0x90, v146
	v_ashrrev_i32_e32 v51, 31, v50
	v_lshlrev_b64 v[66:67], 11, v[50:51]
	v_lshl_add_u64 v[60:61], s[48:49], 0, v[66:67]
	v_lshl_add_u64 v[60:61], v[60:61], 0, v[142:143]
	global_load_dwordx4 v[62:65], v[60:61], off
	s_waitcnt vmcnt(0)
	v_ffbh_u32_e32 v54, v53
	v_min_u32_e32 v54, 32, v54
	v_lshlrev_b64 v[52:53], v54, v[52:53]
	v_min_u32_e32 v52, 1, v52
	v_or_b32_e32 v52, v53, v52
	v_cvt_f32_u32_e32 v52, v52
	v_sub_u32_e32 v53, 32, v54
	v_lshlrev_b32_e32 v70, 16, v62
	v_and_b32_e32 v71, 0xffff0000, v62
	v_ldexp_f32 v52, v52, v53
	v_mul_f32_e32 v52, 0x35800000, v52
	v_fmamk_f32 v52, v52, 0x3a800000, v196
	v_cmp_gt_f32_e32 vcc, s23, v52
	v_mul_f32_e32 v53, 0x4b800000, v52
	v_lshlrev_b32_e32 v62, 16, v63
	v_cndmask_b32_e32 v52, v52, v53, vcc
	v_rsq_f32_e32 v52, v52
	v_and_b32_e32 v63, 0xffff0000, v63
	v_mul_f32_e32 v53, 0x45800000, v52
	v_cndmask_b32_e32 v52, v52, v53, vcc
	v_mul_f32_e32 v56, 0x3fb8aa3b, v52
	v_lshl_add_u64 v[52:53], s[8:9], 0, v[66:67]
	v_lshl_add_u64 v[58:59], v[52:53], 0, v[142:143]
	global_load_dwordx4 v[52:55], v[58:59], off
	v_pk_mul_f32 v[48:49], v[48:49], v[56:57] op_sel_hi:[1,0]
	v_pk_mul_f32 v[42:43], v[42:43], v[56:57] op_sel_hi:[1,0]
	v_exp_f32_e64 v48, -v48
	v_exp_f32_e64 v49, -v49
	v_exp_f32_e64 v42, -v42
	v_exp_f32_e64 v43, -v43
	v_add_f32_e32 v48, 1.0, v48
	v_add_f32_e32 v49, 1.0, v49
	v_rcp_f32_e32 v48, v48
	v_rcp_f32_e32 v49, v49
	v_add_f32_e32 v42, 1.0, v42
	v_add_f32_e32 v43, 1.0, v43
	v_rcp_f32_e32 v42, v42
	v_rcp_f32_e32 v43, v43
	v_pk_mul_f32 v[46:47], v[46:47], v[56:57] op_sel_hi:[1,0]
	v_pk_mul_f32 v[44:45], v[44:45], v[56:57] op_sel_hi:[1,0]
	v_exp_f32_e64 v46, -v46
	v_exp_f32_e64 v47, -v47
	v_pk_mul_f32 v[40:41], v[40:41], v[56:57] op_sel_hi:[1,0]
	v_pk_mul_f32 v[34:35], v[34:35], v[56:57] op_sel_hi:[1,0]
	v_add_f32_e32 v46, 1.0, v46
	v_add_f32_e32 v47, 1.0, v47
	v_rcp_f32_e32 v46, v46
	v_rcp_f32_e32 v47, v47
	v_exp_f32_e64 v40, -v40
	v_exp_f32_e64 v41, -v41
	v_exp_f32_e64 v34, -v34
	v_exp_f32_e64 v35, -v35
	v_add_f32_e32 v40, 1.0, v40
	v_add_f32_e32 v41, 1.0, v41
	v_rcp_f32_e32 v40, v40
	v_rcp_f32_e32 v41, v41
	v_add_f32_e32 v34, 1.0, v34
	v_add_f32_e32 v35, 1.0, v35
	v_rcp_f32_e32 v34, v34
	v_rcp_f32_e32 v35, v35
	v_pk_mul_f32 v[38:39], v[38:39], v[56:57] op_sel_hi:[1,0]
	v_pk_mul_f32 v[36:37], v[36:37], v[56:57] op_sel_hi:[1,0]
	v_exp_f32_e64 v38, -v38
	v_exp_f32_e64 v39, -v39
	v_add_f32_e32 v38, 1.0, v38
	v_add_f32_e32 v39, 1.0, v39
	v_rcp_f32_e32 v38, v38
	v_rcp_f32_e32 v39, v39
	s_waitcnt vmcnt(0)
; __device__ __forceinline__ unsigned pk2(float lo, float hi) { f32x2 v = {lo, hi}; bf16x2_t b = __builtin_convertvector(v, bf16x2_t); return __builtin_bit_cast(unsigned, b); }
; __device__ __forceinline__ float bflo(unsigned u) { return __uint_as_float(u << 16); }
; __device__ __forceinline__ float bfhi(unsigned u) { return __uint_as_float(u & 0xffff0000u); }
; __device__ __forceinline__ float ex2(float x) { return __builtin_amdgcn_exp2f(x); }
; __device__ __forceinline__ float rcpf_(float x) { return __builtin_amdgcn_rcpf(x); }
;     __device__ __forceinline__ void operator()(const f32x4 (&acc)[2][2][4][2], const pg8::Unit& u, int wr, int wc, int fr, int fq) const {
;     ...
;                 const int row = u.pm * 256 + ai * 128 + wr * 64 + m * 16 + fr;
;                 const float r = rsqrtf(ssf(SSin + row) * (1.0f / D) + EPS) * LOG2E;
;                 float ss = 0.f;
; #pragma unroll
;                 for (int bj = 0; bj < 2; ++bj) {
;                     const int col = u.pn * 256 + bj * 128 + wc * 32 + fq * 8;
;                     const u32x4 hw = *(const u32x4*)(Hin + (size_t)row * D + col);
;                     const u32x4 pw = *(const u32x4*)(PP_ + (size_t)row * D + col);
;                     const f32x4 a0 = acc[ai][bj][m][0] * r, a1 = acc[ai][bj][m][1] * r;
;                     float h[8];
;                     h[0] = bflo(hw.x) + rcpf_(1.0f + ex2(-a0[0])) * bflo(pw.x); h[1] = bfhi(hw.x) + rcpf_(1.0f + ex2(-a0[1])) * bfhi(pw.x);
;                     h[2] = bflo(hw.y) + rcpf_(1.0f + ex2(-a0[2])) * bflo(pw.y); h[3] = bfhi(hw.y) + rcpf_(1.0f + ex2(-a0[3])) * bfhi(pw.y);
;                     h[4] = bflo(hw.z) + rcpf_(1.0f + ex2(-a1[0])) * bflo(pw.z); h[5] = bfhi(hw.z) + rcpf_(1.0f + ex2(-a1[1])) * bfhi(pw.z);
;                     h[6] = bflo(hw.w) + rcpf_(1.0f + ex2(-a1[2])) * bflo(pw.w); h[7] = bfhi(hw.w) + rcpf_(1.0f + ex2(-a1[3])) * bfhi(pw.w);
; #pragma unroll
;                     for (int i = 0; i < 8; ++i) ss += h[i] * h[i];
;                     u32x4 w; w.x = pk2(h[0], h[1]); w.y = pk2(h[2], h[3]); w.z = pk2(h[4], h[5]); w.w = pk2(h[6], h[7]);
;                     *(u32x4*)(Hout + (size_t)row * D + col) = w;
;                 }
;                 ss = xor16_sum(ss); ss = xor32_sum(ss);
;                 if (fq == 0) atomic_addf(SSout + row, ss);
	v_lshlrev_b32_e32 v68, 16, v52
	v_and_b32_e32 v69, 0xffff0000, v52
	v_lshlrev_b32_e32 v52, 16, v53
	v_and_b32_e32 v53, 0xffff0000, v53
	v_pk_fma_f32 v[48:49], v[48:49], v[62:63], v[52:53]
	v_lshlrev_b32_e32 v52, 16, v54
	v_and_b32_e32 v53, 0xffff0000, v54
	v_lshlrev_b32_e32 v62, 16, v64
	v_and_b32_e32 v63, 0xffff0000, v64
	v_pk_fma_f32 v[52:53], v[42:43], v[62:63], v[52:53]
	v_exp_f32_e64 v42, -v44
	v_exp_f32_e64 v43, -v45
	v_pk_fma_f32 v[46:47], v[46:47], v[70:71], v[68:69]
	v_lshlrev_b32_e32 v44, 16, v55
	v_add_f32_e32 v42, 1.0, v42
	v_add_f32_e32 v43, 1.0, v43
	v_rcp_f32_e32 v42, v42
	v_rcp_f32_e32 v43, v43
	v_and_b32_e32 v45, 0xffff0000, v55
	v_lshlrev_b32_e32 v54, 16, v65
	v_and_b32_e32 v55, 0xffff0000, v65
	v_pk_fma_f32 v[62:63], v[42:43], v[54:55], v[44:45]
	v_mul_f32_e32 v42, v47, v47
	v_pk_fma_f32 v[42:43], v[46:47], v[46:47], v[42:43] op_sel_hi:[1,1,0]
	v_mul_f32_e32 v44, v49, v49
	v_pk_fma_f32 v[42:43], v[48:49], v[48:49], v[42:43]
	s_nop 0
	v_pk_add_f32 v[42:43], v[44:45], v[42:43] op_sel_hi:[0,1]
	v_pk_fma_f32 v[42:43], v[52:53], v[52:53], v[42:43]
	v_mul_f32_e32 v44, v53, v53
	v_pk_add_f32 v[42:43], v[44:45], v[42:43] op_sel_hi:[0,1]
	v_pk_fma_f32 v[42:43], v[62:63], v[62:63], v[42:43]
	v_mul_f32_e32 v44, v63, v63
	v_pk_add_f32 v[54:55], v[44:45], v[42:43] op_sel_hi:[0,1]
	v_cvt_pk_bf16_f32 v42, v46, v47
	v_lshl_add_u64 v[46:47], s[46:47], 0, v[66:67]
	v_cvt_pk_bf16_f32 v43, v48, v49
	v_cvt_pk_bf16_f32 v44, v52, v53
	v_cvt_pk_bf16_f32 v45, v62, v63
	v_lshl_add_u64 v[52:53], v[46:47], 0, v[142:143]
	global_store_dwordx4 v[52:53], v[42:45], off
	global_load_dwordx4 v[46:49], v[58:59], off offset:256
	global_load_dwordx4 v[42:45], v[60:61], off offset:256
	s_waitcnt vmcnt(0)
	v_lshlrev_b32_e32 v56, 16, v46
	v_and_b32_e32 v57, 0xffff0000, v46
	v_lshlrev_b32_e32 v58, 16, v42
	v_and_b32_e32 v59, 0xffff0000, v42
	v_lshlrev_b32_e32 v46, 16, v47
	v_and_b32_e32 v47, 0xffff0000, v47
	v_lshlrev_b32_e32 v42, 16, v43
	v_and_b32_e32 v43, 0xffff0000, v43
	v_pk_fma_f32 v[40:41], v[40:41], v[42:43], v[46:47]
	v_lshlrev_b32_e32 v42, 16, v48
	v_and_b32_e32 v43, 0xffff0000, v48
	v_lshlrev_b32_e32 v46, 16, v44
	v_and_b32_e32 v47, 0xffff0000, v44
	v_pk_fma_f32 v[42:43], v[34:35], v[46:47], v[42:43]
	v_exp_f32_e64 v34, -v36
	v_exp_f32_e64 v35, -v37
	v_pk_fma_f32 v[38:39], v[38:39], v[58:59], v[56:57]
	v_lshlrev_b32_e32 v36, 16, v49
	v_add_f32_e32 v34, 1.0, v34
	v_add_f32_e32 v35, 1.0, v35
	v_rcp_f32_e32 v34, v34
	v_rcp_f32_e32 v35, v35
	v_and_b32_e32 v37, 0xffff0000, v49
	v_lshlrev_b32_e32 v44, 16, v45
	v_and_b32_e32 v45, 0xffff0000, v45
	v_pk_fma_f32 v[44:45], v[34:35], v[44:45], v[36:37]
	v_pk_fma_f32 v[34:35], v[38:39], v[38:39], v[54:55]
	v_mul_f32_e32 v36, v39, v39
	v_pk_add_f32 v[34:35], v[36:37], v[34:35] op_sel_hi:[0,1]
	v_pk_fma_f32 v[34:35], v[40:41], v[40:41], v[34:35]
	v_mul_f32_e32 v36, v41, v41
	v_pk_add_f32 v[34:35], v[36:37], v[34:35] op_sel_hi:[0,1]
	v_pk_fma_f32 v[34:35], v[42:43], v[42:43], v[34:35]
	v_mul_f32_e32 v36, v43, v43
	v_pk_add_f32 v[34:35], v[36:37], v[34:35] op_sel_hi:[0,1]
	v_pk_fma_f32 v[34:35], v[44:45], v[44:45], v[34:35]
	v_mul_f32_e32 v36, v45, v45
	v_pk_add_f32 v[46:47], v[36:37], v[34:35] op_sel_hi:[0,1]
	v_cvt_pk_bf16_f32 v34, v38, v39
	v_cvt_pk_bf16_f32 v35, v40, v41
	v_cvt_pk_bf16_f32 v36, v42, v43
	v_cvt_pk_bf16_f32 v37, v44, v45
	global_store_dwordx4 v[52:53], v[34:37], off offset:256
	s_nop 1
	v_mov_b32_e32 v34, v46
	s_nop 1
	v_permlane16_swap_b32_e32 v46, v34
	v_add_f32_e32 v34, v46, v34
	v_mov_b32_e32 v35, v34
	s_nop 1
	v_permlane32_swap_b32_e32 v34, v35
	s_and_saveexec_b64 s[34:35], s[42:43]
	s_cbranch_execz .LBB0_1868
	v_add_f32_e32 v34, v34, v35
	s_mov_b32 s1, 0x49800000
	v_fma_f32 v34, v34, s1, 0.5
	v_trunc_f32_e32 v34, v34
	v_mul_f32_e32 v35, 0x2f800000, v34
	v_floor_f32_e32 v35, v35
	v_fmac_f32_e32 v34, 0xcf800000, v35
	v_cvt_u32_f32_e32 v34, v34
	v_cvt_u32_f32_e32 v35, v35
	v_lshl_add_u64 v[36:37], v[50:51], 3, s[52:53]
	global_atomic_add_x2 v[36:37], v[34:35], off
.LBB0_1868:
	s_or_b64 exec, exec, s[34:35]
	global_load_dwordx2 v[36:37], v[144:145], off offset:1280
	v_add_u32_e32 v34, 0xa0, v146
	v_ashrrev_i32_e32 v35, 31, v34
	v_lshlrev_b64 v[50:51], 11, v[34:35]
	v_lshl_add_u64 v[44:45], s[48:49], 0, v[50:51]
	v_lshl_add_u64 v[44:45], v[44:45], 0, v[142:143]
	global_load_dwordx4 v[46:49], v[44:45], off
	s_waitcnt vmcnt(0)
	v_ffbh_u32_e32 v38, v37
	v_min_u32_e32 v38, 32, v38
	v_lshlrev_b64 v[36:37], v38, v[36:37]
	v_min_u32_e32 v36, 1, v36
	v_or_b32_e32 v36, v37, v36
	v_cvt_f32_u32_e32 v36, v36
	v_sub_u32_e32 v37, 32, v38
	v_lshlrev_b32_e32 v54, 16, v46
	v_and_b32_e32 v55, 0xffff0000, v46
	v_ldexp_f32 v36, v36, v37
	v_mul_f32_e32 v36, 0x35800000, v36
	v_fmamk_f32 v36, v36, 0x3a800000, v196
	v_cmp_gt_f32_e32 vcc, s23, v36
	v_mul_f32_e32 v37, 0x4b800000, v36
	v_lshlrev_b32_e32 v46, 16, v47
	v_cndmask_b32_e32 v36, v36, v37, vcc
	v_rsq_f32_e32 v36, v36
	v_and_b32_e32 v47, 0xffff0000, v47
	v_mul_f32_e32 v37, 0x45800000, v36
	v_cndmask_b32_e32 v36, v36, v37, vcc
	v_mul_f32_e32 v40, 0x3fb8aa3b, v36
	v_lshl_add_u64 v[36:37], s[8:9], 0, v[50:51]
	v_lshl_add_u64 v[42:43], v[36:37], 0, v[142:143]
	global_load_dwordx4 v[36:39], v[42:43], off
	v_pk_mul_f32 v[32:33], v[32:33], v[40:41] op_sel_hi:[1,0]
	v_pk_mul_f32 v[26:27], v[26:27], v[40:41] op_sel_hi:[1,0]
	v_exp_f32_e64 v32, -v32
	v_exp_f32_e64 v33, -v33
	v_exp_f32_e64 v26, -v26
	v_exp_f32_e64 v27, -v27
	v_add_f32_e32 v32, 1.0, v32
	v_add_f32_e32 v33, 1.0, v33
	v_rcp_f32_e32 v32, v32
	v_rcp_f32_e32 v33, v33
	v_add_f32_e32 v26, 1.0, v26
	v_add_f32_e32 v27, 1.0, v27
	v_rcp_f32_e32 v26, v26
	v_rcp_f32_e32 v27, v27
	v_pk_mul_f32 v[30:31], v[30:31], v[40:41] op_sel_hi:[1,0]
	v_pk_mul_f32 v[28:29], v[28:29], v[40:41] op_sel_hi:[1,0]
	v_exp_f32_e64 v30, -v30
	v_exp_f32_e64 v31, -v31
	v_pk_mul_f32 v[24:25], v[24:25], v[40:41] op_sel_hi:[1,0]
	v_pk_mul_f32 v[18:19], v[18:19], v[40:41] op_sel_hi:[1,0]
	v_add_f32_e32 v30, 1.0, v30
	v_add_f32_e32 v31, 1.0, v31
	v_rcp_f32_e32 v30, v30
	v_rcp_f32_e32 v31, v31
	v_exp_f32_e64 v24, -v24
	v_exp_f32_e64 v25, -v25
	v_exp_f32_e64 v18, -v18
	v_exp_f32_e64 v19, -v19
	v_add_f32_e32 v24, 1.0, v24
	v_add_f32_e32 v25, 1.0, v25
	v_rcp_f32_e32 v24, v24
	v_rcp_f32_e32 v25, v25
	v_add_f32_e32 v18, 1.0, v18
	v_add_f32_e32 v19, 1.0, v19
	v_rcp_f32_e32 v18, v18
	v_rcp_f32_e32 v19, v19
	v_pk_mul_f32 v[22:23], v[22:23], v[40:41] op_sel_hi:[1,0]
	v_pk_mul_f32 v[20:21], v[20:21], v[40:41] op_sel_hi:[1,0]
	v_exp_f32_e64 v22, -v22
	v_exp_f32_e64 v23, -v23
	v_add_f32_e32 v22, 1.0, v22
	v_add_f32_e32 v23, 1.0, v23
	v_rcp_f32_e32 v22, v22
	v_rcp_f32_e32 v23, v23
	s_waitcnt vmcnt(0)
; __device__ __forceinline__ unsigned pk2(float lo, float hi) { f32x2 v = {lo, hi}; bf16x2_t b = __builtin_convertvector(v, bf16x2_t); return __builtin_bit_cast(unsigned, b); }
; __device__ __forceinline__ float bflo(unsigned u) { return __uint_as_float(u << 16); }
; __device__ __forceinline__ float bfhi(unsigned u) { return __uint_as_float(u & 0xffff0000u); }
; __device__ __forceinline__ float ex2(float x) { return __builtin_amdgcn_exp2f(x); }
; __device__ __forceinline__ float rcpf_(float x) { return __builtin_amdgcn_rcpf(x); }
; __device__ __forceinline__ float xor32_sum(float v) { auto rr = __builtin_amdgcn_permlane32_swap(__float_as_uint(v), __float_as_uint(v), false, false); return __uint_as_float(rr[0]) + __uint_as_float(rr[1]); }
;     __device__ __forceinline__ void operator()(const f32x4 (&acc)[2][2][4][2], const pg8::Unit& u, int wr, int wc, int fr, int fq) const {
;     ...
;                 for (int bj = 0; bj < 2; ++bj) {
;                     const int col = u.pn * 256 + bj * 128 + wc * 32 + fq * 8;
;                     const u32x4 hw = *(const u32x4*)(Hin + (size_t)row * D + col);
;                     const u32x4 pw = *(const u32x4*)(PP_ + (size_t)row * D + col);
;                     const f32x4 a0 = acc[ai][bj][m][0] * r, a1 = acc[ai][bj][m][1] * r;
;                     float h[8];
;                     h[0] = bflo(hw.x) + rcpf_(1.0f + ex2(-a0[0])) * bflo(pw.x); h[1] = bfhi(hw.x) + rcpf_(1.0f + ex2(-a0[1])) * bfhi(pw.x);
;                     h[2] = bflo(hw.y) + rcpf_(1.0f + ex2(-a0[2])) * bflo(pw.y); h[3] = bfhi(hw.y) + rcpf_(1.0f + ex2(-a0[3])) * bfhi(pw.y);
;                     h[4] = bflo(hw.z) + rcpf_(1.0f + ex2(-a1[0])) * bflo(pw.z); h[5] = bfhi(hw.z) + rcpf_(1.0f + ex2(-a1[1])) * bfhi(pw.z);
;                     h[6] = bflo(hw.w) + rcpf_(1.0f + ex2(-a1[2])) * bflo(pw.w); h[7] = bfhi(hw.w) + rcpf_(1.0f + ex2(-a1[3])) * bfhi(pw.w);
; #pragma unroll
;                     for (int i = 0; i < 8; ++i) ss += h[i] * h[i];
;                     u32x4 w; w.x = pk2(h[0], h[1]); w.y = pk2(h[2], h[3]); w.z = pk2(h[4], h[5]); w.w = pk2(h[6], h[7]);
;                     *(u32x4*)(Hout + (size_t)row * D + col) = w;
;                 }
;                 ss = xor16_sum(ss); ss = xor32_sum(ss);
;                 if (fq == 0) atomic_addf(SSout + row, ss);
	v_lshlrev_b32_e32 v52, 16, v36
	v_and_b32_e32 v53, 0xffff0000, v36
	v_lshlrev_b32_e32 v36, 16, v37
	v_and_b32_e32 v37, 0xffff0000, v37
	v_pk_fma_f32 v[32:33], v[32:33], v[46:47], v[36:37]
	v_lshlrev_b32_e32 v36, 16, v38
	v_and_b32_e32 v37, 0xffff0000, v38
	v_lshlrev_b32_e32 v46, 16, v48
	v_and_b32_e32 v47, 0xffff0000, v48
	v_pk_fma_f32 v[36:37], v[26:27], v[46:47], v[36:37]
	v_exp_f32_e64 v26, -v28
	v_exp_f32_e64 v27, -v29
	v_pk_fma_f32 v[30:31], v[30:31], v[54:55], v[52:53]
	v_lshlrev_b32_e32 v28, 16, v39
	v_add_f32_e32 v26, 1.0, v26
	v_add_f32_e32 v27, 1.0, v27
	v_rcp_f32_e32 v26, v26
	v_rcp_f32_e32 v27, v27
	v_and_b32_e32 v29, 0xffff0000, v39
	v_lshlrev_b32_e32 v38, 16, v49
	v_and_b32_e32 v39, 0xffff0000, v49
	v_pk_fma_f32 v[46:47], v[26:27], v[38:39], v[28:29]
	v_mul_f32_e32 v26, v31, v31
	v_pk_fma_f32 v[26:27], v[30:31], v[30:31], v[26:27] op_sel_hi:[1,1,0]
	v_mul_f32_e32 v28, v33, v33
	v_pk_fma_f32 v[26:27], v[32:33], v[32:33], v[26:27]
	s_nop 0
	v_pk_add_f32 v[26:27], v[28:29], v[26:27] op_sel_hi:[0,1]
	v_pk_fma_f32 v[26:27], v[36:37], v[36:37], v[26:27]
	v_mul_f32_e32 v28, v37, v37
	v_pk_add_f32 v[26:27], v[28:29], v[26:27] op_sel_hi:[0,1]
	v_pk_fma_f32 v[26:27], v[46:47], v[46:47], v[26:27]
	v_mul_f32_e32 v28, v47, v47
	v_pk_add_f32 v[38:39], v[28:29], v[26:27] op_sel_hi:[0,1]
	v_cvt_pk_bf16_f32 v26, v30, v31
	v_lshl_add_u64 v[30:31], s[46:47], 0, v[50:51]
	v_cvt_pk_bf16_f32 v27, v32, v33
	v_cvt_pk_bf16_f32 v28, v36, v37
	v_cvt_pk_bf16_f32 v29, v46, v47
	v_lshl_add_u64 v[36:37], v[30:31], 0, v[142:143]
	global_store_dwordx4 v[36:37], v[26:29], off
	global_load_dwordx4 v[30:33], v[42:43], off offset:256
	global_load_dwordx4 v[26:29], v[44:45], off offset:256
	s_waitcnt vmcnt(0)
	v_lshlrev_b32_e32 v40, 16, v30
	v_and_b32_e32 v41, 0xffff0000, v30
	v_lshlrev_b32_e32 v42, 16, v26
	v_and_b32_e32 v43, 0xffff0000, v26
	v_lshlrev_b32_e32 v30, 16, v31
	v_and_b32_e32 v31, 0xffff0000, v31
	v_lshlrev_b32_e32 v26, 16, v27
	v_and_b32_e32 v27, 0xffff0000, v27
	v_pk_fma_f32 v[24:25], v[24:25], v[26:27], v[30:31]
	v_lshlrev_b32_e32 v26, 16, v32
	v_and_b32_e32 v27, 0xffff0000, v32
	v_lshlrev_b32_e32 v30, 16, v28
	v_and_b32_e32 v31, 0xffff0000, v28
	v_pk_fma_f32 v[26:27], v[18:19], v[30:31], v[26:27]
	v_exp_f32_e64 v18, -v20
	v_exp_f32_e64 v19, -v21
	v_pk_fma_f32 v[22:23], v[22:23], v[42:43], v[40:41]
	v_lshlrev_b32_e32 v20, 16, v33
	v_add_f32_e32 v18, 1.0, v18
	v_add_f32_e32 v19, 1.0, v19
	v_rcp_f32_e32 v18, v18
	v_rcp_f32_e32 v19, v19
	v_and_b32_e32 v21, 0xffff0000, v33
	v_lshlrev_b32_e32 v28, 16, v29
	v_and_b32_e32 v29, 0xffff0000, v29
	v_pk_fma_f32 v[28:29], v[18:19], v[28:29], v[20:21]
	v_pk_fma_f32 v[18:19], v[22:23], v[22:23], v[38:39]
	v_mul_f32_e32 v20, v23, v23
	v_pk_add_f32 v[18:19], v[20:21], v[18:19] op_sel_hi:[0,1]
	v_pk_fma_f32 v[18:19], v[24:25], v[24:25], v[18:19]
	v_mul_f32_e32 v20, v25, v25
	v_pk_add_f32 v[18:19], v[20:21], v[18:19] op_sel_hi:[0,1]
	v_pk_fma_f32 v[18:19], v[26:27], v[26:27], v[18:19]
	v_mul_f32_e32 v20, v27, v27
	v_pk_add_f32 v[18:19], v[20:21], v[18:19] op_sel_hi:[0,1]
	v_pk_fma_f32 v[18:19], v[28:29], v[28:29], v[18:19]
	v_mul_f32_e32 v20, v29, v29
	v_pk_add_f32 v[30:31], v[20:21], v[18:19] op_sel_hi:[0,1]
	v_cvt_pk_bf16_f32 v18, v22, v23
	v_cvt_pk_bf16_f32 v19, v24, v25
	v_cvt_pk_bf16_f32 v20, v26, v27
	v_cvt_pk_bf16_f32 v21, v28, v29
	global_store_dwordx4 v[36:37], v[18:21], off offset:256
	s_nop 1
	v_mov_b32_e32 v18, v30
	s_nop 1
	v_permlane16_swap_b32_e32 v30, v18
	v_add_f32_e32 v18, v30, v18
	v_mov_b32_e32 v19, v18
	s_nop 1
	v_permlane32_swap_b32_e32 v18, v19
	s_and_saveexec_b64 s[34:35], s[42:43]
	s_cbranch_execz .LBB0_1870
	v_add_f32_e32 v18, v18, v19
	s_mov_b32 s1, 0x49800000
	v_fma_f32 v18, v18, s1, 0.5
	v_trunc_f32_e32 v18, v18
	v_mul_f32_e32 v19, 0x2f800000, v18
	v_floor_f32_e32 v19, v19
	v_fmac_f32_e32 v18, 0xcf800000, v19
	v_cvt_u32_f32_e32 v18, v18
	v_cvt_u32_f32_e32 v19, v19
	v_lshl_add_u64 v[20:21], v[34:35], 3, s[52:53]
	global_atomic_add_x2 v[20:21], v[18:19], off
; __device__ __forceinline__ unsigned pk2(float lo, float hi) { f32x2 v = {lo, hi}; bf16x2_t b = __builtin_convertvector(v, bf16x2_t); return __builtin_bit_cast(unsigned, b); }
; __device__ __forceinline__ float bflo(unsigned u) { return __uint_as_float(u << 16); }
; __device__ __forceinline__ float bfhi(unsigned u) { return __uint_as_float(u & 0xffff0000u); }
; __device__ __forceinline__ float ex2(float x) { return __builtin_amdgcn_exp2f(x); }
; __device__ __forceinline__ float rcpf_(float x) { return __builtin_amdgcn_rcpf(x); }
;     __device__ __forceinline__ void operator()(const f32x4 (&acc)[2][2][4][2], const pg8::Unit& u, int wr, int wc, int fr, int fq) const {
;     ...
;                 const int row = u.pm * 256 + ai * 128 + wr * 64 + m * 16 + fr;
;                 const float r = rsqrtf(ssf(SSin + row) * (1.0f / D) + EPS) * LOG2E;
;                 float ss = 0.f;
; #pragma unroll
;                 for (int bj = 0; bj < 2; ++bj) {
;                     const int col = u.pn * 256 + bj * 128 + wc * 32 + fq * 8;
;                     const u32x4 hw = *(const u32x4*)(Hin + (size_t)row * D + col);
;                     const u32x4 pw = *(const u32x4*)(PP_ + (size_t)row * D + col);
;                     const f32x4 a0 = acc[ai][bj][m][0] * r, a1 = acc[ai][bj][m][1] * r;
;                     float h[8];
;                     h[0] = bflo(hw.x) + rcpf_(1.0f + ex2(-a0[0])) * bflo(pw.x); h[1] = bfhi(hw.x) + rcpf_(1.0f + ex2(-a0[1])) * bfhi(pw.x);
;                     h[2] = bflo(hw.y) + rcpf_(1.0f + ex2(-a0[2])) * bflo(pw.y); h[3] = bfhi(hw.y) + rcpf_(1.0f + ex2(-a0[3])) * bfhi(pw.y);
;                     h[4] = bflo(hw.z) + rcpf_(1.0f + ex2(-a1[0])) * bflo(pw.z); h[5] = bfhi(hw.z) + rcpf_(1.0f + ex2(-a1[1])) * bfhi(pw.z);
;                     h[6] = bflo(hw.w) + rcpf_(1.0f + ex2(-a1[2])) * bflo(pw.w); h[7] = bfhi(hw.w) + rcpf_(1.0f + ex2(-a1[3])) * bfhi(pw.w);
; #pragma unroll
;                     for (int i = 0; i < 8; ++i) ss += h[i] * h[i];
;                     u32x4 w; w.x = pk2(h[0], h[1]); w.y = pk2(h[2], h[3]); w.z = pk2(h[4], h[5]); w.w = pk2(h[6], h[7]);
;                     *(u32x4*)(Hout + (size_t)row * D + col) = w;
;                 }
;                 ss = xor16_sum(ss); ss = xor32_sum(ss);
;                 if (fq == 0) atomic_addf(SSout + row, ss);
.LBB0_1870:
	s_or_b64 exec, exec, s[34:35]
	global_load_dwordx2 v[20:21], v[144:145], off offset:1408
	v_add_u32_e32 v18, 0xb0, v146
	v_ashrrev_i32_e32 v19, 31, v18
	v_lshlrev_b64 v[34:35], 11, v[18:19]
	v_lshl_add_u64 v[28:29], s[48:49], 0, v[34:35]
	v_lshl_add_u64 v[28:29], v[28:29], 0, v[142:143]
	global_load_dwordx4 v[30:33], v[28:29], off
	s_waitcnt vmcnt(0)
	v_ffbh_u32_e32 v22, v21
	v_min_u32_e32 v22, 32, v22
	v_lshlrev_b64 v[20:21], v22, v[20:21]
	v_min_u32_e32 v20, 1, v20
	v_or_b32_e32 v20, v21, v20
	v_cvt_f32_u32_e32 v20, v20
	v_sub_u32_e32 v21, 32, v22
	v_lshlrev_b32_e32 v38, 16, v30
	v_and_b32_e32 v39, 0xffff0000, v30
	v_ldexp_f32 v20, v20, v21
	v_mul_f32_e32 v20, 0x35800000, v20
	v_fmamk_f32 v20, v20, 0x3a800000, v196
	v_cmp_gt_f32_e32 vcc, s23, v20
	v_mul_f32_e32 v21, 0x4b800000, v20
	v_lshlrev_b32_e32 v30, 16, v31
	v_cndmask_b32_e32 v20, v20, v21, vcc
	v_rsq_f32_e32 v20, v20
	v_and_b32_e32 v31, 0xffff0000, v31
	v_mul_f32_e32 v21, 0x45800000, v20
	v_cndmask_b32_e32 v20, v20, v21, vcc
	v_mul_f32_e32 v24, 0x3fb8aa3b, v20
	v_lshl_add_u64 v[20:21], s[8:9], 0, v[34:35]
	v_lshl_add_u64 v[26:27], v[20:21], 0, v[142:143]
	global_load_dwordx4 v[20:23], v[26:27], off
	v_pk_mul_f32 v[16:17], v[16:17], v[24:25] op_sel_hi:[1,0]
	v_pk_mul_f32 v[10:11], v[10:11], v[24:25] op_sel_hi:[1,0]
	v_exp_f32_e64 v16, -v16
	v_exp_f32_e64 v17, -v17
	v_exp_f32_e64 v10, -v10
	v_exp_f32_e64 v11, -v11
	v_add_f32_e32 v16, 1.0, v16
	v_add_f32_e32 v17, 1.0, v17
	v_rcp_f32_e32 v16, v16
	v_rcp_f32_e32 v17, v17
	v_add_f32_e32 v10, 1.0, v10
	v_add_f32_e32 v11, 1.0, v11
	v_rcp_f32_e32 v10, v10
	v_rcp_f32_e32 v11, v11
	v_pk_mul_f32 v[14:15], v[14:15], v[24:25] op_sel_hi:[1,0]
	v_pk_mul_f32 v[12:13], v[12:13], v[24:25] op_sel_hi:[1,0]
	v_exp_f32_e64 v14, -v14
	v_exp_f32_e64 v15, -v15
	v_pk_mul_f32 v[8:9], v[8:9], v[24:25] op_sel_hi:[1,0]
	v_pk_mul_f32 v[2:3], v[2:3], v[24:25] op_sel_hi:[1,0]
	v_add_f32_e32 v14, 1.0, v14
	v_add_f32_e32 v15, 1.0, v15
	v_rcp_f32_e32 v14, v14
	v_rcp_f32_e32 v15, v15
	v_exp_f32_e64 v8, -v8
	v_exp_f32_e64 v9, -v9
	v_exp_f32_e64 v2, -v2
	v_exp_f32_e64 v3, -v3
	v_add_f32_e32 v8, 1.0, v8
	v_add_f32_e32 v9, 1.0, v9
	v_rcp_f32_e32 v8, v8
	v_rcp_f32_e32 v9, v9
	v_add_f32_e32 v2, 1.0, v2
	v_add_f32_e32 v3, 1.0, v3
	v_rcp_f32_e32 v2, v2
	v_rcp_f32_e32 v3, v3
	v_pk_mul_f32 v[6:7], v[6:7], v[24:25] op_sel_hi:[1,0]
	v_pk_mul_f32 v[4:5], v[4:5], v[24:25] op_sel_hi:[1,0]
	v_exp_f32_e64 v6, -v6
	v_exp_f32_e64 v7, -v7
	v_add_f32_e32 v6, 1.0, v6
	v_add_f32_e32 v7, 1.0, v7
	v_rcp_f32_e32 v6, v6
	v_rcp_f32_e32 v7, v7
	s_waitcnt vmcnt(0)
	v_lshlrev_b32_e32 v36, 16, v20
	v_and_b32_e32 v37, 0xffff0000, v20
	v_lshlrev_b32_e32 v20, 16, v21
	v_and_b32_e32 v21, 0xffff0000, v21
	v_pk_fma_f32 v[16:17], v[16:17], v[30:31], v[20:21]
	v_lshlrev_b32_e32 v20, 16, v22
	v_and_b32_e32 v21, 0xffff0000, v22
	v_lshlrev_b32_e32 v30, 16, v32
	v_and_b32_e32 v31, 0xffff0000, v32
	v_pk_fma_f32 v[20:21], v[10:11], v[30:31], v[20:21]
	v_exp_f32_e64 v10, -v12
	v_exp_f32_e64 v11, -v13
	v_pk_fma_f32 v[14:15], v[14:15], v[38:39], v[36:37]
	v_lshlrev_b32_e32 v12, 16, v23
	v_add_f32_e32 v10, 1.0, v10
	v_add_f32_e32 v11, 1.0, v11
	v_rcp_f32_e32 v10, v10
	v_rcp_f32_e32 v11, v11
	v_and_b32_e32 v13, 0xffff0000, v23
	v_lshlrev_b32_e32 v22, 16, v33
	v_and_b32_e32 v23, 0xffff0000, v33
	v_pk_fma_f32 v[30:31], v[10:11], v[22:23], v[12:13]
	v_mul_f32_e32 v10, v15, v15
	v_pk_fma_f32 v[10:11], v[14:15], v[14:15], v[10:11] op_sel_hi:[1,1,0]
	v_mul_f32_e32 v12, v17, v17
	v_pk_fma_f32 v[10:11], v[16:17], v[16:17], v[10:11]
	s_nop 0
	v_pk_add_f32 v[10:11], v[12:13], v[10:11] op_sel_hi:[0,1]
	v_pk_fma_f32 v[10:11], v[20:21], v[20:21], v[10:11]
	v_mul_f32_e32 v12, v21, v21
	v_pk_add_f32 v[10:11], v[12:13], v[10:11] op_sel_hi:[0,1]
	v_pk_fma_f32 v[10:11], v[30:31], v[30:31], v[10:11]
	v_mul_f32_e32 v12, v31, v31
	v_pk_add_f32 v[22:23], v[12:13], v[10:11] op_sel_hi:[0,1]
	v_cvt_pk_bf16_f32 v10, v14, v15
	v_lshl_add_u64 v[14:15], s[46:47], 0, v[34:35]
	v_cvt_pk_bf16_f32 v11, v16, v17
	v_cvt_pk_bf16_f32 v12, v20, v21
	v_cvt_pk_bf16_f32 v13, v30, v31
	v_lshl_add_u64 v[20:21], v[14:15], 0, v[142:143]
	global_store_dwordx4 v[20:21], v[10:13], off
	global_load_dwordx4 v[14:17], v[26:27], off offset:256
	global_load_dwordx4 v[10:13], v[28:29], off offset:256
	s_waitcnt vmcnt(0)
	v_lshlrev_b32_e32 v24, 16, v14
	v_and_b32_e32 v25, 0xffff0000, v14
	v_lshlrev_b32_e32 v26, 16, v10
	v_and_b32_e32 v27, 0xffff0000, v10
	v_lshlrev_b32_e32 v14, 16, v15
	v_and_b32_e32 v15, 0xffff0000, v15
	v_lshlrev_b32_e32 v10, 16, v11
	v_and_b32_e32 v11, 0xffff0000, v11
	v_pk_fma_f32 v[8:9], v[8:9], v[10:11], v[14:15]
	v_lshlrev_b32_e32 v10, 16, v16
	v_and_b32_e32 v11, 0xffff0000, v16
	v_lshlrev_b32_e32 v14, 16, v12
	v_and_b32_e32 v15, 0xffff0000, v12
	v_pk_fma_f32 v[10:11], v[2:3], v[14:15], v[10:11]
	v_exp_f32_e64 v2, -v4
	v_exp_f32_e64 v3, -v5
	v_pk_fma_f32 v[6:7], v[6:7], v[26:27], v[24:25]
	v_lshlrev_b32_e32 v4, 16, v17
	v_add_f32_e32 v2, 1.0, v2
	v_add_f32_e32 v3, 1.0, v3
	v_rcp_f32_e32 v2, v2
	v_rcp_f32_e32 v3, v3
	v_and_b32_e32 v5, 0xffff0000, v17
	v_lshlrev_b32_e32 v12, 16, v13
	v_and_b32_e32 v13, 0xffff0000, v13
	v_pk_fma_f32 v[12:13], v[2:3], v[12:13], v[4:5]
	v_pk_fma_f32 v[2:3], v[6:7], v[6:7], v[22:23]
	v_mul_f32_e32 v4, v7, v7
	v_pk_add_f32 v[2:3], v[4:5], v[2:3] op_sel_hi:[0,1]
	v_pk_fma_f32 v[2:3], v[8:9], v[8:9], v[2:3]
	v_mul_f32_e32 v4, v9, v9
	v_pk_add_f32 v[2:3], v[4:5], v[2:3] op_sel_hi:[0,1]
	v_pk_fma_f32 v[2:3], v[10:11], v[10:11], v[2:3]
	v_mul_f32_e32 v4, v11, v11
	v_pk_add_f32 v[2:3], v[4:5], v[2:3] op_sel_hi:[0,1]
	v_pk_fma_f32 v[2:3], v[12:13], v[12:13], v[2:3]
	v_mul_f32_e32 v4, v13, v13
	v_pk_add_f32 v[14:15], v[4:5], v[2:3] op_sel_hi:[0,1]
	v_cvt_pk_bf16_f32 v2, v6, v7
	v_cvt_pk_bf16_f32 v3, v8, v9
	v_cvt_pk_bf16_f32 v4, v10, v11
	v_cvt_pk_bf16_f32 v5, v12, v13
	global_store_dwordx4 v[20:21], v[2:5], off offset:256
	s_nop 1
	v_mov_b32_e32 v2, v14
	s_nop 1
	v_permlane16_swap_b32_e32 v14, v2
	v_add_f32_e32 v2, v14, v2
	v_mov_b32_e32 v3, v2
	s_nop 1
	v_permlane32_swap_b32_e32 v2, v3
	s_and_saveexec_b64 s[34:35], s[42:43]
	s_cbranch_execz .LBB0_1872
	v_add_f32_e32 v2, v2, v3
	s_mov_b32 s1, 0x49800000
	v_fma_f32 v2, v2, s1, 0.5
	v_trunc_f32_e32 v2, v2
	v_mul_f32_e32 v3, 0x2f800000, v2
	v_floor_f32_e32 v3, v3
	v_fmac_f32_e32 v2, 0xcf800000, v3
	v_cvt_u32_f32_e32 v2, v2
	v_cvt_u32_f32_e32 v3, v3
	v_lshl_add_u64 v[4:5], v[18:19], 3, s[52:53]
	global_atomic_add_x2 v[4:5], v[2:3], off
